# cache policy: the prologue's once-read f32 input streams (x, p, weights) loaded with nt so they do not displace the bf16 working set
# speedup vs baseline: 1.0059x; 1.0013x over previous
.LBB0_10:
	s_mov_b32 s16, 0x2aaaaaab
	v_mul_hi_i32 v9, v151, s16
	v_lshrrev_b32_e32 v10, 31, v9
	v_ashrrev_i32_e32 v9, 10, v9
	v_add_u32_e32 v12, v9, v10
	s_mov_b32 s16, 0x1800000
	v_mul_i32_i24_e32 v14, 0x1800, v12
	v_mad_i64_i32 v[10:11], s[16:17], v12, s16, v[6:7]
	v_sub_u32_e32 v15, v151, v14
	s_movk_i32 s16, 0x27f
	v_ashrrev_i32_e32 v13, 31, v12
	v_cmp_lt_i32_e32 vcc, s16, v15
	s_and_saveexec_b64 s[16:17], vcc
	s_xor_b64 s[16:17], exec, s[16:17]
	s_cbranch_execz .LBB0_42
	s_movk_i32 s18, 0x2ff
	v_cmp_lt_u32_e32 vcc, s18, v15
	s_and_saveexec_b64 s[18:19], vcc
	s_xor_b64 s[18:19], exec, s[18:19]
	s_cbranch_execz .LBB0_39
	s_movk_i32 s20, 0x4ff
	v_cmp_lt_u32_e32 vcc, s20, v15
	s_and_saveexec_b64 s[20:21], vcc
	s_xor_b64 s[20:21], exec, s[20:21]
	s_cbranch_execz .LBB0_34
	s_movk_i32 s22, 0xfff
	v_cmp_lt_u32_e32 vcc, s22, v15
	s_and_saveexec_b64 s[22:23], vcc
	s_xor_b64 s[22:23], exec, s[22:23]
	s_cbranch_execz .LBB0_25
	s_movk_i32 s24, 0x157f
	v_lshlrev_b32_e32 v9, 1, v14
	v_cmp_lt_u32_e32 vcc, s24, v15
	v_sub_u32_e32 v9, v82, v9
	s_and_saveexec_b64 s[24:25], vcc
	s_xor_b64 s[24:25], exec, s[24:25]
	s_cbranch_execz .LBB0_22
	v_lshlrev_b32_e32 v14, 5, v14
	s_movk_i32 s26, 0x177f
	v_sub_u32_e32 v14, v80, v14
	v_cmp_lt_u32_e32 vcc, s26, v15
	v_and_b32_e32 v15, 0x3e0, v14
	v_lshlrev_b32_e32 v14, 2, v15
	v_or_b32_e32 v55, v15, v37
	v_or_b32_e32 v54, v15, v77
	v_or_b32_e32 v53, v15, v78
	v_or_b32_e32 v52, v15, v79
	s_and_saveexec_b64 s[26:27], vcc
	s_xor_b64 s[26:27], exec, s[26:27]
	s_cbranch_execz .LBB0_17
	v_readlane_b32 s36, v247, 26
	v_lshlrev_b64 v[12:13], 20, v[12:13]
	v_readlane_b32 s48, v247, 38
	v_readlane_b32 s49, v247, 39
	v_and_b32_e32 v15, 0x1c0, v9
	v_bitop3_b32 v16, v15, v3, s30 bitop3:0xde
	v_lshl_add_u64 v[12:13], s[48:49], 0, v[12:13]
	v_mov_b32_e32 v15, v5
	v_lshl_add_u64 v[12:13], v[12:13], 0, v[14:15]
	v_lshl_add_u64 v[12:13], v[12:13], 0, v[4:5]
	v_lshlrev_b32_e32 v14, 12, v16
	v_lshl_add_u64 v[12:13], v[12:13], 0, v[14:15]
	v_add_co_u32_e32 v14, vcc, s31, v12
	v_bitop3_b32 v9, v9, s30, v83 bitop3:0x6c
	s_nop 0
	v_addc_co_u32_e32 v15, vcc, 0, v13, vcc
	v_add_co_u32_e32 v16, vcc, s34, v12
	s_mov_b64 s[84:85], 0x1780000
	s_nop 0
	v_addc_co_u32_e32 v17, vcc, 0, v13, vcc
	v_add_co_u32_e32 v18, vcc, s3, v12
	v_readlane_b32 s37, v247, 27
	s_nop 0
	v_addc_co_u32_e32 v19, vcc, 0, v13, vcc
	v_add_co_u32_e32 v20, vcc, s35, v12
	v_readlane_b32 s38, v247, 28
	s_nop 0
	v_addc_co_u32_e32 v21, vcc, 0, v13, vcc
	v_add_co_u32_e32 v22, vcc, s52, v12
	v_readlane_b32 s39, v247, 29
	s_nop 0
	v_addc_co_u32_e32 v23, vcc, 0, v13, vcc
	v_add_co_u32_e32 v24, vcc, s53, v12
	v_readlane_b32 s40, v247, 30
	s_nop 0
	v_addc_co_u32_e32 v25, vcc, 0, v13, vcc
	v_add_co_u32_e32 v26, vcc, s54, v12
	v_readlane_b32 s41, v247, 31
	s_nop 0
	v_addc_co_u32_e32 v27, vcc, 0, v13, vcc
	global_load_dword v30, v[12:13], off nt
	global_load_dword v31, v[14:15], off nt
	global_load_dword v32, v[16:17], off nt
	global_load_dword v33, v[18:19], off nt
	global_load_dword v40, v[20:21], off nt
	global_load_dword v41, v[22:23], off nt
	global_load_dword v42, v[24:25], off nt
	global_load_dword v43, v[26:27], off nt
	v_add_co_u32_e32 v14, vcc, s55, v12
	v_readlane_b32 s42, v247, 32
	s_nop 0
	v_addc_co_u32_e32 v15, vcc, 0, v13, vcc
	v_add_co_u32_e32 v16, vcc, s56, v12
	v_readlane_b32 s43, v247, 33
	s_nop 0
	v_addc_co_u32_e32 v17, vcc, 0, v13, vcc
	v_add_co_u32_e32 v18, vcc, s57, v12
	v_readlane_b32 s44, v247, 34
	s_nop 0
	v_addc_co_u32_e32 v19, vcc, 0, v13, vcc
	v_add_co_u32_e32 v20, vcc, s58, v12
	v_readlane_b32 s45, v247, 35
	s_nop 0
	v_addc_co_u32_e32 v21, vcc, 0, v13, vcc
	v_add_co_u32_e32 v22, vcc, s59, v12
	v_readlane_b32 s46, v247, 36
	s_nop 0
	v_addc_co_u32_e32 v23, vcc, 0, v13, vcc
	v_add_co_u32_e32 v24, vcc, s60, v12
	v_readlane_b32 s47, v247, 37
	s_nop 0
	v_addc_co_u32_e32 v25, vcc, 0, v13, vcc
	v_add_co_u32_e32 v26, vcc, s61, v12
	v_readlane_b32 s50, v247, 40
	s_nop 0
	v_addc_co_u32_e32 v27, vcc, 0, v13, vcc
	v_add_co_u32_e32 v28, vcc, s62, v12
	v_readlane_b32 s51, v247, 41
	s_nop 0
	v_addc_co_u32_e32 v29, vcc, 0, v13, vcc
	global_load_dword v44, v[14:15], off nt
	global_load_dword v45, v[16:17], off nt
	global_load_dword v46, v[18:19], off nt
	global_load_dword v47, v[20:21], off nt
	global_load_dword v48, v[22:23], off nt
	global_load_dword v49, v[24:25], off nt
	global_load_dword v50, v[26:27], off nt
	global_load_dword v51, v[28:29], off nt
	v_add_co_u32_e32 v14, vcc, s63, v12
	s_nop 1
	v_addc_co_u32_e32 v15, vcc, 0, v13, vcc
	v_add_co_u32_e32 v16, vcc, s64, v12
	s_nop 1
	v_addc_co_u32_e32 v17, vcc, 0, v13, vcc
	v_add_co_u32_e32 v18, vcc, s65, v12
	s_nop 1
	v_addc_co_u32_e32 v19, vcc, 0, v13, vcc
	v_add_co_u32_e32 v20, vcc, s67, v12
	s_nop 1
	v_addc_co_u32_e32 v21, vcc, 0, v13, vcc
	v_add_co_u32_e32 v22, vcc, s68, v12
	s_nop 1
	v_addc_co_u32_e32 v23, vcc, 0, v13, vcc
	v_add_co_u32_e32 v24, vcc, s69, v12
	s_nop 1
	v_addc_co_u32_e32 v25, vcc, 0, v13, vcc
	v_add_co_u32_e32 v26, vcc, s70, v12
	s_nop 1
	v_addc_co_u32_e32 v27, vcc, 0, v13, vcc
	v_add_co_u32_e32 v28, vcc, s71, v12
	s_nop 1
	v_addc_co_u32_e32 v29, vcc, 0, v13, vcc
	global_load_dword v56, v[14:15], off nt
	global_load_dword v57, v[16:17], off nt
	global_load_dword v58, v[18:19], off nt
	global_load_dword v59, v[20:21], off nt
	global_load_dword v60, v[22:23], off nt
	global_load_dword v61, v[24:25], off nt
	global_load_dword v62, v[26:27], off nt
	s_nop 0
	global_load_dword v28, v[28:29], off nt
	v_add_co_u32_e32 v14, vcc, s72, v12
	s_nop 1
	v_addc_co_u32_e32 v15, vcc, 0, v13, vcc
	v_add_co_u32_e32 v16, vcc, s73, v12
	s_nop 1
	v_addc_co_u32_e32 v17, vcc, 0, v13, vcc
	v_add_co_u32_e32 v18, vcc, s74, v12
	s_nop 1
	v_addc_co_u32_e32 v19, vcc, 0, v13, vcc
	v_add_co_u32_e32 v20, vcc, s75, v12
	s_nop 1
	v_addc_co_u32_e32 v21, vcc, 0, v13, vcc
	v_add_co_u32_e32 v22, vcc, s76, v12
	s_nop 1
	v_addc_co_u32_e32 v23, vcc, 0, v13, vcc
	v_add_co_u32_e32 v24, vcc, s77, v12
	s_nop 1
	v_addc_co_u32_e32 v25, vcc, 0, v13, vcc
	v_add_co_u32_e32 v26, vcc, s78, v12
	s_nop 1
	v_addc_co_u32_e32 v27, vcc, 0, v13, vcc
	v_add_co_u32_e32 v12, vcc, s79, v12
	s_nop 1
	v_addc_co_u32_e32 v13, vcc, 0, v13, vcc
	global_load_dword v14, v[14:15], off nt
	s_nop 0
	global_load_dword v15, v[16:17], off nt
	s_nop 0
	global_load_dword v16, v[18:19], off nt
	global_load_dword v17, v[20:21], off nt
	s_nop 0
	global_load_dword v18, v[22:23], off nt
	global_load_dword v19, v[24:25], off nt
	global_load_dword v20, v[26:27], off nt
	s_nop 0
	global_load_dword v12, v[12:13], off nt
	s_waitcnt vmcnt(30)
	ds_write2_b32 v35, v30, v31 offset1:66
	s_waitcnt vmcnt(28)
	ds_write2_b32 v35, v32, v33 offset0:132 offset1:198
	s_waitcnt vmcnt(26)
	ds_write2_b32 v84, v40, v41 offset0:8 offset1:74
	s_waitcnt vmcnt(24)
	ds_write2_b32 v84, v42, v43 offset0:140 offset1:206
	s_waitcnt vmcnt(22)
	ds_write2_b32 v85, v44, v45 offset0:16 offset1:82
	s_waitcnt vmcnt(20)
	ds_write2_b32 v85, v46, v47 offset0:148 offset1:214
	s_waitcnt vmcnt(18)
	ds_write2_b32 v86, v48, v49 offset0:24 offset1:90
	s_waitcnt vmcnt(16)
	ds_write2_b32 v86, v50, v51 offset0:156 offset1:222
	s_waitcnt vmcnt(14)
	ds_write2_b32 v87, v56, v57 offset0:32 offset1:98
	s_waitcnt vmcnt(12)
	ds_write2_b32 v87, v58, v59 offset0:164 offset1:230
	s_waitcnt vmcnt(10)
	ds_write2_b32 v88, v60, v61 offset0:40 offset1:106
	s_waitcnt vmcnt(8)
	ds_write2_b32 v88, v62, v28 offset0:172 offset1:238
	s_waitcnt vmcnt(6)
	ds_write2_b32 v89, v14, v15 offset0:48 offset1:114
	s_waitcnt vmcnt(4)
	ds_write2_b32 v89, v16, v17 offset0:180 offset1:246
	s_waitcnt vmcnt(2)
	ds_write2_b32 v90, v18, v19 offset0:56 offset1:122
	s_waitcnt vmcnt(0)
	ds_write2_b32 v90, v20, v12 offset0:188 offset1:254
	s_waitcnt lgkmcnt(0)
	ds_read2_b32 v[12:13], v39 offset1:33
	s_waitcnt lgkmcnt(0)
	v_cvt_pk_bf16_f32 v12, v12, v13
	ds_read2_b32 v[14:15], v39 offset0:66 offset1:99
	v_lshlrev_b32_e32 v16, 1, v9
	v_mov_b32_e32 v17, v5
	s_waitcnt lgkmcnt(0)
	v_cvt_pk_bf16_f32 v13, v14, v15
	ds_read2_b32 v[14:15], v39 offset0:132 offset1:165
	v_lshl_add_u64 v[10:11], v[10:11], 0, v[16:17]
	v_mov_b32_e32 v9, v5
	s_waitcnt lgkmcnt(0)
	v_cvt_pk_bf16_f32 v14, v14, v15
	ds_read2_b32 v[18:19], v39 offset0:198 offset1:231
	v_lshl_add_u64 v[10:11], v[10:11], 0, v[8:9]
	v_lshl_add_u64 v[16:17], v[10:11], 0, s[84:85]
	s_waitcnt lgkmcnt(0)
	v_cvt_pk_bf16_f32 v15, v18, v19
	v_lshlrev_b32_e32 v18, 9, v55
	v_mov_b32_e32 v19, v5
	ds_read2_b32 v[10:11], v39 offset0:8 offset1:41
	v_lshl_add_u64 v[18:19], v[16:17], 0, v[18:19]
	global_store_dwordx4 v[18:19], v[12:15], off
	s_waitcnt lgkmcnt(0)
	v_cvt_pk_bf16_f32 v10, v10, v11
	ds_read2_b32 v[12:13], v39 offset0:74 offset1:107
	s_waitcnt lgkmcnt(0)
	v_cvt_pk_bf16_f32 v11, v12, v13
	ds_read2_b32 v[12:13], v39 offset0:140 offset1:173
	v_lshlrev_b32_e32 v18, 9, v54
	v_mov_b32_e32 v19, v5
	s_waitcnt lgkmcnt(0)
	v_cvt_pk_bf16_f32 v12, v12, v13
	ds_read2_b32 v[14:15], v39 offset0:206 offset1:239
	s_waitcnt lgkmcnt(0)
	v_cvt_pk_bf16_f32 v13, v14, v15
	v_lshl_add_u64 v[18:19], v[16:17], 0, v[18:19]
	ds_read2_b32 v[14:15], v39 offset0:16 offset1:49
	global_store_dwordx4 v[18:19], v[10:13], off
	v_lshlrev_b32_e32 v18, 9, v53
	v_mov_b32_e32 v19, v5
	s_waitcnt lgkmcnt(0)
	v_cvt_pk_bf16_f32 v10, v14, v15
	ds_read2_b32 v[12:13], v39 offset0:82 offset1:115
	s_waitcnt lgkmcnt(0)
	v_cvt_pk_bf16_f32 v11, v12, v13
	ds_read2_b32 v[12:13], v39 offset0:148 offset1:181
	s_waitcnt lgkmcnt(0)
	v_cvt_pk_bf16_f32 v12, v12, v13
	ds_read2_b32 v[14:15], v39 offset0:214 offset1:247
	s_waitcnt lgkmcnt(0)
	v_cvt_pk_bf16_f32 v13, v14, v15
	v_lshl_add_u64 v[18:19], v[16:17], 0, v[18:19]
	ds_read2_b32 v[14:15], v39 offset0:24 offset1:57
	global_store_dwordx4 v[18:19], v[10:13], off
	s_waitcnt lgkmcnt(0)
	s_nop 0
	v_cvt_pk_bf16_f32 v10, v14, v15
	ds_read2_b32 v[12:13], v39 offset0:90 offset1:123
	s_waitcnt lgkmcnt(0)
	v_cvt_pk_bf16_f32 v11, v12, v13
	ds_read2_b32 v[12:13], v39 offset0:156 offset1:189
	s_waitcnt lgkmcnt(0)
	v_cvt_pk_bf16_f32 v12, v12, v13
	ds_read2_b32 v[14:15], v39 offset0:222 offset1:255
	s_waitcnt lgkmcnt(0)
	v_cvt_pk_bf16_f32 v13, v14, v15
	v_lshlrev_b32_e32 v14, 9, v52
	v_mov_b32_e32 v15, v5
	v_lshl_add_u64 v[14:15], v[16:17], 0, v[14:15]
	global_store_dwordx4 v[14:15], v[10:13], off
	s_waitcnt lgkmcnt(0)
.LBB0_17:
	s_andn2_saveexec_b64 s[26:27], s[26:27]
	s_cbranch_execz .LBB0_21
	v_readlane_b32 s36, v247, 26
	v_add_u32_e32 v9, 0x1d500, v9
	v_lshlrev_b64 v[16:17], 22, v[12:13]
	v_readlane_b32 s46, v247, 36
	v_readlane_b32 s47, v247, 37
	v_and_b32_e32 v9, 0x1ffc0, v9
	v_or_b32_e32 v13, v9, v3
	v_lshl_add_u64 v[16:17], s[46:47], 0, v[16:17]
	v_mov_b32_e32 v15, v5
	v_lshl_add_u64 v[14:15], v[16:17], 0, v[14:15]
	v_lshlrev_b32_e32 v46, 12, v13
	v_lshl_add_u64 v[44:45], v[14:15], 0, v[4:5]
	v_mov_b32_e32 v47, v5
	v_or_b32_e32 v16, 0x2000, v46
	v_mov_b32_e32 v17, v5
	v_or_b32_e32 v18, 0x4000, v46
	v_mov_b32_e32 v19, v5
	v_or_b32_e32 v20, 0x6000, v46
	v_mov_b32_e32 v21, v5
	v_or_b32_e32 v22, 0x8000, v46
	v_mov_b32_e32 v23, v5
	v_or_b32_e32 v24, 0xa000, v46
	v_mov_b32_e32 v25, v5
	v_or_b32_e32 v26, 0xc000, v46
	v_mov_b32_e32 v27, v5
	v_or_b32_e32 v28, 0xe000, v46
	v_mov_b32_e32 v29, v5
	v_lshl_add_u64 v[14:15], v[44:45], 0, v[46:47]
	v_lshl_add_u64 v[16:17], v[44:45], 0, v[16:17]
	v_lshl_add_u64 v[18:19], v[44:45], 0, v[18:19]
	v_lshl_add_u64 v[20:21], v[44:45], 0, v[20:21]
	v_lshl_add_u64 v[22:23], v[44:45], 0, v[22:23]
	v_lshl_add_u64 v[24:25], v[44:45], 0, v[24:25]
	v_lshl_add_u64 v[26:27], v[44:45], 0, v[26:27]
	v_lshl_add_u64 v[28:29], v[44:45], 0, v[28:29]
	global_load_dword v14, v[14:15], off nt
	s_nop 0
	global_load_dword v15, v[16:17], off nt
	s_nop 0
	global_load_dword v16, v[18:19], off nt
	global_load_dword v17, v[20:21], off nt
	s_nop 0
	global_load_dword v18, v[22:23], off nt
	global_load_dword v19, v[24:25], off nt
	global_load_dword v20, v[26:27], off nt
	global_load_dword v21, v[28:29], off nt
	v_or_b32_e32 v22, 0x10000, v46
	v_mov_b32_e32 v23, v5
	v_or_b32_e32 v24, 0x12000, v46
	v_mov_b32_e32 v25, v5
	v_or_b32_e32 v26, 0x14000, v46
	v_mov_b32_e32 v27, v5
	v_or_b32_e32 v28, 0x16000, v46
	v_mov_b32_e32 v29, v5
	v_or_b32_e32 v30, 0x18000, v46
	v_mov_b32_e32 v31, v5
	v_or_b32_e32 v32, 0x1a000, v46
	v_mov_b32_e32 v33, v5
	v_or_b32_e32 v40, 0x1c000, v46
	v_mov_b32_e32 v41, v5
	v_or_b32_e32 v42, 0x1e000, v46
	v_mov_b32_e32 v43, v5
	v_lshl_add_u64 v[22:23], v[44:45], 0, v[22:23]
	v_lshl_add_u64 v[24:25], v[44:45], 0, v[24:25]
	v_lshl_add_u64 v[26:27], v[44:45], 0, v[26:27]
	v_lshl_add_u64 v[28:29], v[44:45], 0, v[28:29]
	v_lshl_add_u64 v[30:31], v[44:45], 0, v[30:31]
	v_lshl_add_u64 v[32:33], v[44:45], 0, v[32:33]
	v_lshl_add_u64 v[40:41], v[44:45], 0, v[40:41]
	v_lshl_add_u64 v[42:43], v[44:45], 0, v[42:43]
	global_load_dword v22, v[22:23], off nt
	s_nop 0
	global_load_dword v23, v[24:25], off nt
	s_nop 0
	global_load_dword v24, v[26:27], off nt
	global_load_dword v25, v[28:29], off nt
	s_nop 0
	global_load_dword v26, v[30:31], off nt
	global_load_dword v27, v[32:33], off nt
	global_load_dword v28, v[40:41], off nt
	global_load_dword v29, v[42:43], off nt
	v_or_b32_e32 v30, 0x20000, v46
	v_mov_b32_e32 v31, v5
	v_or_b32_e32 v32, 0x22000, v46
	v_mov_b32_e32 v33, v5
	v_or_b32_e32 v40, 0x24000, v46
	v_mov_b32_e32 v41, v5
	v_or_b32_e32 v42, 0x26000, v46
	v_mov_b32_e32 v43, v5
	v_or_b32_e32 v48, 0x28000, v46
	v_mov_b32_e32 v49, v5
	v_or_b32_e32 v50, 0x2a000, v46
	v_mov_b32_e32 v51, v5
	v_lshl_add_u64 v[30:31], v[44:45], 0, v[30:31]
	v_lshl_add_u64 v[32:33], v[44:45], 0, v[32:33]
	v_lshl_add_u64 v[40:41], v[44:45], 0, v[40:41]
	v_lshl_add_u64 v[42:43], v[44:45], 0, v[42:43]
	v_lshl_add_u64 v[48:49], v[44:45], 0, v[48:49]
	v_lshl_add_u64 v[50:51], v[44:45], 0, v[50:51]
	v_or_b32_e32 v56, 0x2c000, v46
	v_mov_b32_e32 v57, v5
	v_or_b32_e32 v58, 0x2e000, v46
	v_mov_b32_e32 v59, v5
	v_lshl_add_u64 v[56:57], v[44:45], 0, v[56:57]
	v_lshl_add_u64 v[58:59], v[44:45], 0, v[58:59]
	global_load_dword v30, v[30:31], off nt
	s_nop 0
	global_load_dword v31, v[32:33], off nt
	s_nop 0
	global_load_dword v32, v[40:41], off nt
	global_load_dword v33, v[42:43], off nt
	s_nop 0
	global_load_dword v40, v[48:49], off nt
	global_load_dword v41, v[50:51], off nt
	global_load_dword v42, v[56:57], off nt
	global_load_dword v43, v[58:59], off nt
	v_or_b32_e32 v48, 0x30000, v46
	v_mov_b32_e32 v49, v5
	v_or_b32_e32 v50, 0x32000, v46
	v_mov_b32_e32 v51, v5
	v_lshl_add_u64 v[48:49], v[44:45], 0, v[48:49]
	v_lshl_add_u64 v[50:51], v[44:45], 0, v[50:51]
	v_or_b32_e32 v56, 0x34000, v46
	v_mov_b32_e32 v57, v5
	v_or_b32_e32 v58, 0x36000, v46
	v_mov_b32_e32 v59, v5
	v_or_b32_e32 v60, 0x38000, v46
	v_mov_b32_e32 v61, v5
	v_or_b32_e32 v62, 0x3a000, v46
	v_mov_b32_e32 v63, v5
	v_or_b32_e32 v64, 0x3c000, v46
	v_mov_b32_e32 v65, v5
	v_or_b32_e32 v46, 0x3e000, v46
	v_lshl_add_u64 v[56:57], v[44:45], 0, v[56:57]
	v_lshl_add_u64 v[58:59], v[44:45], 0, v[58:59]
	v_lshl_add_u64 v[60:61], v[44:45], 0, v[60:61]
	v_lshl_add_u64 v[62:63], v[44:45], 0, v[62:63]
	v_lshl_add_u64 v[64:65], v[44:45], 0, v[64:65]
	v_lshl_add_u64 v[66:67], v[44:45], 0, v[46:47]
	global_load_dword v44, v[48:49], off nt
	global_load_dword v45, v[50:51], off nt
	global_load_dword v46, v[56:57], off nt
	global_load_dword v47, v[58:59], off nt
	s_nop 0
	global_load_dword v50, v[60:61], off nt
	global_load_dword v51, v[62:63], off nt
	global_load_dword v48, v[64:65], off nt
	global_load_dword v49, v[66:67], off nt
	v_readlane_b32 s44, v247, 34
	v_readlane_b32 s45, v247, 35
	s_andn2_b64 vcc, exec, s[4:5]
	v_readlane_b32 s37, v247, 27
	v_readlane_b32 s38, v247, 28
	v_readlane_b32 s39, v247, 29
	v_readlane_b32 s40, v247, 30
	v_readlane_b32 s41, v247, 31
	v_readlane_b32 s42, v247, 32
	v_readlane_b32 s43, v247, 33
	v_readlane_b32 s48, v247, 38
	v_readlane_b32 s49, v247, 39
	v_readlane_b32 s50, v247, 40
	v_readlane_b32 s51, v247, 41
	s_cbranch_vccnz .LBB0_20
	v_lshlrev_b32_e32 v56, 10, v12
	v_ashrrev_i32_e32 v57, 31, v56
	v_lshl_add_u64 v[56:57], v[56:57], 2, s[44:45]
	v_lshlrev_b32_e32 v12, 2, v13
	v_mov_b32_e32 v13, v5
	v_lshl_add_u64 v[12:13], v[56:57], 0, v[12:13]
	global_load_dword v56, v[12:13], off nt
	global_load_dword v57, v[12:13], off offset:8 nt
	global_load_dword v58, v[12:13], off offset:16 nt
	global_load_dword v59, v[12:13], off offset:24 nt
	global_load_dword v60, v[12:13], off offset:32 nt
	global_load_dword v61, v[12:13], off offset:40 nt
	global_load_dword v62, v[12:13], off offset:48 nt
	global_load_dword v63, v[12:13], off offset:56 nt
	global_load_dword v64, v[12:13], off offset:64 nt
	global_load_dword v65, v[12:13], off offset:72 nt
	global_load_dword v66, v[12:13], off offset:80 nt
	global_load_dword v67, v[12:13], off offset:88 nt
	global_load_dword v68, v[12:13], off offset:96 nt
	global_load_dword v69, v[12:13], off offset:104 nt
	global_load_dword v70, v[12:13], off offset:112 nt
	global_load_dword v71, v[12:13], off offset:120 nt
	global_load_dword v72, v[12:13], off offset:128 nt
	global_load_dword v73, v[12:13], off offset:136 nt
	global_load_dword v74, v[12:13], off offset:144 nt
	global_load_dword v75, v[12:13], off offset:152 nt
	global_load_dword v152, v[12:13], off offset:160 nt
	global_load_dword v153, v[12:13], off offset:168 nt
	global_load_dword v154, v[12:13], off offset:176 nt
	global_load_dword v155, v[12:13], off offset:184 nt
	global_load_dword v156, v[12:13], off offset:192 nt
	global_load_dword v157, v[12:13], off offset:200 nt
	global_load_dword v158, v[12:13], off offset:208 nt
	global_load_dword v159, v[12:13], off offset:216 nt
	global_load_dword v160, v[12:13], off offset:224 nt
	global_load_dword v161, v[12:13], off offset:232 nt
	global_load_dword v162, v[12:13], off offset:240 nt
	global_load_dword v163, v[12:13], off offset:248 nt
	s_waitcnt vmcnt(30)
	v_pk_mul_f32 v[14:15], v[14:15], v[56:57]
	s_waitcnt vmcnt(28)
	v_pk_mul_f32 v[16:17], v[16:17], v[58:59]
	s_waitcnt vmcnt(26)
	v_pk_mul_f32 v[18:19], v[18:19], v[60:61]
	s_waitcnt vmcnt(24)
	v_pk_mul_f32 v[20:21], v[20:21], v[62:63]
	s_waitcnt vmcnt(22)
	v_pk_mul_f32 v[22:23], v[22:23], v[64:65]
	s_waitcnt vmcnt(20)
	v_pk_mul_f32 v[24:25], v[24:25], v[66:67]
	s_waitcnt vmcnt(18)
	v_pk_mul_f32 v[26:27], v[26:27], v[68:69]
	s_waitcnt vmcnt(16)
	v_pk_mul_f32 v[28:29], v[28:29], v[70:71]
	s_waitcnt vmcnt(14)
	v_pk_mul_f32 v[30:31], v[30:31], v[72:73]
	s_waitcnt vmcnt(12)
	v_pk_mul_f32 v[32:33], v[32:33], v[74:75]
	s_waitcnt vmcnt(10)
	v_pk_mul_f32 v[40:41], v[40:41], v[152:153]
	s_waitcnt vmcnt(8)
	v_pk_mul_f32 v[42:43], v[42:43], v[154:155]
	s_waitcnt vmcnt(6)
	v_pk_mul_f32 v[44:45], v[44:45], v[156:157]
	s_waitcnt vmcnt(4)
	v_pk_mul_f32 v[46:47], v[46:47], v[158:159]
	s_waitcnt vmcnt(2)
	v_pk_mul_f32 v[50:51], v[50:51], v[160:161]
	s_waitcnt vmcnt(0)
	v_pk_mul_f32 v[48:49], v[48:49], v[162:163]

.LBB0_22:
	s_andn2_saveexec_b64 s[24:25], s[24:25]
	s_cbranch_execz .LBB0_24
	v_readlane_b32 s36, v247, 26
	v_lshlrev_b32_e32 v14, 5, v14
	v_readlane_b32 s42, v247, 32
	v_readlane_b32 s43, v247, 33
	v_sub_u32_e32 v14, v80, v14
	s_mov_b32 s26, 0xb00000
	v_mov_b64_e32 v[16:17], s[42:43]
	v_add_u32_e32 v9, 0x1e000, v9
	v_and_b32_e32 v30, 0x3e0, v14
	v_mad_i64_i32 v[12:13], s[26:27], v12, s26, v[16:17]
	v_and_b32_e32 v9, 0x1ffc0, v9
	v_lshlrev_b32_e32 v14, 2, v30
	v_mov_b32_e32 v15, v5
	v_or_b32_e32 v16, v9, v3
	v_lshl_add_u64 v[12:13], v[12:13], 0, v[14:15]
	v_lshl_add_u64 v[12:13], v[12:13], 0, v[4:5]
	v_lshlrev_b32_e32 v14, 12, v16
	v_lshl_add_u64 v[12:13], v[12:13], 0, v[14:15]
	v_add_co_u32_e32 v14, vcc, s31, v12
	s_mov_b64 s[26:27], 0x1000000
	s_nop 0
	v_addc_co_u32_e32 v15, vcc, 0, v13, vcc
	v_add_co_u32_e32 v16, vcc, s34, v12
	v_readlane_b32 s37, v247, 27
	s_nop 0
	v_addc_co_u32_e32 v17, vcc, 0, v13, vcc
	v_add_co_u32_e32 v18, vcc, s3, v12
	v_readlane_b32 s38, v247, 28
	s_nop 0
	v_addc_co_u32_e32 v19, vcc, 0, v13, vcc
	v_add_co_u32_e32 v20, vcc, s35, v12
	v_readlane_b32 s39, v247, 29
	s_nop 0
	v_addc_co_u32_e32 v21, vcc, 0, v13, vcc
	v_add_co_u32_e32 v22, vcc, s52, v12
	v_readlane_b32 s40, v247, 30
	s_nop 0
	v_addc_co_u32_e32 v23, vcc, 0, v13, vcc
	v_add_co_u32_e32 v24, vcc, s53, v12
	v_readlane_b32 s41, v247, 31
	s_nop 0
	v_addc_co_u32_e32 v25, vcc, 0, v13, vcc
	v_add_co_u32_e32 v26, vcc, s54, v12
	v_readlane_b32 s44, v247, 34
	s_nop 0
	v_addc_co_u32_e32 v27, vcc, 0, v13, vcc
	global_load_dword v31, v[12:13], off nt
	global_load_dword v32, v[14:15], off nt
	global_load_dword v33, v[16:17], off nt
	global_load_dword v40, v[18:19], off nt
	global_load_dword v41, v[20:21], off nt
	global_load_dword v42, v[22:23], off nt
	global_load_dword v43, v[24:25], off nt
	global_load_dword v44, v[26:27], off nt
	v_add_co_u32_e32 v14, vcc, s55, v12
	v_readlane_b32 s45, v247, 35
	s_nop 0
	v_addc_co_u32_e32 v15, vcc, 0, v13, vcc
	v_add_co_u32_e32 v16, vcc, s56, v12
	v_readlane_b32 s46, v247, 36
	s_nop 0
	v_addc_co_u32_e32 v17, vcc, 0, v13, vcc
	v_add_co_u32_e32 v18, vcc, s57, v12
	v_readlane_b32 s47, v247, 37
	s_nop 0
	v_addc_co_u32_e32 v19, vcc, 0, v13, vcc
	v_add_co_u32_e32 v20, vcc, s58, v12
	v_readlane_b32 s48, v247, 38
	s_nop 0
	v_addc_co_u32_e32 v21, vcc, 0, v13, vcc
	v_add_co_u32_e32 v22, vcc, s59, v12
	v_readlane_b32 s49, v247, 39
	s_nop 0
	v_addc_co_u32_e32 v23, vcc, 0, v13, vcc
	v_add_co_u32_e32 v24, vcc, s60, v12
	v_readlane_b32 s50, v247, 40
	s_nop 0
	v_addc_co_u32_e32 v25, vcc, 0, v13, vcc
	v_add_co_u32_e32 v26, vcc, s61, v12
	v_readlane_b32 s51, v247, 41
	s_nop 0
	v_addc_co_u32_e32 v27, vcc, 0, v13, vcc
	v_add_co_u32_e32 v28, vcc, s62, v12
	s_nop 1
	v_addc_co_u32_e32 v29, vcc, 0, v13, vcc
	global_load_dword v45, v[14:15], off nt
	global_load_dword v46, v[16:17], off nt
	global_load_dword v47, v[18:19], off nt
	global_load_dword v48, v[20:21], off nt
	global_load_dword v49, v[22:23], off nt
	global_load_dword v50, v[24:25], off nt
	global_load_dword v51, v[26:27], off nt
	global_load_dword v52, v[28:29], off nt
	v_add_co_u32_e32 v14, vcc, s63, v12
	s_nop 1
	v_addc_co_u32_e32 v15, vcc, 0, v13, vcc
	v_add_co_u32_e32 v16, vcc, s64, v12
	s_nop 1
	v_addc_co_u32_e32 v17, vcc, 0, v13, vcc
	v_add_co_u32_e32 v18, vcc, s65, v12
	s_nop 1
	v_addc_co_u32_e32 v19, vcc, 0, v13, vcc
	v_add_co_u32_e32 v20, vcc, s67, v12
	s_nop 1
	v_addc_co_u32_e32 v21, vcc, 0, v13, vcc
	v_add_co_u32_e32 v22, vcc, s68, v12
	s_nop 1
	v_addc_co_u32_e32 v23, vcc, 0, v13, vcc
	v_add_co_u32_e32 v24, vcc, s69, v12
	s_nop 1
	v_addc_co_u32_e32 v25, vcc, 0, v13, vcc
	v_add_co_u32_e32 v26, vcc, s70, v12
	s_nop 1
	v_addc_co_u32_e32 v27, vcc, 0, v13, vcc
	v_add_co_u32_e32 v28, vcc, s71, v12
	s_nop 1
	v_addc_co_u32_e32 v29, vcc, 0, v13, vcc
	global_load_dword v53, v[14:15], off nt
	global_load_dword v54, v[16:17], off nt
	global_load_dword v55, v[18:19], off nt
	global_load_dword v56, v[20:21], off nt
	global_load_dword v57, v[22:23], off nt
	global_load_dword v58, v[24:25], off nt
	global_load_dword v59, v[26:27], off nt
	s_nop 0
	global_load_dword v28, v[28:29], off nt
	v_add_co_u32_e32 v14, vcc, s72, v12
	s_nop 1
	v_addc_co_u32_e32 v15, vcc, 0, v13, vcc
	v_add_co_u32_e32 v16, vcc, s73, v12
	s_nop 1
	v_addc_co_u32_e32 v17, vcc, 0, v13, vcc
	v_add_co_u32_e32 v18, vcc, s74, v12
	s_nop 1
	v_addc_co_u32_e32 v19, vcc, 0, v13, vcc
	v_add_co_u32_e32 v20, vcc, s75, v12
	s_nop 1
	v_addc_co_u32_e32 v21, vcc, 0, v13, vcc
	v_add_co_u32_e32 v22, vcc, s76, v12
	s_nop 1
	v_addc_co_u32_e32 v23, vcc, 0, v13, vcc
	v_add_co_u32_e32 v24, vcc, s77, v12
	s_nop 1
	v_addc_co_u32_e32 v25, vcc, 0, v13, vcc
	v_add_co_u32_e32 v26, vcc, s78, v12
	s_nop 1
	v_addc_co_u32_e32 v27, vcc, 0, v13, vcc
	v_add_co_u32_e32 v12, vcc, s79, v12
	s_nop 1
	v_addc_co_u32_e32 v13, vcc, 0, v13, vcc
	global_load_dword v14, v[14:15], off nt
	s_nop 0
	global_load_dword v15, v[16:17], off nt
	s_nop 0
	global_load_dword v16, v[18:19], off nt
	global_load_dword v17, v[20:21], off nt
	s_nop 0
	global_load_dword v18, v[22:23], off nt
	global_load_dword v19, v[24:25], off nt
	global_load_dword v20, v[26:27], off nt
	s_nop 0
	global_load_dword v12, v[12:13], off nt
	s_waitcnt vmcnt(30)
	ds_write2_b32 v35, v31, v32 offset1:66
	s_waitcnt vmcnt(28)
	ds_write2_b32 v35, v33, v40 offset0:132 offset1:198
	s_waitcnt vmcnt(26)
	ds_write2_b32 v84, v41, v42 offset0:8 offset1:74
	s_waitcnt vmcnt(24)
	ds_write2_b32 v84, v43, v44 offset0:140 offset1:206
	s_waitcnt vmcnt(22)
	ds_write2_b32 v85, v45, v46 offset0:16 offset1:82
	s_waitcnt vmcnt(20)
	ds_write2_b32 v85, v47, v48 offset0:148 offset1:214
	s_waitcnt vmcnt(18)
	ds_write2_b32 v86, v49, v50 offset0:24 offset1:90
	s_waitcnt vmcnt(16)
	ds_write2_b32 v86, v51, v52 offset0:156 offset1:222
	s_waitcnt vmcnt(14)
	ds_write2_b32 v87, v53, v54 offset0:32 offset1:98
	s_waitcnt vmcnt(12)
	ds_write2_b32 v87, v55, v56 offset0:164 offset1:230
	s_waitcnt vmcnt(10)
	ds_write2_b32 v88, v57, v58 offset0:40 offset1:106
	s_waitcnt vmcnt(8)
	ds_write2_b32 v88, v59, v28 offset0:172 offset1:238
	s_waitcnt vmcnt(6)
	ds_write2_b32 v89, v14, v15 offset0:48 offset1:114
	s_waitcnt vmcnt(4)
	ds_write2_b32 v89, v16, v17 offset0:180 offset1:246
	s_waitcnt vmcnt(2)
	ds_write2_b32 v90, v18, v19 offset0:56 offset1:122
	s_waitcnt vmcnt(0)
	ds_write2_b32 v90, v20, v12 offset0:188 offset1:254
	s_waitcnt lgkmcnt(0)
	ds_read2_b32 v[12:13], v39 offset1:33
	v_lshlrev_b32_e32 v16, 1, v9
	v_mov_b32_e32 v17, v5
	s_waitcnt lgkmcnt(0)
	v_cvt_pk_bf16_f32 v12, v12, v13
	ds_read2_b32 v[14:15], v39 offset0:66 offset1:99
	v_lshl_add_u64 v[10:11], v[10:11], 0, v[16:17]
	v_mov_b32_e32 v9, v5
	s_waitcnt lgkmcnt(0)
	v_cvt_pk_bf16_f32 v13, v14, v15
	ds_read2_b32 v[14:15], v39 offset0:132 offset1:165
	v_lshl_add_u64 v[10:11], v[10:11], 0, v[8:9]
	v_or_b32_e32 v9, v30, v37
	s_waitcnt lgkmcnt(0)
	v_cvt_pk_bf16_f32 v14, v14, v15
	ds_read2_b32 v[18:19], v39 offset0:198 offset1:231
	v_mul_u32_u24_e32 v9, 0xb00, v9
	v_lshl_add_u64 v[16:17], v[10:11], 0, s[26:27]
	s_waitcnt lgkmcnt(0)
	v_cvt_pk_bf16_f32 v15, v18, v19
	v_lshlrev_b32_e32 v18, 1, v9
	v_mov_b32_e32 v19, v5
	ds_read2_b32 v[10:11], v39 offset0:8 offset1:41
	v_lshl_add_u64 v[18:19], v[16:17], 0, v[18:19]
	v_or_b32_e32 v9, v30, v77
	global_store_dwordx4 v[18:19], v[12:15], off
	s_waitcnt lgkmcnt(0)
	v_cvt_pk_bf16_f32 v10, v10, v11
	ds_read2_b32 v[12:13], v39 offset0:74 offset1:107
	v_mul_u32_u24_e32 v9, 0xb00, v9
	s_waitcnt lgkmcnt(0)
	v_cvt_pk_bf16_f32 v11, v12, v13
	ds_read2_b32 v[12:13], v39 offset0:140 offset1:173
	v_lshlrev_b32_e32 v18, 1, v9
	v_mov_b32_e32 v19, v5
	s_waitcnt lgkmcnt(0)
	v_cvt_pk_bf16_f32 v12, v12, v13
	ds_read2_b32 v[14:15], v39 offset0:206 offset1:239
	s_waitcnt lgkmcnt(0)
	v_cvt_pk_bf16_f32 v13, v14, v15
	v_lshl_add_u64 v[18:19], v[16:17], 0, v[18:19]
	v_or_b32_e32 v9, v30, v78
	ds_read2_b32 v[14:15], v39 offset0:16 offset1:49
	global_store_dwordx4 v[18:19], v[10:13], off
	v_mul_u32_u24_e32 v9, 0xb00, v9
	v_lshlrev_b32_e32 v18, 1, v9
	s_waitcnt lgkmcnt(0)
	v_cvt_pk_bf16_f32 v10, v14, v15
	ds_read2_b32 v[12:13], v39 offset0:82 offset1:115
	s_waitcnt lgkmcnt(0)
	v_cvt_pk_bf16_f32 v11, v12, v13
	ds_read2_b32 v[12:13], v39 offset0:148 offset1:181
	v_mov_b32_e32 v19, v5
	s_waitcnt lgkmcnt(0)
	v_cvt_pk_bf16_f32 v12, v12, v13
	ds_read2_b32 v[14:15], v39 offset0:214 offset1:247
	s_waitcnt lgkmcnt(0)
	v_cvt_pk_bf16_f32 v13, v14, v15
	v_lshl_add_u64 v[18:19], v[16:17], 0, v[18:19]
	ds_read2_b32 v[14:15], v39 offset0:24 offset1:57
	global_store_dwordx4 v[18:19], v[10:13], off
	v_or_b32_e32 v9, v30, v79
	v_mul_u32_u24_e32 v9, 0xb00, v9
	s_waitcnt lgkmcnt(0)
	v_cvt_pk_bf16_f32 v10, v14, v15
	ds_read2_b32 v[12:13], v39 offset0:90 offset1:123
	s_waitcnt lgkmcnt(0)
	v_cvt_pk_bf16_f32 v11, v12, v13
	ds_read2_b32 v[12:13], v39 offset0:156 offset1:189
	s_waitcnt lgkmcnt(0)
	v_cvt_pk_bf16_f32 v12, v12, v13
	ds_read2_b32 v[14:15], v39 offset0:222 offset1:255
	s_waitcnt lgkmcnt(0)
	v_cvt_pk_bf16_f32 v13, v14, v15
	v_lshlrev_b32_e32 v14, 1, v9
	v_mov_b32_e32 v15, v5
	v_lshl_add_u64 v[14:15], v[16:17], 0, v[14:15]
	global_store_dwordx4 v[14:15], v[10:13], off
	s_waitcnt lgkmcnt(0)

.LBB0_25:
	s_andn2_saveexec_b64 s[22:23], s[22:23]
	s_cbranch_execz .LBB0_33
	v_add_u16_e32 v9, 0xfb00, v15
	v_mul_u32_u24_e32 v13, 0xba2f, v9
	v_readlane_b32 s36, v247, 26
	v_lshrrev_b32_e32 v14, 23, v13
	v_readlane_b32 s40, v247, 30
	v_readlane_b32 s41, v247, 31
	v_mul_lo_u16_e32 v13, 0xb0, v14
	s_mov_b32 s24, 0x1600000
	v_mov_b64_e32 v[16:17], s[40:41]
	v_sub_u16_e32 v13, v9, v13
	v_mad_i64_i32 v[16:17], s[24:25], v12, s24, v[16:17]
	v_lshlrev_b16_e32 v9, 6, v14
	v_lshlrev_b32_e32 v14, 7, v13
	v_mov_b32_e32 v15, v5
	v_or_b32_e32 v52, v3, v9
	v_lshl_add_u64 v[14:15], v[16:17], 0, v[14:15]
	v_lshl_add_u64 v[44:45], v[14:15], 0, v[4:5]
	v_or_b32_e32 v16, 2, v52
	v_or_b32_e32 v18, 4, v52
	v_or_b32_e32 v20, 6, v52
	v_or_b32_e32 v22, 8, v52
	v_or_b32_e32 v24, 10, v52
	v_or_b32_e32 v26, 12, v52
	v_or_b32_e32 v28, 14, v52
	v_mad_u64_u32 v[14:15], s[24:25], v52, s80, v[44:45]
	v_mad_u64_u32 v[16:17], s[24:25], v16, s80, v[44:45]
	v_mad_u64_u32 v[18:19], s[24:25], v18, s80, v[44:45]
	v_mad_u64_u32 v[20:21], s[24:25], v20, s80, v[44:45]
	v_mad_u64_u32 v[22:23], s[24:25], v22, s80, v[44:45]
	v_mad_u64_u32 v[24:25], s[24:25], v24, s80, v[44:45]
	v_mad_u64_u32 v[26:27], s[24:25], v26, s80, v[44:45]
	v_mad_u64_u32 v[28:29], s[24:25], v28, s80, v[44:45]
	global_load_dword v14, v[14:15], off nt
	s_nop 0
	global_load_dword v15, v[16:17], off nt
	s_nop 0
	global_load_dword v16, v[18:19], off nt
	global_load_dword v17, v[20:21], off nt
	s_nop 0
	global_load_dword v18, v[22:23], off nt
	global_load_dword v19, v[24:25], off nt
	global_load_dword v20, v[26:27], off nt
	global_load_dword v21, v[28:29], off nt
	v_or_b32_e32 v22, 16, v52
	v_or_b32_e32 v24, 18, v52
	v_or_b32_e32 v26, 20, v52
	v_or_b32_e32 v28, 22, v52
	v_or_b32_e32 v30, 24, v52
	v_or_b32_e32 v32, 26, v52
	v_or_b32_e32 v40, 28, v52
	v_or_b32_e32 v42, 30, v52
	v_mad_u64_u32 v[22:23], s[24:25], v22, s80, v[44:45]
	v_mad_u64_u32 v[24:25], s[24:25], v24, s80, v[44:45]
	v_mad_u64_u32 v[26:27], s[24:25], v26, s80, v[44:45]
	v_mad_u64_u32 v[28:29], s[24:25], v28, s80, v[44:45]
	v_mad_u64_u32 v[30:31], s[24:25], v30, s80, v[44:45]
	v_mad_u64_u32 v[32:33], s[24:25], v32, s80, v[44:45]
	v_mad_u64_u32 v[40:41], s[24:25], v40, s80, v[44:45]
	v_mad_u64_u32 v[42:43], s[24:25], v42, s80, v[44:45]
	global_load_dword v22, v[22:23], off nt
	s_nop 0
	global_load_dword v23, v[24:25], off nt
	s_nop 0
	global_load_dword v24, v[26:27], off nt
	global_load_dword v25, v[28:29], off nt
	s_nop 0
	global_load_dword v26, v[30:31], off nt
	global_load_dword v27, v[32:33], off nt
	global_load_dword v28, v[40:41], off nt
	global_load_dword v29, v[42:43], off nt
	v_or_b32_e32 v30, 32, v52
	v_or_b32_e32 v32, 34, v52
	v_or_b32_e32 v40, 36, v52
	v_or_b32_e32 v42, 38, v52
	v_or_b32_e32 v53, 46, v52
	v_mad_u64_u32 v[30:31], s[24:25], v30, s80, v[44:45]
	v_mad_u64_u32 v[32:33], s[24:25], v32, s80, v[44:45]
	v_mad_u64_u32 v[40:41], s[24:25], v40, s80, v[44:45]
	v_mad_u64_u32 v[42:43], s[24:25], v42, s80, v[44:45]
	v_or_b32_e32 v46, 40, v52
	v_or_b32_e32 v48, 42, v52
	v_or_b32_e32 v50, 44, v52
	v_mad_u64_u32 v[54:55], s[24:25], v53, s80, v[44:45]
	v_or_b32_e32 v53, 54, v52
	v_mad_u64_u32 v[46:47], s[24:25], v46, s80, v[44:45]
	v_mad_u64_u32 v[48:49], s[24:25], v48, s80, v[44:45]
	v_mad_u64_u32 v[50:51], s[24:25], v50, s80, v[44:45]
	global_load_dword v30, v[30:31], off nt
	s_nop 0
	global_load_dword v31, v[32:33], off nt
	s_nop 0
	global_load_dword v32, v[40:41], off nt
	global_load_dword v33, v[42:43], off nt
	s_nop 0
	global_load_dword v40, v[46:47], off nt
	global_load_dword v41, v[48:49], off nt
	global_load_dword v42, v[50:51], off nt
	global_load_dword v43, v[54:55], off nt
	v_mad_u64_u32 v[54:55], s[24:25], v53, s80, v[44:45]
	v_or_b32_e32 v53, 56, v52
	v_mad_u64_u32 v[56:57], s[24:25], v53, s80, v[44:45]
	v_or_b32_e32 v53, 58, v52
	v_or_b32_e32 v46, 48, v52
	v_or_b32_e32 v48, 50, v52
	v_or_b32_e32 v50, 52, v52
	v_mad_u64_u32 v[58:59], s[24:25], v53, s80, v[44:45]
	v_or_b32_e32 v53, 60, v52
	v_mad_u64_u32 v[46:47], s[24:25], v46, s80, v[44:45]
	v_mad_u64_u32 v[48:49], s[24:25], v48, s80, v[44:45]
	v_mad_u64_u32 v[50:51], s[24:25], v50, s80, v[44:45]
	v_mad_u64_u32 v[60:61], s[24:25], v53, s80, v[44:45]
	v_or_b32_e32 v53, 62, v52
	v_mad_u64_u32 v[62:63], s[24:25], v53, s80, v[44:45]
	global_load_dword v44, v[46:47], off nt
	global_load_dword v45, v[48:49], off nt
	s_nop 0
	global_load_dword v46, v[50:51], off nt
	global_load_dword v47, v[54:55], off nt
	s_nop 0
	global_load_dword v50, v[56:57], off nt
	global_load_dword v51, v[58:59], off nt
	global_load_dword v48, v[60:61], off nt
	global_load_dword v49, v[62:63], off nt
	v_readlane_b32 s38, v247, 28
	v_readlane_b32 s39, v247, 29
	s_andn2_b64 vcc, exec, s[8:9]
	v_readlane_b32 s37, v247, 27
	v_readlane_b32 s42, v247, 32
	v_readlane_b32 s43, v247, 33
	v_readlane_b32 s44, v247, 34
	v_readlane_b32 s45, v247, 35
	v_readlane_b32 s46, v247, 36
	v_readlane_b32 s47, v247, 37
	v_readlane_b32 s48, v247, 38
	v_readlane_b32 s49, v247, 39
	v_readlane_b32 s50, v247, 40
	v_readlane_b32 s51, v247, 41
	s_cbranch_vccnz .LBB0_28
	v_lshlrev_b32_e32 v54, 10, v12
	v_ashrrev_i32_e32 v55, 31, v54
	v_lshl_add_u64 v[54:55], v[54:55], 2, s[38:39]
	v_lshlrev_b32_e32 v52, 2, v52
	v_mov_b32_e32 v53, v5
	v_lshl_add_u64 v[52:53], v[54:55], 0, v[52:53]
	global_load_dword v54, v[52:53], off nt
	global_load_dword v55, v[52:53], off offset:8 nt
	global_load_dword v56, v[52:53], off offset:16 nt
	global_load_dword v57, v[52:53], off offset:24 nt
	global_load_dword v58, v[52:53], off offset:32 nt
	global_load_dword v59, v[52:53], off offset:40 nt
	global_load_dword v60, v[52:53], off offset:48 nt
	global_load_dword v61, v[52:53], off offset:56 nt
	global_load_dword v62, v[52:53], off offset:64 nt
	global_load_dword v63, v[52:53], off offset:72 nt
	global_load_dword v64, v[52:53], off offset:80 nt
	global_load_dword v65, v[52:53], off offset:88 nt
	global_load_dword v66, v[52:53], off offset:96 nt
	global_load_dword v67, v[52:53], off offset:104 nt
	global_load_dword v68, v[52:53], off offset:112 nt
	global_load_dword v69, v[52:53], off offset:120 nt
	global_load_dword v70, v[52:53], off offset:128 nt
	global_load_dword v71, v[52:53], off offset:136 nt
	global_load_dword v72, v[52:53], off offset:144 nt
	global_load_dword v73, v[52:53], off offset:152 nt
	global_load_dword v74, v[52:53], off offset:160 nt
	global_load_dword v75, v[52:53], off offset:168 nt
	global_load_dword v152, v[52:53], off offset:176 nt
	global_load_dword v153, v[52:53], off offset:184 nt
	global_load_dword v154, v[52:53], off offset:192 nt
	global_load_dword v155, v[52:53], off offset:200 nt
	global_load_dword v156, v[52:53], off offset:208 nt
	global_load_dword v157, v[52:53], off offset:216 nt
	global_load_dword v158, v[52:53], off offset:224 nt
	global_load_dword v159, v[52:53], off offset:232 nt
	global_load_dword v160, v[52:53], off offset:240 nt
	global_load_dword v161, v[52:53], off offset:248 nt
	s_waitcnt vmcnt(30)
	v_pk_mul_f32 v[14:15], v[14:15], v[54:55]
	s_waitcnt vmcnt(28)
	v_pk_mul_f32 v[16:17], v[16:17], v[56:57]
	s_waitcnt vmcnt(26)
	v_pk_mul_f32 v[18:19], v[18:19], v[58:59]
	s_waitcnt vmcnt(24)
	v_pk_mul_f32 v[20:21], v[20:21], v[60:61]
	s_waitcnt vmcnt(22)
	v_pk_mul_f32 v[22:23], v[22:23], v[62:63]
	s_waitcnt vmcnt(20)
	v_pk_mul_f32 v[24:25], v[24:25], v[64:65]
	s_waitcnt vmcnt(18)
	v_pk_mul_f32 v[26:27], v[26:27], v[66:67]
	s_waitcnt vmcnt(16)
	v_pk_mul_f32 v[28:29], v[28:29], v[68:69]
	s_waitcnt vmcnt(14)
	v_pk_mul_f32 v[30:31], v[30:31], v[70:71]
	s_waitcnt vmcnt(12)
	v_pk_mul_f32 v[32:33], v[32:33], v[72:73]
	s_waitcnt vmcnt(10)
	v_pk_mul_f32 v[40:41], v[40:41], v[74:75]
	s_waitcnt vmcnt(8)
	v_pk_mul_f32 v[42:43], v[42:43], v[152:153]
	s_waitcnt vmcnt(6)
	v_pk_mul_f32 v[44:45], v[44:45], v[154:155]
	s_waitcnt vmcnt(4)
	v_pk_mul_f32 v[46:47], v[46:47], v[156:157]
	s_waitcnt vmcnt(2)
	v_pk_mul_f32 v[50:51], v[50:51], v[158:159]
	s_waitcnt vmcnt(0)
	v_pk_mul_f32 v[48:49], v[48:49], v[160:161]

.LBB0_34:
	s_andn2_saveexec_b64 s[20:21], s[20:21]
	s_cbranch_execz .LBB0_38
	v_lshlrev_b64 v[16:17], 22, v[12:13]
	v_add_u16_e32 v13, 0xfd00, v15
	v_lshlrev_b32_e32 v14, 5, v14
	v_readlane_b32 s36, v247, 26
	v_lshrrev_b16_e32 v9, 5, v13
	v_sub_u32_e32 v14, v80, v14
	v_readlane_b32 s37, v247, 27
	v_lshlrev_b32_e32 v9, 6, v9
	v_and_b32_e32 v152, 0x3e0, v14
	v_lshl_add_u64 v[16:17], s[36:37], 0, v[16:17]
	v_or_b32_e32 v52, v9, v3
	v_lshlrev_b32_e32 v14, 2, v152
	v_mov_b32_e32 v15, v5
	v_lshl_add_u64 v[14:15], v[16:17], 0, v[14:15]
	v_lshlrev_b32_e32 v46, 12, v52
	v_lshl_add_u64 v[44:45], v[14:15], 0, v[4:5]
	v_mov_b32_e32 v47, v5
	v_or_b32_e32 v16, 0x2000, v46
	v_mov_b32_e32 v17, v5
	v_or_b32_e32 v18, 0x4000, v46
	v_mov_b32_e32 v19, v5
	v_or_b32_e32 v20, 0x6000, v46
	v_mov_b32_e32 v21, v5
	v_or_b32_e32 v22, 0x8000, v46
	v_mov_b32_e32 v23, v5
	v_or_b32_e32 v24, 0xa000, v46
	v_mov_b32_e32 v25, v5
	v_or_b32_e32 v26, 0xc000, v46
	v_mov_b32_e32 v27, v5
	v_or_b32_e32 v28, 0xe000, v46
	v_mov_b32_e32 v29, v5
	v_lshl_add_u64 v[14:15], v[44:45], 0, v[46:47]
	v_lshl_add_u64 v[16:17], v[44:45], 0, v[16:17]
	v_lshl_add_u64 v[18:19], v[44:45], 0, v[18:19]
	v_lshl_add_u64 v[20:21], v[44:45], 0, v[20:21]
	v_lshl_add_u64 v[22:23], v[44:45], 0, v[22:23]
	v_lshl_add_u64 v[24:25], v[44:45], 0, v[24:25]
	v_lshl_add_u64 v[26:27], v[44:45], 0, v[26:27]
	v_lshl_add_u64 v[28:29], v[44:45], 0, v[28:29]
	global_load_dword v14, v[14:15], off nt
	s_nop 0
	global_load_dword v15, v[16:17], off nt
	s_nop 0
	global_load_dword v16, v[18:19], off nt
	global_load_dword v17, v[20:21], off nt
	s_nop 0
	global_load_dword v18, v[22:23], off nt
	global_load_dword v19, v[24:25], off nt
	global_load_dword v20, v[26:27], off nt
	global_load_dword v21, v[28:29], off nt
	v_or_b32_e32 v22, 0x10000, v46
	v_mov_b32_e32 v23, v5
	v_or_b32_e32 v24, 0x12000, v46
	v_mov_b32_e32 v25, v5
	v_or_b32_e32 v26, 0x14000, v46
	v_mov_b32_e32 v27, v5
	v_or_b32_e32 v28, 0x16000, v46
	v_mov_b32_e32 v29, v5
	v_or_b32_e32 v30, 0x18000, v46
	v_mov_b32_e32 v31, v5
	v_or_b32_e32 v32, 0x1a000, v46
	v_mov_b32_e32 v33, v5
	v_or_b32_e32 v40, 0x1c000, v46
	v_mov_b32_e32 v41, v5
	v_or_b32_e32 v42, 0x1e000, v46
	v_mov_b32_e32 v43, v5
	v_lshl_add_u64 v[22:23], v[44:45], 0, v[22:23]
	v_lshl_add_u64 v[24:25], v[44:45], 0, v[24:25]
	v_lshl_add_u64 v[26:27], v[44:45], 0, v[26:27]
	v_lshl_add_u64 v[28:29], v[44:45], 0, v[28:29]
	v_lshl_add_u64 v[30:31], v[44:45], 0, v[30:31]
	v_lshl_add_u64 v[32:33], v[44:45], 0, v[32:33]
	v_lshl_add_u64 v[40:41], v[44:45], 0, v[40:41]
	v_lshl_add_u64 v[42:43], v[44:45], 0, v[42:43]
	global_load_dword v22, v[22:23], off nt
	s_nop 0
	global_load_dword v23, v[24:25], off nt
	s_nop 0
	global_load_dword v24, v[26:27], off nt
	global_load_dword v25, v[28:29], off nt
	s_nop 0
	global_load_dword v26, v[30:31], off nt
	global_load_dword v27, v[32:33], off nt
	global_load_dword v28, v[40:41], off nt
	global_load_dword v29, v[42:43], off nt
	v_or_b32_e32 v30, 0x20000, v46
	v_mov_b32_e32 v31, v5
	v_or_b32_e32 v32, 0x22000, v46
	v_mov_b32_e32 v33, v5
	v_or_b32_e32 v40, 0x24000, v46
	v_mov_b32_e32 v41, v5
	v_or_b32_e32 v42, 0x26000, v46
	v_mov_b32_e32 v43, v5
	v_or_b32_e32 v48, 0x28000, v46
	v_mov_b32_e32 v49, v5
	v_or_b32_e32 v50, 0x2a000, v46
	v_mov_b32_e32 v51, v5
	v_lshl_add_u64 v[30:31], v[44:45], 0, v[30:31]
	v_lshl_add_u64 v[32:33], v[44:45], 0, v[32:33]
	v_lshl_add_u64 v[40:41], v[44:45], 0, v[40:41]
	v_lshl_add_u64 v[42:43], v[44:45], 0, v[42:43]
	v_lshl_add_u64 v[48:49], v[44:45], 0, v[48:49]
	v_lshl_add_u64 v[50:51], v[44:45], 0, v[50:51]
	v_or_b32_e32 v54, 0x2c000, v46
	v_mov_b32_e32 v55, v5
	v_or_b32_e32 v56, 0x2e000, v46
	v_mov_b32_e32 v57, v5
	v_lshl_add_u64 v[54:55], v[44:45], 0, v[54:55]
	v_lshl_add_u64 v[56:57], v[44:45], 0, v[56:57]
	global_load_dword v30, v[30:31], off nt
	s_nop 0
	global_load_dword v31, v[32:33], off nt
	s_nop 0
	global_load_dword v32, v[40:41], off nt
	global_load_dword v33, v[42:43], off nt
	s_nop 0
	global_load_dword v40, v[48:49], off nt
	global_load_dword v41, v[50:51], off nt
	global_load_dword v42, v[54:55], off nt
	global_load_dword v43, v[56:57], off nt
	v_or_b32_e32 v48, 0x30000, v46
	v_mov_b32_e32 v49, v5
	v_or_b32_e32 v50, 0x32000, v46
	v_mov_b32_e32 v51, v5
	v_lshl_add_u64 v[48:49], v[44:45], 0, v[48:49]
	v_lshl_add_u64 v[50:51], v[44:45], 0, v[50:51]
	v_or_b32_e32 v54, 0x34000, v46
	v_mov_b32_e32 v55, v5
	v_or_b32_e32 v56, 0x36000, v46
	v_mov_b32_e32 v57, v5
	v_or_b32_e32 v58, 0x38000, v46
	v_mov_b32_e32 v59, v5
	v_or_b32_e32 v60, 0x3a000, v46
	v_mov_b32_e32 v61, v5
	v_or_b32_e32 v62, 0x3c000, v46
	v_mov_b32_e32 v63, v5
	v_or_b32_e32 v46, 0x3e000, v46
	v_lshl_add_u64 v[54:55], v[44:45], 0, v[54:55]
	v_lshl_add_u64 v[56:57], v[44:45], 0, v[56:57]
	v_lshl_add_u64 v[58:59], v[44:45], 0, v[58:59]
	v_lshl_add_u64 v[60:61], v[44:45], 0, v[60:61]
	v_lshl_add_u64 v[62:63], v[44:45], 0, v[62:63]
	v_lshl_add_u64 v[64:65], v[44:45], 0, v[46:47]
	global_load_dword v44, v[48:49], off nt
	global_load_dword v45, v[50:51], off nt
	global_load_dword v46, v[54:55], off nt
	global_load_dword v47, v[56:57], off nt
	s_nop 0
	global_load_dword v50, v[58:59], off nt
	global_load_dword v51, v[60:61], off nt
	global_load_dword v48, v[62:63], off nt
	global_load_dword v49, v[64:65], off nt
	s_andn2_b64 vcc, exec, s[10:11]
	v_readlane_b32 s38, v247, 28
	v_readlane_b32 s39, v247, 29
	v_readlane_b32 s40, v247, 30
	v_readlane_b32 s41, v247, 31
	v_readlane_b32 s42, v247, 32
	v_readlane_b32 s43, v247, 33
	v_readlane_b32 s44, v247, 34
	v_readlane_b32 s45, v247, 35
	v_readlane_b32 s46, v247, 36
	v_readlane_b32 s47, v247, 37
	v_readlane_b32 s48, v247, 38
	v_readlane_b32 s49, v247, 39
	v_readlane_b32 s50, v247, 40
	v_readlane_b32 s51, v247, 41
	s_cbranch_vccnz .LBB0_37
	v_lshlrev_b32_e32 v54, 9, v12
	v_ashrrev_i32_e32 v55, 31, v54
	v_readlane_b32 s36, v247, 6
	v_lshlrev_b64 v[54:55], 2, v[54:55]
	v_readlane_b32 s48, v247, 18
	v_readlane_b32 s49, v247, 19
	v_readlane_b32 s50, v247, 20
	v_readlane_b32 s51, v247, 21
	v_lshl_add_u64 v[56:57], s[48:49], 0, v[54:55]
	v_lshlrev_b32_e32 v52, 2, v52
	v_lshl_add_u64 v[54:55], s[50:51], 0, v[54:55]
	v_mov_b32_e32 v53, v5
	s_movk_i32 s22, 0xf800
	v_lshl_add_u64 v[58:59], v[54:55], 0, v[52:53]
	s_mov_b32 s23, -1
	v_lshl_add_u64 v[60:61], v[56:57], 0, v[52:53]
	v_lshl_add_u64 v[52:53], v[58:59], 0, s[22:23]
	s_movk_i32 s22, 0xf808
	s_mov_b32 s23, -1
	v_cmp_gt_u16_e32 vcc, s30, v13
	v_lshl_add_u64 v[54:55], v[58:59], 0, s[22:23]
	s_movk_i32 s22, 0xf810
	v_cndmask_b32_e32 v13, v53, v61, vcc
	v_cndmask_b32_e32 v12, v52, v60, vcc
	v_lshl_add_u64 v[52:53], v[60:61], 0, 8
	s_mov_b32 s23, -1
	v_cndmask_b32_e32 v53, v55, v53, vcc
	v_cndmask_b32_e32 v52, v54, v52, vcc
	v_lshl_add_u64 v[54:55], v[58:59], 0, s[22:23]
	s_movk_i32 s22, 0xf818
	s_mov_b32 s23, -1
	global_load_dword v12, v[12:13], off nt
	v_lshl_add_u64 v[56:57], v[58:59], 0, s[22:23]
	global_load_dword v13, v[52:53], off nt
	v_lshl_add_u64 v[52:53], v[60:61], 0, 16
	s_movk_i32 s22, 0xf820
	v_cndmask_b32_e32 v53, v55, v53, vcc
	v_cndmask_b32_e32 v52, v54, v52, vcc
	v_lshl_add_u64 v[54:55], v[60:61], 0, 24
	s_mov_b32 s23, -1
	v_cndmask_b32_e32 v55, v57, v55, vcc
	v_cndmask_b32_e32 v54, v56, v54, vcc
	v_lshl_add_u64 v[56:57], v[58:59], 0, s[22:23]
	s_movk_i32 s22, 0xf828
	s_mov_b32 s23, -1
	global_load_dword v52, v[52:53], off nt
	v_lshl_add_u64 v[62:63], v[58:59], 0, s[22:23]
	global_load_dword v53, v[54:55], off nt
	v_lshl_add_u64 v[54:55], v[60:61], 0, 32
	s_movk_i32 s22, 0xf830
	v_cndmask_b32_e32 v55, v57, v55, vcc
	v_cndmask_b32_e32 v54, v56, v54, vcc
	v_lshl_add_u64 v[56:57], v[60:61], 0, 40
	s_mov_b32 s23, -1
	v_cndmask_b32_e32 v57, v63, v57, vcc
	v_cndmask_b32_e32 v56, v62, v56, vcc
	v_lshl_add_u64 v[62:63], v[58:59], 0, s[22:23]
	s_movk_i32 s22, 0xf838
	global_load_dword v54, v[54:55], off nt
	s_mov_b32 s23, -1
	global_load_dword v55, v[56:57], off nt
	v_lshl_add_u64 v[56:57], v[60:61], 0, 48
	v_cndmask_b32_e32 v57, v63, v57, vcc
	v_cndmask_b32_e32 v56, v62, v56, vcc
	v_lshl_add_u64 v[62:63], v[60:61], 0, 56
	v_lshl_add_u64 v[64:65], v[58:59], 0, s[22:23]
	s_movk_i32 s22, 0xf840
	v_cndmask_b32_e32 v63, v65, v63, vcc
	v_cndmask_b32_e32 v62, v64, v62, vcc
	s_mov_b32 s23, -1
	global_load_dword v56, v[56:57], off nt
	v_lshl_add_u64 v[64:65], v[58:59], 0, s[22:23]
	global_load_dword v57, v[62:63], off nt
	v_lshl_add_u64 v[62:63], v[60:61], 0, 64
	s_mov_b64 s[22:23], 0x48
	v_cndmask_b32_e32 v63, v65, v63, vcc
	v_cndmask_b32_e32 v62, v64, v62, vcc
	v_lshl_add_u64 v[64:65], v[60:61], 0, s[22:23]
	s_movk_i32 s22, 0xf848
	s_mov_b32 s23, -1
	v_lshl_add_u64 v[66:67], v[58:59], 0, s[22:23]
	v_cndmask_b32_e32 v65, v67, v65, vcc
	v_cndmask_b32_e32 v64, v66, v64, vcc
	s_mov_b64 s[22:23], 0x50
	global_load_dword v62, v[62:63], off nt
	v_readlane_b32 s37, v247, 7
	global_load_dword v63, v[64:65], off nt
	v_lshl_add_u64 v[64:65], v[60:61], 0, s[22:23]
	s_movk_i32 s22, 0xf850
	s_mov_b32 s23, -1
	v_lshl_add_u64 v[66:67], v[58:59], 0, s[22:23]
	s_mov_b64 s[22:23], 0x58
	v_cndmask_b32_e32 v65, v67, v65, vcc
	v_cndmask_b32_e32 v64, v66, v64, vcc
	v_lshl_add_u64 v[66:67], v[60:61], 0, s[22:23]
	s_movk_i32 s22, 0xf858
	s_mov_b32 s23, -1
	v_lshl_add_u64 v[68:69], v[58:59], 0, s[22:23]
	v_cndmask_b32_e32 v67, v69, v67, vcc
	v_cndmask_b32_e32 v66, v68, v66, vcc
	s_mov_b64 s[22:23], 0x60
	global_load_dword v64, v[64:65], off nt
	v_readlane_b32 s38, v247, 8
	global_load_dword v65, v[66:67], off nt
	v_lshl_add_u64 v[66:67], v[60:61], 0, s[22:23]
	s_movk_i32 s22, 0xf860
	s_mov_b32 s23, -1
	v_lshl_add_u64 v[68:69], v[58:59], 0, s[22:23]
	s_mov_b64 s[22:23], 0x68
	v_cndmask_b32_e32 v67, v69, v67, vcc
	v_cndmask_b32_e32 v66, v68, v66, vcc
	v_lshl_add_u64 v[68:69], v[60:61], 0, s[22:23]
	s_movk_i32 s22, 0xf868
	s_mov_b32 s23, -1
	v_lshl_add_u64 v[70:71], v[58:59], 0, s[22:23]
	v_cndmask_b32_e32 v69, v71, v69, vcc
	v_cndmask_b32_e32 v68, v70, v68, vcc
	s_mov_b64 s[22:23], 0x70
	global_load_dword v66, v[66:67], off nt
	s_waitcnt vmcnt(11)
	v_pk_mul_f32 v[14:15], v[14:15], v[12:13]
	global_load_dword v67, v[68:69], off nt
	v_lshl_add_u64 v[68:69], v[60:61], 0, s[22:23]
	s_movk_i32 s22, 0xf870
	s_mov_b32 s23, -1
	v_lshl_add_u64 v[70:71], v[58:59], 0, s[22:23]
	s_mov_b64 s[22:23], 0x78
	v_cndmask_b32_e32 v69, v71, v69, vcc
	v_cndmask_b32_e32 v68, v70, v68, vcc
	v_lshl_add_u64 v[70:71], v[60:61], 0, s[22:23]
	s_movk_i32 s22, 0xf878
	s_mov_b32 s23, -1
	v_lshl_add_u64 v[72:73], v[58:59], 0, s[22:23]
	v_cndmask_b32_e32 v71, v73, v71, vcc
	v_cndmask_b32_e32 v70, v72, v70, vcc
	s_mov_b64 s[22:23], 0x80
	global_load_dword v68, v[68:69], off nt
	s_waitcnt vmcnt(11)
	v_pk_mul_f32 v[16:17], v[16:17], v[52:53]
	global_load_dword v69, v[70:71], off nt
	v_lshl_add_u64 v[70:71], v[60:61], 0, s[22:23]
	s_movk_i32 s22, 0xf880
	s_mov_b32 s23, -1
	v_lshl_add_u64 v[72:73], v[58:59], 0, s[22:23]
	s_mov_b64 s[22:23], 0x88
	v_cndmask_b32_e32 v71, v73, v71, vcc
	v_cndmask_b32_e32 v70, v72, v70, vcc
	v_lshl_add_u64 v[72:73], v[60:61], 0, s[22:23]
	s_movk_i32 s22, 0xf888
	s_mov_b32 s23, -1
	v_lshl_add_u64 v[74:75], v[58:59], 0, s[22:23]
	v_cndmask_b32_e32 v73, v75, v73, vcc
	v_cndmask_b32_e32 v72, v74, v72, vcc
	s_mov_b64 s[22:23], 0x90
	global_load_dword v70, v[70:71], off nt
	s_waitcnt vmcnt(11)
	v_pk_mul_f32 v[18:19], v[18:19], v[54:55]
	global_load_dword v71, v[72:73], off nt
	v_lshl_add_u64 v[72:73], v[60:61], 0, s[22:23]
	s_movk_i32 s22, 0xf890
	s_mov_b32 s23, -1
	v_lshl_add_u64 v[74:75], v[58:59], 0, s[22:23]
	s_mov_b64 s[22:23], 0x98
	v_cndmask_b32_e32 v73, v75, v73, vcc
	v_cndmask_b32_e32 v72, v74, v72, vcc
	v_lshl_add_u64 v[74:75], v[60:61], 0, s[22:23]
	s_movk_i32 s22, 0xf898
	s_mov_b32 s23, -1
	v_lshl_add_u64 v[154:155], v[58:59], 0, s[22:23]
	v_cndmask_b32_e32 v75, v155, v75, vcc
	v_cndmask_b32_e32 v74, v154, v74, vcc
	s_mov_b64 s[22:23], 0xa0
	global_load_dword v72, v[72:73], off nt
	s_waitcnt vmcnt(11)
	v_pk_mul_f32 v[20:21], v[20:21], v[56:57]
	global_load_dword v73, v[74:75], off nt
	v_lshl_add_u64 v[74:75], v[60:61], 0, s[22:23]
	s_movk_i32 s22, 0xf8a0
	s_mov_b32 s23, -1
	v_lshl_add_u64 v[154:155], v[58:59], 0, s[22:23]
	s_mov_b64 s[22:23], 0xa8
	v_cndmask_b32_e32 v75, v155, v75, vcc
	v_cndmask_b32_e32 v74, v154, v74, vcc
	v_lshl_add_u64 v[154:155], v[60:61], 0, s[22:23]
	s_movk_i32 s22, 0xf8a8
	s_mov_b32 s23, -1
	v_lshl_add_u64 v[156:157], v[58:59], 0, s[22:23]
	v_cndmask_b32_e32 v155, v157, v155, vcc
	v_cndmask_b32_e32 v154, v156, v154, vcc
	s_mov_b64 s[22:23], 0xb0
	global_load_dword v74, v[74:75], off nt
	s_waitcnt vmcnt(11)
	v_pk_mul_f32 v[22:23], v[22:23], v[62:63]
	global_load_dword v75, v[154:155], off nt
	v_lshl_add_u64 v[154:155], v[60:61], 0, s[22:23]
	s_movk_i32 s22, 0xf8b0
	s_mov_b32 s23, -1
	v_lshl_add_u64 v[156:157], v[58:59], 0, s[22:23]
	s_mov_b64 s[22:23], 0xb8
	v_cndmask_b32_e32 v155, v157, v155, vcc
	v_cndmask_b32_e32 v154, v156, v154, vcc
	v_lshl_add_u64 v[156:157], v[60:61], 0, s[22:23]
	s_movk_i32 s22, 0xf8b8
	s_mov_b32 s23, -1
	v_lshl_add_u64 v[158:159], v[58:59], 0, s[22:23]
	v_cndmask_b32_e32 v157, v159, v157, vcc
	v_cndmask_b32_e32 v156, v158, v156, vcc
	s_mov_b64 s[22:23], 0xc0
	global_load_dword v154, v[154:155], off nt
	s_waitcnt vmcnt(11)
	v_pk_mul_f32 v[24:25], v[24:25], v[64:65]
	global_load_dword v155, v[156:157], off nt
	v_lshl_add_u64 v[156:157], v[60:61], 0, s[22:23]
	s_movk_i32 s22, 0xf8c0
	s_mov_b32 s23, -1
	v_lshl_add_u64 v[158:159], v[58:59], 0, s[22:23]
	s_mov_b64 s[22:23], 0xc8
	v_cndmask_b32_e32 v157, v159, v157, vcc
	v_cndmask_b32_e32 v156, v158, v156, vcc
	v_lshl_add_u64 v[158:159], v[60:61], 0, s[22:23]
	s_movk_i32 s22, 0xf8c8
	s_mov_b32 s23, -1
	v_lshl_add_u64 v[160:161], v[58:59], 0, s[22:23]
	v_cndmask_b32_e32 v159, v161, v159, vcc
	v_cndmask_b32_e32 v158, v160, v158, vcc
	s_mov_b64 s[22:23], 0xd0
	global_load_dword v156, v[156:157], off nt
	s_waitcnt vmcnt(11)
	v_pk_mul_f32 v[26:27], v[26:27], v[66:67]
	global_load_dword v157, v[158:159], off nt
	v_lshl_add_u64 v[158:159], v[60:61], 0, s[22:23]
	s_movk_i32 s22, 0xf8d0
	s_mov_b32 s23, -1
	v_lshl_add_u64 v[160:161], v[58:59], 0, s[22:23]
	s_mov_b64 s[22:23], 0xd8
	v_cndmask_b32_e32 v159, v161, v159, vcc
	v_cndmask_b32_e32 v158, v160, v158, vcc
	v_lshl_add_u64 v[160:161], v[60:61], 0, s[22:23]
	s_movk_i32 s22, 0xf8d8
	s_mov_b32 s23, -1
	v_lshl_add_u64 v[162:163], v[58:59], 0, s[22:23]
	v_cndmask_b32_e32 v161, v163, v161, vcc
	v_cndmask_b32_e32 v160, v162, v160, vcc
	s_mov_b64 s[22:23], 0xe0
	global_load_dword v158, v[158:159], off nt
	s_waitcnt vmcnt(11)
	v_pk_mul_f32 v[28:29], v[28:29], v[68:69]
	global_load_dword v159, v[160:161], off nt
	v_lshl_add_u64 v[160:161], v[60:61], 0, s[22:23]
	s_movk_i32 s22, 0xf8e0
	s_mov_b32 s23, -1
	v_lshl_add_u64 v[162:163], v[58:59], 0, s[22:23]
	s_mov_b64 s[22:23], 0xe8
	v_cndmask_b32_e32 v161, v163, v161, vcc
	v_cndmask_b32_e32 v160, v162, v160, vcc
	v_lshl_add_u64 v[162:163], v[60:61], 0, s[22:23]
	s_movk_i32 s22, 0xf8e8
	s_mov_b32 s23, -1
	v_lshl_add_u64 v[164:165], v[58:59], 0, s[22:23]
	v_cndmask_b32_e32 v163, v165, v163, vcc
	v_cndmask_b32_e32 v162, v164, v162, vcc
	s_mov_b64 s[22:23], 0xf0
	global_load_dword v160, v[160:161], off nt
	s_waitcnt vmcnt(11)
	v_pk_mul_f32 v[30:31], v[30:31], v[70:71]
	global_load_dword v161, v[162:163], off nt
	v_lshl_add_u64 v[162:163], v[60:61], 0, s[22:23]
	s_movk_i32 s22, 0xf8f0
	s_mov_b32 s23, -1
	v_lshl_add_u64 v[164:165], v[58:59], 0, s[22:23]
	s_mov_b64 s[22:23], 0xf8
	v_lshl_add_u64 v[60:61], v[60:61], 0, s[22:23]
	s_movk_i32 s22, 0xf8f8
	s_mov_b32 s23, -1
	v_lshl_add_u64 v[58:59], v[58:59], 0, s[22:23]
	v_cndmask_b32_e32 v163, v165, v163, vcc
	v_cndmask_b32_e32 v162, v164, v162, vcc
	v_cndmask_b32_e32 v59, v59, v61, vcc
	v_cndmask_b32_e32 v58, v58, v60, vcc
	global_load_dword v162, v[162:163], off nt
	s_waitcnt vmcnt(11)
	v_pk_mul_f32 v[32:33], v[32:33], v[72:73]
	global_load_dword v163, v[58:59], off nt
	s_waitcnt vmcnt(10)
	v_pk_mul_f32 v[40:41], v[40:41], v[74:75]
	v_readlane_b32 s39, v247, 9
	v_readlane_b32 s40, v247, 10
	v_readlane_b32 s41, v247, 11
	v_readlane_b32 s42, v247, 12
	v_readlane_b32 s43, v247, 13
	v_readlane_b32 s44, v247, 14
	v_readlane_b32 s45, v247, 15
	v_readlane_b32 s46, v247, 16
	v_readlane_b32 s47, v247, 17
	s_waitcnt vmcnt(8)
	v_pk_mul_f32 v[42:43], v[42:43], v[154:155]
	s_waitcnt vmcnt(6)
	v_pk_mul_f32 v[44:45], v[44:45], v[156:157]
	s_waitcnt vmcnt(4)
	v_pk_mul_f32 v[46:47], v[46:47], v[158:159]
	s_waitcnt vmcnt(2)
	v_pk_mul_f32 v[50:51], v[50:51], v[160:161]
	s_waitcnt vmcnt(0)
	v_pk_mul_f32 v[48:49], v[48:49], v[162:163]

.LBB0_39:
	s_andn2_saveexec_b64 s[18:19], s[18:19]
	s_cbranch_execz .LBB0_41
	v_lshlrev_b32_e32 v9, 2, v14
	v_lshlrev_b32_e32 v14, 5, v14
	v_readlane_b32 s36, v247, 6
	v_sub_u32_e32 v9, v81, v9
	v_sub_u32_e32 v14, v80, v14
	v_lshlrev_b64 v[12:13], 20, v[12:13]
	v_readlane_b32 s44, v247, 14
	v_readlane_b32 s45, v247, 15
	v_and_b32_e32 v15, 0x3c0, v9
	v_and_b32_e32 v22, 0x1e0, v14
	v_lshl_add_u64 v[12:13], s[44:45], 0, v[12:13]
	v_bitop3_b32 v16, v15, v3, s81 bitop3:0xde
	v_lshlrev_b32_e32 v14, 2, v22
	v_mov_b32_e32 v15, v5
	v_lshl_add_u64 v[12:13], v[12:13], 0, v[14:15]
	v_lshl_add_u64 v[12:13], v[12:13], 0, v[4:5]
	v_lshlrev_b32_e32 v14, 11, v16
	v_lshl_add_u64 v[12:13], v[12:13], 0, v[14:15]
	v_add_co_u32_e32 v14, vcc, s31, v12
	s_mov_b32 s20, 0x1f000
	s_nop 0
	v_addc_co_u32_e32 v15, vcc, 0, v13, vcc
	v_add_co_u32_e32 v16, vcc, s34, v12
	v_bitop3_b32 v9, v9, s81, v92 bitop3:0x6c
	s_nop 0
	v_addc_co_u32_e32 v17, vcc, 0, v13, vcc
	v_add_co_u32_e32 v18, vcc, s3, v12
	v_readlane_b32 s37, v247, 7
	s_nop 0
	v_addc_co_u32_e32 v19, vcc, 0, v13, vcc
	global_load_dword v23, v[12:13], off nt
	global_load_dword v24, v[14:15], off offset:-4096 nt
	global_load_dword v25, v[14:15], off nt
	global_load_dword v26, v[16:17], off offset:-4096 nt
	global_load_dword v27, v[16:17], off nt
	global_load_dword v28, v[18:19], off offset:-4096 nt
	global_load_dword v29, v[18:19], off nt
	v_add_co_u32_e32 v14, vcc, s35, v12
	v_readlane_b32 s38, v247, 8
	s_nop 0
	v_addc_co_u32_e32 v15, vcc, 0, v13, vcc
	v_add_co_u32_e32 v16, vcc, s52, v12
	v_readlane_b32 s39, v247, 9
	s_nop 0
	v_addc_co_u32_e32 v17, vcc, 0, v13, vcc
	v_add_co_u32_e32 v18, vcc, s53, v12
	v_readlane_b32 s40, v247, 10
	s_nop 0
	v_addc_co_u32_e32 v19, vcc, 0, v13, vcc
	v_add_co_u32_e32 v20, vcc, s54, v12
	v_readlane_b32 s41, v247, 11
	s_nop 0
	v_addc_co_u32_e32 v21, vcc, 0, v13, vcc
	global_load_dword v30, v[14:15], off offset:-4096 nt
	global_load_dword v31, v[14:15], off nt
	global_load_dword v32, v[16:17], off offset:-4096 nt
	global_load_dword v33, v[16:17], off nt
	global_load_dword v40, v[18:19], off offset:-4096 nt
	global_load_dword v41, v[18:19], off nt
	global_load_dword v42, v[20:21], off offset:-4096 nt
	global_load_dword v43, v[20:21], off nt
	v_add_co_u32_e32 v14, vcc, s55, v12
	v_readlane_b32 s42, v247, 12
	s_nop 0
	v_addc_co_u32_e32 v15, vcc, 0, v13, vcc
	v_add_co_u32_e32 v16, vcc, s56, v12
	v_readlane_b32 s43, v247, 13
	s_nop 0
	v_addc_co_u32_e32 v17, vcc, 0, v13, vcc
	v_add_co_u32_e32 v18, vcc, s57, v12
	v_readlane_b32 s46, v247, 16
	s_nop 0
	v_addc_co_u32_e32 v19, vcc, 0, v13, vcc
	v_add_co_u32_e32 v20, vcc, s58, v12
	v_readlane_b32 s47, v247, 17
	s_nop 0
	v_addc_co_u32_e32 v21, vcc, 0, v13, vcc
	global_load_dword v44, v[14:15], off offset:-4096 nt
	global_load_dword v45, v[14:15], off nt
	global_load_dword v46, v[16:17], off offset:-4096 nt
	global_load_dword v47, v[16:17], off nt
	global_load_dword v48, v[18:19], off offset:-4096 nt
	global_load_dword v49, v[18:19], off nt
	global_load_dword v50, v[20:21], off offset:-4096 nt
	global_load_dword v51, v[20:21], off nt
	v_add_co_u32_e32 v14, vcc, s59, v12
	v_readlane_b32 s48, v247, 18
	s_nop 0
	v_addc_co_u32_e32 v15, vcc, 0, v13, vcc
	v_add_co_u32_e32 v16, vcc, s60, v12
	v_readlane_b32 s49, v247, 19
	s_nop 0
	v_addc_co_u32_e32 v17, vcc, 0, v13, vcc
	v_add_co_u32_e32 v18, vcc, s61, v12
	v_readlane_b32 s50, v247, 20
	s_nop 0
	v_addc_co_u32_e32 v19, vcc, 0, v13, vcc
	v_add_co_u32_e32 v20, vcc, s62, v12
	v_readlane_b32 s51, v247, 21
	s_nop 0
	v_addc_co_u32_e32 v21, vcc, 0, v13, vcc
	global_load_dword v52, v[14:15], off offset:-4096 nt
	s_nop 0
	global_load_dword v14, v[14:15], off nt
	s_nop 0
	global_load_dword v15, v[16:17], off offset:-4096 nt
	s_nop 0
	global_load_dword v16, v[16:17], off nt
	s_nop 0
	global_load_dword v17, v[18:19], off offset:-4096 nt
	s_nop 0
	global_load_dword v18, v[18:19], off nt
	s_nop 0
	global_load_dword v19, v[20:21], off offset:-4096 nt
	s_nop 0
	global_load_dword v20, v[20:21], off nt
	v_add_co_u32_e32 v12, vcc, s20, v12
	s_mov_b64 s[20:21], 0x280000
	s_nop 0
	v_addc_co_u32_e32 v13, vcc, 0, v13, vcc
	global_load_dword v12, v[12:13], off nt
	s_waitcnt vmcnt(30)
	ds_write2_b32 v35, v23, v24 offset1:66
	s_waitcnt vmcnt(28)
	ds_write2_b32 v35, v25, v26 offset0:132 offset1:198
	s_waitcnt vmcnt(26)
	ds_write2_b32 v84, v27, v28 offset0:8 offset1:74
	s_waitcnt vmcnt(24)
	ds_write2_b32 v84, v29, v30 offset0:140 offset1:206
	s_waitcnt vmcnt(22)
	ds_write2_b32 v85, v31, v32 offset0:16 offset1:82
	s_waitcnt vmcnt(20)
	ds_write2_b32 v85, v33, v40 offset0:148 offset1:214
	s_waitcnt vmcnt(18)
	ds_write2_b32 v86, v41, v42 offset0:24 offset1:90
	s_waitcnt vmcnt(16)
	ds_write2_b32 v86, v43, v44 offset0:156 offset1:222
	s_waitcnt vmcnt(14)
	ds_write2_b32 v87, v45, v46 offset0:32 offset1:98
	s_waitcnt vmcnt(12)
	ds_write2_b32 v87, v47, v48 offset0:164 offset1:230
	s_waitcnt vmcnt(10)
	ds_write2_b32 v88, v49, v50 offset0:40 offset1:106
	s_waitcnt vmcnt(8)
	ds_write2_b32 v88, v51, v52 offset0:172 offset1:238
	s_waitcnt vmcnt(6)
	ds_write2_b32 v89, v14, v15 offset0:48 offset1:114
	s_waitcnt vmcnt(4)
	ds_write2_b32 v89, v16, v17 offset0:180 offset1:246
	s_waitcnt vmcnt(2)
	ds_write2_b32 v90, v18, v19 offset0:56 offset1:122
	s_waitcnt vmcnt(0)
	ds_write2_b32 v90, v20, v12 offset0:188 offset1:254
	s_waitcnt lgkmcnt(0)
	ds_read2_b32 v[12:13], v39 offset1:33
	s_waitcnt lgkmcnt(0)
	v_cvt_pk_bf16_f32 v12, v12, v13
	ds_read2_b32 v[14:15], v39 offset0:66 offset1:99
	v_lshlrev_b32_e32 v16, 1, v9
	v_mov_b32_e32 v17, v5
	s_waitcnt lgkmcnt(0)
	v_cvt_pk_bf16_f32 v13, v14, v15
	ds_read2_b32 v[14:15], v39 offset0:132 offset1:165
	v_lshl_add_u64 v[10:11], v[10:11], 0, v[16:17]
	v_mov_b32_e32 v9, v5
	s_waitcnt lgkmcnt(0)
	v_cvt_pk_bf16_f32 v14, v14, v15
	ds_read2_b32 v[18:19], v39 offset0:198 offset1:231
	v_lshl_add_u64 v[10:11], v[10:11], 0, v[8:9]
	v_or_b32_e32 v9, v22, v37
	v_lshl_add_u64 v[16:17], v[10:11], 0, s[20:21]
	s_waitcnt lgkmcnt(0)
	v_cvt_pk_bf16_f32 v15, v18, v19
	v_lshlrev_b32_e32 v18, 10, v9
	v_mov_b32_e32 v19, v5
	ds_read2_b32 v[10:11], v39 offset0:8 offset1:41
	v_lshl_add_u64 v[18:19], v[16:17], 0, v[18:19]
	global_store_dwordx4 v[18:19], v[12:15], off
	s_waitcnt lgkmcnt(0)
	v_cvt_pk_bf16_f32 v10, v10, v11
	ds_read2_b32 v[12:13], v39 offset0:74 offset1:107
	v_or_b32_e32 v9, v22, v77
	s_waitcnt lgkmcnt(0)
	v_cvt_pk_bf16_f32 v11, v12, v13
	ds_read2_b32 v[12:13], v39 offset0:140 offset1:173
	v_lshlrev_b32_e32 v18, 10, v9
	v_mov_b32_e32 v19, v5
	s_waitcnt lgkmcnt(0)
	v_cvt_pk_bf16_f32 v12, v12, v13
	ds_read2_b32 v[14:15], v39 offset0:206 offset1:239
	s_waitcnt lgkmcnt(0)
	v_cvt_pk_bf16_f32 v13, v14, v15
	v_lshl_add_u64 v[18:19], v[16:17], 0, v[18:19]
	ds_read2_b32 v[14:15], v39 offset0:16 offset1:49
	global_store_dwordx4 v[18:19], v[10:13], off
	v_or_b32_e32 v9, v22, v78
	v_lshlrev_b32_e32 v18, 10, v9
	s_waitcnt lgkmcnt(0)
	v_cvt_pk_bf16_f32 v10, v14, v15
	ds_read2_b32 v[12:13], v39 offset0:82 offset1:115
	s_waitcnt lgkmcnt(0)
	v_cvt_pk_bf16_f32 v11, v12, v13
	ds_read2_b32 v[12:13], v39 offset0:148 offset1:181
	v_mov_b32_e32 v19, v5
	s_waitcnt lgkmcnt(0)
	v_cvt_pk_bf16_f32 v12, v12, v13
	ds_read2_b32 v[14:15], v39 offset0:214 offset1:247
	s_waitcnt lgkmcnt(0)
	v_cvt_pk_bf16_f32 v13, v14, v15
	v_lshl_add_u64 v[18:19], v[16:17], 0, v[18:19]
	ds_read2_b32 v[14:15], v39 offset0:24 offset1:57
	global_store_dwordx4 v[18:19], v[10:13], off
	v_or_b32_e32 v9, v22, v79
	s_waitcnt lgkmcnt(0)
	v_cvt_pk_bf16_f32 v10, v14, v15
	ds_read2_b32 v[12:13], v39 offset0:90 offset1:123
	s_waitcnt lgkmcnt(0)
	v_cvt_pk_bf16_f32 v11, v12, v13
	ds_read2_b32 v[12:13], v39 offset0:156 offset1:189
	s_waitcnt lgkmcnt(0)
	v_cvt_pk_bf16_f32 v12, v12, v13
	ds_read2_b32 v[14:15], v39 offset0:222 offset1:255
	s_waitcnt lgkmcnt(0)
	v_cvt_pk_bf16_f32 v13, v14, v15
	v_lshlrev_b32_e32 v14, 10, v9
	v_mov_b32_e32 v15, v5
	v_lshl_add_u64 v[14:15], v[16:17], 0, v[14:15]
	global_store_dwordx4 v[14:15], v[10:13], off
	s_waitcnt lgkmcnt(0)

.LBB0_42:
	s_andn2_saveexec_b64 s[16:17], s[16:17]
	s_cbranch_execz .LBB0_9
	v_mul_i32_i24_e32 v9, 0x6667, v15
	v_ashrrev_i16_sdwa v13, v93, v9 dst_sel:DWORD dst_unused:UNUSED_PAD src0_sel:DWORD src1_sel:WORD_1
	v_lshrrev_b32_e32 v9, 31, v9
	v_add_u16_e32 v9, v13, v9
	v_readlane_b32 s36, v247, 42
	v_mul_lo_u16_e32 v13, 40, v9
	v_mul_hi_i32_i24_e32 v17, 0x500000, v12
	v_mul_i32_i24_e32 v16, 0x500000, v12
	v_readlane_b32 s42, v247, 48
	v_readlane_b32 s43, v247, 49
	v_sub_u16_e32 v13, v15, v13
	v_lshlrev_b32_sdwa v14, v95, sext(v13) dst_sel:DWORD dst_unused:UNUSED_PAD src0_sel:DWORD src1_sel:WORD_0
	v_lshl_add_u64 v[18:19], s[42:43], 0, v[16:17]
	v_lshlrev_b32_sdwa v16, v94, sext(v9) dst_sel:DWORD dst_unused:UNUSED_PAD src0_sel:DWORD src1_sel:WORD_0
	v_or_b32_e32 v56, v16, v3
	v_ashrrev_i32_e32 v15, 31, v14
	v_lshl_add_u64 v[18:19], v[14:15], 2, v[18:19]
	v_or_b32_e32 v13, 2, v56
	v_lshl_add_u64 v[58:59], v[18:19], 0, v[4:5]
	v_mul_hi_i32_i24_e32 v19, 0x1400, v56
	v_mul_i32_i24_e32 v18, 0x1400, v56
	v_mul_hi_i32_i24_e32 v21, 0x1400, v13
	v_mul_i32_i24_e32 v20, 0x1400, v13
	v_lshl_add_u64 v[18:19], v[58:59], 0, v[18:19]
	v_lshl_add_u64 v[20:21], v[58:59], 0, v[20:21]
	v_or_b32_e32 v161, 4, v56
	v_or_b32_e32 v162, 6, v56
	global_load_dword v18, v[18:19], off nt
	v_mul_hi_i32_i24_e32 v23, 0x1400, v162
	global_load_dword v19, v[20:21], off nt
	v_mul_hi_i32_i24_e32 v21, 0x1400, v161
	v_mul_i32_i24_e32 v20, 0x1400, v161
	v_mul_i32_i24_e32 v22, 0x1400, v162
	v_lshl_add_u64 v[20:21], v[58:59], 0, v[20:21]
	v_lshl_add_u64 v[22:23], v[58:59], 0, v[22:23]
	v_or_b32_e32 v60, 8, v56
	v_or_b32_e32 v61, 10, v56
	global_load_dword v20, v[20:21], off nt
	v_mul_hi_i32_i24_e32 v25, 0x1400, v61
	global_load_dword v21, v[22:23], off nt
	v_mul_hi_i32_i24_e32 v23, 0x1400, v60
	v_mul_i32_i24_e32 v22, 0x1400, v60
	v_mul_i32_i24_e32 v24, 0x1400, v61
	v_lshl_add_u64 v[22:23], v[58:59], 0, v[22:23]
	v_lshl_add_u64 v[24:25], v[58:59], 0, v[24:25]
	v_or_b32_e32 v62, 12, v56
	v_or_b32_e32 v63, 14, v56
	global_load_dword v22, v[22:23], off nt
	v_mul_hi_i32_i24_e32 v27, 0x1400, v63
	global_load_dword v23, v[24:25], off nt
	v_mul_hi_i32_i24_e32 v25, 0x1400, v62
	v_mul_i32_i24_e32 v24, 0x1400, v62
	v_mul_i32_i24_e32 v26, 0x1400, v63
	v_lshl_add_u64 v[24:25], v[58:59], 0, v[24:25]
	v_lshl_add_u64 v[26:27], v[58:59], 0, v[26:27]
	v_or_b32_e32 v64, 16, v56
	v_or_b32_e32 v65, 18, v56
	global_load_dword v24, v[24:25], off nt
	v_mul_hi_i32_i24_e32 v29, 0x1400, v65
	global_load_dword v25, v[26:27], off nt
	v_mul_hi_i32_i24_e32 v27, 0x1400, v64
	v_mul_i32_i24_e32 v26, 0x1400, v64
	v_mul_i32_i24_e32 v28, 0x1400, v65
	v_lshl_add_u64 v[26:27], v[58:59], 0, v[26:27]
	v_lshl_add_u64 v[28:29], v[58:59], 0, v[28:29]
	v_or_b32_e32 v66, 20, v56
	v_or_b32_e32 v67, 22, v56
	global_load_dword v26, v[26:27], off nt
	v_mul_hi_i32_i24_e32 v31, 0x1400, v67
	global_load_dword v27, v[28:29], off nt
	v_mul_hi_i32_i24_e32 v29, 0x1400, v66
	v_mul_i32_i24_e32 v28, 0x1400, v66
	v_mul_i32_i24_e32 v30, 0x1400, v67
	v_lshl_add_u64 v[28:29], v[58:59], 0, v[28:29]
	v_lshl_add_u64 v[30:31], v[58:59], 0, v[30:31]
	v_or_b32_e32 v68, 24, v56
	v_or_b32_e32 v69, 26, v56
	global_load_dword v28, v[28:29], off nt
	v_mul_hi_i32_i24_e32 v33, 0x1400, v69
	global_load_dword v29, v[30:31], off nt
	v_mul_hi_i32_i24_e32 v31, 0x1400, v68
	v_mul_i32_i24_e32 v30, 0x1400, v68
	v_mul_i32_i24_e32 v32, 0x1400, v69
	v_lshl_add_u64 v[30:31], v[58:59], 0, v[30:31]
	v_lshl_add_u64 v[32:33], v[58:59], 0, v[32:33]
	v_or_b32_e32 v70, 28, v56
	v_or_b32_e32 v71, 30, v56
	global_load_dword v30, v[30:31], off nt
	v_mul_hi_i32_i24_e32 v41, 0x1400, v71
	global_load_dword v31, v[32:33], off nt
	v_mul_hi_i32_i24_e32 v33, 0x1400, v70
	v_mul_i32_i24_e32 v32, 0x1400, v70
	v_mul_i32_i24_e32 v40, 0x1400, v71
	v_lshl_add_u64 v[32:33], v[58:59], 0, v[32:33]
	v_lshl_add_u64 v[40:41], v[58:59], 0, v[40:41]
	v_or_b32_e32 v159, 32, v56
	v_or_b32_e32 v160, 34, v56
	global_load_dword v32, v[32:33], off nt
	v_mul_hi_i32_i24_e32 v43, 0x1400, v160
	global_load_dword v33, v[40:41], off nt
	v_mul_hi_i32_i24_e32 v41, 0x1400, v159
	v_mul_i32_i24_e32 v40, 0x1400, v159
	v_mul_i32_i24_e32 v42, 0x1400, v160
	v_lshl_add_u64 v[40:41], v[58:59], 0, v[40:41]
	v_lshl_add_u64 v[42:43], v[58:59], 0, v[42:43]
	v_or_b32_e32 v157, 36, v56
	v_or_b32_e32 v158, 38, v56
	global_load_dword v40, v[40:41], off nt
	v_mul_hi_i32_i24_e32 v45, 0x1400, v158
	global_load_dword v41, v[42:43], off nt
	v_mul_hi_i32_i24_e32 v43, 0x1400, v157
	v_mul_i32_i24_e32 v42, 0x1400, v157
	v_mul_i32_i24_e32 v44, 0x1400, v158
	v_lshl_add_u64 v[42:43], v[58:59], 0, v[42:43]
	v_lshl_add_u64 v[44:45], v[58:59], 0, v[44:45]
	v_or_b32_e32 v155, 40, v56
	v_or_b32_e32 v156, 42, v56
	global_load_dword v42, v[42:43], off nt
	v_mul_hi_i32_i24_e32 v47, 0x1400, v156
	global_load_dword v43, v[44:45], off nt
	v_mul_hi_i32_i24_e32 v45, 0x1400, v155
	v_mul_i32_i24_e32 v44, 0x1400, v155
	v_mul_i32_i24_e32 v46, 0x1400, v156
	v_lshl_add_u64 v[44:45], v[58:59], 0, v[44:45]
	v_lshl_add_u64 v[46:47], v[58:59], 0, v[46:47]
	v_or_b32_e32 v153, 44, v56
	v_or_b32_e32 v154, 46, v56
	global_load_dword v44, v[44:45], off nt
	v_mul_hi_i32_i24_e32 v49, 0x1400, v154
	global_load_dword v45, v[46:47], off nt
	v_mul_hi_i32_i24_e32 v47, 0x1400, v153
	v_mul_i32_i24_e32 v46, 0x1400, v153
	v_mul_i32_i24_e32 v48, 0x1400, v154
	v_lshl_add_u64 v[46:47], v[58:59], 0, v[46:47]
	v_lshl_add_u64 v[48:49], v[58:59], 0, v[48:49]
	v_or_b32_e32 v75, 48, v56
	v_or_b32_e32 v152, 50, v56
	global_load_dword v46, v[46:47], off nt
	v_mul_hi_i32_i24_e32 v51, 0x1400, v152
	global_load_dword v47, v[48:49], off nt
	v_mul_hi_i32_i24_e32 v49, 0x1400, v75
	v_mul_i32_i24_e32 v48, 0x1400, v75
	v_mul_i32_i24_e32 v50, 0x1400, v152
	v_lshl_add_u64 v[48:49], v[58:59], 0, v[48:49]
	v_lshl_add_u64 v[50:51], v[58:59], 0, v[50:51]
	v_or_b32_e32 v73, 52, v56
	v_or_b32_e32 v74, 54, v56
	global_load_dword v48, v[48:49], off nt
	v_mul_hi_i32_i24_e32 v53, 0x1400, v74
	global_load_dword v49, v[50:51], off nt
	v_mul_hi_i32_i24_e32 v51, 0x1400, v73
	v_mul_i32_i24_e32 v50, 0x1400, v73
	v_mul_i32_i24_e32 v52, 0x1400, v74
	v_lshl_add_u64 v[50:51], v[58:59], 0, v[50:51]
	v_lshl_add_u64 v[52:53], v[58:59], 0, v[52:53]
	v_or_b32_e32 v17, 56, v56
	v_or_b32_e32 v72, 58, v56
	global_load_dword v50, v[50:51], off nt
	v_mul_hi_i32_i24_e32 v55, 0x1400, v72
	global_load_dword v51, v[52:53], off nt
	v_mul_hi_i32_i24_e32 v53, 0x1400, v17
	v_mul_i32_i24_e32 v52, 0x1400, v17
	v_mul_i32_i24_e32 v54, 0x1400, v72
	v_lshl_add_u64 v[52:53], v[58:59], 0, v[52:53]
	v_lshl_add_u64 v[54:55], v[58:59], 0, v[54:55]
	v_or_b32_e32 v9, 60, v56
	v_or_b32_e32 v15, 62, v56
	global_load_dword v52, v[52:53], off nt
	v_mul_hi_i32_i24_e32 v165, 0x1400, v15
	global_load_dword v53, v[54:55], off nt
	v_mul_hi_i32_i24_e32 v55, 0x1400, v9
	v_mul_i32_i24_e32 v54, 0x1400, v9
	v_mul_i32_i24_e32 v164, 0x1400, v15
	v_lshl_add_u64 v[54:55], v[58:59], 0, v[54:55]
	v_lshl_add_u64 v[58:59], v[58:59], 0, v[164:165]
	global_load_dword v54, v[54:55], off nt
	v_readlane_b32 s40, v247, 46
	global_load_dword v55, v[58:59], off nt
	v_readlane_b32 s41, v247, 47
	s_andn2_b64 vcc, exec, s[12:13]
	v_readlane_b32 s37, v247, 43
	v_readlane_b32 s38, v247, 44
	v_readlane_b32 s39, v247, 45
	v_readlane_b32 s44, v247, 50
	v_readlane_b32 s45, v247, 51
	v_readlane_b32 s46, v247, 52
	v_readlane_b32 s47, v247, 53
	v_readlane_b32 s48, v247, 54
	v_readlane_b32 s49, v247, 55
	v_readlane_b32 s50, v247, 56
	v_readlane_b32 s51, v247, 57
	s_cbranch_vccnz .LBB0_8
	v_lshlrev_b32_e32 v58, 10, v12
	v_ashrrev_i32_e32 v59, 31, v58
	v_ashrrev_i32_e32 v57, 31, v56
	v_lshl_add_u64 v[58:59], v[58:59], 2, s[40:41]
	v_cmp_gt_i32_e32 vcc, s82, v56
	v_lshl_add_u64 v[56:57], v[56:57], 2, v[58:59]
	s_nop 0
	v_cndmask_b32_e64 v59, -1, 0, vcc
	v_cndmask_b32_e64 v58, v96, 0, vcc
	v_lshl_add_u64 v[58:59], v[56:57], 0, v[58:59]
	v_cmp_gt_i32_e32 vcc, s82, v13
	global_load_dword v12, v[58:59], off nt
	s_nop 0
	v_cndmask_b32_e64 v59, -1, 0, vcc
	v_cndmask_b32_e64 v58, v97, 8, vcc
	v_lshl_add_u64 v[58:59], v[56:57], 0, v[58:59]
	v_cmp_gt_i32_e32 vcc, s82, v161
	global_load_dword v13, v[58:59], off nt
	s_waitcnt vmcnt(0)
	v_pk_mul_f32 v[18:19], v[18:19], v[12:13]
	v_cndmask_b32_e64 v59, -1, 0, vcc
	v_cndmask_b32_e64 v58, v98, 16, vcc
	v_cmp_gt_i32_e32 vcc, s82, v162
	v_lshl_add_u64 v[58:59], v[56:57], 0, v[58:59]
	global_load_dword v58, v[58:59], off nt
	v_cndmask_b32_e64 v163, -1, 0, vcc
	v_cndmask_b32_e64 v162, v99, 24, vcc
	v_lshl_add_u64 v[162:163], v[56:57], 0, v[162:163]
	v_cmp_gt_i32_e32 vcc, s82, v60
	global_load_dword v59, v[162:163], off nt
	s_waitcnt vmcnt(0)
	v_pk_mul_f32 v[20:21], v[20:21], v[58:59]
	v_cndmask_b32_e64 v163, -1, 0, vcc
	v_cndmask_b32_e64 v162, v100, 32, vcc
	v_lshl_add_u64 v[162:163], v[56:57], 0, v[162:163]
	v_cmp_gt_i32_e32 vcc, s82, v61
	global_load_dword v60, v[162:163], off nt
	s_nop 0
	v_cndmask_b32_e64 v163, -1, 0, vcc
	v_cndmask_b32_e64 v162, v101, 40, vcc
	v_lshl_add_u64 v[162:163], v[56:57], 0, v[162:163]
	v_cmp_gt_i32_e32 vcc, s82, v62
	global_load_dword v61, v[162:163], off nt
	s_waitcnt vmcnt(0)
	v_pk_mul_f32 v[22:23], v[22:23], v[60:61]
	v_cndmask_b32_e64 v163, -1, 0, vcc
	v_cndmask_b32_e64 v162, v102, 48, vcc
	v_lshl_add_u64 v[162:163], v[56:57], 0, v[162:163]
	v_cmp_gt_i32_e32 vcc, s82, v63
	global_load_dword v62, v[162:163], off nt
	s_nop 0
	v_cndmask_b32_e64 v163, -1, 0, vcc
	v_cndmask_b32_e64 v162, v103, 56, vcc
	v_lshl_add_u64 v[162:163], v[56:57], 0, v[162:163]
	v_cmp_gt_i32_e32 vcc, s82, v64
	global_load_dword v63, v[162:163], off nt
	s_waitcnt vmcnt(0)
	v_pk_mul_f32 v[24:25], v[24:25], v[62:63]
	v_cndmask_b32_e64 v163, -1, 0, vcc
	v_cndmask_b32_e64 v162, v104, 64, vcc
	v_lshl_add_u64 v[162:163], v[56:57], 0, v[162:163]
	v_cmp_gt_i32_e32 vcc, s82, v65
	global_load_dword v64, v[162:163], off nt
	s_nop 0
	v_cndmask_b32_e64 v163, -1, 0, vcc
	v_cndmask_b32_e32 v162, v105, v106, vcc
	v_lshl_add_u64 v[162:163], v[56:57], 0, v[162:163]
	v_cmp_gt_i32_e32 vcc, s82, v66
	global_load_dword v65, v[162:163], off nt
	s_waitcnt vmcnt(0)
	v_pk_mul_f32 v[26:27], v[26:27], v[64:65]
	v_cndmask_b32_e64 v163, -1, 0, vcc
	v_cndmask_b32_e32 v162, v107, v108, vcc
	v_lshl_add_u64 v[162:163], v[56:57], 0, v[162:163]
	v_cmp_gt_i32_e32 vcc, s82, v67
	global_load_dword v66, v[162:163], off nt
	s_nop 0
	v_cndmask_b32_e64 v163, -1, 0, vcc
	v_cndmask_b32_e32 v162, v109, v110, vcc
	v_lshl_add_u64 v[162:163], v[56:57], 0, v[162:163]
	v_cmp_gt_i32_e32 vcc, s82, v68
	global_load_dword v67, v[162:163], off nt
	s_waitcnt vmcnt(0)
	v_pk_mul_f32 v[28:29], v[28:29], v[66:67]
	v_cndmask_b32_e64 v163, -1, 0, vcc
	v_cndmask_b32_e32 v162, v111, v112, vcc
	v_lshl_add_u64 v[162:163], v[56:57], 0, v[162:163]
	v_cmp_gt_i32_e32 vcc, s82, v69
	global_load_dword v68, v[162:163], off nt
	s_nop 0
	v_cndmask_b32_e64 v163, -1, 0, vcc
	v_cndmask_b32_e32 v162, v113, v114, vcc
	v_lshl_add_u64 v[162:163], v[56:57], 0, v[162:163]
	v_cmp_gt_i32_e32 vcc, s82, v70
	global_load_dword v69, v[162:163], off nt
	s_waitcnt vmcnt(0)
	v_pk_mul_f32 v[30:31], v[30:31], v[68:69]
	v_cndmask_b32_e64 v163, -1, 0, vcc
	v_cndmask_b32_e32 v162, v115, v116, vcc
	v_lshl_add_u64 v[162:163], v[56:57], 0, v[162:163]
	v_cmp_gt_i32_e32 vcc, s82, v71
	global_load_dword v70, v[162:163], off nt
	s_nop 0
	v_cndmask_b32_e64 v163, -1, 0, vcc
	v_cndmask_b32_e32 v162, v117, v118, vcc
	v_lshl_add_u64 v[162:163], v[56:57], 0, v[162:163]
	v_cmp_gt_i32_e32 vcc, s82, v159
	global_load_dword v71, v[162:163], off nt
	s_waitcnt vmcnt(0)
	v_pk_mul_f32 v[32:33], v[32:33], v[70:71]
	v_cndmask_b32_e64 v163, -1, 0, vcc
	v_cndmask_b32_e32 v162, v119, v120, vcc
	v_cmp_gt_i32_e32 vcc, s82, v160
	v_lshl_add_u64 v[162:163], v[56:57], 0, v[162:163]
	global_load_dword v162, v[162:163], off nt
	v_cndmask_b32_e64 v161, -1, 0, vcc
	v_cndmask_b32_e32 v160, v121, v122, vcc
	v_lshl_add_u64 v[160:161], v[56:57], 0, v[160:161]
	v_cmp_gt_i32_e32 vcc, s82, v157
	global_load_dword v163, v[160:161], off nt
	s_waitcnt vmcnt(0)
	v_pk_mul_f32 v[40:41], v[40:41], v[162:163]
	v_cndmask_b32_e64 v161, -1, 0, vcc
	v_cndmask_b32_e32 v160, v123, v124, vcc
	v_cmp_gt_i32_e32 vcc, s82, v158
	v_lshl_add_u64 v[160:161], v[56:57], 0, v[160:161]
	global_load_dword v160, v[160:161], off nt
	v_cndmask_b32_e64 v159, -1, 0, vcc
	v_cndmask_b32_e32 v158, v125, v126, vcc
	v_lshl_add_u64 v[158:159], v[56:57], 0, v[158:159]
	v_cmp_gt_i32_e32 vcc, s82, v155
	global_load_dword v161, v[158:159], off nt
	s_waitcnt vmcnt(0)
	v_pk_mul_f32 v[42:43], v[42:43], v[160:161]
	v_cndmask_b32_e64 v159, -1, 0, vcc
	v_cndmask_b32_e32 v158, v127, v128, vcc
	v_cmp_gt_i32_e32 vcc, s82, v156
	v_lshl_add_u64 v[158:159], v[56:57], 0, v[158:159]
	global_load_dword v158, v[158:159], off nt
	v_cndmask_b32_e64 v157, -1, 0, vcc
	v_cndmask_b32_e32 v156, v129, v130, vcc
	v_lshl_add_u64 v[156:157], v[56:57], 0, v[156:157]
	v_cmp_gt_i32_e32 vcc, s82, v153
	global_load_dword v159, v[156:157], off nt
	s_waitcnt vmcnt(0)
	v_pk_mul_f32 v[44:45], v[44:45], v[158:159]
	v_cndmask_b32_e64 v157, -1, 0, vcc
	v_cndmask_b32_e32 v156, v131, v132, vcc
	v_cmp_gt_i32_e32 vcc, s82, v154
	v_lshl_add_u64 v[156:157], v[56:57], 0, v[156:157]
	global_load_dword v156, v[156:157], off nt
	v_cndmask_b32_e64 v155, -1, 0, vcc
	v_cndmask_b32_e32 v154, v133, v134, vcc
	v_lshl_add_u64 v[154:155], v[56:57], 0, v[154:155]
	v_cmp_gt_i32_e32 vcc, s82, v75
	global_load_dword v157, v[154:155], off nt
	s_waitcnt vmcnt(0)
	v_pk_mul_f32 v[46:47], v[46:47], v[156:157]
	v_cndmask_b32_e64 v155, -1, 0, vcc
	v_cndmask_b32_e32 v154, v135, v136, vcc
	v_cmp_gt_i32_e32 vcc, s82, v152
	v_lshl_add_u64 v[154:155], v[56:57], 0, v[154:155]
	global_load_dword v154, v[154:155], off nt
	v_cndmask_b32_e64 v153, -1, 0, vcc
	v_cndmask_b32_e32 v152, v137, v138, vcc
	v_lshl_add_u64 v[152:153], v[56:57], 0, v[152:153]
	v_cmp_gt_i32_e32 vcc, s82, v73
	global_load_dword v155, v[152:153], off nt
	s_waitcnt vmcnt(0)
	v_pk_mul_f32 v[48:49], v[48:49], v[154:155]
	v_cndmask_b32_e64 v153, -1, 0, vcc
	v_cndmask_b32_e32 v152, v139, v140, vcc
	v_cmp_gt_i32_e32 vcc, s82, v74
	v_lshl_add_u64 v[152:153], v[56:57], 0, v[152:153]
	global_load_dword v152, v[152:153], off nt
	v_cndmask_b32_e64 v75, -1, 0, vcc
	v_cndmask_b32_e32 v74, v141, v142, vcc
	v_lshl_add_u64 v[74:75], v[56:57], 0, v[74:75]
	v_cmp_gt_i32_e32 vcc, s82, v17
	global_load_dword v153, v[74:75], off nt
	s_waitcnt vmcnt(0)
	v_pk_mul_f32 v[50:51], v[50:51], v[152:153]
	v_cndmask_b32_e64 v75, -1, 0, vcc
	v_cndmask_b32_e32 v74, v143, v144, vcc
	v_cmp_gt_i32_e32 vcc, s82, v72
	v_lshl_add_u64 v[74:75], v[56:57], 0, v[74:75]
	global_load_dword v74, v[74:75], off nt
	v_cndmask_b32_e64 v73, -1, 0, vcc
	v_cndmask_b32_e32 v72, v145, v146, vcc
	v_lshl_add_u64 v[72:73], v[56:57], 0, v[72:73]
	v_cmp_gt_i32_e32 vcc, s82, v9
	global_load_dword v75, v[72:73], off nt
	s_waitcnt vmcnt(0)
	v_pk_mul_f32 v[52:53], v[52:53], v[74:75]
	v_cndmask_b32_e64 v73, -1, 0, vcc
	v_cndmask_b32_e32 v72, v147, v148, vcc
	v_cmp_gt_i32_e32 vcc, s82, v15
	v_lshl_add_u64 v[72:73], v[56:57], 0, v[72:73]
	global_load_dword v72, v[72:73], off nt
	v_cndmask_b32_e64 v165, -1, 0, vcc
	v_cndmask_b32_e32 v164, v149, v150, vcc
	v_lshl_add_u64 v[56:57], v[56:57], 0, v[164:165]
	global_load_dword v73, v[56:57], off nt
	s_waitcnt vmcnt(0)
	v_pk_mul_f32 v[54:55], v[54:55], v[72:73]
	s_branch .LBB0_8

.LBB0_48:
	v_add_u32_e32 v35, s6, v38
	v_cmp_gt_i32_e64 s[4:5], s3, v35
	v_ashrrev_i32_e32 v39, 31, v38
	s_waitcnt lgkmcnt(1)
	v_lshlrev_b64 v[2:3], 12, v[38:39]
	v_cndmask_b32_e64 v44, v38, v35, s[4:5]
	v_ashrrev_i32_e32 v45, 31, v44
	v_lshl_add_u64 v[46:47], v[42:43], 0, v[2:3]
	v_lshlrev_b64 v[2:3], 12, v[44:45]
	v_lshl_add_u64 v[48:49], v[42:43], 0, v[2:3]
	global_load_dwordx4 v[30:33], v[46:47], off nt
	global_load_dwordx4 v[22:25], v[46:47], off offset:1024 nt
	global_load_dwordx4 v[26:29], v[48:49], off nt
	global_load_dwordx4 v[18:21], v[48:49], off offset:1024 nt
	global_load_dwordx4 v[14:17], v[46:47], off offset:2048 nt
	global_load_dwordx4 v[10:13], v[46:47], off offset:3072 nt
	global_load_dwordx4 v[6:9], v[48:49], off offset:2048 nt
	s_waitcnt lgkmcnt(0)
	global_load_dwordx4 v[2:5], v[48:49], off offset:3072 nt
	v_lshlrev_b64 v[46:47], 11, v[38:39]
	v_lshlrev_b64 v[44:45], 11, v[44:45]
	v_lshl_add_u64 v[46:47], v[40:41], 0, v[46:47]
	v_lshl_add_u64 v[44:45], v[40:41], 0, v[44:45]
	s_waitcnt vmcnt(7)
	v_cvt_pk_bf16_f32 v48, v30, v31
	v_cvt_pk_bf16_f32 v49, v32, v33
	global_store_dwordx2 v[46:47], v[48:49], off
	s_waitcnt vmcnt(6)
	v_cvt_pk_bf16_f32 v48, v26, v27
	v_cvt_pk_bf16_f32 v49, v28, v29
	s_and_saveexec_b64 s[0:1], s[4:5]
	s_cbranch_execz .LBB0_50
	global_store_dwordx2 v[44:45], v[48:49], off

.LBB0_61:
	v_ashrrev_i32_e32 v7, 31, v6
	v_lshl_add_u64 v[18:19], v[6:7], 4, s[18:19]
	global_load_dwordx4 v[10:13], v[18:19], off nt
	global_load_dwordx4 v[14:17], v[18:19], off offset:16 nt
	v_add_u32_e32 v1, s0, v1
	v_cmp_lt_i32_e32 vcc, s3, v1
	v_add_u32_e32 v6, s1, v6
	s_or_b64 s[10:11], vcc, s[10:11]
	s_waitcnt vmcnt(1)
	v_cvt_pk_bf16_f32 v10, v10, v11
	v_cvt_pk_bf16_f32 v11, v12, v13
	s_waitcnt vmcnt(0)
	v_cvt_pk_bf16_f32 v12, v14, v15
	v_cvt_pk_bf16_f32 v13, v16, v17
	global_store_dwordx4 v[4:5], v[10:13], off
	v_lshl_add_u64 v[4:5], v[4:5], 0, s[6:7]
	s_andn2_b64 exec, exec, s[10:11]
	s_cbranch_execnz .LBB0_61

.LBB0_71:
	s_ashr_i32 s68, s88, 1
	s_ashr_i32 s69, s68, 31
	s_and_saveexec_b64 s[74:75], s[4:5]
	s_cbranch_execz .LBB0_73
	v_readlane_b32 s44, v247, 42
	v_readlane_b32 s45, v247, 43
	v_readlane_b32 s46, v247, 44
	v_readlane_b32 s47, v247, 45
	v_readlane_b32 s48, v247, 46
	v_readlane_b32 s49, v247, 47
	v_readlane_b32 s50, v247, 48
	v_readlane_b32 s51, v247, 49
	v_readlane_b32 s52, v247, 50
	v_readlane_b32 s53, v247, 51
	v_readlane_b32 s54, v247, 52
	v_readlane_b32 s55, v247, 53
	v_readlane_b32 s56, v247, 54
	v_readlane_b32 s57, v247, 55
	v_readlane_b32 s58, v247, 56
	v_readlane_b32 s59, v247, 57
	s_mov_b64 s[44:45], s[52:53]
	s_lshl_b64 s[78:79], s[68:69], 2
	s_mov_b64 s[48:49], s[56:57]
	s_add_u32 s78, s48, s78
	s_addc_u32 s79, s49, s79
	global_load_dword v20, v21, s[78:79] nt
	v_lshl_add_u32 v2, s68, 6, v34
	v_ashrrev_i32_e32 v3, 31, v2
	s_mov_b64 s[46:47], s[54:55]
	v_lshlrev_b64 v[2:3], 2, v[2:3]
	v_lshl_add_u64 v[4:5], s[44:45], 0, v[2:3]
	v_lshl_add_u64 v[2:3], s[46:47], 0, v[2:3]
	global_load_dword v162, v[4:5], off nt
	global_load_dword v163, v[2:3], off nt
	s_lshl_b64 s[78:79], s[68:69], 10
	v_lshl_add_u64 v[2:3], s[78:79], 0, v[18:19]
	s_mov_b64 s[50:51], s[58:59]
	v_lshlrev_b64 v[2:3], 2, v[2:3]
	v_lshl_add_u64 v[6:7], s[50:51], 0, v[2:3]
	v_readlane_b32 s44, v247, 6
	v_readlane_b32 s45, v247, 7
	v_mov_b32_e32 v165, v78
	v_mov_b32_e32 v79, v21
	v_lshl_add_u64 v[158:159], s[44:45], 0, v[2:3]
	global_load_dwordx4 v[2:5], v[6:7], off offset:48 nt
	global_load_dwordx4 v[10:13], v[6:7], off offset:32 nt
	global_load_dwordx4 v[146:149], v[6:7], off offset:16 nt
	global_load_dwordx4 v[150:153], v[6:7], off nt
	s_nop 0
	global_load_dwordx4 v[6:9], v[158:159], off offset:48 nt
	global_load_dwordx4 v[14:17], v[158:159], off offset:32 nt
	global_load_dwordx4 v[154:157], v[158:159], off offset:16 nt
	s_nop 0
	global_load_dwordx4 v[158:161], v[158:159], off nt
	v_readlane_b32 s46, v247, 8
	v_readlane_b32 s47, v247, 9
	v_readlane_b32 s48, v247, 10
	v_readlane_b32 s49, v247, 11
	v_readlane_b32 s50, v247, 12
	v_readlane_b32 s51, v247, 13
	v_readlane_b32 s52, v247, 14
	v_readlane_b32 s53, v247, 15
	v_readlane_b32 s54, v247, 16
	v_readlane_b32 s55, v247, 17
	v_readlane_b32 s56, v247, 18
	v_readlane_b32 s57, v247, 19
	v_readlane_b32 s58, v247, 20
	v_readlane_b32 s59, v247, 21
	s_waitcnt vmcnt(10)
	v_mul_f32_e32 v20, 0x3fb8aa3b, v20
	v_exp_f32_e32 v81, v20
	s_waitcnt vmcnt(9)
	v_mov_b32_e32 v169, v162
	s_waitcnt vmcnt(8)
	v_pk_mul_f32 v[166:167], v[162:163], v[162:163]
	v_mul_f32_e32 v145, v162, v81
	v_mul_f32_e32 v162, v81, v163
	v_mul_f32_e32 v81, 0x3fb8aa3b, v145
	v_mul_f32_e32 v145, 0x3f22f983, v162
	v_exp_f32_e32 v170, v81
	v_rndne_f32_e32 v81, v145
	v_fmac_f32_e32 v162, 0xbfc90fda, v81
	v_cvt_i32_f32_e32 v145, v81
	v_fmac_f32_e32 v162, 0xb3a22168, v81
	v_fmac_f32_e32 v162, 0xa7c234c5, v81
	v_mul_f32_e32 v175, v162, v162
	v_fmamk_f32 v171, v175, 0x3638ef1d, v35
	v_fmamk_f32 v172, v175, 0xb493f27e, v135
	v_mov_b32_e32 v20, v163
	v_mov_b32_e32 v168, v163
	v_add_u32_e32 v163, 1, v145
	v_fmaak_f32 v171, v171, v175, 0x3c088889
	v_fmaak_f32 v172, v172, v175, 0xbab60b61
	v_and_b32_e32 v176, 2, v163
	v_fmaak_f32 v163, v171, v175, 0xbe2aaaab
	v_fmaak_f32 v171, v172, v175, 0x3d2aaaab
	v_mov_b32_e32 v164, v162
	v_and_b32_e32 v81, 1, v145
	v_mul_f32_e32 v174, v175, v163
	v_fma_f32 v163, v171, v175, -0.5
	v_pk_fma_f32 v[162:163], v[162:163], v[174:175], v[164:165]
	v_cmp_eq_u32_e32 vcc, 0, v81
	v_and_b32_e32 v145, 2, v145
	v_pk_add_f32 v[166:167], v[166:167], v[166:167] op_sel:[0,1] op_sel_hi:[0,1]
	v_cndmask_b32_e32 v81, v163, v162, vcc
	v_cndmask_b32_e32 v162, v162, v163, vcc
	v_cmp_eq_u32_e32 vcc, 0, v176
	s_nop 1
	v_cndmask_b32_e64 v163, -v162, v162, vcc
	v_cmp_eq_u32_e32 vcc, 0, v145
	s_nop 1
	v_cndmask_b32_e64 v162, -v81, v81, vcc
	v_pk_mul_f32 v[162:163], v[170:171], v[162:163] op_sel_hi:[0,1]
	v_fma_f32 v171, 0, v163, v162
	v_add_f32_e32 v164, -1.0, v163
	v_mov_b32_e32 v172, v171
	v_fmamk_f32 v170, v162, 0x80000000, v163
	v_pk_mul_f32 v[164:165], v[168:169], v[164:165] op_sel:[1,0] op_sel_hi:[0,0]
	v_pk_mul_f32 v[174:175], v[162:163], v[172:173] op_sel_hi:[1,0]
	ds_write2st64_b64 v1, v[78:79], v[170:171] offset1:1
	v_pk_fma_f32 v[176:177], v[20:21], v[162:163], v[164:165]
	v_pk_fma_f32 v[164:165], v[168:169], v[162:163], v[164:165] op_sel_hi:[1,0,1] neg_lo:[0,0,1] neg_hi:[0,0,1]
	v_pk_fma_f32 v[168:169], v[162:163], v[170:171], v[174:175] op_sel:[1,0,0] op_sel_hi:[0,0,1]
	v_pk_fma_f32 v[170:171], v[162:163], v[170:171], v[174:175] op_sel:[1,0,0] op_sel_hi:[0,0,1] neg_lo:[0,0,1] neg_hi:[0,0,1]
	v_mov_b32_e32 v171, v169
	v_mul_f32_e32 v20, v162, v169
	v_mul_f32_e32 v164, v163, v169
	v_pk_fma_f32 v[168:169], v[162:163], v[170:171], v[20:21] op_sel:[1,0,0] op_sel_hi:[0,1,0] neg_lo:[0,0,1] neg_hi:[0,0,1]
	v_pk_fma_f32 v[174:175], v[162:163], v[170:171], v[164:165] op_sel_hi:[1,1,0]
	v_mov_b32_e32 v178, v168
	v_mov_b32_e32 v179, v174
	v_pk_mul_f32 v[174:175], v[162:163], v[174:175] op_sel_hi:[1,0]
	ds_write2st64_b64 v1, v[170:171], v[178:179] offset0:2 offset1:3
	v_pk_fma_f32 v[170:171], v[162:163], v[168:169], v[174:175] op_sel:[1,0,0] op_sel_hi:[0,1,1] neg_lo:[0,0,1] neg_hi:[0,0,1]
	v_pk_fma_f32 v[168:169], v[162:163], v[168:169], v[174:175] op_sel:[1,0,0] op_sel_hi:[0,0,1]
	v_mov_b32_e32 v171, v169
	v_pk_mul_f32 v[168:169], v[162:163], v[170:171] op_sel_hi:[0,1]
	v_pk_fma_f32 v[174:175], v[162:163], v[170:171], v[168:169] op_sel:[1,0,1] op_sel_hi:[1,1,0] neg_lo:[0,0,1] neg_hi:[0,0,1]
	v_pk_fma_f32 v[168:169], v[162:163], v[170:171], v[168:169] op_sel:[1,0,1] op_sel_hi:[1,1,0]
	v_div_scale_f32 v79, s[78:79], v167, v167, v165
	v_mov_b32_e32 v168, v174
	ds_write2st64_b64 v1, v[170:171], v[168:169] offset0:4 offset1:5
	v_pk_mul_f32 v[170:171], v[162:163], v[168:169] op_sel_hi:[0,1]
	v_pk_fma_f32 v[174:175], v[162:163], v[174:175], v[170:171] op_sel:[1,0,1] op_sel_hi:[1,1,0] neg_lo:[0,0,1] neg_hi:[0,0,1]
	v_pk_fma_f32 v[168:169], v[162:163], v[168:169], v[170:171] op_sel:[1,0,1] op_sel_hi:[1,1,0]
	v_rcp_f32_e32 v81, v79
	v_mov_b32_e32 v175, v169
	v_pk_mul_f32 v[168:169], v[162:163], v[174:175] op_sel_hi:[0,1]
	v_pk_fma_f32 v[170:171], v[162:163], v[174:175], v[168:169] op_sel:[1,0,1] op_sel_hi:[1,1,0] neg_lo:[0,0,1] neg_hi:[0,0,1]
	v_pk_fma_f32 v[168:169], v[162:163], v[174:175], v[168:169] op_sel:[1,0,1] op_sel_hi:[1,1,0]
	v_fma_f32 v20, -v79, v81, 1.0
	v_mov_b32_e32 v168, v170
	ds_write2st64_b64 v1, v[174:175], v[168:169] offset0:6 offset1:7
	v_pk_mul_f32 v[174:175], v[162:163], v[168:169] op_sel_hi:[0,1]
	v_pk_fma_f32 v[170:171], v[162:163], v[170:171], v[174:175] op_sel:[1,0,1] op_sel_hi:[1,1,0] neg_lo:[0,0,1] neg_hi:[0,0,1]
	v_pk_fma_f32 v[168:169], v[162:163], v[168:169], v[174:175] op_sel:[1,0,1] op_sel_hi:[1,1,0]
	v_fmac_f32_e32 v81, v20, v81
	v_mov_b32_e32 v171, v169
	v_pk_mul_f32 v[168:169], v[162:163], v[170:171] op_sel_hi:[0,1]
	v_pk_fma_f32 v[174:175], v[162:163], v[170:171], v[168:169] op_sel:[1,0,1] op_sel_hi:[1,1,0] neg_lo:[0,0,1] neg_hi:[0,0,1]
	v_pk_fma_f32 v[168:169], v[162:163], v[170:171], v[168:169] op_sel:[1,0,1] op_sel_hi:[1,1,0]
	v_div_scale_f32 v20, vcc, v165, v167, v165
	v_mov_b32_e32 v168, v174
	ds_write2st64_b64 v1, v[170:171], v[168:169] offset0:8 offset1:9
	v_pk_mul_f32 v[170:171], v[162:163], v[168:169] op_sel_hi:[0,1]
	v_pk_fma_f32 v[174:175], v[162:163], v[174:175], v[170:171] op_sel:[1,0,1] op_sel_hi:[1,1,0] neg_lo:[0,0,1] neg_hi:[0,0,1]
	v_pk_fma_f32 v[168:169], v[162:163], v[168:169], v[170:171] op_sel:[1,0,1] op_sel_hi:[1,1,0]
	v_mul_f32_e32 v145, v20, v81
	v_mov_b32_e32 v175, v169
	v_pk_mul_f32 v[168:169], v[162:163], v[174:175] op_sel_hi:[0,1]
	v_pk_fma_f32 v[170:171], v[162:163], v[174:175], v[168:169] op_sel:[1,0,1] op_sel_hi:[1,1,0] neg_lo:[0,0,1] neg_hi:[0,0,1]
	v_pk_fma_f32 v[168:169], v[162:163], v[174:175], v[168:169] op_sel:[1,0,1] op_sel_hi:[1,1,0]
	s_nop 0
	v_mov_b32_e32 v168, v170
	ds_write2st64_b64 v1, v[174:175], v[168:169] offset0:10 offset1:11
	v_pk_mul_f32 v[174:175], v[162:163], v[168:169] op_sel_hi:[0,1]
	v_pk_fma_f32 v[170:171], v[162:163], v[170:171], v[174:175] op_sel:[1,0,1] op_sel_hi:[1,1,0] neg_lo:[0,0,1] neg_hi:[0,0,1]
	v_pk_fma_f32 v[168:169], v[162:163], v[168:169], v[174:175] op_sel:[1,0,1] op_sel_hi:[1,1,0]
	s_nop 0
	v_mov_b32_e32 v171, v169
	v_pk_mul_f32 v[168:169], v[162:163], v[170:171] op_sel_hi:[0,1]
	v_pk_fma_f32 v[174:175], v[162:163], v[170:171], v[168:169] op_sel:[1,0,1] op_sel_hi:[1,1,0] neg_lo:[0,0,1] neg_hi:[0,0,1]
	v_pk_fma_f32 v[168:169], v[162:163], v[170:171], v[168:169] op_sel:[1,0,1] op_sel_hi:[1,1,0]
	s_nop 0
	v_mov_b32_e32 v168, v174
	ds_write2st64_b64 v1, v[170:171], v[168:169] offset0:12 offset1:13
	v_pk_mul_f32 v[170:171], v[162:163], v[168:169] op_sel_hi:[0,1]
	v_pk_fma_f32 v[174:175], v[162:163], v[174:175], v[170:171] op_sel:[1,0,1] op_sel_hi:[1,1,0] neg_lo:[0,0,1] neg_hi:[0,0,1]
	v_pk_fma_f32 v[168:169], v[162:163], v[168:169], v[170:171] op_sel:[1,0,1] op_sel_hi:[1,1,0]
	s_nop 0
	v_mov_b32_e32 v175, v169
	v_pk_mul_f32 v[168:169], v[162:163], v[174:175] op_sel_hi:[0,1]
	v_pk_fma_f32 v[170:171], v[162:163], v[174:175], v[168:169] op_sel:[1,0,1] op_sel_hi:[1,1,0] neg_lo:[0,0,1] neg_hi:[0,0,1]
	v_pk_fma_f32 v[168:169], v[162:163], v[174:175], v[168:169] op_sel:[1,0,1] op_sel_hi:[1,1,0]
	s_nop 0
	v_mov_b32_e32 v168, v170
	ds_write2st64_b64 v1, v[174:175], v[168:169] offset0:14 offset1:15
	v_pk_mul_f32 v[174:175], v[162:163], v[168:169] op_sel_hi:[0,1]
	v_pk_fma_f32 v[170:171], v[162:163], v[170:171], v[174:175] op_sel:[1,0,1] op_sel_hi:[1,1,0] neg_lo:[0,0,1] neg_hi:[0,0,1]
	v_pk_fma_f32 v[162:163], v[162:163], v[168:169], v[174:175] op_sel:[1,0,1] op_sel_hi:[1,1,0]
	s_nop 0
	v_fma_f32 v162, -v79, v145, v20
	v_fmac_f32_e32 v145, v162, v81
	v_fma_f32 v20, -v79, v145, v20
	v_div_scale_f32 v79, s[78:79], v166, v166, v176
	v_rcp_f32_e32 v162, v79
	v_div_fmas_f32 v20, v20, v81, v145
	v_div_fixup_f32 v167, v20, v167, v165
	v_mov_b32_e32 v171, v163
	v_fma_f32 v20, -v79, v162, 1.0
	v_fmac_f32_e32 v162, v20, v162
	v_div_scale_f32 v20, vcc, v176, v166, v176
	v_mul_f32_e32 v81, v20, v162
	v_fma_f32 v145, -v79, v81, v20
	v_fmac_f32_e32 v81, v145, v162
	v_fma_f32 v20, -v79, v81, v20
	v_div_fmas_f32 v20, v20, v162, v81
	v_div_fixup_f32 v166, v20, v166, v176
	s_waitcnt vmcnt(0)
	v_pk_mul_f32 v[164:165], v[166:167], v[158:159] op_sel:[1,0] op_sel_hi:[0,0]
	v_pk_mul_f32 v[158:159], v[166:167], v[158:159] op_sel:[1,1] op_sel_hi:[0,1]
	v_mov_b32_e32 v20, v151
	v_pk_fma_f32 v[162:163], v[150:151], v[166:167], v[164:165] neg_lo:[0,0,1] neg_hi:[0,0,1]
	v_pk_fma_f32 v[168:169], v[150:151], v[166:167], v[164:165] op_sel_hi:[0,1,1]
	v_pk_fma_f32 v[164:165], v[166:167], v[20:21], v[158:159] neg_lo:[0,0,1] neg_hi:[0,0,1]
	v_pk_fma_f32 v[150:151], v[166:167], v[150:151], v[158:159] op_sel:[0,1,0]
	v_pk_mul_f32 v[158:159], v[166:167], v[160:161] op_sel:[1,0] op_sel_hi:[0,0]
	v_mov_b32_e32 v165, v151
	v_pk_fma_f32 v[150:151], v[166:167], v[152:153], v[158:159] neg_lo:[0,0,1] neg_hi:[0,0,1]
	v_pk_fma_f32 v[158:159], v[166:167], v[152:153], v[158:159] op_sel_hi:[1,0,1]
	v_mov_b32_e32 v20, v161
	v_pk_mul_f32 v[160:161], v[166:167], v[20:21] op_sel:[1,0] op_sel_hi:[0,0]
	v_mov_b32_e32 v20, v153
	v_mov_b32_e32 v158, v153
	v_pk_fma_f32 v[152:153], v[166:167], v[20:21], v[160:161] neg_lo:[0,0,1] neg_hi:[0,0,1]
	v_pk_fma_f32 v[160:161], v[166:167], v[158:159], v[160:161] op_sel_hi:[1,0,1]
	v_mov_b32_e32 v151, v159
	v_mov_b32_e32 v153, v161
	ds_write_b64 v1, v[170:171] offset:8192
	ds_write_b128 v136, v[150:153] offset:8720
	v_pk_mul_f32 v[152:153], v[166:167], v[154:155] op_sel:[1,0] op_sel_hi:[0,0]
	v_pk_mul_f32 v[154:155], v[166:167], v[154:155] op_sel:[1,1] op_sel_hi:[0,1]
	v_mov_b32_e32 v20, v147
	v_pk_fma_f32 v[150:151], v[166:167], v[146:147], v[152:153] neg_lo:[0,0,1] neg_hi:[0,0,1]
	v_pk_fma_f32 v[158:159], v[166:167], v[146:147], v[152:153] op_sel_hi:[1,0,1]
	v_pk_fma_f32 v[152:153], v[166:167], v[20:21], v[154:155] neg_lo:[0,0,1] neg_hi:[0,0,1]
	v_pk_fma_f32 v[146:147], v[166:167], v[146:147], v[154:155] op_sel:[0,1,0]
	v_mov_b32_e32 v151, v159
	v_mov_b32_e32 v153, v147
	ds_write_b128 v136, v[150:153] offset:8736
	v_pk_mul_f32 v[150:151], v[166:167], v[156:157] op_sel:[1,0] op_sel_hi:[0,0]
	v_pk_fma_f32 v[146:147], v[166:167], v[148:149], v[150:151] neg_lo:[0,0,1] neg_hi:[0,0,1]
	v_pk_fma_f32 v[150:151], v[166:167], v[148:149], v[150:151] op_sel_hi:[1,0,1]
	v_mov_b32_e32 v20, v157
	v_pk_mul_f32 v[152:153], v[166:167], v[20:21] op_sel:[1,0] op_sel_hi:[0,0]
	v_mov_b32_e32 v20, v149
	v_mov_b32_e32 v150, v149
	v_pk_fma_f32 v[148:149], v[166:167], v[20:21], v[152:153] neg_lo:[0,0,1] neg_hi:[0,0,1]
	v_pk_fma_f32 v[152:153], v[166:167], v[150:151], v[152:153] op_sel_hi:[1,0,1]
	v_mov_b32_e32 v147, v151
	v_mov_b32_e32 v149, v153
	ds_write_b128 v136, v[146:149] offset:8752
	v_pk_mul_f32 v[148:149], v[166:167], v[14:15] op_sel:[1,0] op_sel_hi:[0,0]
	v_pk_mul_f32 v[14:15], v[166:167], v[14:15] op_sel:[1,1] op_sel_hi:[0,1]
	v_mov_b32_e32 v20, v11
	v_pk_fma_f32 v[146:147], v[166:167], v[10:11], v[148:149] neg_lo:[0,0,1] neg_hi:[0,0,1]
	v_pk_fma_f32 v[150:151], v[166:167], v[10:11], v[148:149] op_sel_hi:[1,0,1]
	v_pk_fma_f32 v[148:149], v[166:167], v[20:21], v[14:15] neg_lo:[0,0,1] neg_hi:[0,0,1]
	v_pk_fma_f32 v[10:11], v[166:167], v[10:11], v[14:15] op_sel:[0,1,0]
	v_pk_mul_f32 v[14:15], v[166:167], v[16:17] op_sel:[1,0] op_sel_hi:[0,0]
	v_mov_b32_e32 v149, v11
	v_pk_fma_f32 v[10:11], v[166:167], v[12:13], v[14:15] neg_lo:[0,0,1] neg_hi:[0,0,1]
	v_pk_fma_f32 v[14:15], v[166:167], v[12:13], v[14:15] op_sel_hi:[1,0,1]
	v_mov_b32_e32 v12, v17
	v_pk_mul_f32 v[16:17], v[166:167], v[12:13] op_sel:[1,0] op_sel_hi:[0,0]
	v_mov_b32_e32 v12, v13
	v_mov_b32_e32 v14, v13
	v_pk_fma_f32 v[12:13], v[166:167], v[12:13], v[16:17] neg_lo:[0,0,1] neg_hi:[0,0,1]
	v_pk_fma_f32 v[16:17], v[166:167], v[14:15], v[16:17] op_sel_hi:[1,0,1]
	v_mov_b32_e32 v11, v15
	v_mov_b32_e32 v13, v17
	ds_write_b128 v136, v[10:13] offset:8784
	v_pk_mul_f32 v[12:13], v[166:167], v[6:7] op_sel:[1,0] op_sel_hi:[0,0]
	v_pk_fma_f32 v[10:11], v[166:167], v[2:3], v[12:13] neg_lo:[0,0,1] neg_hi:[0,0,1]
	v_pk_fma_f32 v[14:15], v[166:167], v[2:3], v[12:13] op_sel_hi:[1,0,1]
	v_pk_mul_f32 v[6:7], v[166:167], v[6:7] op_sel:[1,1] op_sel_hi:[0,1]
	v_mov_b32_e32 v12, v3
	v_pk_fma_f32 v[12:13], v[166:167], v[12:13], v[6:7] neg_lo:[0,0,1] neg_hi:[0,0,1]
	v_pk_fma_f32 v[2:3], v[166:167], v[2:3], v[6:7] op_sel:[0,1,0]
	v_pk_mul_f32 v[6:7], v[166:167], v[8:9] op_sel:[1,0] op_sel_hi:[0,0]
	v_mov_b32_e32 v13, v3
	v_pk_fma_f32 v[2:3], v[166:167], v[4:5], v[6:7] neg_lo:[0,0,1] neg_hi:[0,0,1]
	v_pk_fma_f32 v[6:7], v[166:167], v[4:5], v[6:7] op_sel_hi:[1,0,1]
	v_mov_b32_e32 v4, v9
	v_pk_mul_f32 v[8:9], v[166:167], v[4:5] op_sel:[1,0] op_sel_hi:[0,0]
	v_mov_b32_e32 v4, v5
	v_mov_b32_e32 v6, v5
	v_pk_fma_f32 v[4:5], v[166:167], v[4:5], v[8:9] neg_lo:[0,0,1] neg_hi:[0,0,1]
	v_pk_fma_f32 v[8:9], v[166:167], v[6:7], v[8:9] op_sel_hi:[1,0,1]
	v_mov_b32_e32 v163, v169
	v_mov_b32_e32 v147, v151
	v_mov_b32_e32 v11, v15
	v_mov_b32_e32 v3, v7
	v_mov_b32_e32 v5, v9
	ds_write_b128 v136, v[162:165] offset:8704
	ds_write_b128 v136, v[146:149] offset:8768
	ds_write_b128 v136, v[10:13] offset:8800
	ds_write_b128 v136, v[2:5] offset:8816

.LBB0_75:
	global_load_dword v8, v[2:3], off nt
	global_load_dword v9, v[4:5], off nt
	v_add_u32_e32 v6, 0x200, v6
	s_movk_i32 s82, 0x1ff
	v_cmp_lt_i32_e32 vcc, s82, v6
	v_lshl_add_u64 v[2:3], v[2:3], 0, s[70:71]
	v_lshl_add_u64 v[4:5], v[4:5], 0, s[70:71]
	s_or_b64 s[78:79], vcc, s[78:79]
	s_waitcnt vmcnt(0)
	ds_write_b64 v7, v[8:9]
	v_add_u32_e32 v7, 0x1000, v7
	s_andn2_b64 exec, exec, s[78:79]
	s_cbranch_execnz .LBB0_75

.LBB0_80:
	s_and_b64 vcc, exec, s[74:75]
	s_cbranch_vccz .LBB0_70
	ds_read_b128 v[8:11], v84
	ds_read_b128 v[12:15], v84 offset:16
	ds_read_b128 v[146:149], v84 offset:32
	ds_read_b128 v[150:153], v84 offset:48
	v_add_u32_e32 v7, 0x2000, v82
	ds_read2_b64 v[154:157], v7 offset0:64 offset1:80
	ds_read_b128 v[158:161], v83 offset:16896
	ds_read_b128 v[162:165], v83 offset:16912
	ds_read_b128 v[166:169], v83 offset:16928
	ds_read_b128 v[174:177], v83 offset:16944
	s_waitcnt lgkmcnt(4)
	v_pk_mul_f32 v[4:5], v[8:9], v[154:155]
	ds_read2_b64 v[178:181], v7 offset0:96 offset1:112
	v_sub_f32_e32 v4, v4, v5
	v_mul_f32_e32 v5, v8, v155
	s_waitcnt lgkmcnt(4)
	v_mul_f32_e32 v4, v158, v4
	v_fmac_f32_e32 v5, v9, v154
	v_fma_f32 v4, -v159, v5, v4
	v_add_f32_e32 v6, 0, v4
	v_pk_mul_f32 v[4:5], v[10:11], v[156:157]
	s_lshl_b32 s69, s88, 3
	v_sub_f32_e32 v4, v4, v5
	v_mul_f32_e32 v5, v10, v157
	v_mul_f32_e32 v4, v160, v4
	v_fmac_f32_e32 v5, v11, v156
	v_fma_f32 v4, -v161, v5, v4
	v_add_f32_e32 v6, v6, v4
	s_waitcnt lgkmcnt(0)
	v_pk_mul_f32 v[4:5], v[12:13], v[178:179]
	ds_read2_b64 v[8:11], v7 offset0:128 offset1:144
	v_sub_f32_e32 v4, v4, v5
	v_mul_f32_e32 v5, v12, v179
	v_mul_f32_e32 v4, v162, v4
	v_fmac_f32_e32 v5, v13, v178
	v_fma_f32 v4, -v163, v5, v4
	v_add_f32_e32 v6, v6, v4
	v_pk_mul_f32 v[4:5], v[14:15], v[180:181]
	s_lshl_b32 s68, s68, 4
	v_sub_f32_e32 v4, v4, v5
	v_mul_f32_e32 v5, v14, v181
	v_mul_f32_e32 v4, v164, v4
	v_fmac_f32_e32 v5, v15, v180
	v_fma_f32 v4, -v165, v5, v4
	v_add_f32_e32 v6, v6, v4
	s_waitcnt lgkmcnt(0)
	v_pk_mul_f32 v[4:5], v[146:147], v[8:9]
	ds_read2_b64 v[12:15], v7 offset0:160 offset1:176
	v_sub_f32_e32 v4, v4, v5
	v_mul_f32_e32 v5, v146, v9
	v_mul_f32_e32 v4, v166, v4
	v_fmac_f32_e32 v5, v147, v8
	v_fma_f32 v4, -v167, v5, v4
	v_add_f32_e32 v6, v6, v4
	v_pk_mul_f32 v[4:5], v[148:149], v[10:11]
	s_and_b32 s69, s69, 0xfffffe00
	v_sub_f32_e32 v4, v4, v5
	v_mul_f32_e32 v5, v148, v11
	v_mul_f32_e32 v4, v168, v4
	v_fmac_f32_e32 v5, v149, v10
	v_fma_f32 v4, -v169, v5, v4
	v_add_f32_e32 v6, v6, v4
	s_waitcnt lgkmcnt(0)
	v_pk_mul_f32 v[4:5], v[150:151], v[12:13]
	s_and_b32 s68, s68, 0x1f0
	v_sub_f32_e32 v4, v4, v5
	v_mul_f32_e32 v5, v150, v13
	v_mul_f32_e32 v4, v174, v4
	v_fmac_f32_e32 v5, v151, v12
	v_fma_f32 v4, -v175, v5, v4
	v_add_f32_e32 v6, v6, v4
	v_pk_mul_f32 v[4:5], v[152:153], v[14:15]
	s_or_b32 s68, s69, s68
	v_sub_f32_e32 v4, v4, v5
	v_mul_f32_e32 v5, v152, v15
	v_fmac_f32_e32 v5, v153, v14
	ds_read_b128 v[8:11], v84 offset:64
	ds_read2_b64 v[12:15], v7 offset0:192 offset1:208
	v_mul_f32_e32 v4, v176, v4
	ds_read_b128 v[146:149], v83 offset:16960
	ds_read_b128 v[150:153], v84 offset:80
	v_fma_f32 v4, -v177, v5, v4
	v_add_f32_e32 v6, v6, v4
	s_waitcnt lgkmcnt(2)
	v_pk_mul_f32 v[4:5], v[8:9], v[12:13]
	ds_read2_b64 v[158:161], v7 offset0:224 offset1:240
	v_sub_f32_e32 v4, v4, v5
	v_mul_f32_e32 v5, v8, v13
	s_waitcnt lgkmcnt(2)
	v_mul_f32_e32 v4, v146, v4
	v_fmac_f32_e32 v5, v9, v12
	v_fma_f32 v4, -v147, v5, v4
	v_add_f32_e32 v6, v6, v4
	v_pk_mul_f32 v[4:5], v[10:11], v[14:15]
	ds_read_b128 v[154:157], v83 offset:16976
	v_sub_f32_e32 v4, v4, v5
	v_mul_f32_e32 v5, v10, v15
	v_mul_f32_e32 v4, v148, v4
	v_fmac_f32_e32 v5, v11, v14
	v_fma_f32 v4, -v149, v5, v4
	v_add_f32_e32 v6, v6, v4
	s_waitcnt lgkmcnt(1)
	v_pk_mul_f32 v[4:5], v[150:151], v[158:159]
	ds_read_b128 v[8:11], v84 offset:96
	v_sub_f32_e32 v4, v4, v5
	v_mul_f32_e32 v5, v150, v159
	s_waitcnt lgkmcnt(1)
	v_mul_f32_e32 v4, v154, v4
	v_fmac_f32_e32 v5, v151, v158
	v_fma_f32 v4, -v155, v5, v4
	v_add_f32_e32 v6, v6, v4
	v_pk_mul_f32 v[4:5], v[152:153], v[160:161]
	v_mul_f32_e32 v16, v152, v161
	v_sub_f32_e32 v4, v4, v5
	v_add_u32_e32 v5, 0x2800, v82
	ds_read2_b64 v[12:15], v5 offset1:16
	v_fmac_f32_e32 v16, v153, v160
	ds_read_b128 v[146:149], v83 offset:16992
	ds_read_b128 v[150:153], v84 offset:112
	v_mul_f32_e32 v4, v156, v4
	v_fma_f32 v4, -v157, v16, v4
	s_waitcnt lgkmcnt(2)
	v_pk_mul_f32 v[16:17], v[8:9], v[12:13]
	v_add_f32_e32 v4, v6, v4
	v_sub_f32_e32 v6, v16, v17
	v_mul_f32_e32 v8, v8, v13
	ds_read2_b64 v[158:161], v5 offset0:32 offset1:48
	s_waitcnt lgkmcnt(2)
	v_mul_f32_e32 v6, v146, v6
	v_fmac_f32_e32 v8, v9, v12
	ds_read_b128 v[154:157], v83 offset:17008
	v_fma_f32 v6, -v147, v8, v6
	v_pk_mul_f32 v[8:9], v[10:11], v[14:15]
	v_add_f32_e32 v4, v4, v6
	v_sub_f32_e32 v6, v8, v9
	v_mul_f32_e32 v8, v10, v15
	v_mul_f32_e32 v6, v148, v6
	v_fmac_f32_e32 v8, v11, v14
	v_fma_f32 v6, -v149, v8, v6
	s_waitcnt lgkmcnt(1)
	v_pk_mul_f32 v[8:9], v[150:151], v[158:159]
	v_add_f32_e32 v4, v4, v6
	v_sub_f32_e32 v6, v8, v9
	v_mul_f32_e32 v8, v150, v159
	s_waitcnt lgkmcnt(0)
	v_mul_f32_e32 v6, v154, v6
	v_fmac_f32_e32 v8, v151, v158
	v_fma_f32 v6, -v155, v8, v6
	v_pk_mul_f32 v[8:9], v[152:153], v[160:161]
	v_add_f32_e32 v4, v4, v6
	v_sub_f32_e32 v6, v8, v9
	ds_read_b128 v[8:11], v84 offset:128
	ds_read2_b64 v[12:15], v5 offset0:64 offset1:80
	v_mul_f32_e32 v16, v152, v161
	v_fmac_f32_e32 v16, v153, v160
	ds_read_b128 v[146:149], v83 offset:17024
	ds_read_b128 v[150:153], v84 offset:144
	v_mul_f32_e32 v6, v156, v6
	v_fma_f32 v6, -v157, v16, v6
	s_waitcnt lgkmcnt(2)
	v_pk_mul_f32 v[16:17], v[8:9], v[12:13]
	v_add_f32_e32 v4, v4, v6
	v_sub_f32_e32 v6, v16, v17
	v_mul_f32_e32 v8, v8, v13
	ds_read2_b64 v[158:161], v5 offset0:96 offset1:112
	s_waitcnt lgkmcnt(2)
	v_mul_f32_e32 v6, v146, v6
	v_fmac_f32_e32 v8, v9, v12
	ds_read_b128 v[154:157], v83 offset:17040
	v_fma_f32 v6, -v147, v8, v6
	v_pk_mul_f32 v[8:9], v[10:11], v[14:15]
	v_add_f32_e32 v4, v4, v6
	v_sub_f32_e32 v6, v8, v9
	v_mul_f32_e32 v8, v10, v15
	v_mul_f32_e32 v6, v148, v6
	v_fmac_f32_e32 v8, v11, v14
	v_fma_f32 v6, -v149, v8, v6
	s_waitcnt lgkmcnt(1)
	v_pk_mul_f32 v[8:9], v[150:151], v[158:159]
	v_add_f32_e32 v4, v4, v6
	v_sub_f32_e32 v6, v8, v9
	v_mul_f32_e32 v8, v150, v159
	s_waitcnt lgkmcnt(0)
	v_mul_f32_e32 v6, v154, v6
	v_fmac_f32_e32 v8, v151, v158
	v_fma_f32 v6, -v155, v8, v6
	v_pk_mul_f32 v[8:9], v[152:153], v[160:161]
	v_add_f32_e32 v4, v4, v6
	v_sub_f32_e32 v6, v8, v9
	ds_read_b128 v[8:11], v84 offset:160
	ds_read2_b64 v[12:15], v5 offset0:128 offset1:144
	v_mul_f32_e32 v16, v152, v161
	v_fmac_f32_e32 v16, v153, v160
	ds_read_b128 v[146:149], v83 offset:17056
	ds_read_b128 v[150:153], v84 offset:176
	v_mul_f32_e32 v6, v156, v6
	v_fma_f32 v6, -v157, v16, v6
	s_waitcnt lgkmcnt(2)
	v_pk_mul_f32 v[16:17], v[8:9], v[12:13]
	v_add_f32_e32 v4, v4, v6
	v_sub_f32_e32 v6, v16, v17
	v_mul_f32_e32 v8, v8, v13
	ds_read2_b64 v[158:161], v5 offset0:160 offset1:176
	s_waitcnt lgkmcnt(2)
	v_mul_f32_e32 v6, v146, v6
	v_fmac_f32_e32 v8, v9, v12
	ds_read_b128 v[154:157], v83 offset:17072
	v_fma_f32 v6, -v147, v8, v6
	v_pk_mul_f32 v[8:9], v[10:11], v[14:15]
	v_add_f32_e32 v4, v4, v6
	v_sub_f32_e32 v6, v8, v9
	v_mul_f32_e32 v8, v10, v15
	v_mul_f32_e32 v6, v148, v6
	v_fmac_f32_e32 v8, v11, v14
	v_fma_f32 v6, -v149, v8, v6
	s_waitcnt lgkmcnt(1)
	v_pk_mul_f32 v[8:9], v[150:151], v[158:159]
	v_add_f32_e32 v4, v4, v6
	v_sub_f32_e32 v6, v8, v9
	v_mul_f32_e32 v8, v150, v159
	s_waitcnt lgkmcnt(0)
	v_mul_f32_e32 v6, v154, v6
	v_fmac_f32_e32 v8, v151, v158
	v_fma_f32 v6, -v155, v8, v6
	v_pk_mul_f32 v[8:9], v[152:153], v[160:161]
	v_add_f32_e32 v4, v4, v6
	v_sub_f32_e32 v6, v8, v9
	ds_read_b128 v[8:11], v84 offset:192
	ds_read2_b64 v[12:15], v5 offset0:192 offset1:208
	v_mul_f32_e32 v16, v152, v161
	v_fmac_f32_e32 v16, v153, v160
	ds_read_b128 v[146:149], v83 offset:17088
	ds_read_b128 v[150:153], v84 offset:208
	v_mul_f32_e32 v6, v156, v6
	v_fma_f32 v6, -v157, v16, v6
	s_waitcnt lgkmcnt(2)
	v_pk_mul_f32 v[16:17], v[8:9], v[12:13]
	v_add_f32_e32 v4, v4, v6
	v_sub_f32_e32 v6, v16, v17
	v_mul_f32_e32 v8, v8, v13
	ds_read2_b64 v[158:161], v5 offset0:224 offset1:240
	s_waitcnt lgkmcnt(2)
	v_mul_f32_e32 v6, v146, v6
	v_fmac_f32_e32 v8, v9, v12
	ds_read_b128 v[154:157], v83 offset:17104
	v_fma_f32 v6, -v147, v8, v6
	v_pk_mul_f32 v[8:9], v[10:11], v[14:15]
	v_add_f32_e32 v4, v4, v6
	v_sub_f32_e32 v6, v8, v9
	v_mul_f32_e32 v8, v10, v15
	v_mul_f32_e32 v6, v148, v6
	v_fmac_f32_e32 v8, v11, v14
	v_fma_f32 v6, -v149, v8, v6
	s_waitcnt lgkmcnt(1)
	v_pk_mul_f32 v[8:9], v[150:151], v[158:159]
	v_add_f32_e32 v4, v4, v6
	v_sub_f32_e32 v6, v8, v9
	v_mul_f32_e32 v8, v150, v159
	s_waitcnt lgkmcnt(0)
	v_mul_f32_e32 v6, v154, v6
	v_fmac_f32_e32 v8, v151, v158
	v_fma_f32 v6, -v155, v8, v6
	v_pk_mul_f32 v[8:9], v[152:153], v[160:161]
	v_add_f32_e32 v4, v4, v6
	v_sub_f32_e32 v6, v8, v9
	v_mul_f32_e32 v16, v156, v6
	v_add_u32_e32 v6, 0x3000, v82
	ds_read_b128 v[8:11], v84 offset:224
	ds_read2_b64 v[12:15], v6 offset1:16
	v_mul_f32_e32 v17, v152, v161
	v_fmac_f32_e32 v17, v153, v160
	ds_read_b128 v[146:149], v83 offset:17120
	ds_read_b128 v[150:153], v84 offset:240
	v_fma_f32 v16, -v157, v17, v16
	v_add_f32_e32 v4, v4, v16
	s_waitcnt lgkmcnt(2)
	v_pk_mul_f32 v[16:17], v[8:9], v[12:13]
	v_mul_f32_e32 v8, v8, v13
	v_sub_f32_e32 v16, v16, v17
	s_waitcnt lgkmcnt(1)
	v_mul_f32_e32 v16, v146, v16
	v_fmac_f32_e32 v8, v9, v12
	v_fma_f32 v8, -v147, v8, v16
	ds_read2_b64 v[158:161], v6 offset0:32 offset1:48
	v_add_f32_e32 v4, v4, v8
	v_pk_mul_f32 v[8:9], v[10:11], v[14:15]
	ds_read_b128 v[154:157], v83 offset:17136
	v_sub_f32_e32 v8, v8, v9
	v_mul_f32_e32 v9, v10, v15
	v_mul_f32_e32 v8, v148, v8
	v_fmac_f32_e32 v9, v11, v14
	v_fma_f32 v8, -v149, v9, v8
	v_add_f32_e32 v4, v4, v8
	s_waitcnt lgkmcnt(1)
	v_pk_mul_f32 v[8:9], v[150:151], v[158:159]
	v_mul_f32_e32 v17, v152, v161
	v_sub_f32_e32 v8, v8, v9
	v_mul_f32_e32 v9, v150, v159
	s_waitcnt lgkmcnt(0)
	v_mul_f32_e32 v8, v154, v8
	v_fmac_f32_e32 v9, v151, v158
	v_fma_f32 v8, -v155, v9, v8
	v_add_f32_e32 v4, v4, v8
	v_pk_mul_f32 v[8:9], v[152:153], v[160:161]
	v_fmac_f32_e32 v17, v153, v160
	v_sub_f32_e32 v8, v8, v9
	v_mul_f32_e32 v16, v156, v8
	ds_read_b128 v[8:11], v84 offset:256
	ds_read2_b64 v[12:15], v6 offset0:64 offset1:80
	ds_read_b128 v[146:149], v83 offset:17152
	ds_read_b128 v[150:153], v84 offset:272
	v_fma_f32 v16, -v157, v17, v16
	v_add_f32_e32 v4, v4, v16
	ds_read2_b64 v[158:161], v6 offset0:96 offset1:112
	s_waitcnt lgkmcnt(3)
	v_pk_mul_f32 v[16:17], v[8:9], v[12:13]
	v_mul_f32_e32 v8, v8, v13
	v_sub_f32_e32 v16, v16, v17
	s_waitcnt lgkmcnt(2)
	v_mul_f32_e32 v16, v146, v16
	v_fmac_f32_e32 v8, v9, v12
	v_fma_f32 v8, -v147, v8, v16
	v_add_f32_e32 v4, v4, v8
	v_pk_mul_f32 v[8:9], v[10:11], v[14:15]
	ds_read_b128 v[154:157], v83 offset:17168
	v_sub_f32_e32 v8, v8, v9
	v_mul_f32_e32 v9, v10, v15
	v_mul_f32_e32 v8, v148, v8
	v_fmac_f32_e32 v9, v11, v14
	v_fma_f32 v8, -v149, v9, v8
	v_add_f32_e32 v4, v4, v8
	s_waitcnt lgkmcnt(1)
	v_pk_mul_f32 v[8:9], v[150:151], v[158:159]
	v_mul_f32_e32 v17, v152, v161
	v_sub_f32_e32 v8, v8, v9
	v_mul_f32_e32 v9, v150, v159
	s_waitcnt lgkmcnt(0)
	v_mul_f32_e32 v8, v154, v8
	v_fmac_f32_e32 v9, v151, v158
	v_fma_f32 v8, -v155, v9, v8
	v_add_f32_e32 v4, v4, v8
	v_pk_mul_f32 v[8:9], v[152:153], v[160:161]
	v_fmac_f32_e32 v17, v153, v160
	v_sub_f32_e32 v8, v8, v9
	v_mul_f32_e32 v16, v156, v8
	ds_read_b128 v[8:11], v84 offset:288
	ds_read2_b64 v[12:15], v6 offset0:128 offset1:144
	ds_read_b128 v[146:149], v83 offset:17184
	ds_read_b128 v[150:153], v84 offset:304
	v_fma_f32 v16, -v157, v17, v16
	v_add_f32_e32 v4, v4, v16
	ds_read2_b64 v[158:161], v6 offset0:160 offset1:176
	s_waitcnt lgkmcnt(3)
	v_pk_mul_f32 v[16:17], v[8:9], v[12:13]
	v_mul_f32_e32 v8, v8, v13
	v_sub_f32_e32 v16, v16, v17
	s_waitcnt lgkmcnt(2)
	v_mul_f32_e32 v16, v146, v16
	v_fmac_f32_e32 v8, v9, v12
	v_fma_f32 v8, -v147, v8, v16
	v_add_f32_e32 v4, v4, v8
	v_pk_mul_f32 v[8:9], v[10:11], v[14:15]
	ds_read_b128 v[154:157], v83 offset:17200
	v_sub_f32_e32 v8, v8, v9
	v_mul_f32_e32 v9, v10, v15
	v_mul_f32_e32 v8, v148, v8
	v_fmac_f32_e32 v9, v11, v14
	v_fma_f32 v8, -v149, v9, v8
	v_add_f32_e32 v4, v4, v8
	s_waitcnt lgkmcnt(1)
	v_pk_mul_f32 v[8:9], v[150:151], v[158:159]
	v_mul_f32_e32 v17, v152, v161
	v_sub_f32_e32 v8, v8, v9
	v_mul_f32_e32 v9, v150, v159
	s_waitcnt lgkmcnt(0)
	v_mul_f32_e32 v8, v154, v8
	v_fmac_f32_e32 v9, v151, v158
	v_fma_f32 v8, -v155, v9, v8
	v_add_f32_e32 v4, v4, v8
	v_pk_mul_f32 v[8:9], v[152:153], v[160:161]
	v_fmac_f32_e32 v17, v153, v160
	v_sub_f32_e32 v8, v8, v9
	v_mul_f32_e32 v16, v156, v8
	ds_read_b128 v[8:11], v84 offset:320
	ds_read2_b64 v[12:15], v6 offset0:192 offset1:208
	ds_read_b128 v[146:149], v83 offset:17216
	ds_read_b128 v[150:153], v84 offset:336
	v_fma_f32 v16, -v157, v17, v16
	v_add_f32_e32 v4, v4, v16
	ds_read2_b64 v[158:161], v6 offset0:224 offset1:240
	s_waitcnt lgkmcnt(3)
	v_pk_mul_f32 v[16:17], v[8:9], v[12:13]
	v_mul_f32_e32 v8, v8, v13
	v_sub_f32_e32 v16, v16, v17
	s_waitcnt lgkmcnt(2)
	v_mul_f32_e32 v16, v146, v16
	v_fmac_f32_e32 v8, v9, v12
	v_fma_f32 v8, -v147, v8, v16
	v_add_f32_e32 v4, v4, v8
	v_pk_mul_f32 v[8:9], v[10:11], v[14:15]
	ds_read_b128 v[154:157], v83 offset:17232
	v_sub_f32_e32 v8, v8, v9
	v_mul_f32_e32 v9, v10, v15
	v_mul_f32_e32 v8, v148, v8
	v_fmac_f32_e32 v9, v11, v14
	v_fma_f32 v8, -v149, v9, v8
	v_add_f32_e32 v4, v4, v8
	s_waitcnt lgkmcnt(1)
	v_pk_mul_f32 v[8:9], v[150:151], v[158:159]
	v_mul_f32_e32 v20, v152, v161
	v_sub_f32_e32 v8, v8, v9
	v_mul_f32_e32 v9, v150, v159
	s_waitcnt lgkmcnt(0)
	v_mul_f32_e32 v8, v154, v8
	v_fmac_f32_e32 v9, v151, v158
	v_fma_f32 v8, -v155, v9, v8
	v_add_f32_e32 v16, v4, v8
	v_pk_mul_f32 v[8:9], v[152:153], v[160:161]
	v_fmac_f32_e32 v20, v153, v160
	v_sub_f32_e32 v4, v8, v9
	v_mul_f32_e32 v17, v156, v4
	v_add_u32_e32 v4, 0x3800, v82
	ds_read_b128 v[8:11], v84 offset:352
	ds_read2_b64 v[12:15], v4 offset1:16
	ds_read_b128 v[146:149], v83 offset:17248
	ds_read_b128 v[150:153], v84 offset:368
	v_fma_f32 v17, -v157, v20, v17
	v_add_f32_e32 v20, v16, v17
	ds_read2_b64 v[158:161], v4 offset0:32 offset1:48
	s_waitcnt lgkmcnt(3)
	v_pk_mul_f32 v[16:17], v[8:9], v[12:13]
	v_mul_f32_e32 v8, v8, v13
	v_sub_f32_e32 v16, v16, v17
	s_waitcnt lgkmcnt(2)
	v_mul_f32_e32 v16, v146, v16
	v_fmac_f32_e32 v8, v9, v12
	v_fma_f32 v8, -v147, v8, v16
	v_add_f32_e32 v12, v20, v8
	v_pk_mul_f32 v[8:9], v[10:11], v[14:15]
	ds_read_b128 v[154:157], v83 offset:17264
	v_sub_f32_e32 v8, v8, v9
	v_mul_f32_e32 v9, v10, v15
	v_mul_f32_e32 v8, v148, v8
	v_fmac_f32_e32 v9, v11, v14
	v_fma_f32 v8, -v149, v9, v8
	v_add_f32_e32 v10, v12, v8
	s_waitcnt lgkmcnt(1)
	v_pk_mul_f32 v[8:9], v[150:151], v[158:159]
	v_mul_f32_e32 v20, v152, v161
	v_sub_f32_e32 v8, v8, v9
	v_mul_f32_e32 v9, v150, v159
	s_waitcnt lgkmcnt(0)
	v_mul_f32_e32 v8, v154, v8
	v_fmac_f32_e32 v9, v151, v158
	v_fma_f32 v8, -v155, v9, v8
	v_add_f32_e32 v16, v10, v8
	v_pk_mul_f32 v[8:9], v[152:153], v[160:161]
	v_fmac_f32_e32 v20, v153, v160
	v_sub_f32_e32 v8, v8, v9
	v_mul_f32_e32 v17, v156, v8
	ds_read_b128 v[8:11], v84 offset:384
	ds_read2_b64 v[12:15], v4 offset0:64 offset1:80
	ds_read_b128 v[146:149], v83 offset:17280
	ds_read_b128 v[150:153], v84 offset:400
	v_fma_f32 v17, -v157, v20, v17
	v_add_f32_e32 v20, v16, v17
	ds_read2_b64 v[158:161], v4 offset0:96 offset1:112
	s_waitcnt lgkmcnt(3)
	v_pk_mul_f32 v[16:17], v[8:9], v[12:13]
	v_mul_f32_e32 v8, v8, v13
	v_sub_f32_e32 v16, v16, v17
	s_waitcnt lgkmcnt(2)
	v_mul_f32_e32 v16, v146, v16
	v_fmac_f32_e32 v8, v9, v12
	v_fma_f32 v8, -v147, v8, v16
	v_add_f32_e32 v12, v20, v8
	v_pk_mul_f32 v[8:9], v[10:11], v[14:15]
	ds_read_b128 v[154:157], v83 offset:17296
	v_sub_f32_e32 v8, v8, v9
	v_mul_f32_e32 v9, v10, v15
	v_mul_f32_e32 v8, v148, v8
	v_fmac_f32_e32 v9, v11, v14
	v_fma_f32 v8, -v149, v9, v8
	v_add_f32_e32 v10, v12, v8
	s_waitcnt lgkmcnt(1)
	v_pk_mul_f32 v[8:9], v[150:151], v[158:159]
	v_or_b32_e32 v2, s68, v23
	v_sub_f32_e32 v8, v8, v9
	v_mul_f32_e32 v9, v150, v159
	s_waitcnt lgkmcnt(0)
	v_mul_f32_e32 v8, v154, v8
	v_fmac_f32_e32 v9, v151, v158
	v_fma_f32 v8, -v155, v9, v8
	v_add_f32_e32 v12, v10, v8
	v_pk_mul_f32 v[8:9], v[152:153], v[160:161]
	v_readlane_b32 s44, v247, 6
	v_sub_f32_e32 v8, v8, v9
	v_mul_f32_e32 v9, v152, v161
	v_mul_f32_e32 v8, v156, v8
	v_fmac_f32_e32 v9, v153, v160
	v_fma_f32 v13, -v157, v9, v8
	ds_read_b128 v[8:11], v84 offset:416
	v_add_f32_e32 v20, v12, v13
	ds_read2_b64 v[12:15], v4 offset0:128 offset1:144
	ds_read_b128 v[146:149], v83 offset:17312
	ds_read_b128 v[150:153], v84 offset:432
	v_ashrrev_i32_e32 v3, 31, v2
	v_readlane_b32 s50, v247, 12
	s_waitcnt lgkmcnt(3)
	v_mov_b32_e32 v17, v10
	s_waitcnt lgkmcnt(2)
	v_mov_b32_e32 v155, v14
	v_mov_b32_e32 v10, v9
	v_mov_b32_e32 v14, v13
	v_mov_b32_e32 v16, v8
	v_mov_b32_e32 v154, v12
	v_pk_mul_f32 v[8:9], v[10:11], v[14:15]
	v_readlane_b32 s51, v247, 13
	v_pk_fma_f32 v[12:13], v[16:17], v[154:155], v[8:9] neg_lo:[0,0,1] neg_hi:[0,0,1]
	v_pk_mul_f32 v[8:9], v[10:11], v[154:155]
	v_lshl_add_u64 v[2:3], v[2:3], 2, s[50:51]
	v_pk_fma_f32 v[14:15], v[16:17], v[14:15], v[8:9]
	s_waitcnt lgkmcnt(1)
	v_mov_b32_e32 v17, v148
	v_mov_b32_e32 v148, v147
	v_mov_b32_e32 v16, v146
	v_pk_mul_f32 v[14:15], v[148:149], v[14:15]
	ds_read_b128 v[8:11], v83 offset:17328
	v_pk_fma_f32 v[16:17], v[16:17], v[12:13], v[14:15] neg_lo:[0,0,1] neg_hi:[0,0,1]
	ds_read2_b64 v[12:15], v4 offset0:160 offset1:176
	v_add_f32_e32 v16, v20, v16
	v_add_f32_e32 v20, v16, v17
	s_waitcnt lgkmcnt(2)
	v_mov_b32_e32 v17, v152
	v_mov_b32_e32 v152, v151
	s_waitcnt lgkmcnt(0)
	v_mov_b32_e32 v147, v14
	v_mov_b32_e32 v14, v13
	v_mov_b32_e32 v16, v150
	v_mov_b32_e32 v146, v12
	v_pk_mul_f32 v[12:13], v[152:153], v[14:15]
	v_readlane_b32 s45, v247, 7
	v_pk_fma_f32 v[12:13], v[16:17], v[146:147], v[12:13] neg_lo:[0,0,1] neg_hi:[0,0,1]
	v_pk_mul_f32 v[146:147], v[152:153], v[146:147]
	v_readlane_b32 s46, v247, 8
	v_pk_fma_f32 v[14:15], v[16:17], v[14:15], v[146:147]
	v_mov_b32_e32 v17, v10
	v_mov_b32_e32 v10, v9
	v_mov_b32_e32 v16, v8
	v_pk_mul_f32 v[8:9], v[10:11], v[14:15]
	v_readlane_b32 s47, v247, 9
	v_pk_fma_f32 v[12:13], v[16:17], v[12:13], v[8:9] neg_lo:[0,0,1] neg_hi:[0,0,1]
	ds_read_b128 v[8:11], v84 offset:448
	v_add_f32_e32 v12, v20, v12
	v_add_f32_e32 v20, v12, v13
	ds_read2_b64 v[12:15], v4 offset0:192 offset1:208
	ds_read_b128 v[146:149], v83 offset:17344
	ds_read_b128 v[150:153], v84 offset:464
	v_readlane_b32 s48, v247, 10
	s_waitcnt lgkmcnt(3)
	v_mov_b32_e32 v17, v10
	s_waitcnt lgkmcnt(2)
	v_mov_b32_e32 v155, v14
	v_mov_b32_e32 v10, v9
	v_mov_b32_e32 v14, v13
	v_mov_b32_e32 v16, v8
	v_mov_b32_e32 v154, v12
	v_pk_mul_f32 v[8:9], v[10:11], v[14:15]
	v_readlane_b32 s49, v247, 11
	v_pk_fma_f32 v[12:13], v[16:17], v[154:155], v[8:9] neg_lo:[0,0,1] neg_hi:[0,0,1]
	v_pk_mul_f32 v[8:9], v[10:11], v[154:155]
	v_readlane_b32 s52, v247, 14
	v_pk_fma_f32 v[14:15], v[16:17], v[14:15], v[8:9]
	s_waitcnt lgkmcnt(1)
	v_mov_b32_e32 v17, v148
	v_mov_b32_e32 v148, v147
	v_mov_b32_e32 v16, v146
	v_pk_mul_f32 v[14:15], v[148:149], v[14:15]
	ds_read_b128 v[8:11], v83 offset:17360
	v_pk_fma_f32 v[16:17], v[16:17], v[12:13], v[14:15] neg_lo:[0,0,1] neg_hi:[0,0,1]
	ds_read2_b64 v[12:15], v4 offset0:224 offset1:240
	v_add_f32_e32 v16, v20, v16
	v_add_f32_e32 v20, v16, v17
	s_waitcnt lgkmcnt(2)
	v_mov_b32_e32 v17, v152
	v_mov_b32_e32 v152, v151
	s_waitcnt lgkmcnt(0)
	v_mov_b32_e32 v147, v14
	v_mov_b32_e32 v14, v13
	v_mov_b32_e32 v16, v150
	v_mov_b32_e32 v146, v12
	v_pk_mul_f32 v[12:13], v[152:153], v[14:15]
	v_readlane_b32 s53, v247, 15
	v_pk_fma_f32 v[12:13], v[16:17], v[146:147], v[12:13] neg_lo:[0,0,1] neg_hi:[0,0,1]
	v_pk_mul_f32 v[146:147], v[152:153], v[146:147]
	v_readlane_b32 s54, v247, 16
	v_pk_fma_f32 v[14:15], v[16:17], v[14:15], v[146:147]
	v_mov_b32_e32 v17, v10
	v_mov_b32_e32 v10, v9
	v_mov_b32_e32 v16, v8
	v_pk_mul_f32 v[8:9], v[10:11], v[14:15]
	v_readlane_b32 s55, v247, 17
	v_pk_fma_f32 v[8:9], v[16:17], v[12:13], v[8:9] neg_lo:[0,0,1] neg_hi:[0,0,1]
	ds_read_b128 v[10:13], v84 offset:480
	v_add_f32_e32 v8, v20, v8
	v_add_f32_e32 v9, v8, v9
	v_add_u32_e32 v8, 0x4000, v82
	ds_read2_b64 v[14:17], v8 offset1:16
	ds_read_b128 v[146:149], v83 offset:17376
	ds_read_b128 v[150:153], v84 offset:496
	s_waitcnt lgkmcnt(3)
	v_mov_b32_e32 v155, v12
	v_mov_b32_e32 v12, v11
	s_waitcnt lgkmcnt(2)
	v_mov_b32_e32 v157, v16
	v_mov_b32_e32 v16, v15
	v_mov_b32_e32 v154, v10
	v_mov_b32_e32 v156, v14
	v_pk_mul_f32 v[10:11], v[12:13], v[16:17]
	v_readlane_b32 s56, v247, 18
	v_pk_fma_f32 v[14:15], v[154:155], v[156:157], v[10:11] neg_lo:[0,0,1] neg_hi:[0,0,1]
	v_pk_mul_f32 v[10:11], v[12:13], v[156:157]
	v_readlane_b32 s57, v247, 19
	v_pk_fma_f32 v[16:17], v[154:155], v[16:17], v[10:11]
	s_waitcnt lgkmcnt(1)
	v_mov_b32_e32 v155, v148
	v_mov_b32_e32 v148, v147
	v_mov_b32_e32 v154, v146
	v_pk_mul_f32 v[16:17], v[148:149], v[16:17]
	ds_read_b128 v[10:13], v83 offset:17392
	v_pk_fma_f32 v[146:147], v[154:155], v[14:15], v[16:17] neg_lo:[0,0,1] neg_hi:[0,0,1]
	ds_read2_b64 v[14:17], v8 offset0:32 offset1:48
	v_add_f32_e32 v9, v9, v146
	v_add_f32_e32 v9, v9, v147
	s_waitcnt lgkmcnt(2)
	v_mov_b32_e32 v147, v152
	v_mov_b32_e32 v152, v151
	s_waitcnt lgkmcnt(0)
	v_mov_b32_e32 v149, v16
	v_mov_b32_e32 v16, v15
	v_mov_b32_e32 v146, v150
	v_mov_b32_e32 v148, v14
	v_pk_mul_f32 v[14:15], v[152:153], v[16:17]
	v_readlane_b32 s58, v247, 20
	v_pk_fma_f32 v[14:15], v[146:147], v[148:149], v[14:15] neg_lo:[0,0,1] neg_hi:[0,0,1]
	v_pk_mul_f32 v[148:149], v[152:153], v[148:149]
	v_readlane_b32 s59, v247, 21
	v_pk_fma_f32 v[16:17], v[146:147], v[16:17], v[148:149]
	v_mov_b32_e32 v147, v12
	v_mov_b32_e32 v12, v11
	v_mov_b32_e32 v146, v10
	v_pk_mul_f32 v[10:11], v[12:13], v[16:17]
	s_nop 0
	v_pk_fma_f32 v[10:11], v[146:147], v[14:15], v[10:11] neg_lo:[0,0,1] neg_hi:[0,0,1]
	s_nop 0
	v_add_f32_e32 v9, v9, v10
	v_add_f32_e32 v9, v9, v11
	s_and_saveexec_b64 s[68:69], s[90:91]
	s_cbranch_execz .LBB0_83
	global_load_dword v10, v[2:3], off nt
	s_waitcnt vmcnt(0)
	v_add_f32_e32 v9, v9, v10
.LBB0_83:
	s_or_b64 exec, exec, s[68:69]
	ds_write_b32 v116, v9 offset:25088
	ds_read_b128 v[10:13], v87
	ds_read_b128 v[14:17], v87 offset:16
	ds_read_b128 v[146:149], v87 offset:32
	ds_read_b128 v[150:153], v87 offset:48
	ds_read2_b64 v[154:157], v7 offset0:64 offset1:80
	ds_read_b128 v[158:161], v83 offset:16896
	ds_read_b128 v[162:165], v83 offset:16912
	ds_read_b128 v[166:169], v83 offset:16928
	ds_read_b128 v[174:177], v83 offset:16944
	s_waitcnt lgkmcnt(4)
	v_pk_mul_f32 v[170:171], v[10:11], v[154:155]
	v_mul_f32_e32 v10, v10, v155
	v_sub_f32_e32 v9, v170, v171
	s_waitcnt lgkmcnt(3)
	v_mul_f32_e32 v9, v158, v9
	v_fmac_f32_e32 v10, v11, v154
	ds_read2_b64 v[178:181], v7 offset0:96 offset1:112
	v_fma_f32 v9, -v159, v10, v9
	v_pk_mul_f32 v[10:11], v[12:13], v[156:157]
	v_add_f32_e32 v9, 0, v9
	v_sub_f32_e32 v10, v10, v11
	v_mul_f32_e32 v11, v12, v157
	v_mul_f32_e32 v10, v160, v10
	v_fmac_f32_e32 v11, v13, v156
	v_fma_f32 v10, -v161, v11, v10
	v_add_f32_e32 v9, v9, v10
	s_waitcnt lgkmcnt(0)
	v_pk_mul_f32 v[10:11], v[14:15], v[178:179]
	s_nop 0
	v_sub_f32_e32 v10, v10, v11
	v_mul_f32_e32 v11, v14, v179
	v_mul_f32_e32 v10, v162, v10
	v_fmac_f32_e32 v11, v15, v178
	v_fma_f32 v10, -v163, v11, v10
	v_add_f32_e32 v9, v9, v10
	v_pk_mul_f32 v[10:11], v[16:17], v[180:181]
	v_mul_f32_e32 v15, v16, v181
	v_sub_f32_e32 v10, v10, v11
	v_mul_f32_e32 v14, v164, v10
	ds_read2_b64 v[10:13], v7 offset0:128 offset1:144
	v_fmac_f32_e32 v15, v17, v180
	v_fma_f32 v14, -v165, v15, v14
	v_add_f32_e32 v9, v9, v14
	s_waitcnt lgkmcnt(0)
	v_pk_mul_f32 v[14:15], v[146:147], v[10:11]
	s_nop 0
	v_sub_f32_e32 v14, v14, v15
	v_mul_f32_e32 v11, v146, v11
	v_mul_f32_e32 v14, v166, v14
	v_fmac_f32_e32 v11, v147, v10
	v_fma_f32 v10, -v167, v11, v14
	ds_read2_b64 v[14:17], v7 offset0:160 offset1:176
	v_add_f32_e32 v9, v9, v10
	v_pk_mul_f32 v[10:11], v[148:149], v[12:13]
	s_waitcnt lgkmcnt(0)
	v_mul_f32_e32 v79, v152, v17
	v_sub_f32_e32 v10, v10, v11
	v_mul_f32_e32 v11, v148, v13
	v_mul_f32_e32 v10, v168, v10
	v_fmac_f32_e32 v11, v149, v12
	v_fma_f32 v10, -v169, v11, v10
	v_add_f32_e32 v9, v9, v10
	v_pk_mul_f32 v[10:11], v[150:151], v[14:15]
	v_fmac_f32_e32 v79, v153, v16
	v_sub_f32_e32 v10, v10, v11
	v_mul_f32_e32 v11, v150, v15
	v_mul_f32_e32 v10, v174, v10
	v_fmac_f32_e32 v11, v151, v14
	v_fma_f32 v10, -v175, v11, v10
	v_add_f32_e32 v9, v9, v10
	v_pk_mul_f32 v[10:11], v[152:153], v[16:17]
	s_nop 0
	v_sub_f32_e32 v10, v10, v11
	v_mul_f32_e32 v20, v176, v10
	ds_read_b128 v[10:13], v87 offset:64
	ds_read2_b64 v[14:17], v7 offset0:192 offset1:208
	ds_read_b128 v[146:149], v83 offset:16960
	ds_read_b128 v[150:153], v87 offset:80
	v_fma_f32 v20, -v177, v79, v20
	v_add_f32_e32 v9, v9, v20
	ds_read2_b64 v[158:161], v7 offset0:224 offset1:240
	s_waitcnt lgkmcnt(3)
	v_pk_mul_f32 v[154:155], v[10:11], v[14:15]
	v_mul_f32_e32 v10, v10, v15
	v_sub_f32_e32 v20, v154, v155
	s_waitcnt lgkmcnt(2)
	v_mul_f32_e32 v20, v146, v20
	v_fmac_f32_e32 v10, v11, v14
	v_fma_f32 v10, -v147, v10, v20
	v_add_f32_e32 v9, v9, v10
	v_pk_mul_f32 v[10:11], v[12:13], v[16:17]
	ds_read_b128 v[154:157], v83 offset:16976
	v_sub_f32_e32 v10, v10, v11
	v_mul_f32_e32 v11, v12, v17
	v_mul_f32_e32 v10, v148, v10
	v_fmac_f32_e32 v11, v13, v16
	v_fma_f32 v10, -v149, v11, v10
	v_add_f32_e32 v9, v9, v10
	s_waitcnt lgkmcnt(1)
	v_pk_mul_f32 v[10:11], v[150:151], v[158:159]
	v_mul_f32_e32 v79, v152, v161
	v_sub_f32_e32 v10, v10, v11
	v_mul_f32_e32 v11, v150, v159
	s_waitcnt lgkmcnt(0)
	v_mul_f32_e32 v10, v154, v10
	v_fmac_f32_e32 v11, v151, v158
	v_fma_f32 v10, -v155, v11, v10
	v_add_f32_e32 v9, v9, v10
	v_pk_mul_f32 v[10:11], v[152:153], v[160:161]
	v_fmac_f32_e32 v79, v153, v160
	v_sub_f32_e32 v10, v10, v11
	v_mul_f32_e32 v20, v156, v10
	ds_read_b128 v[10:13], v87 offset:96
	ds_read2_b64 v[14:17], v5 offset1:16
	ds_read_b128 v[146:149], v83 offset:16992
	ds_read_b128 v[150:153], v87 offset:112
	v_fma_f32 v20, -v157, v79, v20
	v_add_f32_e32 v9, v9, v20
	ds_read2_b64 v[158:161], v5 offset0:32 offset1:48
	s_waitcnt lgkmcnt(3)
	v_pk_mul_f32 v[154:155], v[10:11], v[14:15]
	v_mul_f32_e32 v10, v10, v15
	v_sub_f32_e32 v20, v154, v155
	s_waitcnt lgkmcnt(2)
	v_mul_f32_e32 v20, v146, v20
	v_fmac_f32_e32 v10, v11, v14
	v_fma_f32 v10, -v147, v10, v20
	v_add_f32_e32 v9, v9, v10
	v_pk_mul_f32 v[10:11], v[12:13], v[16:17]
	ds_read_b128 v[154:157], v83 offset:17008
	v_sub_f32_e32 v10, v10, v11
	v_mul_f32_e32 v11, v12, v17
	v_mul_f32_e32 v10, v148, v10
	v_fmac_f32_e32 v11, v13, v16
	v_fma_f32 v10, -v149, v11, v10
	v_add_f32_e32 v9, v9, v10
	s_waitcnt lgkmcnt(1)
	v_pk_mul_f32 v[10:11], v[150:151], v[158:159]
	v_mul_f32_e32 v79, v152, v161
	v_sub_f32_e32 v10, v10, v11
	v_mul_f32_e32 v11, v150, v159
	s_waitcnt lgkmcnt(0)
	v_mul_f32_e32 v10, v154, v10
	v_fmac_f32_e32 v11, v151, v158
	v_fma_f32 v10, -v155, v11, v10
	v_add_f32_e32 v9, v9, v10
	v_pk_mul_f32 v[10:11], v[152:153], v[160:161]
	v_fmac_f32_e32 v79, v153, v160
	v_sub_f32_e32 v10, v10, v11
	v_mul_f32_e32 v20, v156, v10
	ds_read_b128 v[10:13], v87 offset:128
	ds_read2_b64 v[14:17], v5 offset0:64 offset1:80
	ds_read_b128 v[146:149], v83 offset:17024
	ds_read_b128 v[150:153], v87 offset:144
	v_fma_f32 v20, -v157, v79, v20
	v_add_f32_e32 v9, v9, v20
	ds_read2_b64 v[158:161], v5 offset0:96 offset1:112
	s_waitcnt lgkmcnt(3)
	v_pk_mul_f32 v[154:155], v[10:11], v[14:15]
	v_mul_f32_e32 v10, v10, v15
	v_sub_f32_e32 v20, v154, v155
	s_waitcnt lgkmcnt(2)
	v_mul_f32_e32 v20, v146, v20
	v_fmac_f32_e32 v10, v11, v14
	v_fma_f32 v10, -v147, v10, v20
	v_add_f32_e32 v9, v9, v10
	v_pk_mul_f32 v[10:11], v[12:13], v[16:17]
	ds_read_b128 v[154:157], v83 offset:17040
	v_sub_f32_e32 v10, v10, v11
	v_mul_f32_e32 v11, v12, v17
	v_mul_f32_e32 v10, v148, v10
	v_fmac_f32_e32 v11, v13, v16
	v_fma_f32 v10, -v149, v11, v10
	v_add_f32_e32 v9, v9, v10
	s_waitcnt lgkmcnt(1)
	v_pk_mul_f32 v[10:11], v[150:151], v[158:159]
	v_mul_f32_e32 v79, v152, v161
	v_sub_f32_e32 v10, v10, v11
	v_mul_f32_e32 v11, v150, v159
	s_waitcnt lgkmcnt(0)
	v_mul_f32_e32 v10, v154, v10
	v_fmac_f32_e32 v11, v151, v158
	v_fma_f32 v10, -v155, v11, v10
	v_add_f32_e32 v9, v9, v10
	v_pk_mul_f32 v[10:11], v[152:153], v[160:161]
	v_fmac_f32_e32 v79, v153, v160
	v_sub_f32_e32 v10, v10, v11
	v_mul_f32_e32 v20, v156, v10
	ds_read_b128 v[10:13], v87 offset:160
	ds_read2_b64 v[14:17], v5 offset0:128 offset1:144
	ds_read_b128 v[146:149], v83 offset:17056
	ds_read_b128 v[150:153], v87 offset:176
	v_fma_f32 v20, -v157, v79, v20
	v_add_f32_e32 v9, v9, v20
	ds_read2_b64 v[158:161], v5 offset0:160 offset1:176
	s_waitcnt lgkmcnt(3)
	v_pk_mul_f32 v[154:155], v[10:11], v[14:15]
	v_mul_f32_e32 v10, v10, v15
	v_sub_f32_e32 v20, v154, v155
	s_waitcnt lgkmcnt(2)
	v_mul_f32_e32 v20, v146, v20
	v_fmac_f32_e32 v10, v11, v14
	v_fma_f32 v10, -v147, v10, v20
	v_add_f32_e32 v9, v9, v10
	v_pk_mul_f32 v[10:11], v[12:13], v[16:17]
	ds_read_b128 v[154:157], v83 offset:17072
	v_sub_f32_e32 v10, v10, v11
	v_mul_f32_e32 v11, v12, v17
	v_mul_f32_e32 v10, v148, v10
	v_fmac_f32_e32 v11, v13, v16
	v_fma_f32 v10, -v149, v11, v10
	v_add_f32_e32 v9, v9, v10
	s_waitcnt lgkmcnt(1)
	v_pk_mul_f32 v[10:11], v[150:151], v[158:159]
	v_mul_f32_e32 v79, v152, v161
	v_sub_f32_e32 v10, v10, v11
	v_mul_f32_e32 v11, v150, v159
	s_waitcnt lgkmcnt(0)
	v_mul_f32_e32 v10, v154, v10
	v_fmac_f32_e32 v11, v151, v158
	v_fma_f32 v10, -v155, v11, v10
	v_add_f32_e32 v9, v9, v10
	v_pk_mul_f32 v[10:11], v[152:153], v[160:161]
	v_fmac_f32_e32 v79, v153, v160
	v_sub_f32_e32 v10, v10, v11
	v_mul_f32_e32 v20, v156, v10
	ds_read_b128 v[10:13], v87 offset:192
	ds_read2_b64 v[14:17], v5 offset0:192 offset1:208
	ds_read_b128 v[146:149], v83 offset:17088
	ds_read_b128 v[150:153], v87 offset:208
	v_fma_f32 v20, -v157, v79, v20
	v_add_f32_e32 v9, v9, v20
	ds_read2_b64 v[158:161], v5 offset0:224 offset1:240
	s_waitcnt lgkmcnt(3)
	v_pk_mul_f32 v[154:155], v[10:11], v[14:15]
	v_mul_f32_e32 v10, v10, v15
	v_sub_f32_e32 v20, v154, v155
	s_waitcnt lgkmcnt(2)
	v_mul_f32_e32 v20, v146, v20
	v_fmac_f32_e32 v10, v11, v14
	v_fma_f32 v10, -v147, v10, v20
	v_add_f32_e32 v9, v9, v10
	v_pk_mul_f32 v[10:11], v[12:13], v[16:17]
	ds_read_b128 v[154:157], v83 offset:17104
	v_sub_f32_e32 v10, v10, v11
	v_mul_f32_e32 v11, v12, v17
	v_mul_f32_e32 v10, v148, v10
	v_fmac_f32_e32 v11, v13, v16
	v_fma_f32 v10, -v149, v11, v10
	v_add_f32_e32 v9, v9, v10
	s_waitcnt lgkmcnt(1)
	v_pk_mul_f32 v[10:11], v[150:151], v[158:159]
	v_mul_f32_e32 v79, v152, v161
	v_sub_f32_e32 v10, v10, v11
	v_mul_f32_e32 v11, v150, v159
	s_waitcnt lgkmcnt(0)
	v_mul_f32_e32 v10, v154, v10
	v_fmac_f32_e32 v11, v151, v158
	v_fma_f32 v10, -v155, v11, v10
	v_add_f32_e32 v9, v9, v10
	v_pk_mul_f32 v[10:11], v[152:153], v[160:161]
	v_fmac_f32_e32 v79, v153, v160
	v_sub_f32_e32 v10, v10, v11
	v_mul_f32_e32 v20, v156, v10
	ds_read_b128 v[10:13], v87 offset:224
	ds_read2_b64 v[14:17], v6 offset1:16
	ds_read_b128 v[146:149], v83 offset:17120
	ds_read_b128 v[150:153], v87 offset:240
	v_fma_f32 v20, -v157, v79, v20
	v_add_f32_e32 v9, v9, v20
	ds_read2_b64 v[158:161], v6 offset0:32 offset1:48
	s_waitcnt lgkmcnt(3)
	v_pk_mul_f32 v[154:155], v[10:11], v[14:15]
	v_mul_f32_e32 v10, v10, v15
	v_sub_f32_e32 v20, v154, v155
	s_waitcnt lgkmcnt(2)
	v_mul_f32_e32 v20, v146, v20
	v_fmac_f32_e32 v10, v11, v14
	v_fma_f32 v10, -v147, v10, v20
	v_add_f32_e32 v9, v9, v10
	v_pk_mul_f32 v[10:11], v[12:13], v[16:17]
	ds_read_b128 v[154:157], v83 offset:17136
	v_sub_f32_e32 v10, v10, v11
	v_mul_f32_e32 v11, v12, v17
	v_mul_f32_e32 v10, v148, v10
	v_fmac_f32_e32 v11, v13, v16
	v_fma_f32 v10, -v149, v11, v10
	v_add_f32_e32 v9, v9, v10
	s_waitcnt lgkmcnt(1)
	v_pk_mul_f32 v[10:11], v[150:151], v[158:159]
	v_mul_f32_e32 v79, v152, v161
	v_sub_f32_e32 v10, v10, v11
	v_mul_f32_e32 v11, v150, v159
	s_waitcnt lgkmcnt(0)
	v_mul_f32_e32 v10, v154, v10
	v_fmac_f32_e32 v11, v151, v158
	v_fma_f32 v10, -v155, v11, v10
	v_add_f32_e32 v9, v9, v10
	v_pk_mul_f32 v[10:11], v[152:153], v[160:161]
	v_fmac_f32_e32 v79, v153, v160
	v_sub_f32_e32 v10, v10, v11
	v_mul_f32_e32 v20, v156, v10
	ds_read_b128 v[10:13], v87 offset:256
	ds_read2_b64 v[14:17], v6 offset0:64 offset1:80
	ds_read_b128 v[146:149], v83 offset:17152
	ds_read_b128 v[150:153], v87 offset:272
	v_fma_f32 v20, -v157, v79, v20
	v_add_f32_e32 v9, v9, v20
	ds_read2_b64 v[158:161], v6 offset0:96 offset1:112
	s_waitcnt lgkmcnt(3)
	v_pk_mul_f32 v[154:155], v[10:11], v[14:15]
	v_mul_f32_e32 v10, v10, v15
	v_sub_f32_e32 v20, v154, v155
	s_waitcnt lgkmcnt(2)
	v_mul_f32_e32 v20, v146, v20
	v_fmac_f32_e32 v10, v11, v14
	v_fma_f32 v10, -v147, v10, v20
	v_add_f32_e32 v9, v9, v10
	v_pk_mul_f32 v[10:11], v[12:13], v[16:17]
	ds_read_b128 v[154:157], v83 offset:17168
	v_sub_f32_e32 v10, v10, v11
	v_mul_f32_e32 v11, v12, v17
	v_mul_f32_e32 v10, v148, v10
	v_fmac_f32_e32 v11, v13, v16
	v_fma_f32 v10, -v149, v11, v10
	v_add_f32_e32 v9, v9, v10
	s_waitcnt lgkmcnt(1)
	v_pk_mul_f32 v[10:11], v[150:151], v[158:159]
	v_mul_f32_e32 v79, v152, v161
	v_sub_f32_e32 v10, v10, v11
	v_mul_f32_e32 v11, v150, v159
	s_waitcnt lgkmcnt(0)
	v_mul_f32_e32 v10, v154, v10
	v_fmac_f32_e32 v11, v151, v158
	v_fma_f32 v10, -v155, v11, v10
	v_add_f32_e32 v9, v9, v10
	v_pk_mul_f32 v[10:11], v[152:153], v[160:161]
	v_fmac_f32_e32 v79, v153, v160
	v_sub_f32_e32 v10, v10, v11
	v_mul_f32_e32 v20, v156, v10
	ds_read_b128 v[10:13], v87 offset:288
	ds_read2_b64 v[14:17], v6 offset0:128 offset1:144
	ds_read_b128 v[146:149], v83 offset:17184
	ds_read_b128 v[150:153], v87 offset:304
	v_fma_f32 v20, -v157, v79, v20
	v_add_f32_e32 v9, v9, v20
	ds_read2_b64 v[158:161], v6 offset0:160 offset1:176
	s_waitcnt lgkmcnt(3)
	v_pk_mul_f32 v[154:155], v[10:11], v[14:15]
	v_mul_f32_e32 v10, v10, v15
	v_sub_f32_e32 v20, v154, v155
	s_waitcnt lgkmcnt(2)
	v_mul_f32_e32 v20, v146, v20
	v_fmac_f32_e32 v10, v11, v14
	v_fma_f32 v10, -v147, v10, v20
	v_add_f32_e32 v9, v9, v10
	v_pk_mul_f32 v[10:11], v[12:13], v[16:17]
	ds_read_b128 v[154:157], v83 offset:17200
	v_sub_f32_e32 v10, v10, v11
	v_mul_f32_e32 v11, v12, v17
	v_mul_f32_e32 v10, v148, v10
	v_fmac_f32_e32 v11, v13, v16
	v_fma_f32 v10, -v149, v11, v10
	v_add_f32_e32 v9, v9, v10
	s_waitcnt lgkmcnt(1)
	v_pk_mul_f32 v[10:11], v[150:151], v[158:159]
	v_mul_f32_e32 v79, v152, v161
	v_sub_f32_e32 v10, v10, v11
	v_mul_f32_e32 v11, v150, v159
	s_waitcnt lgkmcnt(0)
	v_mul_f32_e32 v10, v154, v10
	v_fmac_f32_e32 v11, v151, v158
	v_fma_f32 v10, -v155, v11, v10
	v_add_f32_e32 v9, v9, v10
	v_pk_mul_f32 v[10:11], v[152:153], v[160:161]
	v_fmac_f32_e32 v79, v153, v160
	v_sub_f32_e32 v10, v10, v11
	v_mul_f32_e32 v20, v156, v10
	ds_read_b128 v[10:13], v87 offset:320
	ds_read2_b64 v[14:17], v6 offset0:192 offset1:208
	ds_read_b128 v[146:149], v83 offset:17216
	ds_read_b128 v[150:153], v87 offset:336
	v_fma_f32 v20, -v157, v79, v20
	v_add_f32_e32 v9, v9, v20
	ds_read2_b64 v[158:161], v6 offset0:224 offset1:240
	s_waitcnt lgkmcnt(3)
	v_pk_mul_f32 v[154:155], v[10:11], v[14:15]
	v_mul_f32_e32 v10, v10, v15
	v_sub_f32_e32 v20, v154, v155
	s_waitcnt lgkmcnt(2)
	v_mul_f32_e32 v20, v146, v20
	v_fmac_f32_e32 v10, v11, v14
	v_fma_f32 v10, -v147, v10, v20
	v_add_f32_e32 v9, v9, v10
	v_pk_mul_f32 v[10:11], v[12:13], v[16:17]
	ds_read_b128 v[154:157], v83 offset:17232
	v_sub_f32_e32 v10, v10, v11
	v_mul_f32_e32 v11, v12, v17
	v_mul_f32_e32 v10, v148, v10
	v_fmac_f32_e32 v11, v13, v16
	v_fma_f32 v10, -v149, v11, v10
	v_add_f32_e32 v9, v9, v10
	s_waitcnt lgkmcnt(1)
	v_pk_mul_f32 v[10:11], v[150:151], v[158:159]
	v_mul_f32_e32 v79, v152, v161
	v_sub_f32_e32 v10, v10, v11
	v_mul_f32_e32 v11, v150, v159
	s_waitcnt lgkmcnt(0)
	v_mul_f32_e32 v10, v154, v10
	v_fmac_f32_e32 v11, v151, v158
	v_fma_f32 v10, -v155, v11, v10
	v_add_f32_e32 v9, v9, v10
	v_pk_mul_f32 v[10:11], v[152:153], v[160:161]
	v_fmac_f32_e32 v79, v153, v160
	v_sub_f32_e32 v10, v10, v11
	v_mul_f32_e32 v20, v156, v10
	ds_read_b128 v[10:13], v87 offset:352
	ds_read2_b64 v[14:17], v4 offset1:16
	ds_read_b128 v[146:149], v83 offset:17248
	ds_read_b128 v[150:153], v87 offset:368
	v_fma_f32 v20, -v157, v79, v20
	v_add_f32_e32 v9, v9, v20
	ds_read2_b64 v[158:161], v4 offset0:32 offset1:48
	s_waitcnt lgkmcnt(3)
	v_pk_mul_f32 v[154:155], v[10:11], v[14:15]
	v_mul_f32_e32 v10, v10, v15
	v_sub_f32_e32 v20, v154, v155
	s_waitcnt lgkmcnt(2)
	v_mul_f32_e32 v20, v146, v20
	v_fmac_f32_e32 v10, v11, v14
	v_fma_f32 v10, -v147, v10, v20
	v_add_f32_e32 v9, v9, v10
	v_pk_mul_f32 v[10:11], v[12:13], v[16:17]
	ds_read_b128 v[154:157], v83 offset:17264
	v_sub_f32_e32 v10, v10, v11
	v_mul_f32_e32 v11, v12, v17
	v_mul_f32_e32 v10, v148, v10
	v_fmac_f32_e32 v11, v13, v16
	v_fma_f32 v10, -v149, v11, v10
	v_add_f32_e32 v9, v9, v10
	s_waitcnt lgkmcnt(1)
	v_pk_mul_f32 v[10:11], v[150:151], v[158:159]
	v_mul_f32_e32 v79, v152, v161
	v_sub_f32_e32 v10, v10, v11
	v_mul_f32_e32 v11, v150, v159
	s_waitcnt lgkmcnt(0)
	v_mul_f32_e32 v10, v154, v10
	v_fmac_f32_e32 v11, v151, v158
	v_fma_f32 v10, -v155, v11, v10
	v_add_f32_e32 v9, v9, v10
	v_pk_mul_f32 v[10:11], v[152:153], v[160:161]
	v_fmac_f32_e32 v79, v153, v160
	v_sub_f32_e32 v10, v10, v11
	v_mul_f32_e32 v20, v156, v10
	ds_read_b128 v[10:13], v87 offset:384
	ds_read2_b64 v[14:17], v4 offset0:64 offset1:80
	ds_read_b128 v[146:149], v83 offset:17280
	ds_read_b128 v[150:153], v87 offset:400
	v_fma_f32 v20, -v157, v79, v20
	v_add_f32_e32 v9, v9, v20
	ds_read2_b64 v[158:161], v4 offset0:96 offset1:112
	s_waitcnt lgkmcnt(3)
	v_pk_mul_f32 v[154:155], v[10:11], v[14:15]
	v_mul_f32_e32 v10, v10, v15
	v_sub_f32_e32 v20, v154, v155
	s_waitcnt lgkmcnt(2)
	v_mul_f32_e32 v20, v146, v20
	v_fmac_f32_e32 v10, v11, v14
	v_fma_f32 v10, -v147, v10, v20
	v_add_f32_e32 v9, v9, v10
	v_pk_mul_f32 v[10:11], v[12:13], v[16:17]
	ds_read_b128 v[154:157], v83 offset:17296
	v_sub_f32_e32 v10, v10, v11
	v_mul_f32_e32 v11, v12, v17
	v_mul_f32_e32 v10, v148, v10
	v_fmac_f32_e32 v11, v13, v16
	v_fma_f32 v10, -v149, v11, v10
	v_add_f32_e32 v9, v9, v10
	s_waitcnt lgkmcnt(1)
	v_pk_mul_f32 v[10:11], v[150:151], v[158:159]
	s_nop 0
	v_sub_f32_e32 v10, v10, v11
	v_mul_f32_e32 v11, v150, v159
	s_waitcnt lgkmcnt(0)
	v_mul_f32_e32 v10, v154, v10
	v_fmac_f32_e32 v11, v151, v158
	v_fma_f32 v10, -v155, v11, v10
	v_add_f32_e32 v9, v9, v10
	v_pk_mul_f32 v[10:11], v[152:153], v[160:161]
	s_nop 0
	v_sub_f32_e32 v10, v10, v11
	v_mul_f32_e32 v11, v152, v161
	v_mul_f32_e32 v10, v156, v10
	v_fmac_f32_e32 v11, v153, v160
	v_fma_f32 v14, -v157, v11, v10
	ds_read_b128 v[10:13], v87 offset:416
	v_add_f32_e32 v9, v9, v14
	ds_read2_b64 v[14:17], v4 offset0:128 offset1:144
	ds_read_b128 v[146:149], v83 offset:17312
	ds_read_b128 v[150:153], v87 offset:432
	s_waitcnt lgkmcnt(3)
	v_mov_b32_e32 v155, v12
	s_waitcnt lgkmcnt(2)
	v_mov_b32_e32 v157, v16
	v_mov_b32_e32 v12, v11
	v_mov_b32_e32 v16, v15
	v_mov_b32_e32 v154, v10
	v_mov_b32_e32 v156, v14
	v_pk_mul_f32 v[10:11], v[12:13], v[16:17]
	s_nop 0
	v_pk_fma_f32 v[14:15], v[154:155], v[156:157], v[10:11] neg_lo:[0,0,1] neg_hi:[0,0,1]
	v_pk_mul_f32 v[10:11], v[12:13], v[156:157]
	s_nop 0
	v_pk_fma_f32 v[16:17], v[154:155], v[16:17], v[10:11]
	s_waitcnt lgkmcnt(1)
	v_mov_b32_e32 v155, v148
	v_mov_b32_e32 v148, v147
	v_mov_b32_e32 v154, v146
	v_pk_mul_f32 v[16:17], v[148:149], v[16:17]
	ds_read_b128 v[10:13], v83 offset:17328
	v_pk_fma_f32 v[146:147], v[154:155], v[14:15], v[16:17] neg_lo:[0,0,1] neg_hi:[0,0,1]
	ds_read2_b64 v[14:17], v4 offset0:160 offset1:176
	v_add_f32_e32 v9, v9, v146
	v_add_f32_e32 v9, v9, v147
	s_waitcnt lgkmcnt(2)
	v_mov_b32_e32 v147, v152
	v_mov_b32_e32 v152, v151
	s_waitcnt lgkmcnt(0)
	v_mov_b32_e32 v149, v16
	v_mov_b32_e32 v16, v15
	v_mov_b32_e32 v146, v150
	v_mov_b32_e32 v148, v14
	v_pk_mul_f32 v[14:15], v[152:153], v[16:17]
	s_nop 0
	v_pk_fma_f32 v[14:15], v[146:147], v[148:149], v[14:15] neg_lo:[0,0,1] neg_hi:[0,0,1]
	v_pk_mul_f32 v[148:149], v[152:153], v[148:149]
	s_nop 0
	v_pk_fma_f32 v[16:17], v[146:147], v[16:17], v[148:149]
	v_mov_b32_e32 v147, v12
	v_mov_b32_e32 v12, v11
	v_mov_b32_e32 v146, v10
	v_pk_mul_f32 v[10:11], v[12:13], v[16:17]
	s_nop 0
	v_pk_fma_f32 v[14:15], v[146:147], v[14:15], v[10:11] neg_lo:[0,0,1] neg_hi:[0,0,1]
	ds_read_b128 v[10:13], v87 offset:448
	v_add_f32_e32 v9, v9, v14
	v_add_f32_e32 v9, v9, v15
	ds_read2_b64 v[14:17], v4 offset0:192 offset1:208
	ds_read_b128 v[146:149], v83 offset:17344
	ds_read_b128 v[150:153], v87 offset:464
	s_waitcnt lgkmcnt(3)
	v_mov_b32_e32 v155, v12
	s_waitcnt lgkmcnt(2)
	v_mov_b32_e32 v157, v16
	v_mov_b32_e32 v12, v11
	v_mov_b32_e32 v16, v15
	v_mov_b32_e32 v154, v10
	v_mov_b32_e32 v156, v14
	v_pk_mul_f32 v[10:11], v[12:13], v[16:17]
	s_nop 0
	v_pk_fma_f32 v[14:15], v[154:155], v[156:157], v[10:11] neg_lo:[0,0,1] neg_hi:[0,0,1]
	v_pk_mul_f32 v[10:11], v[12:13], v[156:157]
	s_nop 0
	v_pk_fma_f32 v[16:17], v[154:155], v[16:17], v[10:11]
	s_waitcnt lgkmcnt(1)
	v_mov_b32_e32 v155, v148
	v_mov_b32_e32 v148, v147
	v_mov_b32_e32 v154, v146
	v_pk_mul_f32 v[16:17], v[148:149], v[16:17]
	ds_read_b128 v[10:13], v83 offset:17360
	v_pk_fma_f32 v[146:147], v[154:155], v[14:15], v[16:17] neg_lo:[0,0,1] neg_hi:[0,0,1]
	ds_read2_b64 v[14:17], v4 offset0:224 offset1:240
	v_add_f32_e32 v9, v9, v146
	v_add_f32_e32 v9, v9, v147
	s_waitcnt lgkmcnt(2)
	v_mov_b32_e32 v147, v152
	v_mov_b32_e32 v152, v151
	s_waitcnt lgkmcnt(0)
	v_mov_b32_e32 v149, v16
	v_mov_b32_e32 v16, v15
	v_mov_b32_e32 v146, v150
	v_mov_b32_e32 v148, v14
	v_pk_mul_f32 v[14:15], v[152:153], v[16:17]
	s_nop 0
	v_pk_fma_f32 v[14:15], v[146:147], v[148:149], v[14:15] neg_lo:[0,0,1] neg_hi:[0,0,1]
	v_pk_mul_f32 v[148:149], v[152:153], v[148:149]
	s_nop 0
	v_pk_fma_f32 v[16:17], v[146:147], v[16:17], v[148:149]
	v_mov_b32_e32 v147, v12
	v_mov_b32_e32 v12, v11
	v_mov_b32_e32 v146, v10
	v_pk_mul_f32 v[10:11], v[12:13], v[16:17]
	s_nop 0
	v_pk_fma_f32 v[14:15], v[146:147], v[14:15], v[10:11] neg_lo:[0,0,1] neg_hi:[0,0,1]
	ds_read_b128 v[10:13], v87 offset:480
	v_add_f32_e32 v9, v9, v14
	v_add_f32_e32 v9, v9, v15
	ds_read2_b64 v[14:17], v8 offset1:16
	ds_read_b128 v[146:149], v83 offset:17376
	ds_read_b128 v[150:153], v87 offset:496
	s_waitcnt lgkmcnt(3)
	v_mov_b32_e32 v155, v12
	s_waitcnt lgkmcnt(2)
	v_mov_b32_e32 v157, v16
	v_mov_b32_e32 v12, v11
	v_mov_b32_e32 v16, v15
	v_mov_b32_e32 v154, v10
	v_mov_b32_e32 v156, v14
	v_pk_mul_f32 v[10:11], v[12:13], v[16:17]
	s_nop 0
	v_pk_fma_f32 v[14:15], v[154:155], v[156:157], v[10:11] neg_lo:[0,0,1] neg_hi:[0,0,1]
	v_pk_mul_f32 v[10:11], v[12:13], v[156:157]
	s_nop 0
	v_pk_fma_f32 v[16:17], v[154:155], v[16:17], v[10:11]
	s_waitcnt lgkmcnt(1)
	v_mov_b32_e32 v155, v148
	v_mov_b32_e32 v148, v147
	v_mov_b32_e32 v154, v146
	v_pk_mul_f32 v[16:17], v[148:149], v[16:17]
	ds_read_b128 v[10:13], v83 offset:17392
	v_pk_fma_f32 v[146:147], v[154:155], v[14:15], v[16:17] neg_lo:[0,0,1] neg_hi:[0,0,1]
	ds_read2_b64 v[14:17], v8 offset0:32 offset1:48
	v_add_f32_e32 v9, v9, v146
	v_add_f32_e32 v9, v9, v147
	s_waitcnt lgkmcnt(2)
	v_mov_b32_e32 v147, v152
	v_mov_b32_e32 v152, v151
	s_waitcnt lgkmcnt(0)
	v_mov_b32_e32 v149, v16
	v_mov_b32_e32 v16, v15
	v_mov_b32_e32 v146, v150
	v_mov_b32_e32 v148, v14
	v_pk_mul_f32 v[14:15], v[152:153], v[16:17]
	s_nop 0
	v_pk_fma_f32 v[14:15], v[146:147], v[148:149], v[14:15] neg_lo:[0,0,1] neg_hi:[0,0,1]
	v_pk_mul_f32 v[148:149], v[152:153], v[148:149]
	s_nop 0
	v_pk_fma_f32 v[16:17], v[146:147], v[16:17], v[148:149]
	v_mov_b32_e32 v147, v12
	v_mov_b32_e32 v12, v11
	v_mov_b32_e32 v146, v10
	v_pk_mul_f32 v[10:11], v[12:13], v[16:17]
	s_nop 0
	v_pk_fma_f32 v[10:11], v[146:147], v[14:15], v[10:11] neg_lo:[0,0,1] neg_hi:[0,0,1]
	s_nop 0
	v_add_f32_e32 v9, v9, v10
	v_add_f32_e32 v9, v9, v11
	s_and_saveexec_b64 s[68:69], s[92:93]
	s_cbranch_execz .LBB0_85
	global_load_dword v10, v[2:3], off nt
	s_waitcnt vmcnt(0)
	v_add_f32_e32 v9, v9, v10
.LBB0_85:
	s_or_b64 exec, exec, s[68:69]
	ds_write_b32 v116, v9 offset:27136
	ds_read_b128 v[10:13], v90
	ds_read_b128 v[14:17], v90 offset:16
	ds_read_b128 v[146:149], v90 offset:32
	ds_read_b128 v[150:153], v90 offset:48
	ds_read2_b64 v[154:157], v7 offset0:64 offset1:80
	ds_read_b128 v[158:161], v83 offset:16896
	ds_read_b128 v[162:165], v83 offset:16912
	ds_read_b128 v[166:169], v83 offset:16928
	ds_read_b128 v[174:177], v83 offset:16944
	s_waitcnt lgkmcnt(4)
	v_pk_mul_f32 v[170:171], v[10:11], v[154:155]
	v_mul_f32_e32 v10, v10, v155
	v_sub_f32_e32 v9, v170, v171
	s_waitcnt lgkmcnt(3)
	v_mul_f32_e32 v9, v158, v9
	v_fmac_f32_e32 v10, v11, v154
	ds_read2_b64 v[178:181], v7 offset0:96 offset1:112
	v_fma_f32 v9, -v159, v10, v9
	v_pk_mul_f32 v[10:11], v[12:13], v[156:157]
	v_add_f32_e32 v9, 0, v9
	v_sub_f32_e32 v10, v10, v11
	v_mul_f32_e32 v11, v12, v157
	v_mul_f32_e32 v10, v160, v10
	v_fmac_f32_e32 v11, v13, v156
	v_fma_f32 v10, -v161, v11, v10
	v_add_f32_e32 v9, v9, v10
	s_waitcnt lgkmcnt(0)
	v_pk_mul_f32 v[10:11], v[14:15], v[178:179]
	s_nop 0
	v_sub_f32_e32 v10, v10, v11
	v_mul_f32_e32 v11, v14, v179
	v_mul_f32_e32 v10, v162, v10
	v_fmac_f32_e32 v11, v15, v178
	v_fma_f32 v10, -v163, v11, v10
	v_add_f32_e32 v9, v9, v10
	v_pk_mul_f32 v[10:11], v[16:17], v[180:181]
	v_mul_f32_e32 v15, v16, v181
	v_sub_f32_e32 v10, v10, v11
	v_mul_f32_e32 v14, v164, v10
	ds_read2_b64 v[10:13], v7 offset0:128 offset1:144
	v_fmac_f32_e32 v15, v17, v180
	v_fma_f32 v14, -v165, v15, v14
	v_add_f32_e32 v9, v9, v14
	s_waitcnt lgkmcnt(0)
	v_pk_mul_f32 v[14:15], v[146:147], v[10:11]
	s_nop 0
	v_sub_f32_e32 v14, v14, v15
	v_mul_f32_e32 v11, v146, v11
	v_mul_f32_e32 v14, v166, v14
	v_fmac_f32_e32 v11, v147, v10
	v_fma_f32 v10, -v167, v11, v14
	ds_read2_b64 v[14:17], v7 offset0:160 offset1:176
	v_add_f32_e32 v9, v9, v10
	v_pk_mul_f32 v[10:11], v[148:149], v[12:13]
	s_waitcnt lgkmcnt(0)
	v_mul_f32_e32 v79, v152, v17
	v_sub_f32_e32 v10, v10, v11
	v_mul_f32_e32 v11, v148, v13
	v_mul_f32_e32 v10, v168, v10
	v_fmac_f32_e32 v11, v149, v12
	v_fma_f32 v10, -v169, v11, v10
	v_add_f32_e32 v9, v9, v10
	v_pk_mul_f32 v[10:11], v[150:151], v[14:15]
	v_fmac_f32_e32 v79, v153, v16
	v_sub_f32_e32 v10, v10, v11
	v_mul_f32_e32 v11, v150, v15
	v_mul_f32_e32 v10, v174, v10
	v_fmac_f32_e32 v11, v151, v14
	v_fma_f32 v10, -v175, v11, v10
	v_add_f32_e32 v9, v9, v10
	v_pk_mul_f32 v[10:11], v[152:153], v[16:17]
	s_nop 0
	v_sub_f32_e32 v10, v10, v11
	v_mul_f32_e32 v20, v176, v10
	ds_read_b128 v[10:13], v90 offset:64
	ds_read2_b64 v[14:17], v7 offset0:192 offset1:208
	ds_read_b128 v[146:149], v83 offset:16960
	ds_read_b128 v[150:153], v90 offset:80
	v_fma_f32 v20, -v177, v79, v20
	v_add_f32_e32 v9, v9, v20
	ds_read2_b64 v[158:161], v7 offset0:224 offset1:240
	s_waitcnt lgkmcnt(3)
	v_pk_mul_f32 v[154:155], v[10:11], v[14:15]
	v_mul_f32_e32 v10, v10, v15
	v_sub_f32_e32 v20, v154, v155
	s_waitcnt lgkmcnt(2)
	v_mul_f32_e32 v20, v146, v20
	v_fmac_f32_e32 v10, v11, v14
	v_fma_f32 v10, -v147, v10, v20
	v_add_f32_e32 v9, v9, v10
	v_pk_mul_f32 v[10:11], v[12:13], v[16:17]
	ds_read_b128 v[154:157], v83 offset:16976
	v_sub_f32_e32 v10, v10, v11
	v_mul_f32_e32 v11, v12, v17
	v_mul_f32_e32 v10, v148, v10
	v_fmac_f32_e32 v11, v13, v16
	v_fma_f32 v10, -v149, v11, v10
	v_add_f32_e32 v9, v9, v10
	s_waitcnt lgkmcnt(1)
	v_pk_mul_f32 v[10:11], v[150:151], v[158:159]
	v_mul_f32_e32 v79, v152, v161
	v_sub_f32_e32 v10, v10, v11
	v_mul_f32_e32 v11, v150, v159
	s_waitcnt lgkmcnt(0)
	v_mul_f32_e32 v10, v154, v10
	v_fmac_f32_e32 v11, v151, v158
	v_fma_f32 v10, -v155, v11, v10
	v_add_f32_e32 v9, v9, v10
	v_pk_mul_f32 v[10:11], v[152:153], v[160:161]
	v_fmac_f32_e32 v79, v153, v160
	v_sub_f32_e32 v10, v10, v11
	v_mul_f32_e32 v20, v156, v10
	ds_read_b128 v[10:13], v90 offset:96
	ds_read2_b64 v[14:17], v5 offset1:16
	ds_read_b128 v[146:149], v83 offset:16992
	ds_read_b128 v[150:153], v90 offset:112
	v_fma_f32 v20, -v157, v79, v20
	v_add_f32_e32 v9, v9, v20
	ds_read2_b64 v[158:161], v5 offset0:32 offset1:48
	s_waitcnt lgkmcnt(3)
	v_pk_mul_f32 v[154:155], v[10:11], v[14:15]
	v_mul_f32_e32 v10, v10, v15
	v_sub_f32_e32 v20, v154, v155
	s_waitcnt lgkmcnt(2)
	v_mul_f32_e32 v20, v146, v20
	v_fmac_f32_e32 v10, v11, v14
	v_fma_f32 v10, -v147, v10, v20
	v_add_f32_e32 v9, v9, v10
	v_pk_mul_f32 v[10:11], v[12:13], v[16:17]
	ds_read_b128 v[154:157], v83 offset:17008
	v_sub_f32_e32 v10, v10, v11
	v_mul_f32_e32 v11, v12, v17
	v_mul_f32_e32 v10, v148, v10
	v_fmac_f32_e32 v11, v13, v16
	v_fma_f32 v10, -v149, v11, v10
	v_add_f32_e32 v9, v9, v10
	s_waitcnt lgkmcnt(1)
	v_pk_mul_f32 v[10:11], v[150:151], v[158:159]
	v_mul_f32_e32 v79, v152, v161
	v_sub_f32_e32 v10, v10, v11
	v_mul_f32_e32 v11, v150, v159
	s_waitcnt lgkmcnt(0)
	v_mul_f32_e32 v10, v154, v10
	v_fmac_f32_e32 v11, v151, v158
	v_fma_f32 v10, -v155, v11, v10
	v_add_f32_e32 v9, v9, v10
	v_pk_mul_f32 v[10:11], v[152:153], v[160:161]
	v_fmac_f32_e32 v79, v153, v160
	v_sub_f32_e32 v10, v10, v11
	v_mul_f32_e32 v20, v156, v10
	ds_read_b128 v[10:13], v90 offset:128
	ds_read2_b64 v[14:17], v5 offset0:64 offset1:80
	ds_read_b128 v[146:149], v83 offset:17024
	ds_read_b128 v[150:153], v90 offset:144
	v_fma_f32 v20, -v157, v79, v20
	v_add_f32_e32 v9, v9, v20
	ds_read2_b64 v[158:161], v5 offset0:96 offset1:112
	s_waitcnt lgkmcnt(3)
	v_pk_mul_f32 v[154:155], v[10:11], v[14:15]
	v_mul_f32_e32 v10, v10, v15
	v_sub_f32_e32 v20, v154, v155
	s_waitcnt lgkmcnt(2)
	v_mul_f32_e32 v20, v146, v20
	v_fmac_f32_e32 v10, v11, v14
	v_fma_f32 v10, -v147, v10, v20
	v_add_f32_e32 v9, v9, v10
	v_pk_mul_f32 v[10:11], v[12:13], v[16:17]
	ds_read_b128 v[154:157], v83 offset:17040
	v_sub_f32_e32 v10, v10, v11
	v_mul_f32_e32 v11, v12, v17
	v_mul_f32_e32 v10, v148, v10
	v_fmac_f32_e32 v11, v13, v16
	v_fma_f32 v10, -v149, v11, v10
	v_add_f32_e32 v9, v9, v10
	s_waitcnt lgkmcnt(1)
	v_pk_mul_f32 v[10:11], v[150:151], v[158:159]
	v_mul_f32_e32 v79, v152, v161
	v_sub_f32_e32 v10, v10, v11
	v_mul_f32_e32 v11, v150, v159
	s_waitcnt lgkmcnt(0)
	v_mul_f32_e32 v10, v154, v10
	v_fmac_f32_e32 v11, v151, v158
	v_fma_f32 v10, -v155, v11, v10
	v_add_f32_e32 v9, v9, v10
	v_pk_mul_f32 v[10:11], v[152:153], v[160:161]
	v_fmac_f32_e32 v79, v153, v160
	v_sub_f32_e32 v10, v10, v11
	v_mul_f32_e32 v20, v156, v10
	ds_read_b128 v[10:13], v90 offset:160
	ds_read2_b64 v[14:17], v5 offset0:128 offset1:144
	ds_read_b128 v[146:149], v83 offset:17056
	ds_read_b128 v[150:153], v90 offset:176
	v_fma_f32 v20, -v157, v79, v20
	v_add_f32_e32 v9, v9, v20
	ds_read2_b64 v[158:161], v5 offset0:160 offset1:176
	s_waitcnt lgkmcnt(3)
	v_pk_mul_f32 v[154:155], v[10:11], v[14:15]
	v_mul_f32_e32 v10, v10, v15
	v_sub_f32_e32 v20, v154, v155
	s_waitcnt lgkmcnt(2)
	v_mul_f32_e32 v20, v146, v20
	v_fmac_f32_e32 v10, v11, v14
	v_fma_f32 v10, -v147, v10, v20
	v_add_f32_e32 v9, v9, v10
	v_pk_mul_f32 v[10:11], v[12:13], v[16:17]
	ds_read_b128 v[154:157], v83 offset:17072
	v_sub_f32_e32 v10, v10, v11
	v_mul_f32_e32 v11, v12, v17
	v_mul_f32_e32 v10, v148, v10
	v_fmac_f32_e32 v11, v13, v16
	v_fma_f32 v10, -v149, v11, v10
	v_add_f32_e32 v9, v9, v10
	s_waitcnt lgkmcnt(1)
	v_pk_mul_f32 v[10:11], v[150:151], v[158:159]
	v_mul_f32_e32 v79, v152, v161
	v_sub_f32_e32 v10, v10, v11
	v_mul_f32_e32 v11, v150, v159
	s_waitcnt lgkmcnt(0)
	v_mul_f32_e32 v10, v154, v10
	v_fmac_f32_e32 v11, v151, v158
	v_fma_f32 v10, -v155, v11, v10
	v_add_f32_e32 v9, v9, v10
	v_pk_mul_f32 v[10:11], v[152:153], v[160:161]
	v_fmac_f32_e32 v79, v153, v160
	v_sub_f32_e32 v10, v10, v11
	v_mul_f32_e32 v20, v156, v10
	ds_read_b128 v[10:13], v90 offset:192
	ds_read2_b64 v[14:17], v5 offset0:192 offset1:208
	ds_read_b128 v[146:149], v83 offset:17088
	ds_read_b128 v[150:153], v90 offset:208
	v_fma_f32 v20, -v157, v79, v20
	v_add_f32_e32 v9, v9, v20
	ds_read2_b64 v[158:161], v5 offset0:224 offset1:240
	s_waitcnt lgkmcnt(3)
	v_pk_mul_f32 v[154:155], v[10:11], v[14:15]
	v_mul_f32_e32 v10, v10, v15
	v_sub_f32_e32 v20, v154, v155
	s_waitcnt lgkmcnt(2)
	v_mul_f32_e32 v20, v146, v20
	v_fmac_f32_e32 v10, v11, v14
	v_fma_f32 v10, -v147, v10, v20
	v_add_f32_e32 v9, v9, v10
	v_pk_mul_f32 v[10:11], v[12:13], v[16:17]
	ds_read_b128 v[154:157], v83 offset:17104
	v_sub_f32_e32 v10, v10, v11
	v_mul_f32_e32 v11, v12, v17
	v_mul_f32_e32 v10, v148, v10
	v_fmac_f32_e32 v11, v13, v16
	v_fma_f32 v10, -v149, v11, v10
	v_add_f32_e32 v9, v9, v10
	s_waitcnt lgkmcnt(1)
	v_pk_mul_f32 v[10:11], v[150:151], v[158:159]
	v_mul_f32_e32 v79, v152, v161
	v_sub_f32_e32 v10, v10, v11
	v_mul_f32_e32 v11, v150, v159
	s_waitcnt lgkmcnt(0)
	v_mul_f32_e32 v10, v154, v10
	v_fmac_f32_e32 v11, v151, v158
	v_fma_f32 v10, -v155, v11, v10
	v_add_f32_e32 v9, v9, v10
	v_pk_mul_f32 v[10:11], v[152:153], v[160:161]
	v_fmac_f32_e32 v79, v153, v160
	v_sub_f32_e32 v10, v10, v11
	v_mul_f32_e32 v20, v156, v10
	ds_read_b128 v[10:13], v90 offset:224
	ds_read2_b64 v[14:17], v6 offset1:16
	ds_read_b128 v[146:149], v83 offset:17120
	ds_read_b128 v[150:153], v90 offset:240
	v_fma_f32 v20, -v157, v79, v20
	v_add_f32_e32 v9, v9, v20
	ds_read2_b64 v[158:161], v6 offset0:32 offset1:48
	s_waitcnt lgkmcnt(3)
	v_pk_mul_f32 v[154:155], v[10:11], v[14:15]
	v_mul_f32_e32 v10, v10, v15
	v_sub_f32_e32 v20, v154, v155
	s_waitcnt lgkmcnt(2)
	v_mul_f32_e32 v20, v146, v20
	v_fmac_f32_e32 v10, v11, v14
	v_fma_f32 v10, -v147, v10, v20
	v_add_f32_e32 v9, v9, v10
	v_pk_mul_f32 v[10:11], v[12:13], v[16:17]
	ds_read_b128 v[154:157], v83 offset:17136
	v_sub_f32_e32 v10, v10, v11
	v_mul_f32_e32 v11, v12, v17
	v_mul_f32_e32 v10, v148, v10
	v_fmac_f32_e32 v11, v13, v16
	v_fma_f32 v10, -v149, v11, v10
	v_add_f32_e32 v9, v9, v10
	s_waitcnt lgkmcnt(1)
	v_pk_mul_f32 v[10:11], v[150:151], v[158:159]
	v_mul_f32_e32 v79, v152, v161
	v_sub_f32_e32 v10, v10, v11
	v_mul_f32_e32 v11, v150, v159
	s_waitcnt lgkmcnt(0)
	v_mul_f32_e32 v10, v154, v10
	v_fmac_f32_e32 v11, v151, v158
	v_fma_f32 v10, -v155, v11, v10
	v_add_f32_e32 v9, v9, v10
	v_pk_mul_f32 v[10:11], v[152:153], v[160:161]
	v_fmac_f32_e32 v79, v153, v160
	v_sub_f32_e32 v10, v10, v11
	v_mul_f32_e32 v20, v156, v10
	ds_read_b128 v[10:13], v90 offset:256
	ds_read2_b64 v[14:17], v6 offset0:64 offset1:80
	ds_read_b128 v[146:149], v83 offset:17152
	ds_read_b128 v[150:153], v90 offset:272
	v_fma_f32 v20, -v157, v79, v20
	v_add_f32_e32 v9, v9, v20
	ds_read2_b64 v[158:161], v6 offset0:96 offset1:112
	s_waitcnt lgkmcnt(3)
	v_pk_mul_f32 v[154:155], v[10:11], v[14:15]
	v_mul_f32_e32 v10, v10, v15
	v_sub_f32_e32 v20, v154, v155
	s_waitcnt lgkmcnt(2)
	v_mul_f32_e32 v20, v146, v20
	v_fmac_f32_e32 v10, v11, v14
	v_fma_f32 v10, -v147, v10, v20
	v_add_f32_e32 v9, v9, v10
	v_pk_mul_f32 v[10:11], v[12:13], v[16:17]
	ds_read_b128 v[154:157], v83 offset:17168
	v_sub_f32_e32 v10, v10, v11
	v_mul_f32_e32 v11, v12, v17
	v_mul_f32_e32 v10, v148, v10
	v_fmac_f32_e32 v11, v13, v16
	v_fma_f32 v10, -v149, v11, v10
	v_add_f32_e32 v9, v9, v10
	s_waitcnt lgkmcnt(1)
	v_pk_mul_f32 v[10:11], v[150:151], v[158:159]
	v_mul_f32_e32 v79, v152, v161
	v_sub_f32_e32 v10, v10, v11
	v_mul_f32_e32 v11, v150, v159
	s_waitcnt lgkmcnt(0)
	v_mul_f32_e32 v10, v154, v10
	v_fmac_f32_e32 v11, v151, v158
	v_fma_f32 v10, -v155, v11, v10
	v_add_f32_e32 v9, v9, v10
	v_pk_mul_f32 v[10:11], v[152:153], v[160:161]
	v_fmac_f32_e32 v79, v153, v160
	v_sub_f32_e32 v10, v10, v11
	v_mul_f32_e32 v20, v156, v10
	ds_read_b128 v[10:13], v90 offset:288
	ds_read2_b64 v[14:17], v6 offset0:128 offset1:144
	ds_read_b128 v[146:149], v83 offset:17184
	ds_read_b128 v[150:153], v90 offset:304
	v_fma_f32 v20, -v157, v79, v20
	v_add_f32_e32 v9, v9, v20
	ds_read2_b64 v[158:161], v6 offset0:160 offset1:176
	s_waitcnt lgkmcnt(3)
	v_pk_mul_f32 v[154:155], v[10:11], v[14:15]
	v_mul_f32_e32 v10, v10, v15
	v_sub_f32_e32 v20, v154, v155
	s_waitcnt lgkmcnt(2)
	v_mul_f32_e32 v20, v146, v20
	v_fmac_f32_e32 v10, v11, v14
	v_fma_f32 v10, -v147, v10, v20
	v_add_f32_e32 v9, v9, v10
	v_pk_mul_f32 v[10:11], v[12:13], v[16:17]
	ds_read_b128 v[154:157], v83 offset:17200
	v_sub_f32_e32 v10, v10, v11
	v_mul_f32_e32 v11, v12, v17
	v_mul_f32_e32 v10, v148, v10
	v_fmac_f32_e32 v11, v13, v16
	v_fma_f32 v10, -v149, v11, v10
	v_add_f32_e32 v9, v9, v10
	s_waitcnt lgkmcnt(1)
	v_pk_mul_f32 v[10:11], v[150:151], v[158:159]
	v_mul_f32_e32 v79, v152, v161
	v_sub_f32_e32 v10, v10, v11
	v_mul_f32_e32 v11, v150, v159
	s_waitcnt lgkmcnt(0)
	v_mul_f32_e32 v10, v154, v10
	v_fmac_f32_e32 v11, v151, v158
	v_fma_f32 v10, -v155, v11, v10
	v_add_f32_e32 v9, v9, v10
	v_pk_mul_f32 v[10:11], v[152:153], v[160:161]
	v_fmac_f32_e32 v79, v153, v160
	v_sub_f32_e32 v10, v10, v11
	v_mul_f32_e32 v20, v156, v10
	ds_read_b128 v[10:13], v90 offset:320
	ds_read2_b64 v[14:17], v6 offset0:192 offset1:208
	ds_read_b128 v[146:149], v83 offset:17216
	ds_read_b128 v[150:153], v90 offset:336
	v_fma_f32 v20, -v157, v79, v20
	v_add_f32_e32 v9, v9, v20
	ds_read2_b64 v[158:161], v6 offset0:224 offset1:240
	s_waitcnt lgkmcnt(3)
	v_pk_mul_f32 v[154:155], v[10:11], v[14:15]
	v_mul_f32_e32 v10, v10, v15
	v_sub_f32_e32 v20, v154, v155
	s_waitcnt lgkmcnt(2)
	v_mul_f32_e32 v20, v146, v20
	v_fmac_f32_e32 v10, v11, v14
	v_fma_f32 v10, -v147, v10, v20
	v_add_f32_e32 v9, v9, v10
	v_pk_mul_f32 v[10:11], v[12:13], v[16:17]
	ds_read_b128 v[154:157], v83 offset:17232
	v_sub_f32_e32 v10, v10, v11
	v_mul_f32_e32 v11, v12, v17
	v_mul_f32_e32 v10, v148, v10
	v_fmac_f32_e32 v11, v13, v16
	v_fma_f32 v10, -v149, v11, v10
	v_add_f32_e32 v9, v9, v10
	s_waitcnt lgkmcnt(1)
	v_pk_mul_f32 v[10:11], v[150:151], v[158:159]
	v_mul_f32_e32 v79, v152, v161
	v_sub_f32_e32 v10, v10, v11
	v_mul_f32_e32 v11, v150, v159
	s_waitcnt lgkmcnt(0)
	v_mul_f32_e32 v10, v154, v10
	v_fmac_f32_e32 v11, v151, v158
	v_fma_f32 v10, -v155, v11, v10
	v_add_f32_e32 v9, v9, v10
	v_pk_mul_f32 v[10:11], v[152:153], v[160:161]
	v_fmac_f32_e32 v79, v153, v160
	v_sub_f32_e32 v10, v10, v11
	v_mul_f32_e32 v20, v156, v10
	ds_read_b128 v[10:13], v90 offset:352
	ds_read2_b64 v[14:17], v4 offset1:16
	ds_read_b128 v[146:149], v83 offset:17248
	ds_read_b128 v[150:153], v90 offset:368
	v_fma_f32 v20, -v157, v79, v20
	v_add_f32_e32 v9, v9, v20
	ds_read2_b64 v[158:161], v4 offset0:32 offset1:48
	s_waitcnt lgkmcnt(3)
	v_pk_mul_f32 v[154:155], v[10:11], v[14:15]
	v_mul_f32_e32 v10, v10, v15
	v_sub_f32_e32 v20, v154, v155
	s_waitcnt lgkmcnt(2)
	v_mul_f32_e32 v20, v146, v20
	v_fmac_f32_e32 v10, v11, v14
	v_fma_f32 v10, -v147, v10, v20
	v_add_f32_e32 v9, v9, v10
	v_pk_mul_f32 v[10:11], v[12:13], v[16:17]
	ds_read_b128 v[154:157], v83 offset:17264
	v_sub_f32_e32 v10, v10, v11
	v_mul_f32_e32 v11, v12, v17
	v_mul_f32_e32 v10, v148, v10
	v_fmac_f32_e32 v11, v13, v16
	v_fma_f32 v10, -v149, v11, v10
	v_add_f32_e32 v9, v9, v10
	s_waitcnt lgkmcnt(1)
	v_pk_mul_f32 v[10:11], v[150:151], v[158:159]
	v_mul_f32_e32 v79, v152, v161
	v_sub_f32_e32 v10, v10, v11
	v_mul_f32_e32 v11, v150, v159
	s_waitcnt lgkmcnt(0)
	v_mul_f32_e32 v10, v154, v10
	v_fmac_f32_e32 v11, v151, v158
	v_fma_f32 v10, -v155, v11, v10
	v_add_f32_e32 v9, v9, v10
	v_pk_mul_f32 v[10:11], v[152:153], v[160:161]
	v_fmac_f32_e32 v79, v153, v160
	v_sub_f32_e32 v10, v10, v11
	v_mul_f32_e32 v20, v156, v10
	ds_read_b128 v[10:13], v90 offset:384
	ds_read2_b64 v[14:17], v4 offset0:64 offset1:80
	ds_read_b128 v[146:149], v83 offset:17280
	ds_read_b128 v[150:153], v90 offset:400
	v_fma_f32 v20, -v157, v79, v20
	v_add_f32_e32 v9, v9, v20
	ds_read2_b64 v[158:161], v4 offset0:96 offset1:112
	s_waitcnt lgkmcnt(3)
	v_pk_mul_f32 v[154:155], v[10:11], v[14:15]
	v_mul_f32_e32 v10, v10, v15
	v_sub_f32_e32 v20, v154, v155
	s_waitcnt lgkmcnt(2)
	v_mul_f32_e32 v20, v146, v20
	v_fmac_f32_e32 v10, v11, v14
	v_fma_f32 v10, -v147, v10, v20
	v_add_f32_e32 v9, v9, v10
	v_pk_mul_f32 v[10:11], v[12:13], v[16:17]
	ds_read_b128 v[154:157], v83 offset:17296
	v_sub_f32_e32 v10, v10, v11
	v_mul_f32_e32 v11, v12, v17
	v_mul_f32_e32 v10, v148, v10
	v_fmac_f32_e32 v11, v13, v16
	v_fma_f32 v10, -v149, v11, v10
	v_add_f32_e32 v9, v9, v10
	s_waitcnt lgkmcnt(1)
	v_pk_mul_f32 v[10:11], v[150:151], v[158:159]
	s_nop 0
	v_sub_f32_e32 v10, v10, v11
	v_mul_f32_e32 v11, v150, v159
	s_waitcnt lgkmcnt(0)
	v_mul_f32_e32 v10, v154, v10
	v_fmac_f32_e32 v11, v151, v158
	v_fma_f32 v10, -v155, v11, v10
	v_add_f32_e32 v9, v9, v10
	v_pk_mul_f32 v[10:11], v[152:153], v[160:161]
	s_nop 0
	v_sub_f32_e32 v10, v10, v11
	v_mul_f32_e32 v11, v152, v161
	v_mul_f32_e32 v10, v156, v10
	v_fmac_f32_e32 v11, v153, v160
	v_fma_f32 v14, -v157, v11, v10
	ds_read_b128 v[10:13], v90 offset:416
	v_add_f32_e32 v9, v9, v14
	ds_read2_b64 v[14:17], v4 offset0:128 offset1:144
	ds_read_b128 v[146:149], v83 offset:17312
	ds_read_b128 v[150:153], v90 offset:432
	s_waitcnt lgkmcnt(3)
	v_mov_b32_e32 v155, v12
	s_waitcnt lgkmcnt(2)
	v_mov_b32_e32 v157, v16
	v_mov_b32_e32 v12, v11
	v_mov_b32_e32 v16, v15
	v_mov_b32_e32 v154, v10
	v_mov_b32_e32 v156, v14
	v_pk_mul_f32 v[10:11], v[12:13], v[16:17]
	s_nop 0
	v_pk_fma_f32 v[14:15], v[154:155], v[156:157], v[10:11] neg_lo:[0,0,1] neg_hi:[0,0,1]
	v_pk_mul_f32 v[10:11], v[12:13], v[156:157]
	s_nop 0
	v_pk_fma_f32 v[16:17], v[154:155], v[16:17], v[10:11]
	s_waitcnt lgkmcnt(1)
	v_mov_b32_e32 v155, v148
	v_mov_b32_e32 v148, v147
	v_mov_b32_e32 v154, v146
	v_pk_mul_f32 v[16:17], v[148:149], v[16:17]
	ds_read_b128 v[10:13], v83 offset:17328
	v_pk_fma_f32 v[146:147], v[154:155], v[14:15], v[16:17] neg_lo:[0,0,1] neg_hi:[0,0,1]
	ds_read2_b64 v[14:17], v4 offset0:160 offset1:176
	v_add_f32_e32 v9, v9, v146
	v_add_f32_e32 v9, v9, v147
	s_waitcnt lgkmcnt(2)
	v_mov_b32_e32 v147, v152
	v_mov_b32_e32 v152, v151
	s_waitcnt lgkmcnt(0)
	v_mov_b32_e32 v149, v16
	v_mov_b32_e32 v16, v15
	v_mov_b32_e32 v146, v150
	v_mov_b32_e32 v148, v14
	v_pk_mul_f32 v[14:15], v[152:153], v[16:17]
	s_nop 0
	v_pk_fma_f32 v[14:15], v[146:147], v[148:149], v[14:15] neg_lo:[0,0,1] neg_hi:[0,0,1]
	v_pk_mul_f32 v[148:149], v[152:153], v[148:149]
	s_nop 0
	v_pk_fma_f32 v[16:17], v[146:147], v[16:17], v[148:149]
	v_mov_b32_e32 v147, v12
	v_mov_b32_e32 v12, v11
	v_mov_b32_e32 v146, v10
	v_pk_mul_f32 v[10:11], v[12:13], v[16:17]
	s_nop 0
	v_pk_fma_f32 v[14:15], v[146:147], v[14:15], v[10:11] neg_lo:[0,0,1] neg_hi:[0,0,1]
	ds_read_b128 v[10:13], v90 offset:448
	v_add_f32_e32 v9, v9, v14
	v_add_f32_e32 v9, v9, v15
	ds_read2_b64 v[14:17], v4 offset0:192 offset1:208
	ds_read_b128 v[146:149], v83 offset:17344
	ds_read_b128 v[150:153], v90 offset:464
	s_waitcnt lgkmcnt(3)
	v_mov_b32_e32 v155, v12
	s_waitcnt lgkmcnt(2)
	v_mov_b32_e32 v157, v16
	v_mov_b32_e32 v12, v11
	v_mov_b32_e32 v16, v15
	v_mov_b32_e32 v154, v10
	v_mov_b32_e32 v156, v14
	v_pk_mul_f32 v[10:11], v[12:13], v[16:17]
	s_nop 0
	v_pk_fma_f32 v[14:15], v[154:155], v[156:157], v[10:11] neg_lo:[0,0,1] neg_hi:[0,0,1]
	v_pk_mul_f32 v[10:11], v[12:13], v[156:157]
	s_nop 0
	v_pk_fma_f32 v[16:17], v[154:155], v[16:17], v[10:11]
	s_waitcnt lgkmcnt(1)
	v_mov_b32_e32 v155, v148
	v_mov_b32_e32 v148, v147
	v_mov_b32_e32 v154, v146
	v_pk_mul_f32 v[16:17], v[148:149], v[16:17]
	ds_read_b128 v[10:13], v83 offset:17360
	v_pk_fma_f32 v[146:147], v[154:155], v[14:15], v[16:17] neg_lo:[0,0,1] neg_hi:[0,0,1]
	ds_read2_b64 v[14:17], v4 offset0:224 offset1:240
	v_add_f32_e32 v9, v9, v146
	v_add_f32_e32 v9, v9, v147
	s_waitcnt lgkmcnt(2)
	v_mov_b32_e32 v147, v152
	v_mov_b32_e32 v152, v151
	s_waitcnt lgkmcnt(0)
	v_mov_b32_e32 v149, v16
	v_mov_b32_e32 v16, v15
	v_mov_b32_e32 v146, v150
	v_mov_b32_e32 v148, v14
	v_pk_mul_f32 v[14:15], v[152:153], v[16:17]
	s_nop 0
	v_pk_fma_f32 v[14:15], v[146:147], v[148:149], v[14:15] neg_lo:[0,0,1] neg_hi:[0,0,1]
	v_pk_mul_f32 v[148:149], v[152:153], v[148:149]
	s_nop 0
	v_pk_fma_f32 v[16:17], v[146:147], v[16:17], v[148:149]
	v_mov_b32_e32 v147, v12
	v_mov_b32_e32 v12, v11
	v_mov_b32_e32 v146, v10
	v_pk_mul_f32 v[10:11], v[12:13], v[16:17]
	s_nop 0
	v_pk_fma_f32 v[14:15], v[146:147], v[14:15], v[10:11] neg_lo:[0,0,1] neg_hi:[0,0,1]
	ds_read_b128 v[10:13], v90 offset:480
	v_add_f32_e32 v9, v9, v14
	v_add_f32_e32 v9, v9, v15
	ds_read2_b64 v[14:17], v8 offset1:16
	ds_read_b128 v[146:149], v83 offset:17376
	ds_read_b128 v[150:153], v90 offset:496
	s_waitcnt lgkmcnt(3)
	v_mov_b32_e32 v155, v12
	s_waitcnt lgkmcnt(2)
	v_mov_b32_e32 v157, v16
	v_mov_b32_e32 v12, v11
	v_mov_b32_e32 v16, v15
	v_mov_b32_e32 v154, v10
	v_mov_b32_e32 v156, v14
	v_pk_mul_f32 v[10:11], v[12:13], v[16:17]
	s_nop 0
	v_pk_fma_f32 v[14:15], v[154:155], v[156:157], v[10:11] neg_lo:[0,0,1] neg_hi:[0,0,1]
	v_pk_mul_f32 v[10:11], v[12:13], v[156:157]
	s_nop 0
	v_pk_fma_f32 v[16:17], v[154:155], v[16:17], v[10:11]
	s_waitcnt lgkmcnt(1)
	v_mov_b32_e32 v155, v148
	v_mov_b32_e32 v148, v147
	v_mov_b32_e32 v154, v146
	v_pk_mul_f32 v[16:17], v[148:149], v[16:17]
	ds_read_b128 v[10:13], v83 offset:17392
	v_pk_fma_f32 v[146:147], v[154:155], v[14:15], v[16:17] neg_lo:[0,0,1] neg_hi:[0,0,1]
	ds_read2_b64 v[14:17], v8 offset0:32 offset1:48
	v_add_f32_e32 v9, v9, v146
	v_add_f32_e32 v9, v9, v147
	s_waitcnt lgkmcnt(2)
	v_mov_b32_e32 v147, v152
	v_mov_b32_e32 v152, v151
	s_waitcnt lgkmcnt(0)
	v_mov_b32_e32 v149, v16
	v_mov_b32_e32 v16, v15
	v_mov_b32_e32 v146, v150
	v_mov_b32_e32 v148, v14
	v_pk_mul_f32 v[14:15], v[152:153], v[16:17]
	s_nop 0
	v_pk_fma_f32 v[14:15], v[146:147], v[148:149], v[14:15] neg_lo:[0,0,1] neg_hi:[0,0,1]
	v_pk_mul_f32 v[148:149], v[152:153], v[148:149]
	s_nop 0
	v_pk_fma_f32 v[16:17], v[146:147], v[16:17], v[148:149]
	v_mov_b32_e32 v147, v12
	v_mov_b32_e32 v12, v11
	v_mov_b32_e32 v146, v10
	v_pk_mul_f32 v[10:11], v[12:13], v[16:17]
	s_nop 0
	v_pk_fma_f32 v[10:11], v[146:147], v[14:15], v[10:11] neg_lo:[0,0,1] neg_hi:[0,0,1]
	s_nop 0
	v_add_f32_e32 v9, v9, v10
	v_add_f32_e32 v9, v9, v11
	s_and_saveexec_b64 s[68:69], s[94:95]
	s_cbranch_execz .LBB0_87
	global_load_dword v10, v[2:3], off nt
	s_waitcnt vmcnt(0)
	v_add_f32_e32 v9, v9, v10
.LBB0_87:
	s_or_b64 exec, exec, s[68:69]
	ds_write_b32 v116, v9 offset:29184
	ds_read_b128 v[10:13], v93
	ds_read_b128 v[14:17], v93 offset:16
	ds_read_b128 v[146:149], v93 offset:32
	ds_read_b128 v[150:153], v93 offset:48
	ds_read2_b64 v[154:157], v7 offset0:64 offset1:80
	ds_read_b128 v[158:161], v83 offset:16896
	ds_read_b128 v[162:165], v83 offset:16912
	ds_read_b128 v[166:169], v83 offset:16928
	ds_read_b128 v[174:177], v83 offset:16944
	s_waitcnt lgkmcnt(4)
	v_pk_mul_f32 v[170:171], v[10:11], v[154:155]
	v_mul_f32_e32 v10, v10, v155
	v_sub_f32_e32 v9, v170, v171
	s_waitcnt lgkmcnt(3)
	v_mul_f32_e32 v9, v158, v9
	v_fmac_f32_e32 v10, v11, v154
	ds_read2_b64 v[178:181], v7 offset0:96 offset1:112
	v_fma_f32 v9, -v159, v10, v9
	v_pk_mul_f32 v[10:11], v[12:13], v[156:157]
	v_add_f32_e32 v9, 0, v9
	v_sub_f32_e32 v10, v10, v11
	v_mul_f32_e32 v11, v12, v157
	v_mul_f32_e32 v10, v160, v10
	v_fmac_f32_e32 v11, v13, v156
	v_fma_f32 v10, -v161, v11, v10
	v_add_f32_e32 v9, v9, v10
	s_waitcnt lgkmcnt(0)
	v_pk_mul_f32 v[10:11], v[14:15], v[178:179]
	s_nop 0
	v_sub_f32_e32 v10, v10, v11
	v_mul_f32_e32 v11, v14, v179
	v_mul_f32_e32 v10, v162, v10
	v_fmac_f32_e32 v11, v15, v178
	v_fma_f32 v10, -v163, v11, v10
	v_add_f32_e32 v9, v9, v10
	v_pk_mul_f32 v[10:11], v[16:17], v[180:181]
	v_mul_f32_e32 v15, v16, v181
	v_sub_f32_e32 v10, v10, v11
	v_mul_f32_e32 v14, v164, v10
	ds_read2_b64 v[10:13], v7 offset0:128 offset1:144
	v_fmac_f32_e32 v15, v17, v180
	v_fma_f32 v14, -v165, v15, v14
	v_add_f32_e32 v9, v9, v14
	s_waitcnt lgkmcnt(0)
	v_pk_mul_f32 v[14:15], v[146:147], v[10:11]
	s_nop 0
	v_sub_f32_e32 v14, v14, v15
	v_mul_f32_e32 v11, v146, v11
	v_mul_f32_e32 v14, v166, v14
	v_fmac_f32_e32 v11, v147, v10
	v_fma_f32 v10, -v167, v11, v14
	ds_read2_b64 v[14:17], v7 offset0:160 offset1:176
	v_add_f32_e32 v9, v9, v10
	v_pk_mul_f32 v[10:11], v[148:149], v[12:13]
	s_waitcnt lgkmcnt(0)
	v_mul_f32_e32 v79, v152, v17
	v_sub_f32_e32 v10, v10, v11
	v_mul_f32_e32 v11, v148, v13
	v_mul_f32_e32 v10, v168, v10
	v_fmac_f32_e32 v11, v149, v12
	v_fma_f32 v10, -v169, v11, v10
	v_add_f32_e32 v9, v9, v10
	v_pk_mul_f32 v[10:11], v[150:151], v[14:15]
	v_fmac_f32_e32 v79, v153, v16
	v_sub_f32_e32 v10, v10, v11
	v_mul_f32_e32 v11, v150, v15
	v_mul_f32_e32 v10, v174, v10
	v_fmac_f32_e32 v11, v151, v14
	v_fma_f32 v10, -v175, v11, v10
	v_add_f32_e32 v9, v9, v10
	v_pk_mul_f32 v[10:11], v[152:153], v[16:17]
	s_nop 0
	v_sub_f32_e32 v10, v10, v11
	v_mul_f32_e32 v20, v176, v10
	ds_read_b128 v[10:13], v93 offset:64
	ds_read2_b64 v[14:17], v7 offset0:192 offset1:208
	ds_read_b128 v[146:149], v83 offset:16960
	ds_read_b128 v[150:153], v93 offset:80
	v_fma_f32 v20, -v177, v79, v20
	v_add_f32_e32 v9, v9, v20
	ds_read2_b64 v[158:161], v7 offset0:224 offset1:240
	s_waitcnt lgkmcnt(3)
	v_pk_mul_f32 v[154:155], v[10:11], v[14:15]
	v_mul_f32_e32 v10, v10, v15
	v_sub_f32_e32 v20, v154, v155
	s_waitcnt lgkmcnt(2)
	v_mul_f32_e32 v20, v146, v20
	v_fmac_f32_e32 v10, v11, v14
	v_fma_f32 v10, -v147, v10, v20
	v_add_f32_e32 v9, v9, v10
	v_pk_mul_f32 v[10:11], v[12:13], v[16:17]
	ds_read_b128 v[154:157], v83 offset:16976
	v_sub_f32_e32 v10, v10, v11
	v_mul_f32_e32 v11, v12, v17
	v_mul_f32_e32 v10, v148, v10
	v_fmac_f32_e32 v11, v13, v16
	v_fma_f32 v10, -v149, v11, v10
	v_add_f32_e32 v9, v9, v10
	s_waitcnt lgkmcnt(1)
	v_pk_mul_f32 v[10:11], v[150:151], v[158:159]
	v_mul_f32_e32 v79, v152, v161
	v_sub_f32_e32 v10, v10, v11
	v_mul_f32_e32 v11, v150, v159
	s_waitcnt lgkmcnt(0)
	v_mul_f32_e32 v10, v154, v10
	v_fmac_f32_e32 v11, v151, v158
	v_fma_f32 v10, -v155, v11, v10
	v_add_f32_e32 v9, v9, v10
	v_pk_mul_f32 v[10:11], v[152:153], v[160:161]
	v_fmac_f32_e32 v79, v153, v160
	v_sub_f32_e32 v10, v10, v11
	v_mul_f32_e32 v20, v156, v10
	ds_read_b128 v[10:13], v93 offset:96
	ds_read2_b64 v[14:17], v5 offset1:16
	ds_read_b128 v[146:149], v83 offset:16992
	ds_read_b128 v[150:153], v93 offset:112
	v_fma_f32 v20, -v157, v79, v20
	v_add_f32_e32 v9, v9, v20
	ds_read2_b64 v[158:161], v5 offset0:32 offset1:48
	s_waitcnt lgkmcnt(3)
	v_pk_mul_f32 v[154:155], v[10:11], v[14:15]
	v_mul_f32_e32 v10, v10, v15
	v_sub_f32_e32 v20, v154, v155
	s_waitcnt lgkmcnt(2)
	v_mul_f32_e32 v20, v146, v20
	v_fmac_f32_e32 v10, v11, v14
	v_fma_f32 v10, -v147, v10, v20
	v_add_f32_e32 v9, v9, v10
	v_pk_mul_f32 v[10:11], v[12:13], v[16:17]
	ds_read_b128 v[154:157], v83 offset:17008
	v_sub_f32_e32 v10, v10, v11
	v_mul_f32_e32 v11, v12, v17
	v_mul_f32_e32 v10, v148, v10
	v_fmac_f32_e32 v11, v13, v16
	v_fma_f32 v10, -v149, v11, v10
	v_add_f32_e32 v9, v9, v10
	s_waitcnt lgkmcnt(1)
	v_pk_mul_f32 v[10:11], v[150:151], v[158:159]
	v_mul_f32_e32 v79, v152, v161
	v_sub_f32_e32 v10, v10, v11
	v_mul_f32_e32 v11, v150, v159
	s_waitcnt lgkmcnt(0)
	v_mul_f32_e32 v10, v154, v10
	v_fmac_f32_e32 v11, v151, v158
	v_fma_f32 v10, -v155, v11, v10
	v_add_f32_e32 v9, v9, v10
	v_pk_mul_f32 v[10:11], v[152:153], v[160:161]
	v_fmac_f32_e32 v79, v153, v160
	v_sub_f32_e32 v10, v10, v11
	v_mul_f32_e32 v20, v156, v10
	ds_read_b128 v[10:13], v93 offset:128
	ds_read2_b64 v[14:17], v5 offset0:64 offset1:80
	ds_read_b128 v[146:149], v83 offset:17024
	ds_read_b128 v[150:153], v93 offset:144
	v_fma_f32 v20, -v157, v79, v20
	v_add_f32_e32 v9, v9, v20
	ds_read2_b64 v[158:161], v5 offset0:96 offset1:112
	s_waitcnt lgkmcnt(3)
	v_pk_mul_f32 v[154:155], v[10:11], v[14:15]
	v_mul_f32_e32 v10, v10, v15
	v_sub_f32_e32 v20, v154, v155
	s_waitcnt lgkmcnt(2)
	v_mul_f32_e32 v20, v146, v20
	v_fmac_f32_e32 v10, v11, v14
	v_fma_f32 v10, -v147, v10, v20
	v_add_f32_e32 v9, v9, v10
	v_pk_mul_f32 v[10:11], v[12:13], v[16:17]
	ds_read_b128 v[154:157], v83 offset:17040
	v_sub_f32_e32 v10, v10, v11
	v_mul_f32_e32 v11, v12, v17
	v_mul_f32_e32 v10, v148, v10
	v_fmac_f32_e32 v11, v13, v16
	v_fma_f32 v10, -v149, v11, v10
	v_add_f32_e32 v9, v9, v10
	s_waitcnt lgkmcnt(1)
	v_pk_mul_f32 v[10:11], v[150:151], v[158:159]
	v_mul_f32_e32 v79, v152, v161
	v_sub_f32_e32 v10, v10, v11
	v_mul_f32_e32 v11, v150, v159
	s_waitcnt lgkmcnt(0)
	v_mul_f32_e32 v10, v154, v10
	v_fmac_f32_e32 v11, v151, v158
	v_fma_f32 v10, -v155, v11, v10
	v_add_f32_e32 v9, v9, v10
	v_pk_mul_f32 v[10:11], v[152:153], v[160:161]
	v_fmac_f32_e32 v79, v153, v160
	v_sub_f32_e32 v10, v10, v11
	v_mul_f32_e32 v20, v156, v10
	ds_read_b128 v[10:13], v93 offset:160
	ds_read2_b64 v[14:17], v5 offset0:128 offset1:144
	ds_read_b128 v[146:149], v83 offset:17056
	ds_read_b128 v[150:153], v93 offset:176
	v_fma_f32 v20, -v157, v79, v20
	v_add_f32_e32 v9, v9, v20
	ds_read2_b64 v[158:161], v5 offset0:160 offset1:176
	s_waitcnt lgkmcnt(3)
	v_pk_mul_f32 v[154:155], v[10:11], v[14:15]
	v_mul_f32_e32 v10, v10, v15
	v_sub_f32_e32 v20, v154, v155
	s_waitcnt lgkmcnt(2)
	v_mul_f32_e32 v20, v146, v20
	v_fmac_f32_e32 v10, v11, v14
	v_fma_f32 v10, -v147, v10, v20
	v_add_f32_e32 v9, v9, v10
	v_pk_mul_f32 v[10:11], v[12:13], v[16:17]
	ds_read_b128 v[154:157], v83 offset:17072
	v_sub_f32_e32 v10, v10, v11
	v_mul_f32_e32 v11, v12, v17
	v_mul_f32_e32 v10, v148, v10
	v_fmac_f32_e32 v11, v13, v16
	v_fma_f32 v10, -v149, v11, v10
	v_add_f32_e32 v9, v9, v10
	s_waitcnt lgkmcnt(1)
	v_pk_mul_f32 v[10:11], v[150:151], v[158:159]
	v_mul_f32_e32 v79, v152, v161
	v_sub_f32_e32 v10, v10, v11
	v_mul_f32_e32 v11, v150, v159
	s_waitcnt lgkmcnt(0)
	v_mul_f32_e32 v10, v154, v10
	v_fmac_f32_e32 v11, v151, v158
	v_fma_f32 v10, -v155, v11, v10
	v_add_f32_e32 v9, v9, v10
	v_pk_mul_f32 v[10:11], v[152:153], v[160:161]
	v_fmac_f32_e32 v79, v153, v160
	v_sub_f32_e32 v10, v10, v11
	v_mul_f32_e32 v20, v156, v10
	ds_read_b128 v[10:13], v93 offset:192
	ds_read2_b64 v[14:17], v5 offset0:192 offset1:208
	ds_read_b128 v[146:149], v83 offset:17088
	ds_read_b128 v[150:153], v93 offset:208
	v_fma_f32 v20, -v157, v79, v20
	v_add_f32_e32 v9, v9, v20
	ds_read2_b64 v[158:161], v5 offset0:224 offset1:240
	s_waitcnt lgkmcnt(3)
	v_pk_mul_f32 v[154:155], v[10:11], v[14:15]
	v_mul_f32_e32 v10, v10, v15
	v_sub_f32_e32 v20, v154, v155
	s_waitcnt lgkmcnt(2)
	v_mul_f32_e32 v20, v146, v20
	v_fmac_f32_e32 v10, v11, v14
	v_fma_f32 v10, -v147, v10, v20
	v_add_f32_e32 v9, v9, v10
	v_pk_mul_f32 v[10:11], v[12:13], v[16:17]
	ds_read_b128 v[154:157], v83 offset:17104
	v_sub_f32_e32 v10, v10, v11
	v_mul_f32_e32 v11, v12, v17
	v_mul_f32_e32 v10, v148, v10
	v_fmac_f32_e32 v11, v13, v16
	v_fma_f32 v10, -v149, v11, v10
	v_add_f32_e32 v9, v9, v10
	s_waitcnt lgkmcnt(1)
	v_pk_mul_f32 v[10:11], v[150:151], v[158:159]
	v_mul_f32_e32 v79, v152, v161
	v_sub_f32_e32 v10, v10, v11
	v_mul_f32_e32 v11, v150, v159
	s_waitcnt lgkmcnt(0)
	v_mul_f32_e32 v10, v154, v10
	v_fmac_f32_e32 v11, v151, v158
	v_fma_f32 v10, -v155, v11, v10
	v_add_f32_e32 v9, v9, v10
	v_pk_mul_f32 v[10:11], v[152:153], v[160:161]
	v_fmac_f32_e32 v79, v153, v160
	v_sub_f32_e32 v10, v10, v11
	v_mul_f32_e32 v20, v156, v10
	ds_read_b128 v[10:13], v93 offset:224
	ds_read2_b64 v[14:17], v6 offset1:16
	ds_read_b128 v[146:149], v83 offset:17120
	ds_read_b128 v[150:153], v93 offset:240
	v_fma_f32 v20, -v157, v79, v20
	v_add_f32_e32 v9, v9, v20
	ds_read2_b64 v[158:161], v6 offset0:32 offset1:48
	s_waitcnt lgkmcnt(3)
	v_pk_mul_f32 v[154:155], v[10:11], v[14:15]
	v_mul_f32_e32 v10, v10, v15
	v_sub_f32_e32 v20, v154, v155
	s_waitcnt lgkmcnt(2)
	v_mul_f32_e32 v20, v146, v20
	v_fmac_f32_e32 v10, v11, v14
	v_fma_f32 v10, -v147, v10, v20
	v_add_f32_e32 v9, v9, v10
	v_pk_mul_f32 v[10:11], v[12:13], v[16:17]
	ds_read_b128 v[154:157], v83 offset:17136
	v_sub_f32_e32 v10, v10, v11
	v_mul_f32_e32 v11, v12, v17
	v_mul_f32_e32 v10, v148, v10
	v_fmac_f32_e32 v11, v13, v16
	v_fma_f32 v10, -v149, v11, v10
	v_add_f32_e32 v9, v9, v10
	s_waitcnt lgkmcnt(1)
	v_pk_mul_f32 v[10:11], v[150:151], v[158:159]
	v_mul_f32_e32 v79, v152, v161
	v_sub_f32_e32 v10, v10, v11
	v_mul_f32_e32 v11, v150, v159
	s_waitcnt lgkmcnt(0)
	v_mul_f32_e32 v10, v154, v10
	v_fmac_f32_e32 v11, v151, v158
	v_fma_f32 v10, -v155, v11, v10
	v_add_f32_e32 v9, v9, v10
	v_pk_mul_f32 v[10:11], v[152:153], v[160:161]
	v_fmac_f32_e32 v79, v153, v160
	v_sub_f32_e32 v10, v10, v11
	v_mul_f32_e32 v20, v156, v10
	ds_read_b128 v[10:13], v93 offset:256
	ds_read2_b64 v[14:17], v6 offset0:64 offset1:80
	ds_read_b128 v[146:149], v83 offset:17152
	ds_read_b128 v[150:153], v93 offset:272
	v_fma_f32 v20, -v157, v79, v20
	v_add_f32_e32 v9, v9, v20
	ds_read2_b64 v[158:161], v6 offset0:96 offset1:112
	s_waitcnt lgkmcnt(3)
	v_pk_mul_f32 v[154:155], v[10:11], v[14:15]
	v_mul_f32_e32 v10, v10, v15
	v_sub_f32_e32 v20, v154, v155
	s_waitcnt lgkmcnt(2)
	v_mul_f32_e32 v20, v146, v20
	v_fmac_f32_e32 v10, v11, v14
	v_fma_f32 v10, -v147, v10, v20
	v_add_f32_e32 v9, v9, v10
	v_pk_mul_f32 v[10:11], v[12:13], v[16:17]
	ds_read_b128 v[154:157], v83 offset:17168
	v_sub_f32_e32 v10, v10, v11
	v_mul_f32_e32 v11, v12, v17
	v_mul_f32_e32 v10, v148, v10
	v_fmac_f32_e32 v11, v13, v16
	v_fma_f32 v10, -v149, v11, v10
	v_add_f32_e32 v9, v9, v10
	s_waitcnt lgkmcnt(1)
	v_pk_mul_f32 v[10:11], v[150:151], v[158:159]
	v_mul_f32_e32 v79, v152, v161
	v_sub_f32_e32 v10, v10, v11
	v_mul_f32_e32 v11, v150, v159
	s_waitcnt lgkmcnt(0)
	v_mul_f32_e32 v10, v154, v10
	v_fmac_f32_e32 v11, v151, v158
	v_fma_f32 v10, -v155, v11, v10
	v_add_f32_e32 v9, v9, v10
	v_pk_mul_f32 v[10:11], v[152:153], v[160:161]
	v_fmac_f32_e32 v79, v153, v160
	v_sub_f32_e32 v10, v10, v11
	v_mul_f32_e32 v20, v156, v10
	ds_read_b128 v[10:13], v93 offset:288
	ds_read2_b64 v[14:17], v6 offset0:128 offset1:144
	ds_read_b128 v[146:149], v83 offset:17184
	ds_read_b128 v[150:153], v93 offset:304
	v_fma_f32 v20, -v157, v79, v20
	v_add_f32_e32 v9, v9, v20
	ds_read2_b64 v[158:161], v6 offset0:160 offset1:176
	s_waitcnt lgkmcnt(3)
	v_pk_mul_f32 v[154:155], v[10:11], v[14:15]
	v_mul_f32_e32 v10, v10, v15
	v_sub_f32_e32 v20, v154, v155
	s_waitcnt lgkmcnt(2)
	v_mul_f32_e32 v20, v146, v20
	v_fmac_f32_e32 v10, v11, v14
	v_fma_f32 v10, -v147, v10, v20
	v_add_f32_e32 v9, v9, v10
	v_pk_mul_f32 v[10:11], v[12:13], v[16:17]
	ds_read_b128 v[154:157], v83 offset:17200
	v_sub_f32_e32 v10, v10, v11
	v_mul_f32_e32 v11, v12, v17
	v_mul_f32_e32 v10, v148, v10
	v_fmac_f32_e32 v11, v13, v16
	v_fma_f32 v10, -v149, v11, v10
	v_add_f32_e32 v9, v9, v10
	s_waitcnt lgkmcnt(1)
	v_pk_mul_f32 v[10:11], v[150:151], v[158:159]
	v_mul_f32_e32 v79, v152, v161
	v_sub_f32_e32 v10, v10, v11
	v_mul_f32_e32 v11, v150, v159
	s_waitcnt lgkmcnt(0)
	v_mul_f32_e32 v10, v154, v10
	v_fmac_f32_e32 v11, v151, v158
	v_fma_f32 v10, -v155, v11, v10
	v_add_f32_e32 v9, v9, v10
	v_pk_mul_f32 v[10:11], v[152:153], v[160:161]
	v_fmac_f32_e32 v79, v153, v160
	v_sub_f32_e32 v10, v10, v11
	v_mul_f32_e32 v20, v156, v10
	ds_read_b128 v[10:13], v93 offset:320
	ds_read2_b64 v[14:17], v6 offset0:192 offset1:208
	ds_read_b128 v[146:149], v83 offset:17216
	ds_read_b128 v[150:153], v93 offset:336
	v_fma_f32 v20, -v157, v79, v20
	v_add_f32_e32 v9, v9, v20
	ds_read2_b64 v[158:161], v6 offset0:224 offset1:240
	s_waitcnt lgkmcnt(3)
	v_pk_mul_f32 v[154:155], v[10:11], v[14:15]
	v_mul_f32_e32 v10, v10, v15
	v_sub_f32_e32 v20, v154, v155
	s_waitcnt lgkmcnt(2)
	v_mul_f32_e32 v20, v146, v20
	v_fmac_f32_e32 v10, v11, v14
	v_fma_f32 v10, -v147, v10, v20
	v_add_f32_e32 v9, v9, v10
	v_pk_mul_f32 v[10:11], v[12:13], v[16:17]
	ds_read_b128 v[154:157], v83 offset:17232
	v_sub_f32_e32 v10, v10, v11
	v_mul_f32_e32 v11, v12, v17
	v_mul_f32_e32 v10, v148, v10
	v_fmac_f32_e32 v11, v13, v16
	v_fma_f32 v10, -v149, v11, v10
	v_add_f32_e32 v9, v9, v10
	s_waitcnt lgkmcnt(1)
	v_pk_mul_f32 v[10:11], v[150:151], v[158:159]
	v_mul_f32_e32 v79, v152, v161
	v_sub_f32_e32 v10, v10, v11
	v_mul_f32_e32 v11, v150, v159
	s_waitcnt lgkmcnt(0)
	v_mul_f32_e32 v10, v154, v10
	v_fmac_f32_e32 v11, v151, v158
	v_fma_f32 v10, -v155, v11, v10
	v_add_f32_e32 v9, v9, v10
	v_pk_mul_f32 v[10:11], v[152:153], v[160:161]
	v_fmac_f32_e32 v79, v153, v160
	v_sub_f32_e32 v10, v10, v11
	v_mul_f32_e32 v20, v156, v10
	ds_read_b128 v[10:13], v93 offset:352
	ds_read2_b64 v[14:17], v4 offset1:16
	ds_read_b128 v[146:149], v83 offset:17248
	ds_read_b128 v[150:153], v93 offset:368
	v_fma_f32 v20, -v157, v79, v20
	v_add_f32_e32 v9, v9, v20
	ds_read2_b64 v[158:161], v4 offset0:32 offset1:48
	s_waitcnt lgkmcnt(3)
	v_pk_mul_f32 v[154:155], v[10:11], v[14:15]
	v_mul_f32_e32 v10, v10, v15
	v_sub_f32_e32 v20, v154, v155
	s_waitcnt lgkmcnt(2)
	v_mul_f32_e32 v20, v146, v20
	v_fmac_f32_e32 v10, v11, v14
	v_fma_f32 v10, -v147, v10, v20
	v_add_f32_e32 v9, v9, v10
	v_pk_mul_f32 v[10:11], v[12:13], v[16:17]
	ds_read_b128 v[154:157], v83 offset:17264
	v_sub_f32_e32 v10, v10, v11
	v_mul_f32_e32 v11, v12, v17
	v_mul_f32_e32 v10, v148, v10
	v_fmac_f32_e32 v11, v13, v16
	v_fma_f32 v10, -v149, v11, v10
	v_add_f32_e32 v9, v9, v10
	s_waitcnt lgkmcnt(1)
	v_pk_mul_f32 v[10:11], v[150:151], v[158:159]
	v_mul_f32_e32 v79, v152, v161
	v_sub_f32_e32 v10, v10, v11
	v_mul_f32_e32 v11, v150, v159
	s_waitcnt lgkmcnt(0)
	v_mul_f32_e32 v10, v154, v10
	v_fmac_f32_e32 v11, v151, v158
	v_fma_f32 v10, -v155, v11, v10
	v_add_f32_e32 v9, v9, v10
	v_pk_mul_f32 v[10:11], v[152:153], v[160:161]
	v_fmac_f32_e32 v79, v153, v160
	v_sub_f32_e32 v10, v10, v11
	v_mul_f32_e32 v20, v156, v10
	ds_read_b128 v[10:13], v93 offset:384
	ds_read2_b64 v[14:17], v4 offset0:64 offset1:80
	ds_read_b128 v[146:149], v83 offset:17280
	ds_read_b128 v[150:153], v93 offset:400
	v_fma_f32 v20, -v157, v79, v20
	v_add_f32_e32 v9, v9, v20
	ds_read2_b64 v[158:161], v4 offset0:96 offset1:112
	s_waitcnt lgkmcnt(3)
	v_pk_mul_f32 v[154:155], v[10:11], v[14:15]
	v_mul_f32_e32 v10, v10, v15
	v_sub_f32_e32 v20, v154, v155
	s_waitcnt lgkmcnt(2)
	v_mul_f32_e32 v20, v146, v20
	v_fmac_f32_e32 v10, v11, v14
	v_fma_f32 v10, -v147, v10, v20
	v_add_f32_e32 v9, v9, v10
	v_pk_mul_f32 v[10:11], v[12:13], v[16:17]
	ds_read_b128 v[154:157], v83 offset:17296
	v_sub_f32_e32 v10, v10, v11
	v_mul_f32_e32 v11, v12, v17
	v_mul_f32_e32 v10, v148, v10
	v_fmac_f32_e32 v11, v13, v16
	v_fma_f32 v10, -v149, v11, v10
	v_add_f32_e32 v9, v9, v10
	s_waitcnt lgkmcnt(1)
	v_pk_mul_f32 v[10:11], v[150:151], v[158:159]
	s_nop 0
	v_sub_f32_e32 v10, v10, v11
	v_mul_f32_e32 v11, v150, v159
	s_waitcnt lgkmcnt(0)
	v_mul_f32_e32 v10, v154, v10
	v_fmac_f32_e32 v11, v151, v158
	v_fma_f32 v10, -v155, v11, v10
	v_add_f32_e32 v9, v9, v10
	v_pk_mul_f32 v[10:11], v[152:153], v[160:161]
	s_nop 0
	v_sub_f32_e32 v10, v10, v11
	v_mul_f32_e32 v11, v152, v161
	v_mul_f32_e32 v10, v156, v10
	v_fmac_f32_e32 v11, v153, v160
	v_fma_f32 v14, -v157, v11, v10
	ds_read_b128 v[10:13], v93 offset:416
	v_add_f32_e32 v9, v9, v14
	ds_read2_b64 v[14:17], v4 offset0:128 offset1:144
	ds_read_b128 v[146:149], v83 offset:17312
	ds_read_b128 v[150:153], v93 offset:432
	s_waitcnt lgkmcnt(3)
	v_mov_b32_e32 v155, v12
	s_waitcnt lgkmcnt(2)
	v_mov_b32_e32 v157, v16
	v_mov_b32_e32 v12, v11
	v_mov_b32_e32 v16, v15
	v_mov_b32_e32 v154, v10
	v_mov_b32_e32 v156, v14
	v_pk_mul_f32 v[10:11], v[12:13], v[16:17]
	s_nop 0
	v_pk_fma_f32 v[14:15], v[154:155], v[156:157], v[10:11] neg_lo:[0,0,1] neg_hi:[0,0,1]
	v_pk_mul_f32 v[10:11], v[12:13], v[156:157]
	s_nop 0
	v_pk_fma_f32 v[16:17], v[154:155], v[16:17], v[10:11]
	s_waitcnt lgkmcnt(1)
	v_mov_b32_e32 v155, v148
	v_mov_b32_e32 v148, v147
	v_mov_b32_e32 v154, v146
	v_pk_mul_f32 v[16:17], v[148:149], v[16:17]
	ds_read_b128 v[10:13], v83 offset:17328
	v_pk_fma_f32 v[146:147], v[154:155], v[14:15], v[16:17] neg_lo:[0,0,1] neg_hi:[0,0,1]
	ds_read2_b64 v[14:17], v4 offset0:160 offset1:176
	v_add_f32_e32 v9, v9, v146
	v_add_f32_e32 v9, v9, v147
	s_waitcnt lgkmcnt(2)
	v_mov_b32_e32 v147, v152
	v_mov_b32_e32 v152, v151
	s_waitcnt lgkmcnt(0)
	v_mov_b32_e32 v149, v16
	v_mov_b32_e32 v16, v15
	v_mov_b32_e32 v146, v150
	v_mov_b32_e32 v148, v14
	v_pk_mul_f32 v[14:15], v[152:153], v[16:17]
	s_nop 0
	v_pk_fma_f32 v[14:15], v[146:147], v[148:149], v[14:15] neg_lo:[0,0,1] neg_hi:[0,0,1]
	v_pk_mul_f32 v[148:149], v[152:153], v[148:149]
	s_nop 0
	v_pk_fma_f32 v[16:17], v[146:147], v[16:17], v[148:149]
	v_mov_b32_e32 v147, v12
	v_mov_b32_e32 v12, v11
	v_mov_b32_e32 v146, v10
	v_pk_mul_f32 v[10:11], v[12:13], v[16:17]
	s_nop 0
	v_pk_fma_f32 v[14:15], v[146:147], v[14:15], v[10:11] neg_lo:[0,0,1] neg_hi:[0,0,1]
	ds_read_b128 v[10:13], v93 offset:448
	v_add_f32_e32 v9, v9, v14
	v_add_f32_e32 v9, v9, v15
	ds_read2_b64 v[14:17], v4 offset0:192 offset1:208
	ds_read_b128 v[146:149], v83 offset:17344
	ds_read_b128 v[150:153], v93 offset:464
	s_waitcnt lgkmcnt(3)
	v_mov_b32_e32 v155, v12
	s_waitcnt lgkmcnt(2)
	v_mov_b32_e32 v157, v16
	v_mov_b32_e32 v12, v11
	v_mov_b32_e32 v16, v15
	v_mov_b32_e32 v154, v10
	v_mov_b32_e32 v156, v14
	v_pk_mul_f32 v[10:11], v[12:13], v[16:17]
	s_nop 0
	v_pk_fma_f32 v[14:15], v[154:155], v[156:157], v[10:11] neg_lo:[0,0,1] neg_hi:[0,0,1]
	v_pk_mul_f32 v[10:11], v[12:13], v[156:157]
	s_nop 0
	v_pk_fma_f32 v[16:17], v[154:155], v[16:17], v[10:11]
	s_waitcnt lgkmcnt(1)
	v_mov_b32_e32 v155, v148
	v_mov_b32_e32 v148, v147
	v_mov_b32_e32 v154, v146
	v_pk_mul_f32 v[16:17], v[148:149], v[16:17]
	ds_read_b128 v[10:13], v83 offset:17360
	v_pk_fma_f32 v[146:147], v[154:155], v[14:15], v[16:17] neg_lo:[0,0,1] neg_hi:[0,0,1]
	ds_read2_b64 v[14:17], v4 offset0:224 offset1:240
	v_add_f32_e32 v9, v9, v146
	v_add_f32_e32 v9, v9, v147
	s_waitcnt lgkmcnt(2)
	v_mov_b32_e32 v147, v152
	v_mov_b32_e32 v152, v151
	s_waitcnt lgkmcnt(0)
	v_mov_b32_e32 v149, v16
	v_mov_b32_e32 v16, v15
	v_mov_b32_e32 v146, v150
	v_mov_b32_e32 v148, v14
	v_pk_mul_f32 v[14:15], v[152:153], v[16:17]
	s_nop 0
	v_pk_fma_f32 v[14:15], v[146:147], v[148:149], v[14:15] neg_lo:[0,0,1] neg_hi:[0,0,1]
	v_pk_mul_f32 v[148:149], v[152:153], v[148:149]
	s_nop 0
	v_pk_fma_f32 v[16:17], v[146:147], v[16:17], v[148:149]
	v_mov_b32_e32 v147, v12
	v_mov_b32_e32 v12, v11
	v_mov_b32_e32 v146, v10
	v_pk_mul_f32 v[10:11], v[12:13], v[16:17]
	s_nop 0
	v_pk_fma_f32 v[14:15], v[146:147], v[14:15], v[10:11] neg_lo:[0,0,1] neg_hi:[0,0,1]
	ds_read_b128 v[10:13], v93 offset:480
	v_add_f32_e32 v9, v9, v14
	v_add_f32_e32 v9, v9, v15
	ds_read2_b64 v[14:17], v8 offset1:16
	ds_read_b128 v[146:149], v83 offset:17376
	ds_read_b128 v[150:153], v93 offset:496
	s_waitcnt lgkmcnt(3)
	v_mov_b32_e32 v155, v12
	s_waitcnt lgkmcnt(2)
	v_mov_b32_e32 v157, v16
	v_mov_b32_e32 v12, v11
	v_mov_b32_e32 v16, v15
	v_mov_b32_e32 v154, v10
	v_mov_b32_e32 v156, v14
	v_pk_mul_f32 v[10:11], v[12:13], v[16:17]
	s_nop 0
	v_pk_fma_f32 v[14:15], v[154:155], v[156:157], v[10:11] neg_lo:[0,0,1] neg_hi:[0,0,1]
	v_pk_mul_f32 v[10:11], v[12:13], v[156:157]
	s_nop 0
	v_pk_fma_f32 v[16:17], v[154:155], v[16:17], v[10:11]
	s_waitcnt lgkmcnt(1)
	v_mov_b32_e32 v155, v148
	v_mov_b32_e32 v148, v147
	v_mov_b32_e32 v154, v146
	v_pk_mul_f32 v[16:17], v[148:149], v[16:17]
	ds_read_b128 v[10:13], v83 offset:17392
	v_pk_fma_f32 v[146:147], v[154:155], v[14:15], v[16:17] neg_lo:[0,0,1] neg_hi:[0,0,1]
	ds_read2_b64 v[14:17], v8 offset0:32 offset1:48
	v_add_f32_e32 v9, v9, v146
	v_add_f32_e32 v9, v9, v147
	s_waitcnt lgkmcnt(2)
	v_mov_b32_e32 v147, v152
	v_mov_b32_e32 v152, v151
	s_waitcnt lgkmcnt(0)
	v_mov_b32_e32 v149, v16
	v_mov_b32_e32 v16, v15
	v_mov_b32_e32 v146, v150
	v_mov_b32_e32 v148, v14
	v_pk_mul_f32 v[14:15], v[152:153], v[16:17]
	s_nop 0
	v_pk_fma_f32 v[14:15], v[146:147], v[148:149], v[14:15] neg_lo:[0,0,1] neg_hi:[0,0,1]
	v_pk_mul_f32 v[148:149], v[152:153], v[148:149]
	s_nop 0
	v_pk_fma_f32 v[16:17], v[146:147], v[16:17], v[148:149]
	v_mov_b32_e32 v147, v12
	v_mov_b32_e32 v12, v11
	v_mov_b32_e32 v146, v10
	v_pk_mul_f32 v[10:11], v[12:13], v[16:17]
	s_nop 0
	v_pk_fma_f32 v[10:11], v[146:147], v[14:15], v[10:11] neg_lo:[0,0,1] neg_hi:[0,0,1]
	s_nop 0
	v_add_f32_e32 v9, v9, v10
	v_add_f32_e32 v9, v9, v11
	s_and_saveexec_b64 s[68:69], s[60:61]
	s_cbranch_execz .LBB0_89
	global_load_dword v10, v[2:3], off nt
	s_waitcnt vmcnt(0)
	v_add_f32_e32 v9, v9, v10
.LBB0_89:
	s_or_b64 exec, exec, s[68:69]
	ds_write_b32 v116, v9 offset:31232
	ds_read_b128 v[10:13], v96
	ds_read_b128 v[14:17], v96 offset:16
	ds_read_b128 v[146:149], v96 offset:32
	ds_read_b128 v[150:153], v96 offset:48
	ds_read2_b64 v[154:157], v7 offset0:64 offset1:80
	ds_read_b128 v[158:161], v83 offset:16896
	ds_read_b128 v[162:165], v83 offset:16912
	ds_read_b128 v[166:169], v83 offset:16928
	ds_read_b128 v[174:177], v83 offset:16944
	s_waitcnt lgkmcnt(4)
	v_pk_mul_f32 v[170:171], v[10:11], v[154:155]
	v_mul_f32_e32 v10, v10, v155
	v_sub_f32_e32 v9, v170, v171
	s_waitcnt lgkmcnt(3)
	v_mul_f32_e32 v9, v158, v9
	v_fmac_f32_e32 v10, v11, v154
	ds_read2_b64 v[178:181], v7 offset0:96 offset1:112
	v_fma_f32 v9, -v159, v10, v9
	v_pk_mul_f32 v[10:11], v[12:13], v[156:157]
	v_add_f32_e32 v9, 0, v9
	v_sub_f32_e32 v10, v10, v11
	v_mul_f32_e32 v11, v12, v157
	v_mul_f32_e32 v10, v160, v10
	v_fmac_f32_e32 v11, v13, v156
	v_fma_f32 v10, -v161, v11, v10
	v_add_f32_e32 v9, v9, v10
	s_waitcnt lgkmcnt(0)
	v_pk_mul_f32 v[10:11], v[14:15], v[178:179]
	s_nop 0
	v_sub_f32_e32 v10, v10, v11
	v_mul_f32_e32 v11, v14, v179
	v_mul_f32_e32 v10, v162, v10
	v_fmac_f32_e32 v11, v15, v178
	v_fma_f32 v10, -v163, v11, v10
	v_add_f32_e32 v9, v9, v10
	v_pk_mul_f32 v[10:11], v[16:17], v[180:181]
	v_mul_f32_e32 v15, v16, v181
	v_sub_f32_e32 v10, v10, v11
	v_mul_f32_e32 v14, v164, v10
	ds_read2_b64 v[10:13], v7 offset0:128 offset1:144
	v_fmac_f32_e32 v15, v17, v180
	v_fma_f32 v14, -v165, v15, v14
	v_add_f32_e32 v9, v9, v14
	s_waitcnt lgkmcnt(0)
	v_pk_mul_f32 v[14:15], v[146:147], v[10:11]
	s_nop 0
	v_sub_f32_e32 v14, v14, v15
	v_mul_f32_e32 v11, v146, v11
	v_mul_f32_e32 v14, v166, v14
	v_fmac_f32_e32 v11, v147, v10
	v_fma_f32 v10, -v167, v11, v14
	ds_read2_b64 v[14:17], v7 offset0:160 offset1:176
	v_add_f32_e32 v9, v9, v10
	v_pk_mul_f32 v[10:11], v[148:149], v[12:13]
	s_waitcnt lgkmcnt(0)
	v_mul_f32_e32 v79, v152, v17
	v_sub_f32_e32 v10, v10, v11
	v_mul_f32_e32 v11, v148, v13
	v_mul_f32_e32 v10, v168, v10
	v_fmac_f32_e32 v11, v149, v12
	v_fma_f32 v10, -v169, v11, v10
	v_add_f32_e32 v9, v9, v10
	v_pk_mul_f32 v[10:11], v[150:151], v[14:15]
	v_fmac_f32_e32 v79, v153, v16
	v_sub_f32_e32 v10, v10, v11
	v_mul_f32_e32 v11, v150, v15
	v_mul_f32_e32 v10, v174, v10
	v_fmac_f32_e32 v11, v151, v14
	v_fma_f32 v10, -v175, v11, v10
	v_add_f32_e32 v9, v9, v10
	v_pk_mul_f32 v[10:11], v[152:153], v[16:17]
	s_nop 0
	v_sub_f32_e32 v10, v10, v11
	v_mul_f32_e32 v20, v176, v10
	ds_read_b128 v[10:13], v96 offset:64
	ds_read2_b64 v[14:17], v7 offset0:192 offset1:208
	ds_read_b128 v[146:149], v83 offset:16960
	ds_read_b128 v[150:153], v96 offset:80
	v_fma_f32 v20, -v177, v79, v20
	v_add_f32_e32 v9, v9, v20
	ds_read2_b64 v[158:161], v7 offset0:224 offset1:240
	s_waitcnt lgkmcnt(3)
	v_pk_mul_f32 v[154:155], v[10:11], v[14:15]
	v_mul_f32_e32 v10, v10, v15
	v_sub_f32_e32 v20, v154, v155
	s_waitcnt lgkmcnt(2)
	v_mul_f32_e32 v20, v146, v20
	v_fmac_f32_e32 v10, v11, v14
	v_fma_f32 v10, -v147, v10, v20
	v_add_f32_e32 v9, v9, v10
	v_pk_mul_f32 v[10:11], v[12:13], v[16:17]
	ds_read_b128 v[154:157], v83 offset:16976
	v_sub_f32_e32 v10, v10, v11
	v_mul_f32_e32 v11, v12, v17
	v_mul_f32_e32 v10, v148, v10
	v_fmac_f32_e32 v11, v13, v16
	v_fma_f32 v10, -v149, v11, v10
	v_add_f32_e32 v9, v9, v10
	s_waitcnt lgkmcnt(1)
	v_pk_mul_f32 v[10:11], v[150:151], v[158:159]
	v_mul_f32_e32 v79, v152, v161
	v_sub_f32_e32 v10, v10, v11
	v_mul_f32_e32 v11, v150, v159
	s_waitcnt lgkmcnt(0)
	v_mul_f32_e32 v10, v154, v10
	v_fmac_f32_e32 v11, v151, v158
	v_fma_f32 v10, -v155, v11, v10
	v_add_f32_e32 v9, v9, v10
	v_pk_mul_f32 v[10:11], v[152:153], v[160:161]
	v_fmac_f32_e32 v79, v153, v160
	v_sub_f32_e32 v10, v10, v11
	v_mul_f32_e32 v20, v156, v10
	ds_read_b128 v[10:13], v96 offset:96
	ds_read2_b64 v[14:17], v5 offset1:16
	ds_read_b128 v[146:149], v83 offset:16992
	ds_read_b128 v[150:153], v96 offset:112
	v_fma_f32 v20, -v157, v79, v20
	v_add_f32_e32 v9, v9, v20
	ds_read2_b64 v[158:161], v5 offset0:32 offset1:48
	s_waitcnt lgkmcnt(3)
	v_pk_mul_f32 v[154:155], v[10:11], v[14:15]
	v_mul_f32_e32 v10, v10, v15
	v_sub_f32_e32 v20, v154, v155
	s_waitcnt lgkmcnt(2)
	v_mul_f32_e32 v20, v146, v20
	v_fmac_f32_e32 v10, v11, v14
	v_fma_f32 v10, -v147, v10, v20
	v_add_f32_e32 v9, v9, v10
	v_pk_mul_f32 v[10:11], v[12:13], v[16:17]
	ds_read_b128 v[154:157], v83 offset:17008
	v_sub_f32_e32 v10, v10, v11
	v_mul_f32_e32 v11, v12, v17
	v_mul_f32_e32 v10, v148, v10
	v_fmac_f32_e32 v11, v13, v16
	v_fma_f32 v10, -v149, v11, v10
	v_add_f32_e32 v9, v9, v10
	s_waitcnt lgkmcnt(1)
	v_pk_mul_f32 v[10:11], v[150:151], v[158:159]
	v_mul_f32_e32 v79, v152, v161
	v_sub_f32_e32 v10, v10, v11
	v_mul_f32_e32 v11, v150, v159
	s_waitcnt lgkmcnt(0)
	v_mul_f32_e32 v10, v154, v10
	v_fmac_f32_e32 v11, v151, v158
	v_fma_f32 v10, -v155, v11, v10
	v_add_f32_e32 v9, v9, v10
	v_pk_mul_f32 v[10:11], v[152:153], v[160:161]
	v_fmac_f32_e32 v79, v153, v160
	v_sub_f32_e32 v10, v10, v11
	v_mul_f32_e32 v20, v156, v10
	ds_read_b128 v[10:13], v96 offset:128
	ds_read2_b64 v[14:17], v5 offset0:64 offset1:80
	ds_read_b128 v[146:149], v83 offset:17024
	ds_read_b128 v[150:153], v96 offset:144
	v_fma_f32 v20, -v157, v79, v20
	v_add_f32_e32 v9, v9, v20
	ds_read2_b64 v[158:161], v5 offset0:96 offset1:112
	s_waitcnt lgkmcnt(3)
	v_pk_mul_f32 v[154:155], v[10:11], v[14:15]
	v_mul_f32_e32 v10, v10, v15
	v_sub_f32_e32 v20, v154, v155
	s_waitcnt lgkmcnt(2)
	v_mul_f32_e32 v20, v146, v20
	v_fmac_f32_e32 v10, v11, v14
	v_fma_f32 v10, -v147, v10, v20
	v_add_f32_e32 v9, v9, v10
	v_pk_mul_f32 v[10:11], v[12:13], v[16:17]
	ds_read_b128 v[154:157], v83 offset:17040
	v_sub_f32_e32 v10, v10, v11
	v_mul_f32_e32 v11, v12, v17
	v_mul_f32_e32 v10, v148, v10
	v_fmac_f32_e32 v11, v13, v16
	v_fma_f32 v10, -v149, v11, v10
	v_add_f32_e32 v9, v9, v10
	s_waitcnt lgkmcnt(1)
	v_pk_mul_f32 v[10:11], v[150:151], v[158:159]
	v_mul_f32_e32 v79, v152, v161
	v_sub_f32_e32 v10, v10, v11
	v_mul_f32_e32 v11, v150, v159
	s_waitcnt lgkmcnt(0)
	v_mul_f32_e32 v10, v154, v10
	v_fmac_f32_e32 v11, v151, v158
	v_fma_f32 v10, -v155, v11, v10
	v_add_f32_e32 v9, v9, v10
	v_pk_mul_f32 v[10:11], v[152:153], v[160:161]
	v_fmac_f32_e32 v79, v153, v160
	v_sub_f32_e32 v10, v10, v11
	v_mul_f32_e32 v20, v156, v10
	ds_read_b128 v[10:13], v96 offset:160
	ds_read2_b64 v[14:17], v5 offset0:128 offset1:144
	ds_read_b128 v[146:149], v83 offset:17056
	ds_read_b128 v[150:153], v96 offset:176
	v_fma_f32 v20, -v157, v79, v20
	v_add_f32_e32 v9, v9, v20
	ds_read2_b64 v[158:161], v5 offset0:160 offset1:176
	s_waitcnt lgkmcnt(3)
	v_pk_mul_f32 v[154:155], v[10:11], v[14:15]
	v_mul_f32_e32 v10, v10, v15
	v_sub_f32_e32 v20, v154, v155
	s_waitcnt lgkmcnt(2)
	v_mul_f32_e32 v20, v146, v20
	v_fmac_f32_e32 v10, v11, v14
	v_fma_f32 v10, -v147, v10, v20
	v_add_f32_e32 v9, v9, v10
	v_pk_mul_f32 v[10:11], v[12:13], v[16:17]
	ds_read_b128 v[154:157], v83 offset:17072
	v_sub_f32_e32 v10, v10, v11
	v_mul_f32_e32 v11, v12, v17
	v_mul_f32_e32 v10, v148, v10
	v_fmac_f32_e32 v11, v13, v16
	v_fma_f32 v10, -v149, v11, v10
	v_add_f32_e32 v9, v9, v10
	s_waitcnt lgkmcnt(1)
	v_pk_mul_f32 v[10:11], v[150:151], v[158:159]
	v_mul_f32_e32 v79, v152, v161
	v_sub_f32_e32 v10, v10, v11
	v_mul_f32_e32 v11, v150, v159
	s_waitcnt lgkmcnt(0)
	v_mul_f32_e32 v10, v154, v10
	v_fmac_f32_e32 v11, v151, v158
	v_fma_f32 v10, -v155, v11, v10
	v_add_f32_e32 v9, v9, v10
	v_pk_mul_f32 v[10:11], v[152:153], v[160:161]
	v_fmac_f32_e32 v79, v153, v160
	v_sub_f32_e32 v10, v10, v11
	v_mul_f32_e32 v20, v156, v10
	ds_read_b128 v[10:13], v96 offset:192
	ds_read2_b64 v[14:17], v5 offset0:192 offset1:208
	ds_read_b128 v[146:149], v83 offset:17088
	ds_read_b128 v[150:153], v96 offset:208
	v_fma_f32 v20, -v157, v79, v20
	v_add_f32_e32 v9, v9, v20
	ds_read2_b64 v[158:161], v5 offset0:224 offset1:240
	s_waitcnt lgkmcnt(3)
	v_pk_mul_f32 v[154:155], v[10:11], v[14:15]
	v_mul_f32_e32 v10, v10, v15
	v_sub_f32_e32 v20, v154, v155
	s_waitcnt lgkmcnt(2)
	v_mul_f32_e32 v20, v146, v20
	v_fmac_f32_e32 v10, v11, v14
	v_fma_f32 v10, -v147, v10, v20
	v_add_f32_e32 v9, v9, v10
	v_pk_mul_f32 v[10:11], v[12:13], v[16:17]
	ds_read_b128 v[154:157], v83 offset:17104
	v_sub_f32_e32 v10, v10, v11
	v_mul_f32_e32 v11, v12, v17
	v_mul_f32_e32 v10, v148, v10
	v_fmac_f32_e32 v11, v13, v16
	v_fma_f32 v10, -v149, v11, v10
	v_add_f32_e32 v9, v9, v10
	s_waitcnt lgkmcnt(1)
	v_pk_mul_f32 v[10:11], v[150:151], v[158:159]
	v_mul_f32_e32 v79, v152, v161
	v_sub_f32_e32 v10, v10, v11
	v_mul_f32_e32 v11, v150, v159
	s_waitcnt lgkmcnt(0)
	v_mul_f32_e32 v10, v154, v10
	v_fmac_f32_e32 v11, v151, v158
	v_fma_f32 v10, -v155, v11, v10
	v_add_f32_e32 v9, v9, v10
	v_pk_mul_f32 v[10:11], v[152:153], v[160:161]
	v_fmac_f32_e32 v79, v153, v160
	v_sub_f32_e32 v10, v10, v11
	v_mul_f32_e32 v20, v156, v10
	ds_read_b128 v[10:13], v96 offset:224
	ds_read2_b64 v[14:17], v6 offset1:16
	ds_read_b128 v[146:149], v83 offset:17120
	ds_read_b128 v[150:153], v96 offset:240
	v_fma_f32 v20, -v157, v79, v20
	v_add_f32_e32 v9, v9, v20
	ds_read2_b64 v[158:161], v6 offset0:32 offset1:48
	s_waitcnt lgkmcnt(3)
	v_pk_mul_f32 v[154:155], v[10:11], v[14:15]
	v_mul_f32_e32 v10, v10, v15
	v_sub_f32_e32 v20, v154, v155
	s_waitcnt lgkmcnt(2)
	v_mul_f32_e32 v20, v146, v20
	v_fmac_f32_e32 v10, v11, v14
	v_fma_f32 v10, -v147, v10, v20
	v_add_f32_e32 v9, v9, v10
	v_pk_mul_f32 v[10:11], v[12:13], v[16:17]
	ds_read_b128 v[154:157], v83 offset:17136
	v_sub_f32_e32 v10, v10, v11
	v_mul_f32_e32 v11, v12, v17
	v_mul_f32_e32 v10, v148, v10
	v_fmac_f32_e32 v11, v13, v16
	v_fma_f32 v10, -v149, v11, v10
	v_add_f32_e32 v9, v9, v10
	s_waitcnt lgkmcnt(1)
	v_pk_mul_f32 v[10:11], v[150:151], v[158:159]
	v_mul_f32_e32 v79, v152, v161
	v_sub_f32_e32 v10, v10, v11
	v_mul_f32_e32 v11, v150, v159
	s_waitcnt lgkmcnt(0)
	v_mul_f32_e32 v10, v154, v10
	v_fmac_f32_e32 v11, v151, v158
	v_fma_f32 v10, -v155, v11, v10
	v_add_f32_e32 v9, v9, v10
	v_pk_mul_f32 v[10:11], v[152:153], v[160:161]
	v_fmac_f32_e32 v79, v153, v160
	v_sub_f32_e32 v10, v10, v11
	v_mul_f32_e32 v20, v156, v10
	ds_read_b128 v[10:13], v96 offset:256
	ds_read2_b64 v[14:17], v6 offset0:64 offset1:80
	ds_read_b128 v[146:149], v83 offset:17152
	ds_read_b128 v[150:153], v96 offset:272
	v_fma_f32 v20, -v157, v79, v20
	v_add_f32_e32 v9, v9, v20
	ds_read2_b64 v[158:161], v6 offset0:96 offset1:112
	s_waitcnt lgkmcnt(3)
	v_pk_mul_f32 v[154:155], v[10:11], v[14:15]
	v_mul_f32_e32 v10, v10, v15
	v_sub_f32_e32 v20, v154, v155
	s_waitcnt lgkmcnt(2)
	v_mul_f32_e32 v20, v146, v20
	v_fmac_f32_e32 v10, v11, v14
	v_fma_f32 v10, -v147, v10, v20
	v_add_f32_e32 v9, v9, v10
	v_pk_mul_f32 v[10:11], v[12:13], v[16:17]
	ds_read_b128 v[154:157], v83 offset:17168
	v_sub_f32_e32 v10, v10, v11
	v_mul_f32_e32 v11, v12, v17
	v_mul_f32_e32 v10, v148, v10
	v_fmac_f32_e32 v11, v13, v16
	v_fma_f32 v10, -v149, v11, v10
	v_add_f32_e32 v9, v9, v10
	s_waitcnt lgkmcnt(1)
	v_pk_mul_f32 v[10:11], v[150:151], v[158:159]
	v_mul_f32_e32 v79, v152, v161
	v_sub_f32_e32 v10, v10, v11
	v_mul_f32_e32 v11, v150, v159
	s_waitcnt lgkmcnt(0)
	v_mul_f32_e32 v10, v154, v10
	v_fmac_f32_e32 v11, v151, v158
	v_fma_f32 v10, -v155, v11, v10
	v_add_f32_e32 v9, v9, v10
	v_pk_mul_f32 v[10:11], v[152:153], v[160:161]
	v_fmac_f32_e32 v79, v153, v160
	v_sub_f32_e32 v10, v10, v11
	v_mul_f32_e32 v20, v156, v10
	ds_read_b128 v[10:13], v96 offset:288
	ds_read2_b64 v[14:17], v6 offset0:128 offset1:144
	ds_read_b128 v[146:149], v83 offset:17184
	ds_read_b128 v[150:153], v96 offset:304
	v_fma_f32 v20, -v157, v79, v20
	v_add_f32_e32 v9, v9, v20
	ds_read2_b64 v[158:161], v6 offset0:160 offset1:176
	s_waitcnt lgkmcnt(3)
	v_pk_mul_f32 v[154:155], v[10:11], v[14:15]
	v_mul_f32_e32 v10, v10, v15
	v_sub_f32_e32 v20, v154, v155
	s_waitcnt lgkmcnt(2)
	v_mul_f32_e32 v20, v146, v20
	v_fmac_f32_e32 v10, v11, v14
	v_fma_f32 v10, -v147, v10, v20
	v_add_f32_e32 v9, v9, v10
	v_pk_mul_f32 v[10:11], v[12:13], v[16:17]
	ds_read_b128 v[154:157], v83 offset:17200
	v_sub_f32_e32 v10, v10, v11
	v_mul_f32_e32 v11, v12, v17
	v_mul_f32_e32 v10, v148, v10
	v_fmac_f32_e32 v11, v13, v16
	v_fma_f32 v10, -v149, v11, v10
	v_add_f32_e32 v9, v9, v10
	s_waitcnt lgkmcnt(1)
	v_pk_mul_f32 v[10:11], v[150:151], v[158:159]
	v_mul_f32_e32 v79, v152, v161
	v_sub_f32_e32 v10, v10, v11
	v_mul_f32_e32 v11, v150, v159
	s_waitcnt lgkmcnt(0)
	v_mul_f32_e32 v10, v154, v10
	v_fmac_f32_e32 v11, v151, v158
	v_fma_f32 v10, -v155, v11, v10
	v_add_f32_e32 v9, v9, v10
	v_pk_mul_f32 v[10:11], v[152:153], v[160:161]
	v_fmac_f32_e32 v79, v153, v160
	v_sub_f32_e32 v10, v10, v11
	v_mul_f32_e32 v20, v156, v10
	ds_read_b128 v[10:13], v96 offset:320
	ds_read2_b64 v[14:17], v6 offset0:192 offset1:208
	ds_read_b128 v[146:149], v83 offset:17216
	ds_read_b128 v[150:153], v96 offset:336
	v_fma_f32 v20, -v157, v79, v20
	v_add_f32_e32 v9, v9, v20
	ds_read2_b64 v[158:161], v6 offset0:224 offset1:240
	s_waitcnt lgkmcnt(3)
	v_pk_mul_f32 v[154:155], v[10:11], v[14:15]
	v_mul_f32_e32 v10, v10, v15
	v_sub_f32_e32 v20, v154, v155
	s_waitcnt lgkmcnt(2)
	v_mul_f32_e32 v20, v146, v20
	v_fmac_f32_e32 v10, v11, v14
	v_fma_f32 v10, -v147, v10, v20
	v_add_f32_e32 v9, v9, v10
	v_pk_mul_f32 v[10:11], v[12:13], v[16:17]
	ds_read_b128 v[154:157], v83 offset:17232
	v_sub_f32_e32 v10, v10, v11
	v_mul_f32_e32 v11, v12, v17
	v_mul_f32_e32 v10, v148, v10
	v_fmac_f32_e32 v11, v13, v16
	v_fma_f32 v10, -v149, v11, v10
	v_add_f32_e32 v9, v9, v10
	s_waitcnt lgkmcnt(1)
	v_pk_mul_f32 v[10:11], v[150:151], v[158:159]
	v_mul_f32_e32 v79, v152, v161
	v_sub_f32_e32 v10, v10, v11
	v_mul_f32_e32 v11, v150, v159
	s_waitcnt lgkmcnt(0)
	v_mul_f32_e32 v10, v154, v10
	v_fmac_f32_e32 v11, v151, v158
	v_fma_f32 v10, -v155, v11, v10
	v_add_f32_e32 v9, v9, v10
	v_pk_mul_f32 v[10:11], v[152:153], v[160:161]
	v_fmac_f32_e32 v79, v153, v160
	v_sub_f32_e32 v10, v10, v11
	v_mul_f32_e32 v20, v156, v10
	ds_read_b128 v[10:13], v96 offset:352
	ds_read2_b64 v[14:17], v4 offset1:16
	ds_read_b128 v[146:149], v83 offset:17248
	ds_read_b128 v[150:153], v96 offset:368
	v_fma_f32 v20, -v157, v79, v20
	v_add_f32_e32 v9, v9, v20
	ds_read2_b64 v[158:161], v4 offset0:32 offset1:48
	s_waitcnt lgkmcnt(3)
	v_pk_mul_f32 v[154:155], v[10:11], v[14:15]
	v_mul_f32_e32 v10, v10, v15
	v_sub_f32_e32 v20, v154, v155
	s_waitcnt lgkmcnt(2)
	v_mul_f32_e32 v20, v146, v20
	v_fmac_f32_e32 v10, v11, v14
	v_fma_f32 v10, -v147, v10, v20
	v_add_f32_e32 v9, v9, v10
	v_pk_mul_f32 v[10:11], v[12:13], v[16:17]
	ds_read_b128 v[154:157], v83 offset:17264
	v_sub_f32_e32 v10, v10, v11
	v_mul_f32_e32 v11, v12, v17
	v_mul_f32_e32 v10, v148, v10
	v_fmac_f32_e32 v11, v13, v16
	v_fma_f32 v10, -v149, v11, v10
	v_add_f32_e32 v9, v9, v10
	s_waitcnt lgkmcnt(1)
	v_pk_mul_f32 v[10:11], v[150:151], v[158:159]
	v_mul_f32_e32 v79, v152, v161
	v_sub_f32_e32 v10, v10, v11
	v_mul_f32_e32 v11, v150, v159
	s_waitcnt lgkmcnt(0)
	v_mul_f32_e32 v10, v154, v10
	v_fmac_f32_e32 v11, v151, v158
	v_fma_f32 v10, -v155, v11, v10
	v_add_f32_e32 v9, v9, v10
	v_pk_mul_f32 v[10:11], v[152:153], v[160:161]
	v_fmac_f32_e32 v79, v153, v160
	v_sub_f32_e32 v10, v10, v11
	v_mul_f32_e32 v20, v156, v10
	ds_read_b128 v[10:13], v96 offset:384
	ds_read2_b64 v[14:17], v4 offset0:64 offset1:80
	ds_read_b128 v[146:149], v83 offset:17280
	ds_read_b128 v[150:153], v96 offset:400
	v_fma_f32 v20, -v157, v79, v20
	v_add_f32_e32 v9, v9, v20
	ds_read2_b64 v[158:161], v4 offset0:96 offset1:112
	s_waitcnt lgkmcnt(3)
	v_pk_mul_f32 v[154:155], v[10:11], v[14:15]
	v_mul_f32_e32 v10, v10, v15
	v_sub_f32_e32 v20, v154, v155
	s_waitcnt lgkmcnt(2)
	v_mul_f32_e32 v20, v146, v20
	v_fmac_f32_e32 v10, v11, v14
	v_fma_f32 v10, -v147, v10, v20
	v_add_f32_e32 v9, v9, v10
	v_pk_mul_f32 v[10:11], v[12:13], v[16:17]
	ds_read_b128 v[154:157], v83 offset:17296
	v_sub_f32_e32 v10, v10, v11
	v_mul_f32_e32 v11, v12, v17
	v_mul_f32_e32 v10, v148, v10
	v_fmac_f32_e32 v11, v13, v16
	v_fma_f32 v10, -v149, v11, v10
	v_add_f32_e32 v9, v9, v10
	s_waitcnt lgkmcnt(1)
	v_pk_mul_f32 v[10:11], v[150:151], v[158:159]
	s_nop 0
	v_sub_f32_e32 v10, v10, v11
	v_mul_f32_e32 v11, v150, v159
	s_waitcnt lgkmcnt(0)
	v_mul_f32_e32 v10, v154, v10
	v_fmac_f32_e32 v11, v151, v158
	v_fma_f32 v10, -v155, v11, v10
	v_add_f32_e32 v9, v9, v10
	v_pk_mul_f32 v[10:11], v[152:153], v[160:161]
	s_nop 0
	v_sub_f32_e32 v10, v10, v11
	v_mul_f32_e32 v11, v152, v161
	v_mul_f32_e32 v10, v156, v10
	v_fmac_f32_e32 v11, v153, v160
	v_fma_f32 v14, -v157, v11, v10
	ds_read_b128 v[10:13], v96 offset:416
	v_add_f32_e32 v9, v9, v14
	ds_read2_b64 v[14:17], v4 offset0:128 offset1:144
	ds_read_b128 v[146:149], v83 offset:17312
	ds_read_b128 v[150:153], v96 offset:432
	s_waitcnt lgkmcnt(3)
	v_mov_b32_e32 v155, v12
	s_waitcnt lgkmcnt(2)
	v_mov_b32_e32 v157, v16
	v_mov_b32_e32 v12, v11
	v_mov_b32_e32 v16, v15
	v_mov_b32_e32 v154, v10
	v_mov_b32_e32 v156, v14
	v_pk_mul_f32 v[10:11], v[12:13], v[16:17]
	s_nop 0
	v_pk_fma_f32 v[14:15], v[154:155], v[156:157], v[10:11] neg_lo:[0,0,1] neg_hi:[0,0,1]
	v_pk_mul_f32 v[10:11], v[12:13], v[156:157]
	s_nop 0
	v_pk_fma_f32 v[16:17], v[154:155], v[16:17], v[10:11]
	s_waitcnt lgkmcnt(1)
	v_mov_b32_e32 v155, v148
	v_mov_b32_e32 v148, v147
	v_mov_b32_e32 v154, v146
	v_pk_mul_f32 v[16:17], v[148:149], v[16:17]
	ds_read_b128 v[10:13], v83 offset:17328
	v_pk_fma_f32 v[146:147], v[154:155], v[14:15], v[16:17] neg_lo:[0,0,1] neg_hi:[0,0,1]
	ds_read2_b64 v[14:17], v4 offset0:160 offset1:176
	v_add_f32_e32 v9, v9, v146
	v_add_f32_e32 v9, v9, v147
	s_waitcnt lgkmcnt(2)
	v_mov_b32_e32 v147, v152
	v_mov_b32_e32 v152, v151
	s_waitcnt lgkmcnt(0)
	v_mov_b32_e32 v149, v16
	v_mov_b32_e32 v16, v15
	v_mov_b32_e32 v146, v150
	v_mov_b32_e32 v148, v14
	v_pk_mul_f32 v[14:15], v[152:153], v[16:17]
	s_nop 0
	v_pk_fma_f32 v[14:15], v[146:147], v[148:149], v[14:15] neg_lo:[0,0,1] neg_hi:[0,0,1]
	v_pk_mul_f32 v[148:149], v[152:153], v[148:149]
	s_nop 0
	v_pk_fma_f32 v[16:17], v[146:147], v[16:17], v[148:149]
	v_mov_b32_e32 v147, v12
	v_mov_b32_e32 v12, v11
	v_mov_b32_e32 v146, v10
	v_pk_mul_f32 v[10:11], v[12:13], v[16:17]
	s_nop 0
	v_pk_fma_f32 v[14:15], v[146:147], v[14:15], v[10:11] neg_lo:[0,0,1] neg_hi:[0,0,1]
	ds_read_b128 v[10:13], v96 offset:448
	v_add_f32_e32 v9, v9, v14
	v_add_f32_e32 v9, v9, v15
	ds_read2_b64 v[14:17], v4 offset0:192 offset1:208
	ds_read_b128 v[146:149], v83 offset:17344
	ds_read_b128 v[150:153], v96 offset:464
	s_waitcnt lgkmcnt(3)
	v_mov_b32_e32 v155, v12
	s_waitcnt lgkmcnt(2)
	v_mov_b32_e32 v157, v16
	v_mov_b32_e32 v12, v11
	v_mov_b32_e32 v16, v15
	v_mov_b32_e32 v154, v10
	v_mov_b32_e32 v156, v14
	v_pk_mul_f32 v[10:11], v[12:13], v[16:17]
	s_nop 0
	v_pk_fma_f32 v[14:15], v[154:155], v[156:157], v[10:11] neg_lo:[0,0,1] neg_hi:[0,0,1]
	v_pk_mul_f32 v[10:11], v[12:13], v[156:157]
	s_nop 0
	v_pk_fma_f32 v[16:17], v[154:155], v[16:17], v[10:11]
	s_waitcnt lgkmcnt(1)
	v_mov_b32_e32 v155, v148
	v_mov_b32_e32 v148, v147
	v_mov_b32_e32 v154, v146
	v_pk_mul_f32 v[16:17], v[148:149], v[16:17]
	ds_read_b128 v[10:13], v83 offset:17360
	v_pk_fma_f32 v[146:147], v[154:155], v[14:15], v[16:17] neg_lo:[0,0,1] neg_hi:[0,0,1]
	ds_read2_b64 v[14:17], v4 offset0:224 offset1:240
	v_add_f32_e32 v9, v9, v146
	v_add_f32_e32 v9, v9, v147
	s_waitcnt lgkmcnt(2)
	v_mov_b32_e32 v147, v152
	v_mov_b32_e32 v152, v151
	s_waitcnt lgkmcnt(0)
	v_mov_b32_e32 v149, v16
	v_mov_b32_e32 v16, v15
	v_mov_b32_e32 v146, v150
	v_mov_b32_e32 v148, v14
	v_pk_mul_f32 v[14:15], v[152:153], v[16:17]
	s_nop 0
	v_pk_fma_f32 v[14:15], v[146:147], v[148:149], v[14:15] neg_lo:[0,0,1] neg_hi:[0,0,1]
	v_pk_mul_f32 v[148:149], v[152:153], v[148:149]
	s_nop 0
	v_pk_fma_f32 v[16:17], v[146:147], v[16:17], v[148:149]
	v_mov_b32_e32 v147, v12
	v_mov_b32_e32 v12, v11
	v_mov_b32_e32 v146, v10
	v_pk_mul_f32 v[10:11], v[12:13], v[16:17]
	s_nop 0
	v_pk_fma_f32 v[14:15], v[146:147], v[14:15], v[10:11] neg_lo:[0,0,1] neg_hi:[0,0,1]
	ds_read_b128 v[10:13], v96 offset:480
	v_add_f32_e32 v9, v9, v14
	v_add_f32_e32 v9, v9, v15
	ds_read2_b64 v[14:17], v8 offset1:16
	ds_read_b128 v[146:149], v83 offset:17376
	ds_read_b128 v[150:153], v96 offset:496
	s_waitcnt lgkmcnt(3)
	v_mov_b32_e32 v155, v12
	s_waitcnt lgkmcnt(2)
	v_mov_b32_e32 v157, v16
	v_mov_b32_e32 v12, v11
	v_mov_b32_e32 v16, v15
	v_mov_b32_e32 v154, v10
	v_mov_b32_e32 v156, v14
	v_pk_mul_f32 v[10:11], v[12:13], v[16:17]
	s_nop 0
	v_pk_fma_f32 v[14:15], v[154:155], v[156:157], v[10:11] neg_lo:[0,0,1] neg_hi:[0,0,1]
	v_pk_mul_f32 v[10:11], v[12:13], v[156:157]
	s_nop 0
	v_pk_fma_f32 v[16:17], v[154:155], v[16:17], v[10:11]
	s_waitcnt lgkmcnt(1)
	v_mov_b32_e32 v155, v148
	v_mov_b32_e32 v148, v147
	v_mov_b32_e32 v154, v146
	v_pk_mul_f32 v[16:17], v[148:149], v[16:17]
	ds_read_b128 v[10:13], v83 offset:17392
	v_pk_fma_f32 v[146:147], v[154:155], v[14:15], v[16:17] neg_lo:[0,0,1] neg_hi:[0,0,1]
	ds_read2_b64 v[14:17], v8 offset0:32 offset1:48
	v_add_f32_e32 v9, v9, v146
	v_add_f32_e32 v9, v9, v147
	s_waitcnt lgkmcnt(2)
	v_mov_b32_e32 v147, v152
	v_mov_b32_e32 v152, v151
	s_waitcnt lgkmcnt(0)
	v_mov_b32_e32 v149, v16
	v_mov_b32_e32 v16, v15
	v_mov_b32_e32 v146, v150
	v_mov_b32_e32 v148, v14
	v_pk_mul_f32 v[14:15], v[152:153], v[16:17]
	s_nop 0
	v_pk_fma_f32 v[14:15], v[146:147], v[148:149], v[14:15] neg_lo:[0,0,1] neg_hi:[0,0,1]
	v_pk_mul_f32 v[148:149], v[152:153], v[148:149]
	s_nop 0
	v_pk_fma_f32 v[16:17], v[146:147], v[16:17], v[148:149]
	v_mov_b32_e32 v147, v12
	v_mov_b32_e32 v12, v11
	v_mov_b32_e32 v146, v10
	v_pk_mul_f32 v[10:11], v[12:13], v[16:17]
	s_nop 0
	v_pk_fma_f32 v[10:11], v[146:147], v[14:15], v[10:11] neg_lo:[0,0,1] neg_hi:[0,0,1]
	s_nop 0
	v_add_f32_e32 v9, v9, v10
	v_add_f32_e32 v9, v9, v11
	s_and_saveexec_b64 s[68:69], s[62:63]
	s_cbranch_execz .LBB0_91
	global_load_dword v10, v[2:3], off nt
	s_waitcnt vmcnt(0)
	v_add_f32_e32 v9, v9, v10
.LBB0_91:
	s_or_b64 exec, exec, s[68:69]
	ds_write_b32 v116, v9 offset:33280
	ds_read_b128 v[10:13], v99
	ds_read_b128 v[14:17], v99 offset:16
	ds_read_b128 v[146:149], v99 offset:32
	ds_read_b128 v[150:153], v99 offset:48
	ds_read2_b64 v[154:157], v7 offset0:64 offset1:80
	ds_read_b128 v[158:161], v83 offset:16896
	ds_read_b128 v[162:165], v83 offset:16912
	ds_read_b128 v[166:169], v83 offset:16928
	ds_read_b128 v[174:177], v83 offset:16944
	s_waitcnt lgkmcnt(4)
	v_pk_mul_f32 v[170:171], v[10:11], v[154:155]
	v_mul_f32_e32 v10, v10, v155
	v_sub_f32_e32 v9, v170, v171
	s_waitcnt lgkmcnt(3)
	v_mul_f32_e32 v9, v158, v9
	v_fmac_f32_e32 v10, v11, v154
	ds_read2_b64 v[178:181], v7 offset0:96 offset1:112
	v_fma_f32 v9, -v159, v10, v9
	v_pk_mul_f32 v[10:11], v[12:13], v[156:157]
	v_add_f32_e32 v9, 0, v9
	v_sub_f32_e32 v10, v10, v11
	v_mul_f32_e32 v11, v12, v157
	v_mul_f32_e32 v10, v160, v10
	v_fmac_f32_e32 v11, v13, v156
	v_fma_f32 v10, -v161, v11, v10
	v_add_f32_e32 v9, v9, v10
	s_waitcnt lgkmcnt(0)
	v_pk_mul_f32 v[10:11], v[14:15], v[178:179]
	s_nop 0
	v_sub_f32_e32 v10, v10, v11
	v_mul_f32_e32 v11, v14, v179
	v_mul_f32_e32 v10, v162, v10
	v_fmac_f32_e32 v11, v15, v178
	v_fma_f32 v10, -v163, v11, v10
	v_add_f32_e32 v9, v9, v10
	v_pk_mul_f32 v[10:11], v[16:17], v[180:181]
	v_mul_f32_e32 v15, v16, v181
	v_sub_f32_e32 v10, v10, v11
	v_mul_f32_e32 v14, v164, v10
	ds_read2_b64 v[10:13], v7 offset0:128 offset1:144
	v_fmac_f32_e32 v15, v17, v180
	v_fma_f32 v14, -v165, v15, v14
	v_add_f32_e32 v9, v9, v14
	s_waitcnt lgkmcnt(0)
	v_pk_mul_f32 v[14:15], v[146:147], v[10:11]
	s_nop 0
	v_sub_f32_e32 v14, v14, v15
	v_mul_f32_e32 v11, v146, v11
	v_mul_f32_e32 v14, v166, v14
	v_fmac_f32_e32 v11, v147, v10
	v_fma_f32 v10, -v167, v11, v14
	ds_read2_b64 v[14:17], v7 offset0:160 offset1:176
	v_add_f32_e32 v9, v9, v10
	v_pk_mul_f32 v[10:11], v[148:149], v[12:13]
	s_waitcnt lgkmcnt(0)
	v_mul_f32_e32 v79, v152, v17
	v_sub_f32_e32 v10, v10, v11
	v_mul_f32_e32 v11, v148, v13
	v_mul_f32_e32 v10, v168, v10
	v_fmac_f32_e32 v11, v149, v12
	v_fma_f32 v10, -v169, v11, v10
	v_add_f32_e32 v9, v9, v10
	v_pk_mul_f32 v[10:11], v[150:151], v[14:15]
	v_fmac_f32_e32 v79, v153, v16
	v_sub_f32_e32 v10, v10, v11
	v_mul_f32_e32 v11, v150, v15
	v_mul_f32_e32 v10, v174, v10
	v_fmac_f32_e32 v11, v151, v14
	v_fma_f32 v10, -v175, v11, v10
	v_add_f32_e32 v9, v9, v10
	v_pk_mul_f32 v[10:11], v[152:153], v[16:17]
	s_nop 0
	v_sub_f32_e32 v10, v10, v11
	v_mul_f32_e32 v20, v176, v10
	ds_read_b128 v[10:13], v99 offset:64
	ds_read2_b64 v[14:17], v7 offset0:192 offset1:208
	ds_read_b128 v[146:149], v83 offset:16960
	ds_read_b128 v[150:153], v99 offset:80
	v_fma_f32 v20, -v177, v79, v20
	v_add_f32_e32 v9, v9, v20
	ds_read2_b64 v[158:161], v7 offset0:224 offset1:240
	s_waitcnt lgkmcnt(3)
	v_pk_mul_f32 v[154:155], v[10:11], v[14:15]
	v_mul_f32_e32 v10, v10, v15
	v_sub_f32_e32 v20, v154, v155
	s_waitcnt lgkmcnt(2)
	v_mul_f32_e32 v20, v146, v20
	v_fmac_f32_e32 v10, v11, v14
	v_fma_f32 v10, -v147, v10, v20
	v_add_f32_e32 v9, v9, v10
	v_pk_mul_f32 v[10:11], v[12:13], v[16:17]
	ds_read_b128 v[154:157], v83 offset:16976
	v_sub_f32_e32 v10, v10, v11
	v_mul_f32_e32 v11, v12, v17
	v_mul_f32_e32 v10, v148, v10
	v_fmac_f32_e32 v11, v13, v16
	v_fma_f32 v10, -v149, v11, v10
	v_add_f32_e32 v9, v9, v10
	s_waitcnt lgkmcnt(1)
	v_pk_mul_f32 v[10:11], v[150:151], v[158:159]
	v_mul_f32_e32 v79, v152, v161
	v_sub_f32_e32 v10, v10, v11
	v_mul_f32_e32 v11, v150, v159
	s_waitcnt lgkmcnt(0)
	v_mul_f32_e32 v10, v154, v10
	v_fmac_f32_e32 v11, v151, v158
	v_fma_f32 v10, -v155, v11, v10
	v_add_f32_e32 v9, v9, v10
	v_pk_mul_f32 v[10:11], v[152:153], v[160:161]
	v_fmac_f32_e32 v79, v153, v160
	v_sub_f32_e32 v10, v10, v11
	v_mul_f32_e32 v20, v156, v10
	ds_read_b128 v[10:13], v99 offset:96
	ds_read2_b64 v[14:17], v5 offset1:16
	ds_read_b128 v[146:149], v83 offset:16992
	ds_read_b128 v[150:153], v99 offset:112
	v_fma_f32 v20, -v157, v79, v20
	v_add_f32_e32 v9, v9, v20
	ds_read2_b64 v[158:161], v5 offset0:32 offset1:48
	s_waitcnt lgkmcnt(3)
	v_pk_mul_f32 v[154:155], v[10:11], v[14:15]
	v_mul_f32_e32 v10, v10, v15
	v_sub_f32_e32 v20, v154, v155
	s_waitcnt lgkmcnt(2)
	v_mul_f32_e32 v20, v146, v20
	v_fmac_f32_e32 v10, v11, v14
	v_fma_f32 v10, -v147, v10, v20
	v_add_f32_e32 v9, v9, v10
	v_pk_mul_f32 v[10:11], v[12:13], v[16:17]
	ds_read_b128 v[154:157], v83 offset:17008
	v_sub_f32_e32 v10, v10, v11
	v_mul_f32_e32 v11, v12, v17
	v_mul_f32_e32 v10, v148, v10
	v_fmac_f32_e32 v11, v13, v16
	v_fma_f32 v10, -v149, v11, v10
	v_add_f32_e32 v9, v9, v10
	s_waitcnt lgkmcnt(1)
	v_pk_mul_f32 v[10:11], v[150:151], v[158:159]
	v_mul_f32_e32 v79, v152, v161
	v_sub_f32_e32 v10, v10, v11
	v_mul_f32_e32 v11, v150, v159
	s_waitcnt lgkmcnt(0)
	v_mul_f32_e32 v10, v154, v10
	v_fmac_f32_e32 v11, v151, v158
	v_fma_f32 v10, -v155, v11, v10
	v_add_f32_e32 v9, v9, v10
	v_pk_mul_f32 v[10:11], v[152:153], v[160:161]
	v_fmac_f32_e32 v79, v153, v160
	v_sub_f32_e32 v10, v10, v11
	v_mul_f32_e32 v20, v156, v10
	ds_read_b128 v[10:13], v99 offset:128
	ds_read2_b64 v[14:17], v5 offset0:64 offset1:80
	ds_read_b128 v[146:149], v83 offset:17024
	ds_read_b128 v[150:153], v99 offset:144
	v_fma_f32 v20, -v157, v79, v20
	v_add_f32_e32 v9, v9, v20
	ds_read2_b64 v[158:161], v5 offset0:96 offset1:112
	s_waitcnt lgkmcnt(3)
	v_pk_mul_f32 v[154:155], v[10:11], v[14:15]
	v_mul_f32_e32 v10, v10, v15
	v_sub_f32_e32 v20, v154, v155
	s_waitcnt lgkmcnt(2)
	v_mul_f32_e32 v20, v146, v20
	v_fmac_f32_e32 v10, v11, v14
	v_fma_f32 v10, -v147, v10, v20
	v_add_f32_e32 v9, v9, v10
	v_pk_mul_f32 v[10:11], v[12:13], v[16:17]
	ds_read_b128 v[154:157], v83 offset:17040
	v_sub_f32_e32 v10, v10, v11
	v_mul_f32_e32 v11, v12, v17
	v_mul_f32_e32 v10, v148, v10
	v_fmac_f32_e32 v11, v13, v16
	v_fma_f32 v10, -v149, v11, v10
	v_add_f32_e32 v9, v9, v10
	s_waitcnt lgkmcnt(1)
	v_pk_mul_f32 v[10:11], v[150:151], v[158:159]
	v_mul_f32_e32 v79, v152, v161
	v_sub_f32_e32 v10, v10, v11
	v_mul_f32_e32 v11, v150, v159
	s_waitcnt lgkmcnt(0)
	v_mul_f32_e32 v10, v154, v10
	v_fmac_f32_e32 v11, v151, v158
	v_fma_f32 v10, -v155, v11, v10
	v_add_f32_e32 v9, v9, v10
	v_pk_mul_f32 v[10:11], v[152:153], v[160:161]
	v_fmac_f32_e32 v79, v153, v160
	v_sub_f32_e32 v10, v10, v11
	v_mul_f32_e32 v20, v156, v10
	ds_read_b128 v[10:13], v99 offset:160
	ds_read2_b64 v[14:17], v5 offset0:128 offset1:144
	ds_read_b128 v[146:149], v83 offset:17056
	ds_read_b128 v[150:153], v99 offset:176
	v_fma_f32 v20, -v157, v79, v20
	v_add_f32_e32 v9, v9, v20
	ds_read2_b64 v[158:161], v5 offset0:160 offset1:176
	s_waitcnt lgkmcnt(3)
	v_pk_mul_f32 v[154:155], v[10:11], v[14:15]
	v_mul_f32_e32 v10, v10, v15
	v_sub_f32_e32 v20, v154, v155
	s_waitcnt lgkmcnt(2)
	v_mul_f32_e32 v20, v146, v20
	v_fmac_f32_e32 v10, v11, v14
	v_fma_f32 v10, -v147, v10, v20
	v_add_f32_e32 v9, v9, v10
	v_pk_mul_f32 v[10:11], v[12:13], v[16:17]
	ds_read_b128 v[154:157], v83 offset:17072
	v_sub_f32_e32 v10, v10, v11
	v_mul_f32_e32 v11, v12, v17
	v_mul_f32_e32 v10, v148, v10
	v_fmac_f32_e32 v11, v13, v16
	v_fma_f32 v10, -v149, v11, v10
	v_add_f32_e32 v9, v9, v10
	s_waitcnt lgkmcnt(1)
	v_pk_mul_f32 v[10:11], v[150:151], v[158:159]
	v_mul_f32_e32 v79, v152, v161
	v_sub_f32_e32 v10, v10, v11
	v_mul_f32_e32 v11, v150, v159
	s_waitcnt lgkmcnt(0)
	v_mul_f32_e32 v10, v154, v10
	v_fmac_f32_e32 v11, v151, v158
	v_fma_f32 v10, -v155, v11, v10
	v_add_f32_e32 v9, v9, v10
	v_pk_mul_f32 v[10:11], v[152:153], v[160:161]
	v_fmac_f32_e32 v79, v153, v160
	v_sub_f32_e32 v10, v10, v11
	v_mul_f32_e32 v20, v156, v10
	ds_read_b128 v[10:13], v99 offset:192
	ds_read2_b64 v[14:17], v5 offset0:192 offset1:208
	ds_read_b128 v[146:149], v83 offset:17088
	ds_read_b128 v[150:153], v99 offset:208
	v_fma_f32 v20, -v157, v79, v20
	v_add_f32_e32 v9, v9, v20
	ds_read2_b64 v[158:161], v5 offset0:224 offset1:240
	s_waitcnt lgkmcnt(3)
	v_pk_mul_f32 v[154:155], v[10:11], v[14:15]
	v_mul_f32_e32 v10, v10, v15
	v_sub_f32_e32 v20, v154, v155
	s_waitcnt lgkmcnt(2)
	v_mul_f32_e32 v20, v146, v20
	v_fmac_f32_e32 v10, v11, v14
	v_fma_f32 v10, -v147, v10, v20
	v_add_f32_e32 v9, v9, v10
	v_pk_mul_f32 v[10:11], v[12:13], v[16:17]
	ds_read_b128 v[154:157], v83 offset:17104
	v_sub_f32_e32 v10, v10, v11
	v_mul_f32_e32 v11, v12, v17
	v_mul_f32_e32 v10, v148, v10
	v_fmac_f32_e32 v11, v13, v16
	v_fma_f32 v10, -v149, v11, v10
	v_add_f32_e32 v9, v9, v10
	s_waitcnt lgkmcnt(1)
	v_pk_mul_f32 v[10:11], v[150:151], v[158:159]
	v_mul_f32_e32 v79, v152, v161
	v_sub_f32_e32 v10, v10, v11
	v_mul_f32_e32 v11, v150, v159
	s_waitcnt lgkmcnt(0)
	v_mul_f32_e32 v10, v154, v10
	v_fmac_f32_e32 v11, v151, v158
	v_fma_f32 v10, -v155, v11, v10
	v_add_f32_e32 v9, v9, v10
	v_pk_mul_f32 v[10:11], v[152:153], v[160:161]
	v_fmac_f32_e32 v79, v153, v160
	v_sub_f32_e32 v10, v10, v11
	v_mul_f32_e32 v20, v156, v10
	ds_read_b128 v[10:13], v99 offset:224
	ds_read2_b64 v[14:17], v6 offset1:16
	ds_read_b128 v[146:149], v83 offset:17120
	ds_read_b128 v[150:153], v99 offset:240
	v_fma_f32 v20, -v157, v79, v20
	v_add_f32_e32 v9, v9, v20
	ds_read2_b64 v[158:161], v6 offset0:32 offset1:48
	s_waitcnt lgkmcnt(3)
	v_pk_mul_f32 v[154:155], v[10:11], v[14:15]
	v_mul_f32_e32 v10, v10, v15
	v_sub_f32_e32 v20, v154, v155
	s_waitcnt lgkmcnt(2)
	v_mul_f32_e32 v20, v146, v20
	v_fmac_f32_e32 v10, v11, v14
	v_fma_f32 v10, -v147, v10, v20
	v_add_f32_e32 v9, v9, v10
	v_pk_mul_f32 v[10:11], v[12:13], v[16:17]
	ds_read_b128 v[154:157], v83 offset:17136
	v_sub_f32_e32 v10, v10, v11
	v_mul_f32_e32 v11, v12, v17
	v_mul_f32_e32 v10, v148, v10
	v_fmac_f32_e32 v11, v13, v16
	v_fma_f32 v10, -v149, v11, v10
	v_add_f32_e32 v9, v9, v10
	s_waitcnt lgkmcnt(1)
	v_pk_mul_f32 v[10:11], v[150:151], v[158:159]
	v_mul_f32_e32 v79, v152, v161
	v_sub_f32_e32 v10, v10, v11
	v_mul_f32_e32 v11, v150, v159
	s_waitcnt lgkmcnt(0)
	v_mul_f32_e32 v10, v154, v10
	v_fmac_f32_e32 v11, v151, v158
	v_fma_f32 v10, -v155, v11, v10
	v_add_f32_e32 v9, v9, v10
	v_pk_mul_f32 v[10:11], v[152:153], v[160:161]
	v_fmac_f32_e32 v79, v153, v160
	v_sub_f32_e32 v10, v10, v11
	v_mul_f32_e32 v20, v156, v10
	ds_read_b128 v[10:13], v99 offset:256
	ds_read2_b64 v[14:17], v6 offset0:64 offset1:80
	ds_read_b128 v[146:149], v83 offset:17152
	ds_read_b128 v[150:153], v99 offset:272
	v_fma_f32 v20, -v157, v79, v20
	v_add_f32_e32 v9, v9, v20
	ds_read2_b64 v[158:161], v6 offset0:96 offset1:112
	s_waitcnt lgkmcnt(3)
	v_pk_mul_f32 v[154:155], v[10:11], v[14:15]
	v_mul_f32_e32 v10, v10, v15
	v_sub_f32_e32 v20, v154, v155
	s_waitcnt lgkmcnt(2)
	v_mul_f32_e32 v20, v146, v20
	v_fmac_f32_e32 v10, v11, v14
	v_fma_f32 v10, -v147, v10, v20
	v_add_f32_e32 v9, v9, v10
	v_pk_mul_f32 v[10:11], v[12:13], v[16:17]
	ds_read_b128 v[154:157], v83 offset:17168
	v_sub_f32_e32 v10, v10, v11
	v_mul_f32_e32 v11, v12, v17
	v_mul_f32_e32 v10, v148, v10
	v_fmac_f32_e32 v11, v13, v16
	v_fma_f32 v10, -v149, v11, v10
	v_add_f32_e32 v9, v9, v10
	s_waitcnt lgkmcnt(1)
	v_pk_mul_f32 v[10:11], v[150:151], v[158:159]
	v_mul_f32_e32 v79, v152, v161
	v_sub_f32_e32 v10, v10, v11
	v_mul_f32_e32 v11, v150, v159
	s_waitcnt lgkmcnt(0)
	v_mul_f32_e32 v10, v154, v10
	v_fmac_f32_e32 v11, v151, v158
	v_fma_f32 v10, -v155, v11, v10
	v_add_f32_e32 v9, v9, v10
	v_pk_mul_f32 v[10:11], v[152:153], v[160:161]
	v_fmac_f32_e32 v79, v153, v160
	v_sub_f32_e32 v10, v10, v11
	v_mul_f32_e32 v20, v156, v10
	ds_read_b128 v[10:13], v99 offset:288
	ds_read2_b64 v[14:17], v6 offset0:128 offset1:144
	ds_read_b128 v[146:149], v83 offset:17184
	ds_read_b128 v[150:153], v99 offset:304
	v_fma_f32 v20, -v157, v79, v20
	v_add_f32_e32 v9, v9, v20
	ds_read2_b64 v[158:161], v6 offset0:160 offset1:176
	s_waitcnt lgkmcnt(3)
	v_pk_mul_f32 v[154:155], v[10:11], v[14:15]
	v_mul_f32_e32 v10, v10, v15
	v_sub_f32_e32 v20, v154, v155
	s_waitcnt lgkmcnt(2)
	v_mul_f32_e32 v20, v146, v20
	v_fmac_f32_e32 v10, v11, v14
	v_fma_f32 v10, -v147, v10, v20
	v_add_f32_e32 v9, v9, v10
	v_pk_mul_f32 v[10:11], v[12:13], v[16:17]
	ds_read_b128 v[154:157], v83 offset:17200
	v_sub_f32_e32 v10, v10, v11
	v_mul_f32_e32 v11, v12, v17
	v_mul_f32_e32 v10, v148, v10
	v_fmac_f32_e32 v11, v13, v16
	v_fma_f32 v10, -v149, v11, v10
	v_add_f32_e32 v9, v9, v10
	s_waitcnt lgkmcnt(1)
	v_pk_mul_f32 v[10:11], v[150:151], v[158:159]
	v_mul_f32_e32 v79, v152, v161
	v_sub_f32_e32 v10, v10, v11
	v_mul_f32_e32 v11, v150, v159
	s_waitcnt lgkmcnt(0)
	v_mul_f32_e32 v10, v154, v10
	v_fmac_f32_e32 v11, v151, v158
	v_fma_f32 v10, -v155, v11, v10
	v_add_f32_e32 v9, v9, v10
	v_pk_mul_f32 v[10:11], v[152:153], v[160:161]
	v_fmac_f32_e32 v79, v153, v160
	v_sub_f32_e32 v10, v10, v11
	v_mul_f32_e32 v20, v156, v10
	ds_read_b128 v[10:13], v99 offset:320
	ds_read2_b64 v[14:17], v6 offset0:192 offset1:208
	ds_read_b128 v[146:149], v83 offset:17216
	ds_read_b128 v[150:153], v99 offset:336
	v_fma_f32 v20, -v157, v79, v20
	v_add_f32_e32 v9, v9, v20
	ds_read2_b64 v[158:161], v6 offset0:224 offset1:240
	s_waitcnt lgkmcnt(3)
	v_pk_mul_f32 v[154:155], v[10:11], v[14:15]
	v_mul_f32_e32 v10, v10, v15
	v_sub_f32_e32 v20, v154, v155
	s_waitcnt lgkmcnt(2)
	v_mul_f32_e32 v20, v146, v20
	v_fmac_f32_e32 v10, v11, v14
	v_fma_f32 v10, -v147, v10, v20
	v_add_f32_e32 v9, v9, v10
	v_pk_mul_f32 v[10:11], v[12:13], v[16:17]
	ds_read_b128 v[154:157], v83 offset:17232
	v_sub_f32_e32 v10, v10, v11
	v_mul_f32_e32 v11, v12, v17
	v_mul_f32_e32 v10, v148, v10
	v_fmac_f32_e32 v11, v13, v16
	v_fma_f32 v10, -v149, v11, v10
	v_add_f32_e32 v9, v9, v10
	s_waitcnt lgkmcnt(1)
	v_pk_mul_f32 v[10:11], v[150:151], v[158:159]
	v_mul_f32_e32 v79, v152, v161
	v_sub_f32_e32 v10, v10, v11
	v_mul_f32_e32 v11, v150, v159
	s_waitcnt lgkmcnt(0)
	v_mul_f32_e32 v10, v154, v10
	v_fmac_f32_e32 v11, v151, v158
	v_fma_f32 v10, -v155, v11, v10
	v_add_f32_e32 v9, v9, v10
	v_pk_mul_f32 v[10:11], v[152:153], v[160:161]
	v_fmac_f32_e32 v79, v153, v160
	v_sub_f32_e32 v10, v10, v11
	v_mul_f32_e32 v20, v156, v10
	ds_read_b128 v[10:13], v99 offset:352
	ds_read2_b64 v[14:17], v4 offset1:16
	ds_read_b128 v[146:149], v83 offset:17248
	ds_read_b128 v[150:153], v99 offset:368
	v_fma_f32 v20, -v157, v79, v20
	v_add_f32_e32 v9, v9, v20
	ds_read2_b64 v[158:161], v4 offset0:32 offset1:48
	s_waitcnt lgkmcnt(3)
	v_pk_mul_f32 v[154:155], v[10:11], v[14:15]
	v_mul_f32_e32 v10, v10, v15
	v_sub_f32_e32 v20, v154, v155
	s_waitcnt lgkmcnt(2)
	v_mul_f32_e32 v20, v146, v20
	v_fmac_f32_e32 v10, v11, v14
	v_fma_f32 v10, -v147, v10, v20
	v_add_f32_e32 v9, v9, v10
	v_pk_mul_f32 v[10:11], v[12:13], v[16:17]
	ds_read_b128 v[154:157], v83 offset:17264
	v_sub_f32_e32 v10, v10, v11
	v_mul_f32_e32 v11, v12, v17
	v_mul_f32_e32 v10, v148, v10
	v_fmac_f32_e32 v11, v13, v16
	v_fma_f32 v10, -v149, v11, v10
	v_add_f32_e32 v9, v9, v10
	s_waitcnt lgkmcnt(1)
	v_pk_mul_f32 v[10:11], v[150:151], v[158:159]
	v_mul_f32_e32 v79, v152, v161
	v_sub_f32_e32 v10, v10, v11
	v_mul_f32_e32 v11, v150, v159
	s_waitcnt lgkmcnt(0)
	v_mul_f32_e32 v10, v154, v10
	v_fmac_f32_e32 v11, v151, v158
	v_fma_f32 v10, -v155, v11, v10
	v_add_f32_e32 v9, v9, v10
	v_pk_mul_f32 v[10:11], v[152:153], v[160:161]
	v_fmac_f32_e32 v79, v153, v160
	v_sub_f32_e32 v10, v10, v11
	v_mul_f32_e32 v20, v156, v10
	ds_read_b128 v[10:13], v99 offset:384
	ds_read2_b64 v[14:17], v4 offset0:64 offset1:80
	ds_read_b128 v[146:149], v83 offset:17280
	ds_read_b128 v[150:153], v99 offset:400
	v_fma_f32 v20, -v157, v79, v20
	v_add_f32_e32 v9, v9, v20
	ds_read2_b64 v[158:161], v4 offset0:96 offset1:112
	s_waitcnt lgkmcnt(3)
	v_pk_mul_f32 v[154:155], v[10:11], v[14:15]
	v_mul_f32_e32 v10, v10, v15
	v_sub_f32_e32 v20, v154, v155
	s_waitcnt lgkmcnt(2)
	v_mul_f32_e32 v20, v146, v20
	v_fmac_f32_e32 v10, v11, v14
	v_fma_f32 v10, -v147, v10, v20
	v_add_f32_e32 v9, v9, v10
	v_pk_mul_f32 v[10:11], v[12:13], v[16:17]
	ds_read_b128 v[154:157], v83 offset:17296
	v_sub_f32_e32 v10, v10, v11
	v_mul_f32_e32 v11, v12, v17
	v_mul_f32_e32 v10, v148, v10
	v_fmac_f32_e32 v11, v13, v16
	v_fma_f32 v10, -v149, v11, v10
	v_add_f32_e32 v9, v9, v10
	s_waitcnt lgkmcnt(1)
	v_pk_mul_f32 v[10:11], v[150:151], v[158:159]
	s_nop 0
	v_sub_f32_e32 v10, v10, v11
	v_mul_f32_e32 v11, v150, v159
	s_waitcnt lgkmcnt(0)
	v_mul_f32_e32 v10, v154, v10
	v_fmac_f32_e32 v11, v151, v158
	v_fma_f32 v10, -v155, v11, v10
	v_add_f32_e32 v9, v9, v10
	v_pk_mul_f32 v[10:11], v[152:153], v[160:161]
	s_nop 0
	v_sub_f32_e32 v10, v10, v11
	v_mul_f32_e32 v11, v152, v161
	v_mul_f32_e32 v10, v156, v10
	v_fmac_f32_e32 v11, v153, v160
	v_fma_f32 v14, -v157, v11, v10
	ds_read_b128 v[10:13], v99 offset:416
	v_add_f32_e32 v9, v9, v14
	ds_read2_b64 v[14:17], v4 offset0:128 offset1:144
	ds_read_b128 v[146:149], v83 offset:17312
	ds_read_b128 v[150:153], v99 offset:432
	s_waitcnt lgkmcnt(3)
	v_mov_b32_e32 v155, v12
	s_waitcnt lgkmcnt(2)
	v_mov_b32_e32 v157, v16
	v_mov_b32_e32 v12, v11
	v_mov_b32_e32 v16, v15
	v_mov_b32_e32 v154, v10
	v_mov_b32_e32 v156, v14
	v_pk_mul_f32 v[10:11], v[12:13], v[16:17]
	s_nop 0
	v_pk_fma_f32 v[14:15], v[154:155], v[156:157], v[10:11] neg_lo:[0,0,1] neg_hi:[0,0,1]
	v_pk_mul_f32 v[10:11], v[12:13], v[156:157]
	s_nop 0
	v_pk_fma_f32 v[16:17], v[154:155], v[16:17], v[10:11]
	s_waitcnt lgkmcnt(1)
	v_mov_b32_e32 v155, v148
	v_mov_b32_e32 v148, v147
	v_mov_b32_e32 v154, v146
	v_pk_mul_f32 v[16:17], v[148:149], v[16:17]
	ds_read_b128 v[10:13], v83 offset:17328
	v_pk_fma_f32 v[146:147], v[154:155], v[14:15], v[16:17] neg_lo:[0,0,1] neg_hi:[0,0,1]
	ds_read2_b64 v[14:17], v4 offset0:160 offset1:176
	v_add_f32_e32 v9, v9, v146
	v_add_f32_e32 v9, v9, v147
	s_waitcnt lgkmcnt(2)
	v_mov_b32_e32 v147, v152
	v_mov_b32_e32 v152, v151
	s_waitcnt lgkmcnt(0)
	v_mov_b32_e32 v149, v16
	v_mov_b32_e32 v16, v15
	v_mov_b32_e32 v146, v150
	v_mov_b32_e32 v148, v14
	v_pk_mul_f32 v[14:15], v[152:153], v[16:17]
	s_nop 0
	v_pk_fma_f32 v[14:15], v[146:147], v[148:149], v[14:15] neg_lo:[0,0,1] neg_hi:[0,0,1]
	v_pk_mul_f32 v[148:149], v[152:153], v[148:149]
	s_nop 0
	v_pk_fma_f32 v[16:17], v[146:147], v[16:17], v[148:149]
	v_mov_b32_e32 v147, v12
	v_mov_b32_e32 v12, v11
	v_mov_b32_e32 v146, v10
	v_pk_mul_f32 v[10:11], v[12:13], v[16:17]
	s_nop 0
	v_pk_fma_f32 v[14:15], v[146:147], v[14:15], v[10:11] neg_lo:[0,0,1] neg_hi:[0,0,1]
	ds_read_b128 v[10:13], v99 offset:448
	v_add_f32_e32 v9, v9, v14
	v_add_f32_e32 v9, v9, v15
	ds_read2_b64 v[14:17], v4 offset0:192 offset1:208
	ds_read_b128 v[146:149], v83 offset:17344
	ds_read_b128 v[150:153], v99 offset:464
	s_waitcnt lgkmcnt(3)
	v_mov_b32_e32 v155, v12
	s_waitcnt lgkmcnt(2)
	v_mov_b32_e32 v157, v16
	v_mov_b32_e32 v12, v11
	v_mov_b32_e32 v16, v15
	v_mov_b32_e32 v154, v10
	v_mov_b32_e32 v156, v14
	v_pk_mul_f32 v[10:11], v[12:13], v[16:17]
	s_nop 0
	v_pk_fma_f32 v[14:15], v[154:155], v[156:157], v[10:11] neg_lo:[0,0,1] neg_hi:[0,0,1]
	v_pk_mul_f32 v[10:11], v[12:13], v[156:157]
	s_nop 0
	v_pk_fma_f32 v[16:17], v[154:155], v[16:17], v[10:11]
	s_waitcnt lgkmcnt(1)
	v_mov_b32_e32 v155, v148
	v_mov_b32_e32 v148, v147
	v_mov_b32_e32 v154, v146
	v_pk_mul_f32 v[16:17], v[148:149], v[16:17]
	ds_read_b128 v[10:13], v83 offset:17360
	v_pk_fma_f32 v[146:147], v[154:155], v[14:15], v[16:17] neg_lo:[0,0,1] neg_hi:[0,0,1]
	ds_read2_b64 v[14:17], v4 offset0:224 offset1:240
	v_add_f32_e32 v9, v9, v146
	v_add_f32_e32 v9, v9, v147
	s_waitcnt lgkmcnt(2)
	v_mov_b32_e32 v147, v152
	v_mov_b32_e32 v152, v151
	s_waitcnt lgkmcnt(0)
	v_mov_b32_e32 v149, v16
	v_mov_b32_e32 v16, v15
	v_mov_b32_e32 v146, v150
	v_mov_b32_e32 v148, v14
	v_pk_mul_f32 v[14:15], v[152:153], v[16:17]
	s_nop 0
	v_pk_fma_f32 v[14:15], v[146:147], v[148:149], v[14:15] neg_lo:[0,0,1] neg_hi:[0,0,1]
	v_pk_mul_f32 v[148:149], v[152:153], v[148:149]
	s_nop 0
	v_pk_fma_f32 v[16:17], v[146:147], v[16:17], v[148:149]
	v_mov_b32_e32 v147, v12
	v_mov_b32_e32 v12, v11
	v_mov_b32_e32 v146, v10
	v_pk_mul_f32 v[10:11], v[12:13], v[16:17]
	s_nop 0
	v_pk_fma_f32 v[14:15], v[146:147], v[14:15], v[10:11] neg_lo:[0,0,1] neg_hi:[0,0,1]
	ds_read_b128 v[10:13], v99 offset:480
	v_add_f32_e32 v9, v9, v14
	v_add_f32_e32 v9, v9, v15
	ds_read2_b64 v[14:17], v8 offset1:16
	ds_read_b128 v[146:149], v83 offset:17376
	ds_read_b128 v[150:153], v99 offset:496
	s_waitcnt lgkmcnt(3)
	v_mov_b32_e32 v155, v12
	s_waitcnt lgkmcnt(2)
	v_mov_b32_e32 v157, v16
	v_mov_b32_e32 v12, v11
	v_mov_b32_e32 v16, v15
	v_mov_b32_e32 v154, v10
	v_mov_b32_e32 v156, v14
	v_pk_mul_f32 v[10:11], v[12:13], v[16:17]
	s_nop 0
	v_pk_fma_f32 v[14:15], v[154:155], v[156:157], v[10:11] neg_lo:[0,0,1] neg_hi:[0,0,1]
	v_pk_mul_f32 v[10:11], v[12:13], v[156:157]
	s_nop 0
	v_pk_fma_f32 v[16:17], v[154:155], v[16:17], v[10:11]
	s_waitcnt lgkmcnt(1)
	v_mov_b32_e32 v155, v148
	v_mov_b32_e32 v148, v147
	v_mov_b32_e32 v154, v146
	v_pk_mul_f32 v[16:17], v[148:149], v[16:17]
	ds_read_b128 v[10:13], v83 offset:17392
	v_pk_fma_f32 v[146:147], v[154:155], v[14:15], v[16:17] neg_lo:[0,0,1] neg_hi:[0,0,1]
	ds_read2_b64 v[14:17], v8 offset0:32 offset1:48
	v_add_f32_e32 v9, v9, v146
	v_add_f32_e32 v9, v9, v147
	s_waitcnt lgkmcnt(2)
	v_mov_b32_e32 v147, v152
	v_mov_b32_e32 v152, v151
	s_waitcnt lgkmcnt(0)
	v_mov_b32_e32 v149, v16
	v_mov_b32_e32 v16, v15
	v_mov_b32_e32 v146, v150
	v_mov_b32_e32 v148, v14
	v_pk_mul_f32 v[14:15], v[152:153], v[16:17]
	s_nop 0
	v_pk_fma_f32 v[14:15], v[146:147], v[148:149], v[14:15] neg_lo:[0,0,1] neg_hi:[0,0,1]
	v_pk_mul_f32 v[148:149], v[152:153], v[148:149]
	s_nop 0
	v_pk_fma_f32 v[16:17], v[146:147], v[16:17], v[148:149]
	v_mov_b32_e32 v147, v12
	v_mov_b32_e32 v12, v11
	v_mov_b32_e32 v146, v10
	v_pk_mul_f32 v[10:11], v[12:13], v[16:17]
	s_nop 0
	v_pk_fma_f32 v[10:11], v[146:147], v[14:15], v[10:11] neg_lo:[0,0,1] neg_hi:[0,0,1]
	s_nop 0
	v_add_f32_e32 v9, v9, v10
	v_add_f32_e32 v9, v9, v11
	s_and_saveexec_b64 s[68:69], s[64:65]
	s_cbranch_execz .LBB0_93
	global_load_dword v10, v[2:3], off nt
	s_waitcnt vmcnt(0)
	v_add_f32_e32 v9, v9, v10
.LBB0_93:
	s_or_b64 exec, exec, s[68:69]
	ds_write_b32 v116, v9 offset:35328
	ds_read_b128 v[10:13], v102
	ds_read_b128 v[14:17], v102 offset:16
	ds_read_b128 v[146:149], v102 offset:32
	ds_read_b128 v[150:153], v102 offset:48
	ds_read2_b64 v[154:157], v7 offset0:64 offset1:80
	ds_read_b128 v[158:161], v83 offset:16896
	ds_read_b128 v[162:165], v83 offset:16912
	ds_read_b128 v[166:169], v83 offset:16928
	ds_read_b128 v[174:177], v83 offset:16944
	s_waitcnt lgkmcnt(4)
	v_pk_mul_f32 v[170:171], v[10:11], v[154:155]
	v_mul_f32_e32 v10, v10, v155
	v_sub_f32_e32 v9, v170, v171
	s_waitcnt lgkmcnt(3)
	v_mul_f32_e32 v9, v158, v9
	v_fmac_f32_e32 v10, v11, v154
	ds_read2_b64 v[178:181], v7 offset0:96 offset1:112
	v_fma_f32 v9, -v159, v10, v9
	v_pk_mul_f32 v[10:11], v[12:13], v[156:157]
	v_add_f32_e32 v9, 0, v9
	v_sub_f32_e32 v10, v10, v11
	v_mul_f32_e32 v11, v12, v157
	v_mul_f32_e32 v10, v160, v10
	v_fmac_f32_e32 v11, v13, v156
	v_fma_f32 v10, -v161, v11, v10
	v_add_f32_e32 v9, v9, v10
	s_waitcnt lgkmcnt(0)
	v_pk_mul_f32 v[10:11], v[14:15], v[178:179]
	s_nop 0
	v_sub_f32_e32 v10, v10, v11
	v_mul_f32_e32 v11, v14, v179
	v_mul_f32_e32 v10, v162, v10
	v_fmac_f32_e32 v11, v15, v178
	v_fma_f32 v10, -v163, v11, v10
	v_add_f32_e32 v9, v9, v10
	v_pk_mul_f32 v[10:11], v[16:17], v[180:181]
	v_mul_f32_e32 v15, v16, v181
	v_sub_f32_e32 v10, v10, v11
	v_mul_f32_e32 v14, v164, v10
	ds_read2_b64 v[10:13], v7 offset0:128 offset1:144
	v_fmac_f32_e32 v15, v17, v180
	v_fma_f32 v14, -v165, v15, v14
	v_add_f32_e32 v9, v9, v14
	s_waitcnt lgkmcnt(0)
	v_pk_mul_f32 v[14:15], v[146:147], v[10:11]
	s_nop 0
	v_sub_f32_e32 v14, v14, v15
	v_mul_f32_e32 v11, v146, v11
	v_mul_f32_e32 v14, v166, v14
	v_fmac_f32_e32 v11, v147, v10
	v_fma_f32 v10, -v167, v11, v14
	ds_read2_b64 v[14:17], v7 offset0:160 offset1:176
	v_add_f32_e32 v9, v9, v10
	v_pk_mul_f32 v[10:11], v[148:149], v[12:13]
	s_waitcnt lgkmcnt(0)
	v_mul_f32_e32 v79, v152, v17
	v_sub_f32_e32 v10, v10, v11
	v_mul_f32_e32 v11, v148, v13
	v_mul_f32_e32 v10, v168, v10
	v_fmac_f32_e32 v11, v149, v12
	v_fma_f32 v10, -v169, v11, v10
	v_add_f32_e32 v9, v9, v10
	v_pk_mul_f32 v[10:11], v[150:151], v[14:15]
	v_fmac_f32_e32 v79, v153, v16
	v_sub_f32_e32 v10, v10, v11
	v_mul_f32_e32 v11, v150, v15
	v_mul_f32_e32 v10, v174, v10
	v_fmac_f32_e32 v11, v151, v14
	v_fma_f32 v10, -v175, v11, v10
	v_add_f32_e32 v9, v9, v10
	v_pk_mul_f32 v[10:11], v[152:153], v[16:17]
	s_nop 0
	v_sub_f32_e32 v10, v10, v11
	v_mul_f32_e32 v20, v176, v10
	ds_read_b128 v[10:13], v102 offset:64
	ds_read2_b64 v[14:17], v7 offset0:192 offset1:208
	ds_read_b128 v[146:149], v83 offset:16960
	ds_read_b128 v[150:153], v102 offset:80
	v_fma_f32 v20, -v177, v79, v20
	v_add_f32_e32 v9, v9, v20
	ds_read2_b64 v[158:161], v7 offset0:224 offset1:240
	s_waitcnt lgkmcnt(3)
	v_pk_mul_f32 v[154:155], v[10:11], v[14:15]
	v_mul_f32_e32 v10, v10, v15
	v_sub_f32_e32 v20, v154, v155
	s_waitcnt lgkmcnt(2)
	v_mul_f32_e32 v20, v146, v20
	v_fmac_f32_e32 v10, v11, v14
	v_fma_f32 v10, -v147, v10, v20
	v_add_f32_e32 v9, v9, v10
	v_pk_mul_f32 v[10:11], v[12:13], v[16:17]
	ds_read_b128 v[154:157], v83 offset:16976
	v_sub_f32_e32 v10, v10, v11
	v_mul_f32_e32 v11, v12, v17
	v_mul_f32_e32 v10, v148, v10
	v_fmac_f32_e32 v11, v13, v16
	v_fma_f32 v10, -v149, v11, v10
	v_add_f32_e32 v9, v9, v10
	s_waitcnt lgkmcnt(1)
	v_pk_mul_f32 v[10:11], v[150:151], v[158:159]
	v_mul_f32_e32 v79, v152, v161
	v_sub_f32_e32 v10, v10, v11
	v_mul_f32_e32 v11, v150, v159
	s_waitcnt lgkmcnt(0)
	v_mul_f32_e32 v10, v154, v10
	v_fmac_f32_e32 v11, v151, v158
	v_fma_f32 v10, -v155, v11, v10
	v_add_f32_e32 v9, v9, v10
	v_pk_mul_f32 v[10:11], v[152:153], v[160:161]
	v_fmac_f32_e32 v79, v153, v160
	v_sub_f32_e32 v10, v10, v11
	v_mul_f32_e32 v20, v156, v10
	ds_read_b128 v[10:13], v102 offset:96
	ds_read2_b64 v[14:17], v5 offset1:16
	ds_read_b128 v[146:149], v83 offset:16992
	ds_read_b128 v[150:153], v102 offset:112
	v_fma_f32 v20, -v157, v79, v20
	v_add_f32_e32 v9, v9, v20
	ds_read2_b64 v[158:161], v5 offset0:32 offset1:48
	s_waitcnt lgkmcnt(3)
	v_pk_mul_f32 v[154:155], v[10:11], v[14:15]
	v_mul_f32_e32 v10, v10, v15
	v_sub_f32_e32 v20, v154, v155
	s_waitcnt lgkmcnt(2)
	v_mul_f32_e32 v20, v146, v20
	v_fmac_f32_e32 v10, v11, v14
	v_fma_f32 v10, -v147, v10, v20
	v_add_f32_e32 v9, v9, v10
	v_pk_mul_f32 v[10:11], v[12:13], v[16:17]
	ds_read_b128 v[154:157], v83 offset:17008
	v_sub_f32_e32 v10, v10, v11
	v_mul_f32_e32 v11, v12, v17
	v_mul_f32_e32 v10, v148, v10
	v_fmac_f32_e32 v11, v13, v16
	v_fma_f32 v10, -v149, v11, v10
	v_add_f32_e32 v9, v9, v10
	s_waitcnt lgkmcnt(1)
	v_pk_mul_f32 v[10:11], v[150:151], v[158:159]
	v_mul_f32_e32 v79, v152, v161
	v_sub_f32_e32 v10, v10, v11
	v_mul_f32_e32 v11, v150, v159
	s_waitcnt lgkmcnt(0)
	v_mul_f32_e32 v10, v154, v10
	v_fmac_f32_e32 v11, v151, v158
	v_fma_f32 v10, -v155, v11, v10
	v_add_f32_e32 v9, v9, v10
	v_pk_mul_f32 v[10:11], v[152:153], v[160:161]
	v_fmac_f32_e32 v79, v153, v160
	v_sub_f32_e32 v10, v10, v11
	v_mul_f32_e32 v20, v156, v10
	ds_read_b128 v[10:13], v102 offset:128
	ds_read2_b64 v[14:17], v5 offset0:64 offset1:80
	ds_read_b128 v[146:149], v83 offset:17024
	ds_read_b128 v[150:153], v102 offset:144
	v_fma_f32 v20, -v157, v79, v20
	v_add_f32_e32 v9, v9, v20
	ds_read2_b64 v[158:161], v5 offset0:96 offset1:112
	s_waitcnt lgkmcnt(3)
	v_pk_mul_f32 v[154:155], v[10:11], v[14:15]
	v_mul_f32_e32 v10, v10, v15
	v_sub_f32_e32 v20, v154, v155
	s_waitcnt lgkmcnt(2)
	v_mul_f32_e32 v20, v146, v20
	v_fmac_f32_e32 v10, v11, v14
	v_fma_f32 v10, -v147, v10, v20
	v_add_f32_e32 v9, v9, v10
	v_pk_mul_f32 v[10:11], v[12:13], v[16:17]
	ds_read_b128 v[154:157], v83 offset:17040
	v_sub_f32_e32 v10, v10, v11
	v_mul_f32_e32 v11, v12, v17
	v_mul_f32_e32 v10, v148, v10
	v_fmac_f32_e32 v11, v13, v16
	v_fma_f32 v10, -v149, v11, v10
	v_add_f32_e32 v9, v9, v10
	s_waitcnt lgkmcnt(1)
	v_pk_mul_f32 v[10:11], v[150:151], v[158:159]
	v_mul_f32_e32 v79, v152, v161
	v_sub_f32_e32 v10, v10, v11
	v_mul_f32_e32 v11, v150, v159
	s_waitcnt lgkmcnt(0)
	v_mul_f32_e32 v10, v154, v10
	v_fmac_f32_e32 v11, v151, v158
	v_fma_f32 v10, -v155, v11, v10
	v_add_f32_e32 v9, v9, v10
	v_pk_mul_f32 v[10:11], v[152:153], v[160:161]
	v_fmac_f32_e32 v79, v153, v160
	v_sub_f32_e32 v10, v10, v11
	v_mul_f32_e32 v20, v156, v10
	ds_read_b128 v[10:13], v102 offset:160
	ds_read2_b64 v[14:17], v5 offset0:128 offset1:144
	ds_read_b128 v[146:149], v83 offset:17056
	ds_read_b128 v[150:153], v102 offset:176
	v_fma_f32 v20, -v157, v79, v20
	v_add_f32_e32 v9, v9, v20
	ds_read2_b64 v[158:161], v5 offset0:160 offset1:176
	s_waitcnt lgkmcnt(3)
	v_pk_mul_f32 v[154:155], v[10:11], v[14:15]
	v_mul_f32_e32 v10, v10, v15
	v_sub_f32_e32 v20, v154, v155
	s_waitcnt lgkmcnt(2)
	v_mul_f32_e32 v20, v146, v20
	v_fmac_f32_e32 v10, v11, v14
	v_fma_f32 v10, -v147, v10, v20
	v_add_f32_e32 v9, v9, v10
	v_pk_mul_f32 v[10:11], v[12:13], v[16:17]
	ds_read_b128 v[154:157], v83 offset:17072
	v_sub_f32_e32 v10, v10, v11
	v_mul_f32_e32 v11, v12, v17
	v_mul_f32_e32 v10, v148, v10
	v_fmac_f32_e32 v11, v13, v16
	v_fma_f32 v10, -v149, v11, v10
	v_add_f32_e32 v9, v9, v10
	s_waitcnt lgkmcnt(1)
	v_pk_mul_f32 v[10:11], v[150:151], v[158:159]
	v_mul_f32_e32 v79, v152, v161
	v_sub_f32_e32 v10, v10, v11
	v_mul_f32_e32 v11, v150, v159
	s_waitcnt lgkmcnt(0)
	v_mul_f32_e32 v10, v154, v10
	v_fmac_f32_e32 v11, v151, v158
	v_fma_f32 v10, -v155, v11, v10
	v_add_f32_e32 v9, v9, v10
	v_pk_mul_f32 v[10:11], v[152:153], v[160:161]
	v_fmac_f32_e32 v79, v153, v160
	v_sub_f32_e32 v10, v10, v11
	v_mul_f32_e32 v20, v156, v10
	ds_read_b128 v[10:13], v102 offset:192
	ds_read2_b64 v[14:17], v5 offset0:192 offset1:208
	ds_read_b128 v[146:149], v83 offset:17088
	ds_read_b128 v[150:153], v102 offset:208
	v_fma_f32 v20, -v157, v79, v20
	v_add_f32_e32 v9, v9, v20
	ds_read2_b64 v[158:161], v5 offset0:224 offset1:240
	s_waitcnt lgkmcnt(3)
	v_pk_mul_f32 v[154:155], v[10:11], v[14:15]
	v_mul_f32_e32 v10, v10, v15
	v_sub_f32_e32 v20, v154, v155
	s_waitcnt lgkmcnt(2)
	v_mul_f32_e32 v20, v146, v20
	v_fmac_f32_e32 v10, v11, v14
	v_fma_f32 v10, -v147, v10, v20
	v_add_f32_e32 v9, v9, v10
	v_pk_mul_f32 v[10:11], v[12:13], v[16:17]
	ds_read_b128 v[154:157], v83 offset:17104
	v_sub_f32_e32 v10, v10, v11
	v_mul_f32_e32 v11, v12, v17
	v_mul_f32_e32 v10, v148, v10
	v_fmac_f32_e32 v11, v13, v16
	v_fma_f32 v10, -v149, v11, v10
	v_add_f32_e32 v9, v9, v10
	s_waitcnt lgkmcnt(1)
	v_pk_mul_f32 v[10:11], v[150:151], v[158:159]
	v_mul_f32_e32 v79, v152, v161
	v_sub_f32_e32 v10, v10, v11
	v_mul_f32_e32 v11, v150, v159
	s_waitcnt lgkmcnt(0)
	v_mul_f32_e32 v10, v154, v10
	v_fmac_f32_e32 v11, v151, v158
	v_fma_f32 v10, -v155, v11, v10
	v_add_f32_e32 v9, v9, v10
	v_pk_mul_f32 v[10:11], v[152:153], v[160:161]
	v_fmac_f32_e32 v79, v153, v160
	v_sub_f32_e32 v10, v10, v11
	v_mul_f32_e32 v20, v156, v10
	ds_read_b128 v[10:13], v102 offset:224
	ds_read2_b64 v[14:17], v6 offset1:16
	ds_read_b128 v[146:149], v83 offset:17120
	ds_read_b128 v[150:153], v102 offset:240
	v_fma_f32 v20, -v157, v79, v20
	v_add_f32_e32 v9, v9, v20
	ds_read2_b64 v[158:161], v6 offset0:32 offset1:48
	s_waitcnt lgkmcnt(3)
	v_pk_mul_f32 v[154:155], v[10:11], v[14:15]
	v_mul_f32_e32 v10, v10, v15
	v_sub_f32_e32 v20, v154, v155
	s_waitcnt lgkmcnt(2)
	v_mul_f32_e32 v20, v146, v20
	v_fmac_f32_e32 v10, v11, v14
	v_fma_f32 v10, -v147, v10, v20
	v_add_f32_e32 v9, v9, v10
	v_pk_mul_f32 v[10:11], v[12:13], v[16:17]
	ds_read_b128 v[154:157], v83 offset:17136
	v_sub_f32_e32 v10, v10, v11
	v_mul_f32_e32 v11, v12, v17
	v_mul_f32_e32 v10, v148, v10
	v_fmac_f32_e32 v11, v13, v16
	v_fma_f32 v10, -v149, v11, v10
	v_add_f32_e32 v9, v9, v10
	s_waitcnt lgkmcnt(1)
	v_pk_mul_f32 v[10:11], v[150:151], v[158:159]
	v_mul_f32_e32 v79, v152, v161
	v_sub_f32_e32 v10, v10, v11
	v_mul_f32_e32 v11, v150, v159
	s_waitcnt lgkmcnt(0)
	v_mul_f32_e32 v10, v154, v10
	v_fmac_f32_e32 v11, v151, v158
	v_fma_f32 v10, -v155, v11, v10
	v_add_f32_e32 v9, v9, v10
	v_pk_mul_f32 v[10:11], v[152:153], v[160:161]
	v_fmac_f32_e32 v79, v153, v160
	v_sub_f32_e32 v10, v10, v11
	v_mul_f32_e32 v20, v156, v10
	ds_read_b128 v[10:13], v102 offset:256
	ds_read2_b64 v[14:17], v6 offset0:64 offset1:80
	ds_read_b128 v[146:149], v83 offset:17152
	ds_read_b128 v[150:153], v102 offset:272
	v_fma_f32 v20, -v157, v79, v20
	v_add_f32_e32 v9, v9, v20
	ds_read2_b64 v[158:161], v6 offset0:96 offset1:112
	s_waitcnt lgkmcnt(3)
	v_pk_mul_f32 v[154:155], v[10:11], v[14:15]
	v_mul_f32_e32 v10, v10, v15
	v_sub_f32_e32 v20, v154, v155
	s_waitcnt lgkmcnt(2)
	v_mul_f32_e32 v20, v146, v20
	v_fmac_f32_e32 v10, v11, v14
	v_fma_f32 v10, -v147, v10, v20
	v_add_f32_e32 v9, v9, v10
	v_pk_mul_f32 v[10:11], v[12:13], v[16:17]
	ds_read_b128 v[154:157], v83 offset:17168
	v_sub_f32_e32 v10, v10, v11
	v_mul_f32_e32 v11, v12, v17
	v_mul_f32_e32 v10, v148, v10
	v_fmac_f32_e32 v11, v13, v16
	v_fma_f32 v10, -v149, v11, v10
	v_add_f32_e32 v9, v9, v10
	s_waitcnt lgkmcnt(1)
	v_pk_mul_f32 v[10:11], v[150:151], v[158:159]
	v_mul_f32_e32 v79, v152, v161
	v_sub_f32_e32 v10, v10, v11
	v_mul_f32_e32 v11, v150, v159
	s_waitcnt lgkmcnt(0)
	v_mul_f32_e32 v10, v154, v10
	v_fmac_f32_e32 v11, v151, v158
	v_fma_f32 v10, -v155, v11, v10
	v_add_f32_e32 v9, v9, v10
	v_pk_mul_f32 v[10:11], v[152:153], v[160:161]
	v_fmac_f32_e32 v79, v153, v160
	v_sub_f32_e32 v10, v10, v11
	v_mul_f32_e32 v20, v156, v10
	ds_read_b128 v[10:13], v102 offset:288
	ds_read2_b64 v[14:17], v6 offset0:128 offset1:144
	ds_read_b128 v[146:149], v83 offset:17184
	ds_read_b128 v[150:153], v102 offset:304
	v_fma_f32 v20, -v157, v79, v20
	v_add_f32_e32 v9, v9, v20
	ds_read2_b64 v[158:161], v6 offset0:160 offset1:176
	s_waitcnt lgkmcnt(3)
	v_pk_mul_f32 v[154:155], v[10:11], v[14:15]
	v_mul_f32_e32 v10, v10, v15
	v_sub_f32_e32 v20, v154, v155
	s_waitcnt lgkmcnt(2)
	v_mul_f32_e32 v20, v146, v20
	v_fmac_f32_e32 v10, v11, v14
	v_fma_f32 v10, -v147, v10, v20
	v_add_f32_e32 v9, v9, v10
	v_pk_mul_f32 v[10:11], v[12:13], v[16:17]
	ds_read_b128 v[154:157], v83 offset:17200
	v_sub_f32_e32 v10, v10, v11
	v_mul_f32_e32 v11, v12, v17
	v_mul_f32_e32 v10, v148, v10
	v_fmac_f32_e32 v11, v13, v16
	v_fma_f32 v10, -v149, v11, v10
	v_add_f32_e32 v9, v9, v10
	s_waitcnt lgkmcnt(1)
	v_pk_mul_f32 v[10:11], v[150:151], v[158:159]
	v_mul_f32_e32 v79, v152, v161
	v_sub_f32_e32 v10, v10, v11
	v_mul_f32_e32 v11, v150, v159
	s_waitcnt lgkmcnt(0)
	v_mul_f32_e32 v10, v154, v10
	v_fmac_f32_e32 v11, v151, v158
	v_fma_f32 v10, -v155, v11, v10
	v_add_f32_e32 v9, v9, v10
	v_pk_mul_f32 v[10:11], v[152:153], v[160:161]
	v_fmac_f32_e32 v79, v153, v160
	v_sub_f32_e32 v10, v10, v11
	v_mul_f32_e32 v20, v156, v10
	ds_read_b128 v[10:13], v102 offset:320
	ds_read2_b64 v[14:17], v6 offset0:192 offset1:208
	ds_read_b128 v[146:149], v83 offset:17216
	ds_read_b128 v[150:153], v102 offset:336
	v_fma_f32 v20, -v157, v79, v20
	v_add_f32_e32 v9, v9, v20
	ds_read2_b64 v[158:161], v6 offset0:224 offset1:240
	s_waitcnt lgkmcnt(3)
	v_pk_mul_f32 v[154:155], v[10:11], v[14:15]
	v_mul_f32_e32 v10, v10, v15
	v_sub_f32_e32 v20, v154, v155
	s_waitcnt lgkmcnt(2)
	v_mul_f32_e32 v20, v146, v20
	v_fmac_f32_e32 v10, v11, v14
	v_fma_f32 v10, -v147, v10, v20
	v_add_f32_e32 v9, v9, v10
	v_pk_mul_f32 v[10:11], v[12:13], v[16:17]
	ds_read_b128 v[154:157], v83 offset:17232
	v_sub_f32_e32 v10, v10, v11
	v_mul_f32_e32 v11, v12, v17
	v_mul_f32_e32 v10, v148, v10
	v_fmac_f32_e32 v11, v13, v16
	v_fma_f32 v10, -v149, v11, v10
	v_add_f32_e32 v9, v9, v10
	s_waitcnt lgkmcnt(1)
	v_pk_mul_f32 v[10:11], v[150:151], v[158:159]
	v_mul_f32_e32 v79, v152, v161
	v_sub_f32_e32 v10, v10, v11
	v_mul_f32_e32 v11, v150, v159
	s_waitcnt lgkmcnt(0)
	v_mul_f32_e32 v10, v154, v10
	v_fmac_f32_e32 v11, v151, v158
	v_fma_f32 v10, -v155, v11, v10
	v_add_f32_e32 v9, v9, v10
	v_pk_mul_f32 v[10:11], v[152:153], v[160:161]
	v_fmac_f32_e32 v79, v153, v160
	v_sub_f32_e32 v10, v10, v11
	v_mul_f32_e32 v20, v156, v10
	ds_read_b128 v[10:13], v102 offset:352
	ds_read2_b64 v[14:17], v4 offset1:16
	ds_read_b128 v[146:149], v83 offset:17248
	ds_read_b128 v[150:153], v102 offset:368
	v_fma_f32 v20, -v157, v79, v20
	v_add_f32_e32 v9, v9, v20
	ds_read2_b64 v[158:161], v4 offset0:32 offset1:48
	s_waitcnt lgkmcnt(3)
	v_pk_mul_f32 v[154:155], v[10:11], v[14:15]
	v_mul_f32_e32 v10, v10, v15
	v_sub_f32_e32 v20, v154, v155
	s_waitcnt lgkmcnt(2)
	v_mul_f32_e32 v20, v146, v20
	v_fmac_f32_e32 v10, v11, v14
	v_fma_f32 v10, -v147, v10, v20
	v_add_f32_e32 v9, v9, v10
	v_pk_mul_f32 v[10:11], v[12:13], v[16:17]
	ds_read_b128 v[154:157], v83 offset:17264
	v_sub_f32_e32 v10, v10, v11
	v_mul_f32_e32 v11, v12, v17
	v_mul_f32_e32 v10, v148, v10
	v_fmac_f32_e32 v11, v13, v16
	v_fma_f32 v10, -v149, v11, v10
	v_add_f32_e32 v9, v9, v10
	s_waitcnt lgkmcnt(1)
	v_pk_mul_f32 v[10:11], v[150:151], v[158:159]
	v_mul_f32_e32 v79, v152, v161
	v_sub_f32_e32 v10, v10, v11
	v_mul_f32_e32 v11, v150, v159
	s_waitcnt lgkmcnt(0)
	v_mul_f32_e32 v10, v154, v10
	v_fmac_f32_e32 v11, v151, v158
	v_fma_f32 v10, -v155, v11, v10
	v_add_f32_e32 v9, v9, v10
	v_pk_mul_f32 v[10:11], v[152:153], v[160:161]
	v_fmac_f32_e32 v79, v153, v160
	v_sub_f32_e32 v10, v10, v11
	v_mul_f32_e32 v20, v156, v10
	ds_read_b128 v[10:13], v102 offset:384
	ds_read2_b64 v[14:17], v4 offset0:64 offset1:80
	ds_read_b128 v[146:149], v83 offset:17280
	ds_read_b128 v[150:153], v102 offset:400
	v_fma_f32 v20, -v157, v79, v20
	v_add_f32_e32 v9, v9, v20
	ds_read2_b64 v[158:161], v4 offset0:96 offset1:112
	s_waitcnt lgkmcnt(3)
	v_pk_mul_f32 v[154:155], v[10:11], v[14:15]
	v_mul_f32_e32 v10, v10, v15
	v_sub_f32_e32 v20, v154, v155
	s_waitcnt lgkmcnt(2)
	v_mul_f32_e32 v20, v146, v20
	v_fmac_f32_e32 v10, v11, v14
	v_fma_f32 v10, -v147, v10, v20
	v_add_f32_e32 v9, v9, v10
	v_pk_mul_f32 v[10:11], v[12:13], v[16:17]
	ds_read_b128 v[154:157], v83 offset:17296
	v_sub_f32_e32 v10, v10, v11
	v_mul_f32_e32 v11, v12, v17
	v_mul_f32_e32 v10, v148, v10
	v_fmac_f32_e32 v11, v13, v16
	v_fma_f32 v10, -v149, v11, v10
	v_add_f32_e32 v9, v9, v10
	s_waitcnt lgkmcnt(1)
	v_pk_mul_f32 v[10:11], v[150:151], v[158:159]
	s_nop 0
	v_sub_f32_e32 v10, v10, v11
	v_mul_f32_e32 v11, v150, v159
	s_waitcnt lgkmcnt(0)
	v_mul_f32_e32 v10, v154, v10
	v_fmac_f32_e32 v11, v151, v158
	v_fma_f32 v10, -v155, v11, v10
	v_add_f32_e32 v9, v9, v10
	v_pk_mul_f32 v[10:11], v[152:153], v[160:161]
	s_nop 0
	v_sub_f32_e32 v10, v10, v11
	v_mul_f32_e32 v11, v152, v161
	v_mul_f32_e32 v10, v156, v10
	v_fmac_f32_e32 v11, v153, v160
	v_fma_f32 v14, -v157, v11, v10
	ds_read_b128 v[10:13], v102 offset:416
	v_add_f32_e32 v9, v9, v14
	ds_read2_b64 v[14:17], v4 offset0:128 offset1:144
	ds_read_b128 v[146:149], v83 offset:17312
	ds_read_b128 v[150:153], v102 offset:432
	s_waitcnt lgkmcnt(3)
	v_mov_b32_e32 v155, v12
	s_waitcnt lgkmcnt(2)
	v_mov_b32_e32 v157, v16
	v_mov_b32_e32 v12, v11
	v_mov_b32_e32 v16, v15
	v_mov_b32_e32 v154, v10
	v_mov_b32_e32 v156, v14
	v_pk_mul_f32 v[10:11], v[12:13], v[16:17]
	s_nop 0
	v_pk_fma_f32 v[14:15], v[154:155], v[156:157], v[10:11] neg_lo:[0,0,1] neg_hi:[0,0,1]
	v_pk_mul_f32 v[10:11], v[12:13], v[156:157]
	s_nop 0
	v_pk_fma_f32 v[16:17], v[154:155], v[16:17], v[10:11]
	s_waitcnt lgkmcnt(1)
	v_mov_b32_e32 v155, v148
	v_mov_b32_e32 v148, v147
	v_mov_b32_e32 v154, v146
	v_pk_mul_f32 v[16:17], v[148:149], v[16:17]
	ds_read_b128 v[10:13], v83 offset:17328
	v_pk_fma_f32 v[146:147], v[154:155], v[14:15], v[16:17] neg_lo:[0,0,1] neg_hi:[0,0,1]
	ds_read2_b64 v[14:17], v4 offset0:160 offset1:176
	v_add_f32_e32 v9, v9, v146
	v_add_f32_e32 v9, v9, v147
	s_waitcnt lgkmcnt(2)
	v_mov_b32_e32 v147, v152
	v_mov_b32_e32 v152, v151
	s_waitcnt lgkmcnt(0)
	v_mov_b32_e32 v149, v16
	v_mov_b32_e32 v16, v15
	v_mov_b32_e32 v146, v150
	v_mov_b32_e32 v148, v14
	v_pk_mul_f32 v[14:15], v[152:153], v[16:17]
	s_nop 0
	v_pk_fma_f32 v[14:15], v[146:147], v[148:149], v[14:15] neg_lo:[0,0,1] neg_hi:[0,0,1]
	v_pk_mul_f32 v[148:149], v[152:153], v[148:149]
	s_nop 0
	v_pk_fma_f32 v[16:17], v[146:147], v[16:17], v[148:149]
	v_mov_b32_e32 v147, v12
	v_mov_b32_e32 v12, v11
	v_mov_b32_e32 v146, v10
	v_pk_mul_f32 v[10:11], v[12:13], v[16:17]
	s_nop 0
	v_pk_fma_f32 v[14:15], v[146:147], v[14:15], v[10:11] neg_lo:[0,0,1] neg_hi:[0,0,1]
	ds_read_b128 v[10:13], v102 offset:448
	v_add_f32_e32 v9, v9, v14
	v_add_f32_e32 v9, v9, v15
	ds_read2_b64 v[14:17], v4 offset0:192 offset1:208
	ds_read_b128 v[146:149], v83 offset:17344
	ds_read_b128 v[150:153], v102 offset:464
	s_waitcnt lgkmcnt(3)
	v_mov_b32_e32 v155, v12
	s_waitcnt lgkmcnt(2)
	v_mov_b32_e32 v157, v16
	v_mov_b32_e32 v12, v11
	v_mov_b32_e32 v16, v15
	v_mov_b32_e32 v154, v10
	v_mov_b32_e32 v156, v14
	v_pk_mul_f32 v[10:11], v[12:13], v[16:17]
	s_nop 0
	v_pk_fma_f32 v[14:15], v[154:155], v[156:157], v[10:11] neg_lo:[0,0,1] neg_hi:[0,0,1]
	v_pk_mul_f32 v[10:11], v[12:13], v[156:157]
	s_nop 0
	v_pk_fma_f32 v[16:17], v[154:155], v[16:17], v[10:11]
	s_waitcnt lgkmcnt(1)
	v_mov_b32_e32 v155, v148
	v_mov_b32_e32 v148, v147
	v_mov_b32_e32 v154, v146
	v_pk_mul_f32 v[16:17], v[148:149], v[16:17]
	ds_read_b128 v[10:13], v83 offset:17360
	v_pk_fma_f32 v[146:147], v[154:155], v[14:15], v[16:17] neg_lo:[0,0,1] neg_hi:[0,0,1]
	ds_read2_b64 v[14:17], v4 offset0:224 offset1:240
	v_add_f32_e32 v9, v9, v146
	v_add_f32_e32 v9, v9, v147
	s_waitcnt lgkmcnt(2)
	v_mov_b32_e32 v147, v152
	v_mov_b32_e32 v152, v151
	s_waitcnt lgkmcnt(0)
	v_mov_b32_e32 v149, v16
	v_mov_b32_e32 v16, v15
	v_mov_b32_e32 v146, v150
	v_mov_b32_e32 v148, v14
	v_pk_mul_f32 v[14:15], v[152:153], v[16:17]
	s_nop 0
	v_pk_fma_f32 v[14:15], v[146:147], v[148:149], v[14:15] neg_lo:[0,0,1] neg_hi:[0,0,1]
	v_pk_mul_f32 v[148:149], v[152:153], v[148:149]
	s_nop 0
	v_pk_fma_f32 v[16:17], v[146:147], v[16:17], v[148:149]
	v_mov_b32_e32 v147, v12
	v_mov_b32_e32 v12, v11
	v_mov_b32_e32 v146, v10
	v_pk_mul_f32 v[10:11], v[12:13], v[16:17]
	s_nop 0
	v_pk_fma_f32 v[14:15], v[146:147], v[14:15], v[10:11] neg_lo:[0,0,1] neg_hi:[0,0,1]
	ds_read_b128 v[10:13], v102 offset:480
	v_add_f32_e32 v9, v9, v14
	v_add_f32_e32 v9, v9, v15
	ds_read2_b64 v[14:17], v8 offset1:16
	ds_read_b128 v[146:149], v83 offset:17376
	ds_read_b128 v[150:153], v102 offset:496
	s_waitcnt lgkmcnt(3)
	v_mov_b32_e32 v155, v12
	s_waitcnt lgkmcnt(2)
	v_mov_b32_e32 v157, v16
	v_mov_b32_e32 v12, v11
	v_mov_b32_e32 v16, v15
	v_mov_b32_e32 v154, v10
	v_mov_b32_e32 v156, v14
	v_pk_mul_f32 v[10:11], v[12:13], v[16:17]
	s_nop 0
	v_pk_fma_f32 v[14:15], v[154:155], v[156:157], v[10:11] neg_lo:[0,0,1] neg_hi:[0,0,1]
	v_pk_mul_f32 v[10:11], v[12:13], v[156:157]
	s_nop 0
	v_pk_fma_f32 v[16:17], v[154:155], v[16:17], v[10:11]
	s_waitcnt lgkmcnt(1)
	v_mov_b32_e32 v155, v148
	v_mov_b32_e32 v148, v147
	v_mov_b32_e32 v154, v146
	v_pk_mul_f32 v[16:17], v[148:149], v[16:17]
	ds_read_b128 v[10:13], v83 offset:17392
	v_pk_fma_f32 v[146:147], v[154:155], v[14:15], v[16:17] neg_lo:[0,0,1] neg_hi:[0,0,1]
	ds_read2_b64 v[14:17], v8 offset0:32 offset1:48
	v_add_f32_e32 v9, v9, v146
	v_add_f32_e32 v9, v9, v147
	s_waitcnt lgkmcnt(2)
	v_mov_b32_e32 v147, v152
	v_mov_b32_e32 v152, v151
	s_waitcnt lgkmcnt(0)
	v_mov_b32_e32 v149, v16
	v_mov_b32_e32 v16, v15
	v_mov_b32_e32 v146, v150
	v_mov_b32_e32 v148, v14
	v_pk_mul_f32 v[14:15], v[152:153], v[16:17]
	s_nop 0
	v_pk_fma_f32 v[14:15], v[146:147], v[148:149], v[14:15] neg_lo:[0,0,1] neg_hi:[0,0,1]
	v_pk_mul_f32 v[148:149], v[152:153], v[148:149]
	s_nop 0
	v_pk_fma_f32 v[16:17], v[146:147], v[16:17], v[148:149]
	v_mov_b32_e32 v147, v12
	v_mov_b32_e32 v12, v11
	v_mov_b32_e32 v146, v10
	v_pk_mul_f32 v[10:11], v[12:13], v[16:17]
	s_nop 0
	v_pk_fma_f32 v[10:11], v[146:147], v[14:15], v[10:11] neg_lo:[0,0,1] neg_hi:[0,0,1]
	s_nop 0
	v_add_f32_e32 v9, v9, v10
	v_add_f32_e32 v9, v9, v11
	s_and_saveexec_b64 s[68:69], s[76:77]
	s_cbranch_execz .LBB0_95
	global_load_dword v10, v[2:3], off nt
	s_waitcnt vmcnt(0)
	v_add_f32_e32 v9, v9, v10
.LBB0_95:
	s_or_b64 exec, exec, s[68:69]
	ds_write_b32 v116, v9 offset:37376
	ds_read_b128 v[10:13], v105
	ds_read_b128 v[14:17], v105 offset:16
	ds_read_b128 v[146:149], v105 offset:32
	ds_read_b128 v[150:153], v105 offset:48
	ds_read2_b64 v[154:157], v7 offset0:64 offset1:80
	ds_read_b128 v[158:161], v83 offset:16896
	ds_read_b128 v[162:165], v83 offset:16912
	ds_read_b128 v[166:169], v83 offset:16928
	ds_read_b128 v[174:177], v83 offset:16944
	s_waitcnt lgkmcnt(4)
	v_pk_mul_f32 v[170:171], v[10:11], v[154:155]
	v_mul_f32_e32 v10, v10, v155
	v_sub_f32_e32 v9, v170, v171
	s_waitcnt lgkmcnt(3)
	v_mul_f32_e32 v9, v158, v9
	v_fmac_f32_e32 v10, v11, v154
	ds_read2_b64 v[178:181], v7 offset0:96 offset1:112
	v_fma_f32 v9, -v159, v10, v9
	v_pk_mul_f32 v[10:11], v[12:13], v[156:157]
	v_add_f32_e32 v9, 0, v9
	v_sub_f32_e32 v10, v10, v11
	v_mul_f32_e32 v11, v12, v157
	v_mul_f32_e32 v10, v160, v10
	v_fmac_f32_e32 v11, v13, v156
	v_fma_f32 v10, -v161, v11, v10
	v_add_f32_e32 v9, v9, v10
	s_waitcnt lgkmcnt(0)
	v_pk_mul_f32 v[10:11], v[14:15], v[178:179]
	s_nop 0
	v_sub_f32_e32 v10, v10, v11
	v_mul_f32_e32 v11, v14, v179
	v_mul_f32_e32 v10, v162, v10
	v_fmac_f32_e32 v11, v15, v178
	v_fma_f32 v10, -v163, v11, v10
	v_add_f32_e32 v9, v9, v10
	v_pk_mul_f32 v[10:11], v[16:17], v[180:181]
	v_mul_f32_e32 v15, v16, v181
	v_sub_f32_e32 v10, v10, v11
	v_mul_f32_e32 v14, v164, v10
	ds_read2_b64 v[10:13], v7 offset0:128 offset1:144
	v_fmac_f32_e32 v15, v17, v180
	v_fma_f32 v14, -v165, v15, v14
	v_add_f32_e32 v9, v9, v14
	s_waitcnt lgkmcnt(0)
	v_pk_mul_f32 v[14:15], v[146:147], v[10:11]
	s_nop 0
	v_sub_f32_e32 v14, v14, v15
	v_mul_f32_e32 v11, v146, v11
	v_mul_f32_e32 v14, v166, v14
	v_fmac_f32_e32 v11, v147, v10
	v_fma_f32 v10, -v167, v11, v14
	ds_read2_b64 v[14:17], v7 offset0:160 offset1:176
	v_add_f32_e32 v9, v9, v10
	v_pk_mul_f32 v[10:11], v[148:149], v[12:13]
	s_waitcnt lgkmcnt(0)
	v_mul_f32_e32 v79, v152, v17
	v_sub_f32_e32 v10, v10, v11
	v_mul_f32_e32 v11, v148, v13
	v_mul_f32_e32 v10, v168, v10
	v_fmac_f32_e32 v11, v149, v12
	v_fma_f32 v10, -v169, v11, v10
	v_add_f32_e32 v9, v9, v10
	v_pk_mul_f32 v[10:11], v[150:151], v[14:15]
	v_fmac_f32_e32 v79, v153, v16
	v_sub_f32_e32 v10, v10, v11
	v_mul_f32_e32 v11, v150, v15
	v_mul_f32_e32 v10, v174, v10
	v_fmac_f32_e32 v11, v151, v14
	v_fma_f32 v10, -v175, v11, v10
	v_add_f32_e32 v9, v9, v10
	v_pk_mul_f32 v[10:11], v[152:153], v[16:17]
	s_nop 0
	v_sub_f32_e32 v10, v10, v11
	v_mul_f32_e32 v20, v176, v10
	ds_read_b128 v[10:13], v105 offset:64
	ds_read2_b64 v[14:17], v7 offset0:192 offset1:208
	ds_read_b128 v[146:149], v83 offset:16960
	ds_read_b128 v[150:153], v105 offset:80
	v_fma_f32 v20, -v177, v79, v20
	v_add_f32_e32 v9, v9, v20
	ds_read2_b64 v[158:161], v7 offset0:224 offset1:240
	s_waitcnt lgkmcnt(3)
	v_pk_mul_f32 v[154:155], v[10:11], v[14:15]
	v_mul_f32_e32 v10, v10, v15
	v_sub_f32_e32 v20, v154, v155
	s_waitcnt lgkmcnt(2)
	v_mul_f32_e32 v20, v146, v20
	v_fmac_f32_e32 v10, v11, v14
	v_fma_f32 v10, -v147, v10, v20
	ds_read_b128 v[154:157], v83 offset:16976
	v_add_f32_e32 v9, v9, v10
	v_pk_mul_f32 v[10:11], v[12:13], v[16:17]
	v_mul_f32_e32 v7, v12, v17
	v_sub_f32_e32 v10, v10, v11
	v_mul_f32_e32 v10, v148, v10
	v_fmac_f32_e32 v7, v13, v16
	v_fma_f32 v7, -v149, v7, v10
	s_waitcnt lgkmcnt(1)
	v_pk_mul_f32 v[10:11], v[150:151], v[158:159]
	v_add_f32_e32 v7, v9, v7
	v_sub_f32_e32 v9, v10, v11
	v_mul_f32_e32 v10, v150, v159
	s_waitcnt lgkmcnt(0)
	v_mul_f32_e32 v9, v154, v9
	v_fmac_f32_e32 v10, v151, v158
	v_fma_f32 v9, -v155, v10, v9
	v_pk_mul_f32 v[10:11], v[152:153], v[160:161]
	v_add_f32_e32 v7, v7, v9
	v_sub_f32_e32 v9, v10, v11
	ds_read_b128 v[10:13], v105 offset:96
	ds_read2_b64 v[14:17], v5 offset1:16
	v_mul_f32_e32 v20, v152, v161
	v_fmac_f32_e32 v20, v153, v160
	ds_read_b128 v[146:149], v83 offset:16992
	ds_read_b128 v[150:153], v105 offset:112
	v_mul_f32_e32 v9, v156, v9
	v_fma_f32 v9, -v157, v20, v9
	s_waitcnt lgkmcnt(2)
	v_pk_mul_f32 v[154:155], v[10:11], v[14:15]
	v_add_f32_e32 v7, v7, v9
	v_sub_f32_e32 v9, v154, v155
	v_mul_f32_e32 v10, v10, v15
	ds_read2_b64 v[158:161], v5 offset0:32 offset1:48
	s_waitcnt lgkmcnt(2)
	v_mul_f32_e32 v9, v146, v9
	v_fmac_f32_e32 v10, v11, v14
	ds_read_b128 v[154:157], v83 offset:17008
	v_fma_f32 v9, -v147, v10, v9
	v_pk_mul_f32 v[10:11], v[12:13], v[16:17]
	v_add_f32_e32 v7, v7, v9
	v_sub_f32_e32 v9, v10, v11
	v_mul_f32_e32 v10, v12, v17
	v_mul_f32_e32 v9, v148, v9
	v_fmac_f32_e32 v10, v13, v16
	v_fma_f32 v9, -v149, v10, v9
	s_waitcnt lgkmcnt(1)
	v_pk_mul_f32 v[10:11], v[150:151], v[158:159]
	v_add_f32_e32 v7, v7, v9
	v_sub_f32_e32 v9, v10, v11
	v_mul_f32_e32 v10, v150, v159
	s_waitcnt lgkmcnt(0)
	v_mul_f32_e32 v9, v154, v9
	v_fmac_f32_e32 v10, v151, v158
	v_fma_f32 v9, -v155, v10, v9
	v_pk_mul_f32 v[10:11], v[152:153], v[160:161]
	v_add_f32_e32 v7, v7, v9
	v_sub_f32_e32 v9, v10, v11
	ds_read_b128 v[10:13], v105 offset:128
	ds_read2_b64 v[14:17], v5 offset0:64 offset1:80
	v_mul_f32_e32 v20, v152, v161
	v_fmac_f32_e32 v20, v153, v160
	ds_read_b128 v[146:149], v83 offset:17024
	ds_read_b128 v[150:153], v105 offset:144
	v_mul_f32_e32 v9, v156, v9
	v_fma_f32 v9, -v157, v20, v9
	s_waitcnt lgkmcnt(2)
	v_pk_mul_f32 v[154:155], v[10:11], v[14:15]
	v_add_f32_e32 v7, v7, v9
	v_sub_f32_e32 v9, v154, v155
	v_mul_f32_e32 v10, v10, v15
	ds_read2_b64 v[158:161], v5 offset0:96 offset1:112
	s_waitcnt lgkmcnt(2)
	v_mul_f32_e32 v9, v146, v9
	v_fmac_f32_e32 v10, v11, v14
	ds_read_b128 v[154:157], v83 offset:17040
	v_fma_f32 v9, -v147, v10, v9
	v_pk_mul_f32 v[10:11], v[12:13], v[16:17]
	v_add_f32_e32 v7, v7, v9
	v_sub_f32_e32 v9, v10, v11
	v_mul_f32_e32 v10, v12, v17
	v_mul_f32_e32 v9, v148, v9
	v_fmac_f32_e32 v10, v13, v16
	v_fma_f32 v9, -v149, v10, v9
	s_waitcnt lgkmcnt(1)
	v_pk_mul_f32 v[10:11], v[150:151], v[158:159]
	v_add_f32_e32 v7, v7, v9
	v_sub_f32_e32 v9, v10, v11
	v_mul_f32_e32 v10, v150, v159
	s_waitcnt lgkmcnt(0)
	v_mul_f32_e32 v9, v154, v9
	v_fmac_f32_e32 v10, v151, v158
	v_fma_f32 v9, -v155, v10, v9
	v_pk_mul_f32 v[10:11], v[152:153], v[160:161]
	v_add_f32_e32 v7, v7, v9
	v_sub_f32_e32 v9, v10, v11
	ds_read_b128 v[10:13], v105 offset:160
	ds_read2_b64 v[14:17], v5 offset0:128 offset1:144
	v_mul_f32_e32 v20, v152, v161
	v_fmac_f32_e32 v20, v153, v160
	ds_read_b128 v[146:149], v83 offset:17056
	ds_read_b128 v[150:153], v105 offset:176
	v_mul_f32_e32 v9, v156, v9
	v_fma_f32 v9, -v157, v20, v9
	s_waitcnt lgkmcnt(2)
	v_pk_mul_f32 v[154:155], v[10:11], v[14:15]
	v_add_f32_e32 v7, v7, v9
	v_sub_f32_e32 v9, v154, v155
	v_mul_f32_e32 v10, v10, v15
	ds_read2_b64 v[158:161], v5 offset0:160 offset1:176
	s_waitcnt lgkmcnt(2)
	v_mul_f32_e32 v9, v146, v9
	v_fmac_f32_e32 v10, v11, v14
	ds_read_b128 v[154:157], v83 offset:17072
	v_fma_f32 v9, -v147, v10, v9
	v_pk_mul_f32 v[10:11], v[12:13], v[16:17]
	v_add_f32_e32 v7, v7, v9
	v_sub_f32_e32 v9, v10, v11
	v_mul_f32_e32 v10, v12, v17
	v_mul_f32_e32 v9, v148, v9
	v_fmac_f32_e32 v10, v13, v16
	v_fma_f32 v9, -v149, v10, v9
	s_waitcnt lgkmcnt(1)
	v_pk_mul_f32 v[10:11], v[150:151], v[158:159]
	v_add_f32_e32 v7, v7, v9
	v_sub_f32_e32 v9, v10, v11
	v_mul_f32_e32 v10, v150, v159
	s_waitcnt lgkmcnt(0)
	v_mul_f32_e32 v9, v154, v9
	v_fmac_f32_e32 v10, v151, v158
	v_fma_f32 v9, -v155, v10, v9
	v_pk_mul_f32 v[10:11], v[152:153], v[160:161]
	v_add_f32_e32 v7, v7, v9
	v_sub_f32_e32 v9, v10, v11
	ds_read_b128 v[10:13], v105 offset:192
	ds_read2_b64 v[14:17], v5 offset0:192 offset1:208
	v_mul_f32_e32 v20, v152, v161
	v_fmac_f32_e32 v20, v153, v160
	ds_read_b128 v[146:149], v83 offset:17088
	ds_read_b128 v[150:153], v105 offset:208
	v_mul_f32_e32 v9, v156, v9
	v_fma_f32 v9, -v157, v20, v9
	s_waitcnt lgkmcnt(2)
	v_pk_mul_f32 v[154:155], v[10:11], v[14:15]
	v_add_f32_e32 v7, v7, v9
	v_sub_f32_e32 v9, v154, v155
	v_mul_f32_e32 v10, v10, v15
	ds_read2_b64 v[158:161], v5 offset0:224 offset1:240
	s_waitcnt lgkmcnt(2)
	v_mul_f32_e32 v9, v146, v9
	v_fmac_f32_e32 v10, v11, v14
	ds_read_b128 v[154:157], v83 offset:17104
	v_fma_f32 v9, -v147, v10, v9
	v_pk_mul_f32 v[10:11], v[12:13], v[16:17]
	v_add_f32_e32 v7, v7, v9
	v_sub_f32_e32 v9, v10, v11
	v_mul_f32_e32 v5, v12, v17
	v_mul_f32_e32 v9, v148, v9
	v_fmac_f32_e32 v5, v13, v16
	v_fma_f32 v5, -v149, v5, v9
	s_waitcnt lgkmcnt(1)
	v_pk_mul_f32 v[10:11], v[150:151], v[158:159]
	v_add_f32_e32 v5, v7, v5
	v_sub_f32_e32 v7, v10, v11
	v_mul_f32_e32 v9, v150, v159
	s_waitcnt lgkmcnt(0)
	v_mul_f32_e32 v7, v154, v7
	v_fmac_f32_e32 v9, v151, v158
	v_fma_f32 v7, -v155, v9, v7
	v_pk_mul_f32 v[10:11], v[152:153], v[160:161]
	v_add_f32_e32 v5, v5, v7
	v_sub_f32_e32 v7, v10, v11
	ds_read_b128 v[10:13], v105 offset:224
	ds_read2_b64 v[14:17], v6 offset1:16
	v_mul_f32_e32 v9, v152, v161
	v_fmac_f32_e32 v9, v153, v160
	ds_read_b128 v[146:149], v83 offset:17120
	ds_read_b128 v[150:153], v105 offset:240
	v_mul_f32_e32 v7, v156, v7
	v_fma_f32 v7, -v157, v9, v7
	s_waitcnt lgkmcnt(2)
	v_pk_mul_f32 v[154:155], v[10:11], v[14:15]
	v_add_f32_e32 v5, v5, v7
	v_sub_f32_e32 v7, v154, v155
	v_mul_f32_e32 v9, v10, v15
	ds_read2_b64 v[158:161], v6 offset0:32 offset1:48
	s_waitcnt lgkmcnt(2)
	v_mul_f32_e32 v7, v146, v7
	v_fmac_f32_e32 v9, v11, v14
	ds_read_b128 v[154:157], v83 offset:17136
	v_fma_f32 v7, -v147, v9, v7
	v_pk_mul_f32 v[10:11], v[12:13], v[16:17]
	v_add_f32_e32 v5, v5, v7
	v_sub_f32_e32 v7, v10, v11
	v_mul_f32_e32 v9, v12, v17
	v_mul_f32_e32 v7, v148, v7
	v_fmac_f32_e32 v9, v13, v16
	v_fma_f32 v7, -v149, v9, v7
	s_waitcnt lgkmcnt(1)
	v_pk_mul_f32 v[10:11], v[150:151], v[158:159]
	v_add_f32_e32 v5, v5, v7
	v_sub_f32_e32 v7, v10, v11
	v_mul_f32_e32 v9, v150, v159
	s_waitcnt lgkmcnt(0)
	v_mul_f32_e32 v7, v154, v7
	v_fmac_f32_e32 v9, v151, v158
	v_fma_f32 v7, -v155, v9, v7
	v_pk_mul_f32 v[10:11], v[152:153], v[160:161]
	v_add_f32_e32 v5, v5, v7
	v_sub_f32_e32 v7, v10, v11
	ds_read_b128 v[10:13], v105 offset:256
	ds_read2_b64 v[14:17], v6 offset0:64 offset1:80
	v_mul_f32_e32 v9, v152, v161
	v_fmac_f32_e32 v9, v153, v160
	ds_read_b128 v[146:149], v83 offset:17152
	ds_read_b128 v[150:153], v105 offset:272
	v_mul_f32_e32 v7, v156, v7
	v_fma_f32 v7, -v157, v9, v7
	s_waitcnt lgkmcnt(2)
	v_pk_mul_f32 v[154:155], v[10:11], v[14:15]
	v_add_f32_e32 v5, v5, v7
	v_sub_f32_e32 v7, v154, v155
	v_mul_f32_e32 v9, v10, v15
	ds_read2_b64 v[158:161], v6 offset0:96 offset1:112
	s_waitcnt lgkmcnt(2)
	v_mul_f32_e32 v7, v146, v7
	v_fmac_f32_e32 v9, v11, v14
	ds_read_b128 v[154:157], v83 offset:17168
	v_fma_f32 v7, -v147, v9, v7
	v_pk_mul_f32 v[10:11], v[12:13], v[16:17]
	v_add_f32_e32 v5, v5, v7
	v_sub_f32_e32 v7, v10, v11
	v_mul_f32_e32 v9, v12, v17
	v_mul_f32_e32 v7, v148, v7
	v_fmac_f32_e32 v9, v13, v16
	v_fma_f32 v7, -v149, v9, v7
	s_waitcnt lgkmcnt(1)
	v_pk_mul_f32 v[10:11], v[150:151], v[158:159]
	v_add_f32_e32 v5, v5, v7
	v_sub_f32_e32 v7, v10, v11
	v_mul_f32_e32 v9, v150, v159
	s_waitcnt lgkmcnt(0)
	v_mul_f32_e32 v7, v154, v7
	v_fmac_f32_e32 v9, v151, v158
	v_fma_f32 v7, -v155, v9, v7
	v_pk_mul_f32 v[10:11], v[152:153], v[160:161]
	v_add_f32_e32 v5, v5, v7
	v_sub_f32_e32 v7, v10, v11
	ds_read_b128 v[10:13], v105 offset:288
	ds_read2_b64 v[14:17], v6 offset0:128 offset1:144
	v_mul_f32_e32 v9, v152, v161
	v_fmac_f32_e32 v9, v153, v160
	ds_read_b128 v[146:149], v83 offset:17184
	ds_read_b128 v[150:153], v105 offset:304
	v_mul_f32_e32 v7, v156, v7
	v_fma_f32 v7, -v157, v9, v7
	s_waitcnt lgkmcnt(2)
	v_pk_mul_f32 v[154:155], v[10:11], v[14:15]
	v_add_f32_e32 v5, v5, v7
	v_sub_f32_e32 v7, v154, v155
	v_mul_f32_e32 v9, v10, v15
	ds_read2_b64 v[158:161], v6 offset0:160 offset1:176
	s_waitcnt lgkmcnt(2)
	v_mul_f32_e32 v7, v146, v7
	v_fmac_f32_e32 v9, v11, v14
	ds_read_b128 v[154:157], v83 offset:17200
	v_fma_f32 v7, -v147, v9, v7
	v_pk_mul_f32 v[10:11], v[12:13], v[16:17]
	v_add_f32_e32 v5, v5, v7
	v_sub_f32_e32 v7, v10, v11
	v_mul_f32_e32 v9, v12, v17
	v_mul_f32_e32 v7, v148, v7
	v_fmac_f32_e32 v9, v13, v16
	v_fma_f32 v7, -v149, v9, v7
	s_waitcnt lgkmcnt(1)
	v_pk_mul_f32 v[10:11], v[150:151], v[158:159]
	v_add_f32_e32 v5, v5, v7
	v_sub_f32_e32 v7, v10, v11
	v_mul_f32_e32 v9, v150, v159
	s_waitcnt lgkmcnt(0)
	v_mul_f32_e32 v7, v154, v7
	v_fmac_f32_e32 v9, v151, v158
	v_fma_f32 v7, -v155, v9, v7
	v_pk_mul_f32 v[10:11], v[152:153], v[160:161]
	v_add_f32_e32 v5, v5, v7
	v_sub_f32_e32 v7, v10, v11
	ds_read_b128 v[10:13], v105 offset:320
	ds_read2_b64 v[14:17], v6 offset0:192 offset1:208
	v_mul_f32_e32 v9, v152, v161
	v_fmac_f32_e32 v9, v153, v160
	ds_read_b128 v[146:149], v83 offset:17216
	ds_read_b128 v[150:153], v105 offset:336
	v_mul_f32_e32 v7, v156, v7
	v_fma_f32 v7, -v157, v9, v7
	s_waitcnt lgkmcnt(2)
	v_pk_mul_f32 v[154:155], v[10:11], v[14:15]
	v_add_f32_e32 v5, v5, v7
	v_sub_f32_e32 v7, v154, v155
	v_mul_f32_e32 v9, v10, v15
	s_waitcnt lgkmcnt(1)
	v_mul_f32_e32 v7, v146, v7
	v_fmac_f32_e32 v9, v11, v14
	ds_read2_b64 v[158:161], v6 offset0:224 offset1:240
	v_fma_f32 v7, -v147, v9, v7
	v_pk_mul_f32 v[10:11], v[12:13], v[16:17]
	ds_read_b128 v[154:157], v83 offset:17232
	v_add_f32_e32 v5, v5, v7
	v_sub_f32_e32 v7, v10, v11
	v_mul_f32_e32 v6, v12, v17
	v_mul_f32_e32 v7, v148, v7
	v_fmac_f32_e32 v6, v13, v16
	v_fma_f32 v6, -v149, v6, v7
	v_add_f32_e32 v5, v5, v6
	s_waitcnt lgkmcnt(1)
	v_pk_mul_f32 v[6:7], v[150:151], v[158:159]
	ds_read_b128 v[10:13], v105 offset:352
	ds_read2_b64 v[14:17], v4 offset1:16
	v_sub_f32_e32 v6, v6, v7
	v_mul_f32_e32 v7, v150, v159
	s_waitcnt lgkmcnt(2)
	v_mul_f32_e32 v6, v154, v6
	v_fmac_f32_e32 v7, v151, v158
	v_fma_f32 v6, -v155, v7, v6
	v_add_f32_e32 v5, v5, v6
	v_pk_mul_f32 v[6:7], v[152:153], v[160:161]
	s_nop 0
	v_sub_f32_e32 v6, v6, v7
	v_mul_f32_e32 v7, v152, v161
	v_mul_f32_e32 v6, v156, v6
	v_fmac_f32_e32 v7, v153, v160
	ds_read_b128 v[146:149], v83 offset:17248
	ds_read_b128 v[150:153], v105 offset:368
	v_fma_f32 v6, -v157, v7, v6
	v_add_f32_e32 v5, v5, v6
	s_waitcnt lgkmcnt(2)
	v_pk_mul_f32 v[6:7], v[10:11], v[14:15]
	ds_read2_b64 v[158:161], v4 offset0:32 offset1:48
	v_sub_f32_e32 v6, v6, v7
	v_mul_f32_e32 v7, v10, v15
	s_waitcnt lgkmcnt(2)
	v_mul_f32_e32 v6, v146, v6
	v_fmac_f32_e32 v7, v11, v14
	v_fma_f32 v6, -v147, v7, v6
	v_add_f32_e32 v5, v5, v6
	v_pk_mul_f32 v[6:7], v[12:13], v[16:17]
	ds_read_b128 v[154:157], v83 offset:17264
	v_sub_f32_e32 v6, v6, v7
	v_mul_f32_e32 v7, v12, v17
	v_mul_f32_e32 v6, v148, v6
	v_fmac_f32_e32 v7, v13, v16
	v_fma_f32 v6, -v149, v7, v6
	v_add_f32_e32 v5, v5, v6
	s_waitcnt lgkmcnt(1)
	v_pk_mul_f32 v[6:7], v[150:151], v[158:159]
	ds_read_b128 v[10:13], v105 offset:384
	ds_read2_b64 v[14:17], v4 offset0:64 offset1:80
	v_sub_f32_e32 v6, v6, v7
	v_mul_f32_e32 v7, v150, v159
	s_waitcnt lgkmcnt(2)
	v_mul_f32_e32 v6, v154, v6
	v_fmac_f32_e32 v7, v151, v158
	v_fma_f32 v6, -v155, v7, v6
	v_add_f32_e32 v5, v5, v6
	v_pk_mul_f32 v[6:7], v[152:153], v[160:161]
	s_nop 0
	v_sub_f32_e32 v6, v6, v7
	v_mul_f32_e32 v7, v152, v161
	v_mul_f32_e32 v6, v156, v6
	v_fmac_f32_e32 v7, v153, v160
	ds_read_b128 v[146:149], v83 offset:17280
	ds_read_b128 v[150:153], v105 offset:400
	v_fma_f32 v6, -v157, v7, v6
	v_add_f32_e32 v5, v5, v6
	s_waitcnt lgkmcnt(2)
	v_pk_mul_f32 v[6:7], v[10:11], v[14:15]
	ds_read2_b64 v[158:161], v4 offset0:96 offset1:112
	v_sub_f32_e32 v6, v6, v7
	v_mul_f32_e32 v7, v10, v15
	s_waitcnt lgkmcnt(2)
	v_mul_f32_e32 v6, v146, v6
	v_fmac_f32_e32 v7, v11, v14
	v_fma_f32 v6, -v147, v7, v6
	v_add_f32_e32 v5, v5, v6
	v_pk_mul_f32 v[6:7], v[12:13], v[16:17]
	ds_read_b128 v[154:157], v83 offset:17296
	v_sub_f32_e32 v6, v6, v7
	v_mul_f32_e32 v7, v12, v17
	v_mul_f32_e32 v6, v148, v6
	v_fmac_f32_e32 v7, v13, v16
	v_fma_f32 v6, -v149, v7, v6
	v_add_f32_e32 v5, v5, v6
	s_waitcnt lgkmcnt(1)
	v_pk_mul_f32 v[6:7], v[150:151], v[158:159]
	ds_read_b128 v[10:13], v105 offset:416
	v_sub_f32_e32 v6, v6, v7
	v_mul_f32_e32 v7, v150, v159
	s_waitcnt lgkmcnt(1)
	v_mul_f32_e32 v6, v154, v6
	v_fmac_f32_e32 v7, v151, v158
	v_fma_f32 v6, -v155, v7, v6
	v_add_f32_e32 v5, v5, v6
	v_pk_mul_f32 v[6:7], v[152:153], v[160:161]
	s_nop 0
	v_sub_f32_e32 v6, v6, v7
	v_mul_f32_e32 v7, v152, v161
	v_fmac_f32_e32 v7, v153, v160
	ds_read2_b64 v[14:17], v4 offset0:128 offset1:144
	ds_read_b128 v[146:149], v83 offset:17312
	ds_read_b128 v[150:153], v105 offset:432
	v_mul_f32_e32 v6, v156, v6
	v_fma_f32 v6, -v157, v7, v6
	s_waitcnt lgkmcnt(3)
	v_mov_b32_e32 v7, v12
	s_waitcnt lgkmcnt(2)
	v_mov_b32_e32 v155, v16
	v_mov_b32_e32 v12, v11
	v_mov_b32_e32 v16, v15
	v_add_f32_e32 v5, v5, v6
	v_mov_b32_e32 v6, v10
	v_mov_b32_e32 v154, v14
	v_pk_mul_f32 v[10:11], v[12:13], v[16:17]
	s_nop 0
	v_pk_fma_f32 v[14:15], v[6:7], v[154:155], v[10:11] neg_lo:[0,0,1] neg_hi:[0,0,1]
	v_pk_mul_f32 v[10:11], v[12:13], v[154:155]
	s_nop 0
	v_pk_fma_f32 v[6:7], v[6:7], v[16:17], v[10:11]
	s_waitcnt lgkmcnt(1)
	v_mov_b32_e32 v17, v148
	v_mov_b32_e32 v148, v147
	v_mov_b32_e32 v16, v146
	v_pk_mul_f32 v[6:7], v[148:149], v[6:7]
	ds_read_b128 v[10:13], v83 offset:17328
	v_pk_fma_f32 v[6:7], v[16:17], v[14:15], v[6:7] neg_lo:[0,0,1] neg_hi:[0,0,1]
	ds_read2_b64 v[14:17], v4 offset0:160 offset1:176
	v_add_f32_e32 v5, v5, v6
	v_add_f32_e32 v5, v5, v7
	s_waitcnt lgkmcnt(2)
	v_mov_b32_e32 v7, v152
	v_mov_b32_e32 v152, v151
	s_waitcnt lgkmcnt(0)
	v_mov_b32_e32 v147, v16
	v_mov_b32_e32 v16, v15
	v_mov_b32_e32 v6, v150
	v_mov_b32_e32 v146, v14
	v_pk_mul_f32 v[14:15], v[152:153], v[16:17]
	s_nop 0
	v_pk_fma_f32 v[14:15], v[6:7], v[146:147], v[14:15] neg_lo:[0,0,1] neg_hi:[0,0,1]
	v_pk_mul_f32 v[146:147], v[152:153], v[146:147]
	s_nop 0
	v_pk_fma_f32 v[6:7], v[6:7], v[16:17], v[146:147]
	v_mov_b32_e32 v17, v12
	v_mov_b32_e32 v12, v11
	v_mov_b32_e32 v16, v10
	v_pk_mul_f32 v[6:7], v[12:13], v[6:7]
	ds_read_b128 v[10:13], v105 offset:448
	v_pk_fma_f32 v[6:7], v[16:17], v[14:15], v[6:7] neg_lo:[0,0,1] neg_hi:[0,0,1]
	ds_read2_b64 v[14:17], v4 offset0:192 offset1:208
	ds_read_b128 v[146:149], v83 offset:17344
	ds_read_b128 v[150:153], v105 offset:464
	v_add_f32_e32 v5, v5, v6
	v_add_f32_e32 v9, v5, v7
	s_waitcnt lgkmcnt(3)
	v_mov_b32_e32 v7, v12
	s_waitcnt lgkmcnt(2)
	v_mov_b32_e32 v155, v16
	v_mov_b32_e32 v12, v11
	v_mov_b32_e32 v16, v15
	v_mov_b32_e32 v6, v10
	v_mov_b32_e32 v154, v14
	v_pk_mul_f32 v[10:11], v[12:13], v[16:17]
	s_nop 0
	v_pk_fma_f32 v[14:15], v[6:7], v[154:155], v[10:11] neg_lo:[0,0,1] neg_hi:[0,0,1]
	v_pk_mul_f32 v[10:11], v[12:13], v[154:155]
	s_nop 0
	v_pk_fma_f32 v[6:7], v[6:7], v[16:17], v[10:11]
	s_waitcnt lgkmcnt(1)
	v_mov_b32_e32 v17, v148
	v_mov_b32_e32 v148, v147
	v_mov_b32_e32 v16, v146
	v_pk_mul_f32 v[6:7], v[148:149], v[6:7]
	ds_read_b128 v[10:13], v83 offset:17360
	v_pk_fma_f32 v[14:15], v[16:17], v[14:15], v[6:7] neg_lo:[0,0,1] neg_hi:[0,0,1]
	ds_read2_b64 v[4:7], v4 offset0:224 offset1:240
	v_add_f32_e32 v9, v9, v14
	v_add_f32_e32 v9, v9, v15
	s_waitcnt lgkmcnt(2)
	v_mov_b32_e32 v15, v152
	v_mov_b32_e32 v152, v151
	s_waitcnt lgkmcnt(0)
	v_mov_b32_e32 v17, v6
	v_mov_b32_e32 v6, v5
	v_mov_b32_e32 v14, v150
	v_mov_b32_e32 v16, v4
	v_pk_mul_f32 v[4:5], v[152:153], v[6:7]
	s_nop 0
	v_pk_fma_f32 v[4:5], v[14:15], v[16:17], v[4:5] neg_lo:[0,0,1] neg_hi:[0,0,1]
	v_pk_mul_f32 v[16:17], v[152:153], v[16:17]
	s_nop 0
	v_pk_fma_f32 v[6:7], v[14:15], v[6:7], v[16:17]
	v_mov_b32_e32 v15, v12
	v_mov_b32_e32 v12, v11
	v_mov_b32_e32 v14, v10
	v_pk_mul_f32 v[6:7], v[12:13], v[6:7]
	s_nop 0
	v_pk_fma_f32 v[10:11], v[14:15], v[4:5], v[6:7] neg_lo:[0,0,1] neg_hi:[0,0,1]
	ds_read_b128 v[4:7], v105 offset:480
	v_add_f32_e32 v9, v9, v10
	v_add_f32_e32 v20, v9, v11
	ds_read2_b64 v[10:13], v8 offset1:16
	ds_read_b128 v[14:17], v83 offset:17376
	ds_read_b128 v[146:149], v105 offset:496
	s_waitcnt lgkmcnt(3)
	v_mov_b32_e32 v151, v6
	s_waitcnt lgkmcnt(2)
	v_mov_b32_e32 v153, v12
	v_mov_b32_e32 v6, v5
	v_mov_b32_e32 v12, v11
	v_mov_b32_e32 v150, v4
	v_mov_b32_e32 v152, v10
	v_pk_mul_f32 v[4:5], v[6:7], v[12:13]
	s_nop 0
	v_pk_fma_f32 v[10:11], v[150:151], v[152:153], v[4:5] neg_lo:[0,0,1] neg_hi:[0,0,1]
	v_pk_mul_f32 v[4:5], v[6:7], v[152:153]
	s_nop 0
	v_pk_fma_f32 v[12:13], v[150:151], v[12:13], v[4:5]
	s_waitcnt lgkmcnt(1)
	v_mov_b32_e32 v151, v16
	v_mov_b32_e32 v16, v15
	v_mov_b32_e32 v150, v14
	v_pk_mul_f32 v[12:13], v[16:17], v[12:13]
	ds_read_b128 v[4:7], v83 offset:17392
	v_pk_fma_f32 v[12:13], v[150:151], v[10:11], v[12:13] neg_lo:[0,0,1] neg_hi:[0,0,1]
	ds_read2_b64 v[8:11], v8 offset0:32 offset1:48
	v_add_f32_e32 v12, v20, v12
	v_add_f32_e32 v16, v12, v13
	s_waitcnt lgkmcnt(2)
	v_mov_b32_e32 v13, v148
	v_mov_b32_e32 v148, v147
	s_waitcnt lgkmcnt(0)
	v_mov_b32_e32 v15, v10
	v_mov_b32_e32 v10, v9
	v_mov_b32_e32 v12, v146
	v_mov_b32_e32 v14, v8
	v_pk_mul_f32 v[8:9], v[148:149], v[10:11]
	s_nop 0
	v_pk_fma_f32 v[8:9], v[12:13], v[14:15], v[8:9] neg_lo:[0,0,1] neg_hi:[0,0,1]
	v_pk_mul_f32 v[14:15], v[148:149], v[14:15]
	s_nop 0
	v_pk_fma_f32 v[10:11], v[12:13], v[10:11], v[14:15]
	v_mov_b32_e32 v13, v6
	v_mov_b32_e32 v6, v5
	v_mov_b32_e32 v12, v4
	v_pk_mul_f32 v[4:5], v[6:7], v[10:11]
	s_nop 0
	v_pk_fma_f32 v[4:5], v[12:13], v[8:9], v[4:5] neg_lo:[0,0,1] neg_hi:[0,0,1]
	s_nop 0
	v_add_f32_e32 v4, v16, v4
	v_add_f32_e32 v4, v4, v5
	s_and_saveexec_b64 s[68:69], s[0:1]
	s_cbranch_execz .LBB0_97
	global_load_dword v2, v[2:3], off nt
	s_waitcnt vmcnt(0)
	v_add_f32_e32 v4, v4, v2

.LBB0_409:
	s_and_b64 vcc, exec, s[0:1]
	s_cbranch_vccz .LBB0_421
	v_lshrrev_b32_e32 v1, 20, v0
	v_lshrrev_b32_e32 v0, 10, v0
	v_or_b32_e32 v0, v0, v1
	s_movk_i32 s0, 0x3ff
	v_and_or_b32 v0, v0, s0, v173
	v_cmp_eq_u32_e32 vcc, 0, v0
	s_barrier
	s_and_saveexec_b64 s[0:1], vcc
	s_cbranch_execz .LBB0_420
	v_readlane_b32 s4, v247, 2
	v_readlane_b32 s5, v247, 3
	buffer_wbl2 sc1
	s_waitcnt vmcnt(0)
	s_load_dwordx2 s[4:5], s[4:5], 0x58
	v_mov_b32_e32 v2, 0
	s_mov_b64 s[6:7], exec
	v_mbcnt_lo_u32_b32 v1, s6, 0
	v_mbcnt_hi_u32_b32 v1, s7, v1
	s_waitcnt lgkmcnt(0)
	global_load_dword v0, v2, s[4:5] offset:40 nt
	v_cmp_eq_u32_e32 vcc, 0, v1
	s_and_saveexec_b64 s[8:9], vcc
	s_cbranch_execz .LBB0_413
	s_bcnt1_i32_b64 s3, s[6:7]
	v_mov_b32_e32 v3, s3
	global_atomic_add v3, v2, v3, s[4:5] offset:32 sc0
